# v7 + GEMM K-loop barrier hand-off: s_barrier right after last MFMA of a segment, s_setprio 1 before the barrier, one lgkmcnt(0) wait after it
# speedup vs baseline: 1.0127x; 1.0034x over previous
.LBB0_117:
	s_add_u32 s20, s18, 0xfffe0080
	s_addc_u32 s21, s19, -1
	s_add_i32 s46, 0, 0x10000
	v_add_u32_e32 v138, s46, v142
	ds_read_b128 v[144:147], v138
	ds_read_b128 v[148:151], v138 offset:1024
	ds_read_b128 v[152:155], v138 offset:2048
	ds_read_b128 v[156:159], v138 offset:3072
	s_cmp_eq_u32 s45, 4
	s_cselect_b32 s23, s9, s21
	s_cselect_b32 s22, s41, s20
	s_cselect_b32 s21, s7, s44
	s_cselect_b32 s20, s42, s43
	v_lshl_add_u64 v[138:139], s[18:19], 0, v[134:135]
	s_add_i32 m0, s17, 0xc000
	ds_read_b128 v[160:163], v143
	ds_read_b128 v[164:167], v143 offset:1024
	ds_read_b128 v[168:171], v143 offset:2048
	ds_read_b128 v[172:175], v143 offset:3072
	ds_read_b128 v[176:179], v143 offset:4096
	ds_read_b128 v[180:183], v143 offset:5120
	ds_read_b128 v[188:191], v143 offset:6144
	ds_read_b128 v[192:195], v143 offset:7168
	global_load_lds_dwordx4 v[138:139], off
	v_lshl_add_u64 v[138:139], s[18:19], 0, v[136:137]
	s_add_i32 m0, s17, 0xe000
	s_nop 0
	global_load_lds_dwordx4 v[138:139], off
	s_waitcnt lgkmcnt(8)
	s_setprio 1
	s_barrier
	s_waitcnt lgkmcnt(0)
	v_mfma_f32_16x16x32_bf16 v[124:127], v[144:147], v[160:163], v[124:127]
	v_mfma_f32_16x16x32_bf16 v[120:123], v[152:155], v[160:163], v[120:123]
	v_mfma_f32_16x16x32_bf16 v[108:111], v[144:147], v[168:171], v[108:111]
	v_mfma_f32_16x16x32_bf16 v[104:107], v[152:155], v[168:171], v[104:107]
	v_mfma_f32_16x16x32_bf16 v[92:95], v[144:147], v[176:179], v[92:95]
	v_mfma_f32_16x16x32_bf16 v[88:91], v[152:155], v[176:179], v[88:91]
	v_mfma_f32_16x16x32_bf16 v[76:79], v[144:147], v[188:191], v[76:79]
	v_mfma_f32_16x16x32_bf16 v[72:75], v[152:155], v[188:191], v[72:75]
	v_mfma_f32_16x16x32_bf16 v[124:127], v[148:151], v[164:167], v[124:127]
	v_mfma_f32_16x16x32_bf16 v[120:123], v[156:159], v[164:167], v[120:123]
	v_mfma_f32_16x16x32_bf16 v[108:111], v[148:151], v[172:175], v[108:111]
	v_mfma_f32_16x16x32_bf16 v[104:107], v[156:159], v[172:175], v[104:107]
	v_mfma_f32_16x16x32_bf16 v[92:95], v[148:151], v[180:183], v[92:95]
	v_mfma_f32_16x16x32_bf16 v[88:91], v[156:159], v[180:183], v[88:91]
	v_mfma_f32_16x16x32_bf16 v[76:79], v[148:151], v[192:195], v[76:79]
	v_mfma_f32_16x16x32_bf16 v[72:75], v[156:159], v[192:195], v[72:75]
	s_barrier
	s_setprio 0
	s_add_i32 s48, 0, 0x14000
	v_add_u32_e32 v138, s48, v142
	s_add_i32 s46, s46, s30
	ds_read_b128 v[202:205], v138
	ds_read_b128 v[206:209], v138 offset:1024
	ds_read_b128 v[210:213], v138 offset:2048
	ds_read_b128 v[214:217], v138 offset:3072
	v_lshl_add_u64 v[138:139], s[20:21], 0, v[184:185]
	s_mov_b32 m0, s46
	v_lshl_add_u64 v[196:197], s[20:21], 0, v[128:129]
	global_load_lds_dwordx4 v[138:139], off
	s_add_i32 m0, s46, 0x2000
	s_nop 0
	global_load_lds_dwordx4 v[196:197], off
	s_setprio 1
	s_barrier
	s_waitcnt lgkmcnt(0)
	v_mfma_f32_16x16x32_bf16 v[116:119], v[202:205], v[160:163], v[116:119]
	v_mfma_f32_16x16x32_bf16 v[112:115], v[210:213], v[160:163], v[112:115]
	v_mfma_f32_16x16x32_bf16 v[100:103], v[202:205], v[168:171], v[100:103]
	v_mfma_f32_16x16x32_bf16 v[96:99], v[210:213], v[168:171], v[96:99]
	v_mfma_f32_16x16x32_bf16 v[84:87], v[202:205], v[176:179], v[84:87]
	v_mfma_f32_16x16x32_bf16 v[80:83], v[210:213], v[176:179], v[80:83]
	v_mfma_f32_16x16x32_bf16 v[68:71], v[202:205], v[188:191], v[68:71]
	v_mfma_f32_16x16x32_bf16 v[64:67], v[210:213], v[188:191], v[64:67]
	v_mfma_f32_16x16x32_bf16 v[116:119], v[206:209], v[164:167], v[116:119]
	v_mfma_f32_16x16x32_bf16 v[112:115], v[214:217], v[164:167], v[112:115]
	v_mfma_f32_16x16x32_bf16 v[100:103], v[206:209], v[172:175], v[100:103]
	v_mfma_f32_16x16x32_bf16 v[96:99], v[214:217], v[172:175], v[96:99]
	v_mfma_f32_16x16x32_bf16 v[84:87], v[206:209], v[180:183], v[84:87]
	v_mfma_f32_16x16x32_bf16 v[80:83], v[214:217], v[180:183], v[80:83]
	v_mfma_f32_16x16x32_bf16 v[68:71], v[206:209], v[192:195], v[68:71]
	v_mfma_f32_16x16x32_bf16 v[64:67], v[214:217], v[192:195], v[64:67]
	s_barrier
	s_setprio 0
	s_mov_b32 m0, s17
	v_lshl_add_u64 v[218:219], s[22:23], 0, v[132:133]
	ds_read_b128 v[160:163], v143 offset:16384
	ds_read_b128 v[164:167], v143 offset:17408
	ds_read_b128 v[168:171], v143 offset:18432
	ds_read_b128 v[172:175], v143 offset:19456
	ds_read_b128 v[176:179], v143 offset:20480
	ds_read_b128 v[180:183], v143 offset:21504
	ds_read_b128 v[188:191], v143 offset:22528
	ds_read_b128 v[192:195], v143 offset:23552
	global_load_lds_dwordx4 v[218:219], off
	v_lshl_add_u64 v[220:221], s[22:23], 0, v[130:131]
	s_mov_b32 m0, s31
	s_nop 0
	global_load_lds_dwordx4 v[220:221], off
	s_setprio 1
	s_barrier
	s_waitcnt lgkmcnt(0)
	v_mfma_f32_16x16x32_bf16 v[60:63], v[144:147], v[160:163], v[60:63]
	v_mfma_f32_16x16x32_bf16 v[56:59], v[152:155], v[160:163], v[56:59]
	v_mfma_f32_16x16x32_bf16 v[44:47], v[144:147], v[168:171], v[44:47]
	v_mfma_f32_16x16x32_bf16 v[40:43], v[152:155], v[168:171], v[40:43]
	v_mfma_f32_16x16x32_bf16 v[28:31], v[144:147], v[176:179], v[28:31]
	v_mfma_f32_16x16x32_bf16 v[24:27], v[152:155], v[176:179], v[24:27]
	v_mfma_f32_16x16x32_bf16 v[12:15], v[144:147], v[188:191], v[12:15]
	v_mfma_f32_16x16x32_bf16 v[8:11], v[152:155], v[188:191], v[8:11]
	v_mfma_f32_16x16x32_bf16 v[60:63], v[148:151], v[164:167], v[60:63]
	v_mfma_f32_16x16x32_bf16 v[56:59], v[156:159], v[164:167], v[56:59]
	v_mfma_f32_16x16x32_bf16 v[44:47], v[148:151], v[172:175], v[44:47]
	v_mfma_f32_16x16x32_bf16 v[40:43], v[156:159], v[172:175], v[40:43]
	v_mfma_f32_16x16x32_bf16 v[28:31], v[148:151], v[180:183], v[28:31]
	v_mfma_f32_16x16x32_bf16 v[24:27], v[156:159], v[180:183], v[24:27]
	v_mfma_f32_16x16x32_bf16 v[12:15], v[148:151], v[192:195], v[12:15]
	v_mfma_f32_16x16x32_bf16 v[8:11], v[156:159], v[192:195], v[8:11]
	s_barrier
	s_setprio 0
	s_add_u32 s46, s20, 0x20000
	s_addc_u32 s47, s21, 0
	s_add_i32 s48, s48, s30
	v_lshl_add_u64 v[144:145], s[46:47], 0, v[184:185]
	s_mov_b32 m0, s48
	s_nop 0
	global_load_lds_dwordx4 v[144:145], off
	v_lshl_add_u64 v[144:145], s[46:47], 0, v[128:129]
	s_add_i32 m0, s48, 0x2000
	s_nop 0
	global_load_lds_dwordx4 v[144:145], off
	s_waitcnt vmcnt(6)
	s_setprio 1
	s_barrier
	v_mfma_f32_16x16x32_bf16 v[52:55], v[202:205], v[160:163], v[52:55]
	v_mfma_f32_16x16x32_bf16 v[48:51], v[210:213], v[160:163], v[48:51]
	v_mfma_f32_16x16x32_bf16 v[36:39], v[202:205], v[168:171], v[36:39]
	v_mfma_f32_16x16x32_bf16 v[32:35], v[210:213], v[168:171], v[32:35]
	v_mfma_f32_16x16x32_bf16 v[20:23], v[202:205], v[176:179], v[20:23]
	v_mfma_f32_16x16x32_bf16 v[16:19], v[210:213], v[176:179], v[16:19]
	v_mfma_f32_16x16x32_bf16 v[4:7], v[202:205], v[188:191], v[4:7]
	v_mfma_f32_16x16x32_bf16 v[0:3], v[210:213], v[188:191], v[0:3]
	v_mfma_f32_16x16x32_bf16 v[52:55], v[206:209], v[164:167], v[52:55]
	v_mfma_f32_16x16x32_bf16 v[48:51], v[214:217], v[164:167], v[48:51]
	v_mfma_f32_16x16x32_bf16 v[36:39], v[206:209], v[172:175], v[36:39]
	v_mfma_f32_16x16x32_bf16 v[32:35], v[214:217], v[172:175], v[32:35]
	v_mfma_f32_16x16x32_bf16 v[20:23], v[206:209], v[180:183], v[20:23]
	v_mfma_f32_16x16x32_bf16 v[16:19], v[214:217], v[180:183], v[16:19]
	v_mfma_f32_16x16x32_bf16 v[4:7], v[206:209], v[192:195], v[4:7]
	v_mfma_f32_16x16x32_bf16 v[0:3], v[214:217], v[192:195], v[0:3]
	s_barrier
	s_setprio 0
	s_add_i32 s46, 0, 0x18000
	v_add_u32_e32 v156, s46, v142
	ds_read_b128 v[144:147], v156
	ds_read_b128 v[148:151], v156 offset:1024
	ds_read_b128 v[152:155], v156 offset:2048
	ds_read_b128 v[156:159], v156 offset:3072
	s_add_u32 s22, s22, 0x20000
	s_addc_u32 s23, s23, 0
	s_mov_b32 m0, s33
	v_lshl_add_u64 v[202:203], s[22:23], 0, v[132:133]
	ds_read_b128 v[160:163], v143 offset:32768
	ds_read_b128 v[164:167], v143 offset:33792
	ds_read_b128 v[168:171], v143 offset:34816
	ds_read_b128 v[172:175], v143 offset:35840
	ds_read_b128 v[176:179], v143 offset:36864
	ds_read_b128 v[180:183], v143 offset:37888
	ds_read_b128 v[188:191], v143 offset:38912
	ds_read_b128 v[192:195], v143 offset:39936
	global_load_lds_dwordx4 v[202:203], off
	v_lshl_add_u64 v[202:203], s[22:23], 0, v[130:131]
	s_mov_b32 m0, s34
	s_nop 0
	global_load_lds_dwordx4 v[202:203], off
	s_waitcnt lgkmcnt(8)
	s_setprio 1
	s_barrier
	s_waitcnt lgkmcnt(0)
	v_mfma_f32_16x16x32_bf16 v[124:127], v[144:147], v[160:163], v[124:127]
	v_mfma_f32_16x16x32_bf16 v[120:123], v[152:155], v[160:163], v[120:123]
	v_mfma_f32_16x16x32_bf16 v[108:111], v[144:147], v[168:171], v[108:111]
	v_mfma_f32_16x16x32_bf16 v[104:107], v[152:155], v[168:171], v[104:107]
	v_mfma_f32_16x16x32_bf16 v[92:95], v[144:147], v[176:179], v[92:95]
	v_mfma_f32_16x16x32_bf16 v[88:91], v[152:155], v[176:179], v[88:91]
	v_mfma_f32_16x16x32_bf16 v[76:79], v[144:147], v[188:191], v[76:79]
	v_mfma_f32_16x16x32_bf16 v[72:75], v[152:155], v[188:191], v[72:75]
	v_mfma_f32_16x16x32_bf16 v[124:127], v[148:151], v[164:167], v[124:127]
	v_mfma_f32_16x16x32_bf16 v[120:123], v[156:159], v[164:167], v[120:123]
	v_mfma_f32_16x16x32_bf16 v[108:111], v[148:151], v[172:175], v[108:111]
	v_mfma_f32_16x16x32_bf16 v[104:107], v[156:159], v[172:175], v[104:107]
	v_mfma_f32_16x16x32_bf16 v[92:95], v[148:151], v[180:183], v[92:95]
	v_mfma_f32_16x16x32_bf16 v[88:91], v[156:159], v[180:183], v[88:91]
	v_mfma_f32_16x16x32_bf16 v[76:79], v[148:151], v[192:195], v[76:79]
	v_mfma_f32_16x16x32_bf16 v[72:75], v[156:159], v[192:195], v[72:75]
	s_barrier
	s_setprio 0
	s_add_i32 s22, 0, 0x1c000
	s_add_i32 s23, s46, s30
	v_add_u32_e32 v187, s22, v142
	v_lshl_add_u64 v[138:139], v[138:139], 0, s[50:51]
	s_mov_b32 m0, s23
	ds_read_b128 v[202:205], v187
	ds_read_b128 v[206:209], v187 offset:1024
	ds_read_b128 v[210:213], v187 offset:2048
	ds_read_b128 v[214:217], v187 offset:3072
	global_load_lds_dwordx4 v[138:139], off
	v_lshl_add_u64 v[138:139], v[196:197], 0, s[50:51]
	s_add_i32 m0, s23, 0x2000
	s_nop 0
	global_load_lds_dwordx4 v[138:139], off
	s_setprio 1
	s_barrier
	s_waitcnt lgkmcnt(0)
	v_mfma_f32_16x16x32_bf16 v[116:119], v[202:205], v[160:163], v[116:119]
	v_mfma_f32_16x16x32_bf16 v[112:115], v[210:213], v[160:163], v[112:115]
	v_mfma_f32_16x16x32_bf16 v[100:103], v[202:205], v[168:171], v[100:103]
	v_mfma_f32_16x16x32_bf16 v[96:99], v[210:213], v[168:171], v[96:99]
	v_mfma_f32_16x16x32_bf16 v[84:87], v[202:205], v[176:179], v[84:87]
	v_mfma_f32_16x16x32_bf16 v[80:83], v[210:213], v[176:179], v[80:83]
	v_mfma_f32_16x16x32_bf16 v[68:71], v[202:205], v[188:191], v[68:71]
	v_mfma_f32_16x16x32_bf16 v[64:67], v[210:213], v[188:191], v[64:67]
	v_mfma_f32_16x16x32_bf16 v[116:119], v[206:209], v[164:167], v[116:119]
	v_mfma_f32_16x16x32_bf16 v[112:115], v[214:217], v[164:167], v[112:115]
	v_mfma_f32_16x16x32_bf16 v[100:103], v[206:209], v[172:175], v[100:103]
	v_mfma_f32_16x16x32_bf16 v[96:99], v[214:217], v[172:175], v[96:99]
	v_mfma_f32_16x16x32_bf16 v[84:87], v[206:209], v[180:183], v[84:87]
	v_mfma_f32_16x16x32_bf16 v[80:83], v[214:217], v[180:183], v[80:83]
	v_mfma_f32_16x16x32_bf16 v[68:71], v[206:209], v[192:195], v[68:71]
	v_mfma_f32_16x16x32_bf16 v[64:67], v[214:217], v[192:195], v[64:67]
	s_barrier
	s_setprio 0
	s_mov_b32 m0, s37
	v_lshl_add_u64 v[138:139], v[218:219], 0, s[50:51]
	ds_read_b128 v[160:163], v143 offset:49152
	ds_read_b128 v[164:167], v143 offset:50176
	ds_read_b128 v[168:171], v143 offset:51200
	ds_read_b128 v[172:175], v143 offset:52224
	ds_read_b128 v[176:179], v143 offset:53248
	ds_read_b128 v[180:183], v143 offset:54272
	ds_read_b128 v[188:191], v143 offset:55296
	ds_read_b128 v[192:195], v143 offset:56320
	global_load_lds_dwordx4 v[138:139], off
	v_lshl_add_u64 v[138:139], v[220:221], 0, s[50:51]
	s_mov_b32 m0, s38
	s_nop 0
	global_load_lds_dwordx4 v[138:139], off
	s_setprio 1
	s_barrier
	s_waitcnt lgkmcnt(0)
	v_mfma_f32_16x16x32_bf16 v[60:63], v[144:147], v[160:163], v[60:63]
	v_mfma_f32_16x16x32_bf16 v[56:59], v[152:155], v[160:163], v[56:59]
	v_mfma_f32_16x16x32_bf16 v[44:47], v[144:147], v[168:171], v[44:47]
	v_mfma_f32_16x16x32_bf16 v[40:43], v[152:155], v[168:171], v[40:43]
	v_mfma_f32_16x16x32_bf16 v[28:31], v[144:147], v[176:179], v[28:31]
	v_mfma_f32_16x16x32_bf16 v[24:27], v[152:155], v[176:179], v[24:27]
	v_mfma_f32_16x16x32_bf16 v[12:15], v[144:147], v[188:191], v[12:15]
	v_mfma_f32_16x16x32_bf16 v[8:11], v[152:155], v[188:191], v[8:11]
	v_mfma_f32_16x16x32_bf16 v[60:63], v[148:151], v[164:167], v[60:63]
	v_mfma_f32_16x16x32_bf16 v[56:59], v[156:159], v[164:167], v[56:59]
	v_mfma_f32_16x16x32_bf16 v[44:47], v[148:151], v[172:175], v[44:47]
	v_mfma_f32_16x16x32_bf16 v[40:43], v[156:159], v[172:175], v[40:43]
	v_mfma_f32_16x16x32_bf16 v[28:31], v[148:151], v[180:183], v[28:31]
	v_mfma_f32_16x16x32_bf16 v[24:27], v[156:159], v[180:183], v[24:27]
	v_mfma_f32_16x16x32_bf16 v[12:15], v[148:151], v[192:195], v[12:15]
	v_mfma_f32_16x16x32_bf16 v[8:11], v[156:159], v[192:195], v[8:11]
	s_barrier
	s_setprio 0
	s_add_u32 s20, s20, 0x20080
	s_addc_u32 s21, s21, 0
	s_add_i32 s22, s22, s30
	v_lshl_add_u64 v[138:139], s[20:21], 0, v[184:185]
	s_mov_b32 m0, s22
	s_nop 0
	global_load_lds_dwordx4 v[138:139], off
	v_lshl_add_u64 v[138:139], s[20:21], 0, v[128:129]
	s_add_i32 m0, s22, 0x2000
	s_nop 0
	global_load_lds_dwordx4 v[138:139], off
	s_waitcnt vmcnt(6)
	s_setprio 1
	s_barrier
	v_mfma_f32_16x16x32_bf16 v[52:55], v[202:205], v[160:163], v[52:55]
	v_mfma_f32_16x16x32_bf16 v[48:51], v[210:213], v[160:163], v[48:51]
	v_mfma_f32_16x16x32_bf16 v[36:39], v[202:205], v[168:171], v[36:39]
	v_mfma_f32_16x16x32_bf16 v[32:35], v[210:213], v[168:171], v[32:35]
	v_mfma_f32_16x16x32_bf16 v[20:23], v[202:205], v[176:179], v[20:23]
	v_mfma_f32_16x16x32_bf16 v[16:19], v[210:213], v[176:179], v[16:19]
	v_mfma_f32_16x16x32_bf16 v[4:7], v[202:205], v[188:191], v[4:7]
	v_mfma_f32_16x16x32_bf16 v[0:3], v[210:213], v[188:191], v[0:3]
	v_mfma_f32_16x16x32_bf16 v[52:55], v[206:209], v[164:167], v[52:55]
	v_mfma_f32_16x16x32_bf16 v[48:51], v[214:217], v[164:167], v[48:51]
	v_mfma_f32_16x16x32_bf16 v[36:39], v[206:209], v[172:175], v[36:39]
	v_mfma_f32_16x16x32_bf16 v[32:35], v[214:217], v[172:175], v[32:35]
	v_mfma_f32_16x16x32_bf16 v[20:23], v[206:209], v[180:183], v[20:23]
	v_mfma_f32_16x16x32_bf16 v[16:19], v[214:217], v[180:183], v[16:19]
	v_mfma_f32_16x16x32_bf16 v[4:7], v[206:209], v[192:195], v[4:7]
	v_mfma_f32_16x16x32_bf16 v[0:3], v[214:217], v[192:195], v[0:3]
	s_barrier
	s_setprio 0
	s_add_i32 s45, s45, 2
	s_add_u32 s18, s18, 0x100
	s_addc_u32 s19, s19, 0
	s_add_u32 s43, s43, 0x100
	s_addc_u32 s44, s44, 0
	s_cmp_gt_u32 s45, 5
	s_cbranch_scc0 .LBB0_117
	v_mov_b32_e32 v138, v140
	v_mov_b32_e32 v139, v141
	s_lshl_b32 s7, s16, 8
	s_add_i32 s7, s7, s35
	v_add_u32_e32 v138, s7, v138
	s_lshl_b32 s7, s40, 8
	s_or_b32 s7, s7, s36
	v_lshl_add_u32 v152, v139, 3, s7
	v_ashrrev_i32_e32 v139, 31, v138
	v_lshlrev_b64 v[144:145], 5, v[138:139]
	v_lshl_add_u64 v[148:149], s[4:5], 0, v[144:145]
	global_load_dwordx4 v[144:147], v[148:149], off offset:16
	s_nop 0
	global_load_dwordx4 v[148:151], v[148:149], off
	v_ashrrev_i32_e32 v153, 31, v152
	s_mov_b32 s40, s6
	s_mov_b32 s16, s8
	s_mov_b64 s[20:21], s[14:15]
	s_mov_b64 s[18:19], s[12:13]
	s_waitcnt vmcnt(0)
	v_add_f32_e32 v148, v148, v149
	v_add_f32_e32 v148, v150, v148
	v_add_f32_e32 v148, v151, v148
	v_add_f32_e32 v144, v144, v148
	v_add_f32_e32 v144, v145, v144
	v_add_f32_e32 v144, v146, v144
	v_add_f32_e32 v144, v147, v144
	v_add_f32_e32 v144, 0x3a0637bd, v144
	v_mul_f32_e32 v144, 0x3b000000, v144
	v_cmp_gt_f32_e32 vcc, s67, v144
	v_mul_f32_e32 v145, 0x4b800000, v144
	s_nop 0
	v_cndmask_b32_e32 v144, v144, v145, vcc
	v_rsq_f32_e32 v144, v144
	s_nop 0
	v_mul_f32_e32 v145, 0x45800000, v144
	v_cndmask_b32_e32 v144, v144, v145, vcc
	v_mul_f32_e32 v124, v124, v144
	v_mul_f32_e32 v120, v120, v144
	v_mul_f32_e32 v121, v121, v144
	v_mul_f32_e32 v125, v125, v144
	v_mul_f32_e32 v126, v126, v144
	v_mul_f32_e32 v127, v127, v144
	v_mul_f32_e32 v145, v122, v144
	v_mul_f32_e32 v146, v123, v144
	v_cvt_pk_bf16_f32 v122, v124, v125
	v_cvt_pk_bf16_f32 v123, v126, v127
	v_cvt_pk_bf16_f32 v124, v120, v121
	v_lshlrev_b64 v[120:121], 12, v[138:139]
	v_lshl_add_u64 v[126:127], s[2:3], 0, v[120:121]
	v_lshlrev_b64 v[120:121], 1, v[152:153]
	v_lshl_add_u64 v[126:127], v[126:127], 0, v[120:121]
	v_cvt_pk_bf16_f32 v125, v145, v146
	global_store_dwordx4 v[126:127], v[122:125], off
	v_mul_f32_e32 v116, v116, v144
	v_mul_f32_e32 v117, v117, v144
	v_mul_f32_e32 v122, v112, v144
	v_mul_f32_e32 v118, v118, v144
	v_mul_f32_e32 v119, v119, v144
	v_mul_f32_e32 v123, v113, v144
	v_mul_f32_e32 v124, v114, v144
	v_cvt_pk_bf16_f32 v112, v116, v117
	v_cvt_pk_bf16_f32 v113, v118, v119
	v_cvt_pk_bf16_f32 v114, v122, v123
	v_add_u32_e32 v122, 16, v138
	v_mul_f32_e32 v115, v115, v144
	v_ashrrev_i32_e32 v123, 31, v122
	v_cvt_pk_bf16_f32 v115, v124, v115
	global_store_dwordx4 v[126:127], v[112:115], off offset:256
	s_nop 1
	v_lshlrev_b64 v[112:113], 5, v[122:123]
	v_lshl_add_u64 v[116:117], s[4:5], 0, v[112:113]
	global_load_dwordx4 v[112:115], v[116:117], off offset:16
	s_nop 0
	global_load_dwordx4 v[116:119], v[116:117], off
	s_waitcnt vmcnt(0)
	v_add_f32_e32 v116, v116, v117
	v_add_f32_e32 v116, v118, v116
	v_add_f32_e32 v116, v119, v116
	v_add_f32_e32 v112, v112, v116
	v_add_f32_e32 v112, v113, v112
	v_add_f32_e32 v112, v114, v112
	v_add_f32_e32 v112, v115, v112
	v_add_f32_e32 v112, 0x3a0637bd, v112
	v_mul_f32_e32 v112, 0x3b000000, v112
	v_cmp_gt_f32_e32 vcc, s67, v112
	v_mul_f32_e32 v113, 0x4b800000, v112
	s_nop 0
	v_cndmask_b32_e32 v112, v112, v113, vcc
	v_rsq_f32_e32 v112, v112
	s_nop 0
	v_mul_f32_e32 v113, 0x45800000, v112
	v_cndmask_b32_e32 v112, v112, v113, vcc
	v_mul_f32_e32 v108, v108, v112
	v_mul_f32_e32 v109, v109, v112
	v_mul_f32_e32 v113, v104, v112
	v_cvt_pk_bf16_f32 v104, v108, v109
	v_lshlrev_b64 v[108:109], 12, v[122:123]
	v_lshl_add_u64 v[108:109], s[2:3], 0, v[108:109]
	v_mul_f32_e32 v107, v107, v112
	v_lshl_add_u64 v[108:109], v[108:109], 0, v[120:121]
	v_mul_f32_e32 v110, v110, v112
	v_mul_f32_e32 v111, v111, v112
	v_mul_f32_e32 v114, v105, v112
	v_mul_f32_e32 v115, v106, v112
	v_cvt_pk_bf16_f32 v105, v110, v111
	v_cvt_pk_bf16_f32 v106, v113, v114
	v_cvt_pk_bf16_f32 v107, v115, v107
	global_store_dwordx4 v[108:109], v[104:107], off
	v_mul_f32_e32 v100, v100, v112
	v_mul_f32_e32 v101, v101, v112
	v_mul_f32_e32 v104, v96, v112
	v_mul_f32_e32 v102, v102, v112
	v_mul_f32_e32 v103, v103, v112
	v_mul_f32_e32 v105, v97, v112
	v_mul_f32_e32 v106, v98, v112
	v_cvt_pk_bf16_f32 v96, v100, v101
	v_cvt_pk_bf16_f32 v97, v102, v103
	v_cvt_pk_bf16_f32 v98, v104, v105
	v_add_u32_e32 v104, 32, v138
	v_mul_f32_e32 v99, v99, v112
	v_ashrrev_i32_e32 v105, 31, v104
	v_cvt_pk_bf16_f32 v99, v106, v99
	global_store_dwordx4 v[108:109], v[96:99], off offset:256
	s_nop 1
	v_lshlrev_b64 v[96:97], 5, v[104:105]
	v_lshl_add_u64 v[100:101], s[4:5], 0, v[96:97]
	global_load_dwordx4 v[96:99], v[100:101], off offset:16
	s_nop 0
	global_load_dwordx4 v[100:103], v[100:101], off
	s_waitcnt vmcnt(0)
	v_add_f32_e32 v100, v100, v101
	v_add_f32_e32 v100, v102, v100
	v_add_f32_e32 v100, v103, v100
	v_add_f32_e32 v96, v96, v100
	v_add_f32_e32 v96, v97, v96
	v_add_f32_e32 v96, v98, v96
	v_add_f32_e32 v96, v99, v96
	v_add_f32_e32 v96, 0x3a0637bd, v96
	v_mul_f32_e32 v96, 0x3b000000, v96
	v_cmp_gt_f32_e32 vcc, s67, v96
	v_mul_f32_e32 v97, 0x4b800000, v96
	s_nop 0
	v_cndmask_b32_e32 v96, v96, v97, vcc
	v_rsq_f32_e32 v96, v96
	s_nop 0
	v_mul_f32_e32 v97, 0x45800000, v96
	v_cndmask_b32_e32 v96, v96, v97, vcc
	v_mul_f32_e32 v92, v92, v96
	v_mul_f32_e32 v93, v93, v96
	v_mul_f32_e32 v97, v88, v96
	v_cvt_pk_bf16_f32 v88, v92, v93
	v_lshlrev_b64 v[92:93], 12, v[104:105]
	v_lshl_add_u64 v[92:93], s[2:3], 0, v[92:93]
	v_mul_f32_e32 v91, v91, v96
	v_lshl_add_u64 v[92:93], v[92:93], 0, v[120:121]
	v_mul_f32_e32 v94, v94, v96
	v_mul_f32_e32 v95, v95, v96
	v_mul_f32_e32 v98, v89, v96
	v_mul_f32_e32 v99, v90, v96
	v_cvt_pk_bf16_f32 v89, v94, v95
	v_cvt_pk_bf16_f32 v90, v97, v98
	v_cvt_pk_bf16_f32 v91, v99, v91
	global_store_dwordx4 v[92:93], v[88:91], off
	v_mul_f32_e32 v84, v84, v96
	v_mul_f32_e32 v85, v85, v96
	v_mul_f32_e32 v88, v80, v96
	v_mul_f32_e32 v86, v86, v96
	v_mul_f32_e32 v87, v87, v96
	v_mul_f32_e32 v89, v81, v96
	v_mul_f32_e32 v90, v82, v96
	v_cvt_pk_bf16_f32 v80, v84, v85
	v_cvt_pk_bf16_f32 v81, v86, v87
	v_cvt_pk_bf16_f32 v82, v88, v89
	v_add_u32_e32 v88, 48, v138
	v_mul_f32_e32 v83, v83, v96
	v_ashrrev_i32_e32 v89, 31, v88
	v_cvt_pk_bf16_f32 v83, v90, v83
	global_store_dwordx4 v[92:93], v[80:83], off offset:256
	s_nop 1
	v_lshlrev_b64 v[80:81], 5, v[88:89]
	v_lshl_add_u64 v[84:85], s[4:5], 0, v[80:81]
	global_load_dwordx4 v[80:83], v[84:85], off offset:16
	s_nop 0
	global_load_dwordx4 v[84:87], v[84:85], off
	s_waitcnt vmcnt(0)
	v_add_f32_e32 v84, v84, v85
	v_add_f32_e32 v84, v86, v84
	v_add_f32_e32 v84, v87, v84
	v_add_f32_e32 v80, v80, v84
	v_add_f32_e32 v80, v81, v80
	v_add_f32_e32 v80, v82, v80
	v_add_f32_e32 v80, v83, v80
	v_add_f32_e32 v80, 0x3a0637bd, v80
	v_mul_f32_e32 v80, 0x3b000000, v80
	v_cmp_gt_f32_e32 vcc, s67, v80
	v_mul_f32_e32 v81, 0x4b800000, v80
	s_nop 0
	v_cndmask_b32_e32 v80, v80, v81, vcc
	v_rsq_f32_e32 v80, v80
	s_nop 0
	v_mul_f32_e32 v81, 0x45800000, v80
	v_cndmask_b32_e32 v80, v80, v81, vcc
	v_mul_f32_e32 v76, v76, v80
	v_mul_f32_e32 v77, v77, v80
	v_mul_f32_e32 v81, v72, v80
	v_cvt_pk_bf16_f32 v72, v76, v77
	v_lshlrev_b64 v[76:77], 12, v[88:89]
	v_lshl_add_u64 v[76:77], s[2:3], 0, v[76:77]
	v_mul_f32_e32 v75, v75, v80
	v_lshl_add_u64 v[76:77], v[76:77], 0, v[120:121]
	v_mul_f32_e32 v78, v78, v80
	v_mul_f32_e32 v79, v79, v80
	v_mul_f32_e32 v82, v73, v80
	v_mul_f32_e32 v83, v74, v80
	v_cvt_pk_bf16_f32 v73, v78, v79
	v_cvt_pk_bf16_f32 v74, v81, v82
	v_cvt_pk_bf16_f32 v75, v83, v75
	global_store_dwordx4 v[76:77], v[72:75], off
	v_mul_f32_e32 v68, v68, v80
	v_mul_f32_e32 v69, v69, v80
	v_mul_f32_e32 v72, v64, v80
	v_mul_f32_e32 v70, v70, v80
	v_mul_f32_e32 v71, v71, v80
	v_mul_f32_e32 v73, v65, v80
	v_mul_f32_e32 v74, v66, v80
	v_cvt_pk_bf16_f32 v64, v68, v69
	v_cvt_pk_bf16_f32 v65, v70, v71
	v_cvt_pk_bf16_f32 v66, v72, v73
	v_add_u32_e32 v72, 0x80, v138
	v_mul_f32_e32 v67, v67, v80
	v_ashrrev_i32_e32 v73, 31, v72
	v_cvt_pk_bf16_f32 v67, v74, v67
	global_store_dwordx4 v[76:77], v[64:67], off offset:256
	s_nop 1
	v_lshlrev_b64 v[64:65], 5, v[72:73]
	v_lshl_add_u64 v[68:69], s[4:5], 0, v[64:65]
	global_load_dwordx4 v[64:67], v[68:69], off offset:16
	s_nop 0
	global_load_dwordx4 v[68:71], v[68:69], off
	s_waitcnt vmcnt(0)
	v_add_f32_e32 v68, v68, v69
	v_add_f32_e32 v68, v70, v68
	v_add_f32_e32 v68, v71, v68
	v_add_f32_e32 v64, v64, v68
	v_add_f32_e32 v64, v65, v64
	v_add_f32_e32 v64, v66, v64
	v_add_f32_e32 v64, v67, v64
	v_add_f32_e32 v64, 0x3a0637bd, v64
	v_mul_f32_e32 v64, 0x3b000000, v64
	v_cmp_gt_f32_e32 vcc, s67, v64
	v_mul_f32_e32 v65, 0x4b800000, v64
	s_nop 0
	v_cndmask_b32_e32 v64, v64, v65, vcc
	v_rsq_f32_e32 v64, v64
	s_nop 0
	v_mul_f32_e32 v65, 0x45800000, v64
	v_cndmask_b32_e32 v64, v64, v65, vcc
	v_mul_f32_e32 v60, v60, v64
	v_mul_f32_e32 v61, v61, v64
	v_mul_f32_e32 v65, v56, v64
	v_cvt_pk_bf16_f32 v56, v60, v61
	v_lshlrev_b64 v[60:61], 12, v[72:73]
	v_lshl_add_u64 v[60:61], s[2:3], 0, v[60:61]
	v_mul_f32_e32 v59, v59, v64
	v_lshl_add_u64 v[60:61], v[60:61], 0, v[120:121]
	v_mul_f32_e32 v62, v62, v64
	v_mul_f32_e32 v63, v63, v64
	v_mul_f32_e32 v66, v57, v64
	v_mul_f32_e32 v67, v58, v64
	v_cvt_pk_bf16_f32 v57, v62, v63
	v_cvt_pk_bf16_f32 v58, v65, v66
	v_cvt_pk_bf16_f32 v59, v67, v59
	global_store_dwordx4 v[60:61], v[56:59], off
	v_mul_f32_e32 v52, v52, v64
	v_mul_f32_e32 v53, v53, v64
	v_mul_f32_e32 v56, v48, v64
	v_mul_f32_e32 v54, v54, v64
	v_mul_f32_e32 v55, v55, v64
	v_mul_f32_e32 v57, v49, v64
	v_mul_f32_e32 v58, v50, v64
	v_cvt_pk_bf16_f32 v48, v52, v53
	v_cvt_pk_bf16_f32 v49, v54, v55
	v_cvt_pk_bf16_f32 v50, v56, v57
	v_add_u32_e32 v56, 0x90, v138
	v_mul_f32_e32 v51, v51, v64
	v_ashrrev_i32_e32 v57, 31, v56
	v_cvt_pk_bf16_f32 v51, v58, v51
	global_store_dwordx4 v[60:61], v[48:51], off offset:256
	s_nop 1
	v_lshlrev_b64 v[48:49], 5, v[56:57]
	v_lshl_add_u64 v[52:53], s[4:5], 0, v[48:49]
	global_load_dwordx4 v[48:51], v[52:53], off offset:16
	s_nop 0
	global_load_dwordx4 v[52:55], v[52:53], off
	s_waitcnt vmcnt(0)
	v_add_f32_e32 v52, v52, v53
	v_add_f32_e32 v52, v54, v52
	v_add_f32_e32 v52, v55, v52
	v_add_f32_e32 v48, v48, v52
	v_add_f32_e32 v48, v49, v48
	v_add_f32_e32 v48, v50, v48
	v_add_f32_e32 v48, v51, v48
	v_add_f32_e32 v48, 0x3a0637bd, v48
	v_mul_f32_e32 v48, 0x3b000000, v48
	v_cmp_gt_f32_e32 vcc, s67, v48
	v_mul_f32_e32 v49, 0x4b800000, v48
	s_nop 0
	v_cndmask_b32_e32 v48, v48, v49, vcc
	v_rsq_f32_e32 v48, v48
	s_nop 0
	v_mul_f32_e32 v49, 0x45800000, v48
	v_cndmask_b32_e32 v48, v48, v49, vcc
	v_mul_f32_e32 v44, v44, v48
	v_mul_f32_e32 v45, v45, v48
	v_mul_f32_e32 v49, v40, v48
	v_cvt_pk_bf16_f32 v40, v44, v45
	v_lshlrev_b64 v[44:45], 12, v[56:57]
	v_lshl_add_u64 v[44:45], s[2:3], 0, v[44:45]
	v_mul_f32_e32 v43, v43, v48
	v_lshl_add_u64 v[44:45], v[44:45], 0, v[120:121]
	v_mul_f32_e32 v46, v46, v48
	v_mul_f32_e32 v47, v47, v48
	v_mul_f32_e32 v50, v41, v48
	v_mul_f32_e32 v51, v42, v48
	v_cvt_pk_bf16_f32 v41, v46, v47
	v_cvt_pk_bf16_f32 v42, v49, v50
	v_cvt_pk_bf16_f32 v43, v51, v43
	global_store_dwordx4 v[44:45], v[40:43], off
	v_mul_f32_e32 v36, v36, v48
	v_mul_f32_e32 v37, v37, v48
	v_mul_f32_e32 v40, v32, v48
	v_mul_f32_e32 v38, v38, v48
	v_mul_f32_e32 v39, v39, v48
	v_mul_f32_e32 v41, v33, v48
	v_mul_f32_e32 v42, v34, v48
	v_cvt_pk_bf16_f32 v32, v36, v37
	v_cvt_pk_bf16_f32 v33, v38, v39
	v_cvt_pk_bf16_f32 v34, v40, v41
	v_add_u32_e32 v40, 0xa0, v138
	v_mul_f32_e32 v35, v35, v48
	v_ashrrev_i32_e32 v41, 31, v40
	v_cvt_pk_bf16_f32 v35, v42, v35
	global_store_dwordx4 v[44:45], v[32:35], off offset:256
	s_nop 1
	v_lshlrev_b64 v[32:33], 5, v[40:41]
	v_lshl_add_u64 v[36:37], s[4:5], 0, v[32:33]
	global_load_dwordx4 v[32:35], v[36:37], off offset:16
	s_nop 0
	global_load_dwordx4 v[36:39], v[36:37], off
	s_waitcnt vmcnt(0)
	v_add_f32_e32 v36, v36, v37
	v_add_f32_e32 v36, v38, v36
	v_add_f32_e32 v36, v39, v36
	v_add_f32_e32 v32, v32, v36
	v_add_f32_e32 v32, v33, v32
	v_add_f32_e32 v32, v34, v32
	v_add_f32_e32 v32, v35, v32
	v_add_f32_e32 v32, 0x3a0637bd, v32
	v_mul_f32_e32 v32, 0x3b000000, v32
	v_cmp_gt_f32_e32 vcc, s67, v32
	v_mul_f32_e32 v33, 0x4b800000, v32
	s_nop 0
	v_cndmask_b32_e32 v32, v32, v33, vcc
	v_rsq_f32_e32 v32, v32
	s_nop 0
	v_mul_f32_e32 v33, 0x45800000, v32
	v_cndmask_b32_e32 v32, v32, v33, vcc
	v_mul_f32_e32 v28, v28, v32
	v_mul_f32_e32 v29, v29, v32
	v_mul_f32_e32 v33, v24, v32
	v_cvt_pk_bf16_f32 v24, v28, v29
	v_lshlrev_b64 v[28:29], 12, v[40:41]
	v_lshl_add_u64 v[28:29], s[2:3], 0, v[28:29]
	v_mul_f32_e32 v27, v27, v32
	v_lshl_add_u64 v[28:29], v[28:29], 0, v[120:121]
	v_mul_f32_e32 v30, v30, v32
	v_mul_f32_e32 v31, v31, v32
	v_mul_f32_e32 v34, v25, v32
	v_mul_f32_e32 v35, v26, v32
	v_cvt_pk_bf16_f32 v25, v30, v31
	v_cvt_pk_bf16_f32 v26, v33, v34
	v_cvt_pk_bf16_f32 v27, v35, v27
	global_store_dwordx4 v[28:29], v[24:27], off
	v_mul_f32_e32 v20, v20, v32
	v_mul_f32_e32 v21, v21, v32
	v_mul_f32_e32 v24, v16, v32
	v_mul_f32_e32 v22, v22, v32
	v_mul_f32_e32 v23, v23, v32
	v_mul_f32_e32 v25, v17, v32
	v_mul_f32_e32 v26, v18, v32
	v_cvt_pk_bf16_f32 v16, v20, v21
	v_cvt_pk_bf16_f32 v17, v22, v23
	v_cvt_pk_bf16_f32 v18, v24, v25
	v_add_u32_e32 v24, 0xb0, v138
	v_mul_f32_e32 v19, v19, v32
	v_ashrrev_i32_e32 v25, 31, v24
	v_cvt_pk_bf16_f32 v19, v26, v19
	global_store_dwordx4 v[28:29], v[16:19], off offset:256
	s_nop 1
	v_lshlrev_b64 v[16:17], 5, v[24:25]
	v_lshl_add_u64 v[20:21], s[4:5], 0, v[16:17]
	global_load_dwordx4 v[16:19], v[20:21], off offset:16
	s_nop 0
	global_load_dwordx4 v[20:23], v[20:21], off
	s_waitcnt vmcnt(0)
	v_add_f32_e32 v20, v20, v21
	v_add_f32_e32 v20, v22, v20
	v_add_f32_e32 v20, v23, v20
	v_add_f32_e32 v16, v16, v20
	v_add_f32_e32 v16, v17, v16
	v_add_f32_e32 v16, v18, v16
	v_add_f32_e32 v16, v19, v16
	v_add_f32_e32 v16, 0x3a0637bd, v16
	v_mul_f32_e32 v16, 0x3b000000, v16
	v_cmp_gt_f32_e32 vcc, s67, v16
	v_mul_f32_e32 v17, 0x4b800000, v16
	s_nop 0
	v_cndmask_b32_e32 v16, v16, v17, vcc
	v_rsq_f32_e32 v16, v16
	s_nop 0
	v_mul_f32_e32 v17, 0x45800000, v16
	v_cndmask_b32_e32 v16, v16, v17, vcc
	v_mul_f32_e32 v12, v12, v16
	v_mul_f32_e32 v13, v13, v16
	v_mul_f32_e32 v17, v8, v16
	v_cvt_pk_bf16_f32 v8, v12, v13
	v_lshlrev_b64 v[12:13], 12, v[24:25]
	v_lshl_add_u64 v[12:13], s[2:3], 0, v[12:13]
	v_mul_f32_e32 v14, v14, v16
	v_mul_f32_e32 v15, v15, v16
	v_mul_f32_e32 v18, v9, v16
	v_mul_f32_e32 v19, v10, v16
	v_mul_f32_e32 v11, v11, v16
	v_cvt_pk_bf16_f32 v9, v14, v15
	v_cvt_pk_bf16_f32 v10, v17, v18
	v_lshl_add_u64 v[12:13], v[12:13], 0, v[120:121]
	v_mul_f32_e32 v3, v3, v16
	s_and_b64 vcc, exec, s[10:11]
	v_cvt_pk_bf16_f32 v11, v19, v11
	global_store_dwordx4 v[12:13], v[8:11], off
	v_mul_f32_e32 v4, v4, v16
	v_mul_f32_e32 v5, v5, v16
	v_mul_f32_e32 v6, v6, v16
	v_mul_f32_e32 v7, v7, v16
	v_mul_f32_e32 v8, v0, v16
	v_mul_f32_e32 v9, v1, v16
	v_mul_f32_e32 v10, v2, v16
	v_cvt_pk_bf16_f32 v0, v4, v5
	v_cvt_pk_bf16_f32 v1, v6, v7
	v_cvt_pk_bf16_f32 v2, v8, v9
	v_cvt_pk_bf16_f32 v3, v10, v3
	global_store_dwordx4 v[12:13], v[0:3], off offset:256
	s_cbranch_vccz .LBB0_114
	s_waitcnt vmcnt(0)
	v_readlane_b32 s40, v244, 49
	s_cmpk_gt_u32 s27, 0xff
	v_readlane_b32 s41, v244, 50
	v_readlane_b32 s46, v244, 55
	v_readlane_b32 s47, v244, 56
	v_readlane_b32 s48, v244, 57
	v_readlane_b32 s49, v244, 58
	v_readlane_b32 s50, v244, 59
	v_readlane_b32 s51, v244, 60
	v_readlane_b32 s42, v244, 51
	v_readlane_b32 s43, v244, 52
	v_readlane_b32 s44, v244, 53
	v_readlane_b32 s45, v244, 54
	v_readlane_b32 s52, v244, 61
	v_readlane_b32 s53, v244, 62
	v_readlane_b32 s54, v244, 63
	v_readlane_b32 s55, v243, 0
	s_cbranch_scc1 .LBB0_121
	s_barrier

.LBB0_137:
	s_add_u32 s18, s16, 0xfffe0080
	s_addc_u32 s19, s17, -1
	s_add_i32 s44, 0, 0x10000
	v_add_u32_e32 v142, s44, v146
	ds_read_b128 v[134:137], v142
	ds_read_b128 v[138:141], v142 offset:1024
	ds_read_b128 v[148:151], v142 offset:2048
	ds_read_b128 v[152:155], v142 offset:3072
	s_cmp_eq_u32 s43, 4
	s_cselect_b32 s21, s9, s19
	s_cselect_b32 s20, s39, s18
	s_cselect_b32 s19, s11, s42
	s_cselect_b32 s18, s40, s41
	v_lshl_add_u64 v[142:143], s[16:17], 0, v[130:131]
	s_add_i32 m0, s29, 0xc000
	ds_read_b128 v[156:159], v147
	ds_read_b128 v[160:163], v147 offset:1024
	ds_read_b128 v[164:167], v147 offset:2048
	ds_read_b128 v[168:171], v147 offset:3072
	ds_read_b128 v[172:175], v147 offset:4096
	ds_read_b128 v[176:179], v147 offset:5120
	ds_read_b128 v[180:183], v147 offset:6144
	ds_read_b128 v[188:191], v147 offset:7168
	global_load_lds_dwordx4 v[142:143], off
	v_lshl_add_u64 v[142:143], s[16:17], 0, v[132:133]
	s_add_i32 m0, s29, 0xe000
	s_nop 0
	global_load_lds_dwordx4 v[142:143], off
	s_waitcnt lgkmcnt(8)
	s_setprio 1
	s_barrier
	s_waitcnt lgkmcnt(0)
	v_mfma_f32_16x16x32_bf16 v[124:127], v[134:137], v[156:159], v[124:127]
	v_mfma_f32_16x16x32_bf16 v[92:95], v[148:151], v[156:159], v[92:95]
	v_mfma_f32_16x16x32_bf16 v[120:123], v[134:137], v[164:167], v[120:123]
	v_mfma_f32_16x16x32_bf16 v[88:91], v[148:151], v[164:167], v[88:91]
	v_mfma_f32_16x16x32_bf16 v[116:119], v[134:137], v[172:175], v[116:119]
	v_mfma_f32_16x16x32_bf16 v[84:87], v[148:151], v[172:175], v[84:87]
	v_mfma_f32_16x16x32_bf16 v[112:115], v[134:137], v[180:183], v[112:115]
	v_mfma_f32_16x16x32_bf16 v[80:83], v[148:151], v[180:183], v[80:83]
	v_mfma_f32_16x16x32_bf16 v[124:127], v[138:141], v[160:163], v[124:127]
	v_mfma_f32_16x16x32_bf16 v[92:95], v[152:155], v[160:163], v[92:95]
	v_mfma_f32_16x16x32_bf16 v[120:123], v[138:141], v[168:171], v[120:123]
	v_mfma_f32_16x16x32_bf16 v[88:91], v[152:155], v[168:171], v[88:91]
	v_mfma_f32_16x16x32_bf16 v[116:119], v[138:141], v[176:179], v[116:119]
	v_mfma_f32_16x16x32_bf16 v[84:87], v[152:155], v[176:179], v[84:87]
	v_mfma_f32_16x16x32_bf16 v[112:115], v[138:141], v[188:191], v[112:115]
	v_mfma_f32_16x16x32_bf16 v[80:83], v[152:155], v[188:191], v[80:83]
	s_barrier
	s_setprio 0
	s_add_i32 s46, 0, 0x14000
	v_add_u32_e32 v142, s46, v146
	s_add_i32 s44, s44, s28
	ds_read_b128 v[192:195], v142
	ds_read_b128 v[202:205], v142 offset:1024
	ds_read_b128 v[206:209], v142 offset:2048
	ds_read_b128 v[210:213], v142 offset:3072
	v_lshl_add_u64 v[142:143], s[18:19], 0, v[184:185]
	s_mov_b32 m0, s44
	v_lshl_add_u64 v[196:197], s[18:19], 0, v[128:129]
	global_load_lds_dwordx4 v[142:143], off
	s_add_i32 m0, s44, 0x2000
	s_nop 0
	global_load_lds_dwordx4 v[196:197], off
	s_setprio 1
	s_barrier
	s_waitcnt lgkmcnt(0)
	v_mfma_f32_16x16x32_bf16 v[60:63], v[192:195], v[156:159], v[60:63]
	v_mfma_f32_16x16x32_bf16 v[28:31], v[206:209], v[156:159], v[28:31]
	v_mfma_f32_16x16x32_bf16 v[56:59], v[192:195], v[164:167], v[56:59]
	v_mfma_f32_16x16x32_bf16 v[24:27], v[206:209], v[164:167], v[24:27]
	v_mfma_f32_16x16x32_bf16 v[52:55], v[192:195], v[172:175], v[52:55]
	v_mfma_f32_16x16x32_bf16 v[20:23], v[206:209], v[172:175], v[20:23]
	v_mfma_f32_16x16x32_bf16 v[48:51], v[192:195], v[180:183], v[48:51]
	v_mfma_f32_16x16x32_bf16 v[16:19], v[206:209], v[180:183], v[16:19]
	v_mfma_f32_16x16x32_bf16 v[60:63], v[202:205], v[160:163], v[60:63]
	v_mfma_f32_16x16x32_bf16 v[28:31], v[210:213], v[160:163], v[28:31]
	v_mfma_f32_16x16x32_bf16 v[56:59], v[202:205], v[168:171], v[56:59]
	v_mfma_f32_16x16x32_bf16 v[24:27], v[210:213], v[168:171], v[24:27]
	v_mfma_f32_16x16x32_bf16 v[52:55], v[202:205], v[176:179], v[52:55]
	v_mfma_f32_16x16x32_bf16 v[20:23], v[210:213], v[176:179], v[20:23]
	v_mfma_f32_16x16x32_bf16 v[48:51], v[202:205], v[188:191], v[48:51]
	v_mfma_f32_16x16x32_bf16 v[16:19], v[210:213], v[188:191], v[16:19]
	s_barrier
	s_setprio 0
	s_mov_b32 m0, s29
	v_lshl_add_u64 v[214:215], s[20:21], 0, v[184:185]
	ds_read_b128 v[156:159], v147 offset:16384
	ds_read_b128 v[160:163], v147 offset:17408
	ds_read_b128 v[164:167], v147 offset:18432
	ds_read_b128 v[168:171], v147 offset:19456
	ds_read_b128 v[172:175], v147 offset:20480
	ds_read_b128 v[176:179], v147 offset:21504
	ds_read_b128 v[180:183], v147 offset:22528
	ds_read_b128 v[188:191], v147 offset:23552
	global_load_lds_dwordx4 v[214:215], off
	v_lshl_add_u64 v[216:217], s[20:21], 0, v[128:129]
	s_mov_b32 m0, s30
	s_nop 0
	global_load_lds_dwordx4 v[216:217], off
	s_setprio 1
	s_barrier
	s_waitcnt lgkmcnt(0)
	v_mfma_f32_16x16x32_bf16 v[108:111], v[134:137], v[156:159], v[108:111]
	v_mfma_f32_16x16x32_bf16 v[76:79], v[148:151], v[156:159], v[76:79]
	v_mfma_f32_16x16x32_bf16 v[104:107], v[134:137], v[164:167], v[104:107]
	v_mfma_f32_16x16x32_bf16 v[72:75], v[148:151], v[164:167], v[72:75]
	v_mfma_f32_16x16x32_bf16 v[100:103], v[134:137], v[172:175], v[100:103]
	v_mfma_f32_16x16x32_bf16 v[68:71], v[148:151], v[172:175], v[68:71]
	v_mfma_f32_16x16x32_bf16 v[96:99], v[134:137], v[180:183], v[96:99]
	v_mfma_f32_16x16x32_bf16 v[64:67], v[148:151], v[180:183], v[64:67]
	v_mfma_f32_16x16x32_bf16 v[108:111], v[138:141], v[160:163], v[108:111]
	v_mfma_f32_16x16x32_bf16 v[76:79], v[152:155], v[160:163], v[76:79]
	v_mfma_f32_16x16x32_bf16 v[104:107], v[138:141], v[168:171], v[104:107]
	v_mfma_f32_16x16x32_bf16 v[72:75], v[152:155], v[168:171], v[72:75]
	v_mfma_f32_16x16x32_bf16 v[100:103], v[138:141], v[176:179], v[100:103]
	v_mfma_f32_16x16x32_bf16 v[68:71], v[152:155], v[176:179], v[68:71]
	v_mfma_f32_16x16x32_bf16 v[96:99], v[138:141], v[188:191], v[96:99]
	v_mfma_f32_16x16x32_bf16 v[64:67], v[152:155], v[188:191], v[64:67]
	s_barrier
	s_setprio 0
	s_add_u32 s44, s18, 0x20000
	s_addc_u32 s45, s19, 0
	s_add_i32 s46, s46, s28
	v_lshl_add_u64 v[134:135], s[44:45], 0, v[184:185]
	s_mov_b32 m0, s46
	s_nop 0
	global_load_lds_dwordx4 v[134:135], off
	v_lshl_add_u64 v[134:135], s[44:45], 0, v[128:129]
	s_add_i32 m0, s46, 0x2000
	s_nop 0
	global_load_lds_dwordx4 v[134:135], off
	s_waitcnt vmcnt(6)
	s_setprio 1
	s_barrier
	v_mfma_f32_16x16x32_bf16 v[44:47], v[192:195], v[156:159], v[44:47]
	v_mfma_f32_16x16x32_bf16 v[12:15], v[206:209], v[156:159], v[12:15]
	v_mfma_f32_16x16x32_bf16 v[40:43], v[192:195], v[164:167], v[40:43]
	v_mfma_f32_16x16x32_bf16 v[8:11], v[206:209], v[164:167], v[8:11]
	v_mfma_f32_16x16x32_bf16 v[36:39], v[192:195], v[172:175], v[36:39]
	v_mfma_f32_16x16x32_bf16 v[4:7], v[206:209], v[172:175], v[4:7]
	v_mfma_f32_16x16x32_bf16 v[32:35], v[192:195], v[180:183], v[32:35]
	v_mfma_f32_16x16x32_bf16 v[0:3], v[206:209], v[180:183], v[0:3]
	v_mfma_f32_16x16x32_bf16 v[44:47], v[202:205], v[160:163], v[44:47]
	v_mfma_f32_16x16x32_bf16 v[12:15], v[210:213], v[160:163], v[12:15]
	v_mfma_f32_16x16x32_bf16 v[40:43], v[202:205], v[168:171], v[40:43]
	v_mfma_f32_16x16x32_bf16 v[8:11], v[210:213], v[168:171], v[8:11]
	v_mfma_f32_16x16x32_bf16 v[36:39], v[202:205], v[176:179], v[36:39]
	v_mfma_f32_16x16x32_bf16 v[4:7], v[210:213], v[176:179], v[4:7]
	v_mfma_f32_16x16x32_bf16 v[32:35], v[202:205], v[188:191], v[32:35]
	v_mfma_f32_16x16x32_bf16 v[0:3], v[210:213], v[188:191], v[0:3]
	s_barrier
	s_setprio 0
	s_add_i32 s44, 0, 0x18000
	v_add_u32_e32 v152, s44, v146
	ds_read_b128 v[134:137], v152
	ds_read_b128 v[138:141], v152 offset:1024
	ds_read_b128 v[148:151], v152 offset:2048
	ds_read_b128 v[152:155], v152 offset:3072
	s_add_u32 s20, s20, 0x20000
	s_addc_u32 s21, s21, 0
	s_mov_b32 m0, s31
	v_lshl_add_u64 v[192:193], s[20:21], 0, v[184:185]
	ds_read_b128 v[156:159], v147 offset:32768
	ds_read_b128 v[160:163], v147 offset:33792
	ds_read_b128 v[164:167], v147 offset:34816
	ds_read_b128 v[168:171], v147 offset:35840
	ds_read_b128 v[172:175], v147 offset:36864
	ds_read_b128 v[176:179], v147 offset:37888
	ds_read_b128 v[180:183], v147 offset:38912
	ds_read_b128 v[188:191], v147 offset:39936
	global_load_lds_dwordx4 v[192:193], off
	v_lshl_add_u64 v[192:193], s[20:21], 0, v[128:129]
	s_mov_b32 m0, s33
	s_nop 0
	global_load_lds_dwordx4 v[192:193], off
	s_waitcnt lgkmcnt(8)
	s_setprio 1
	s_barrier
	s_waitcnt lgkmcnt(0)
	v_mfma_f32_16x16x32_bf16 v[124:127], v[134:137], v[156:159], v[124:127]
	v_mfma_f32_16x16x32_bf16 v[92:95], v[148:151], v[156:159], v[92:95]
	v_mfma_f32_16x16x32_bf16 v[120:123], v[134:137], v[164:167], v[120:123]
	v_mfma_f32_16x16x32_bf16 v[88:91], v[148:151], v[164:167], v[88:91]
	v_mfma_f32_16x16x32_bf16 v[116:119], v[134:137], v[172:175], v[116:119]
	v_mfma_f32_16x16x32_bf16 v[84:87], v[148:151], v[172:175], v[84:87]
	v_mfma_f32_16x16x32_bf16 v[112:115], v[134:137], v[180:183], v[112:115]
	v_mfma_f32_16x16x32_bf16 v[80:83], v[148:151], v[180:183], v[80:83]
	v_mfma_f32_16x16x32_bf16 v[124:127], v[138:141], v[160:163], v[124:127]
	v_mfma_f32_16x16x32_bf16 v[92:95], v[152:155], v[160:163], v[92:95]
	v_mfma_f32_16x16x32_bf16 v[120:123], v[138:141], v[168:171], v[120:123]
	v_mfma_f32_16x16x32_bf16 v[88:91], v[152:155], v[168:171], v[88:91]
	v_mfma_f32_16x16x32_bf16 v[116:119], v[138:141], v[176:179], v[116:119]
	v_mfma_f32_16x16x32_bf16 v[84:87], v[152:155], v[176:179], v[84:87]
	v_mfma_f32_16x16x32_bf16 v[112:115], v[138:141], v[188:191], v[112:115]
	v_mfma_f32_16x16x32_bf16 v[80:83], v[152:155], v[188:191], v[80:83]
	s_barrier
	s_setprio 0
	s_add_i32 s20, 0, 0x1c000
	s_add_i32 s21, s44, s28
	v_add_u32_e32 v187, s20, v146
	v_lshl_add_u64 v[142:143], v[142:143], 0, s[48:49]
	s_mov_b32 m0, s21
	ds_read_b128 v[192:195], v187
	ds_read_b128 v[202:205], v187 offset:1024
	ds_read_b128 v[206:209], v187 offset:2048
	ds_read_b128 v[210:213], v187 offset:3072
	global_load_lds_dwordx4 v[142:143], off
	v_lshl_add_u64 v[142:143], v[196:197], 0, s[48:49]
	s_add_i32 m0, s21, 0x2000
	s_nop 0
	global_load_lds_dwordx4 v[142:143], off
	s_setprio 1
	s_barrier
	s_waitcnt lgkmcnt(0)
	v_mfma_f32_16x16x32_bf16 v[60:63], v[192:195], v[156:159], v[60:63]
	v_mfma_f32_16x16x32_bf16 v[28:31], v[206:209], v[156:159], v[28:31]
	v_mfma_f32_16x16x32_bf16 v[56:59], v[192:195], v[164:167], v[56:59]
	v_mfma_f32_16x16x32_bf16 v[24:27], v[206:209], v[164:167], v[24:27]
	v_mfma_f32_16x16x32_bf16 v[52:55], v[192:195], v[172:175], v[52:55]
	v_mfma_f32_16x16x32_bf16 v[20:23], v[206:209], v[172:175], v[20:23]
	v_mfma_f32_16x16x32_bf16 v[48:51], v[192:195], v[180:183], v[48:51]
	v_mfma_f32_16x16x32_bf16 v[16:19], v[206:209], v[180:183], v[16:19]
	v_mfma_f32_16x16x32_bf16 v[60:63], v[202:205], v[160:163], v[60:63]
	v_mfma_f32_16x16x32_bf16 v[28:31], v[210:213], v[160:163], v[28:31]
	v_mfma_f32_16x16x32_bf16 v[56:59], v[202:205], v[168:171], v[56:59]
	v_mfma_f32_16x16x32_bf16 v[24:27], v[210:213], v[168:171], v[24:27]
	v_mfma_f32_16x16x32_bf16 v[52:55], v[202:205], v[176:179], v[52:55]
	v_mfma_f32_16x16x32_bf16 v[20:23], v[210:213], v[176:179], v[20:23]
	v_mfma_f32_16x16x32_bf16 v[48:51], v[202:205], v[188:191], v[48:51]
	v_mfma_f32_16x16x32_bf16 v[16:19], v[210:213], v[188:191], v[16:19]
	s_barrier
	s_setprio 0
	s_mov_b32 m0, s36
	v_lshl_add_u64 v[142:143], v[214:215], 0, s[48:49]
	ds_read_b128 v[156:159], v147 offset:49152
	ds_read_b128 v[160:163], v147 offset:50176
	ds_read_b128 v[164:167], v147 offset:51200
	ds_read_b128 v[168:171], v147 offset:52224
	ds_read_b128 v[172:175], v147 offset:53248
	ds_read_b128 v[176:179], v147 offset:54272
	ds_read_b128 v[180:183], v147 offset:55296
	ds_read_b128 v[188:191], v147 offset:56320
	global_load_lds_dwordx4 v[142:143], off
	v_lshl_add_u64 v[142:143], v[216:217], 0, s[48:49]
	s_mov_b32 m0, s37
	s_nop 0
	global_load_lds_dwordx4 v[142:143], off
	s_setprio 1
	s_barrier
	s_waitcnt lgkmcnt(0)
	v_mfma_f32_16x16x32_bf16 v[108:111], v[134:137], v[156:159], v[108:111]
	v_mfma_f32_16x16x32_bf16 v[76:79], v[148:151], v[156:159], v[76:79]
	v_mfma_f32_16x16x32_bf16 v[104:107], v[134:137], v[164:167], v[104:107]
	v_mfma_f32_16x16x32_bf16 v[72:75], v[148:151], v[164:167], v[72:75]
	v_mfma_f32_16x16x32_bf16 v[100:103], v[134:137], v[172:175], v[100:103]
	v_mfma_f32_16x16x32_bf16 v[68:71], v[148:151], v[172:175], v[68:71]
	v_mfma_f32_16x16x32_bf16 v[96:99], v[134:137], v[180:183], v[96:99]
	v_mfma_f32_16x16x32_bf16 v[64:67], v[148:151], v[180:183], v[64:67]
	v_mfma_f32_16x16x32_bf16 v[108:111], v[138:141], v[160:163], v[108:111]
	v_mfma_f32_16x16x32_bf16 v[76:79], v[152:155], v[160:163], v[76:79]
	v_mfma_f32_16x16x32_bf16 v[104:107], v[138:141], v[168:171], v[104:107]
	v_mfma_f32_16x16x32_bf16 v[72:75], v[152:155], v[168:171], v[72:75]
	v_mfma_f32_16x16x32_bf16 v[100:103], v[138:141], v[176:179], v[100:103]
	v_mfma_f32_16x16x32_bf16 v[68:71], v[152:155], v[176:179], v[68:71]
	v_mfma_f32_16x16x32_bf16 v[96:99], v[138:141], v[188:191], v[96:99]
	v_mfma_f32_16x16x32_bf16 v[64:67], v[152:155], v[188:191], v[64:67]
	s_barrier
	s_setprio 0
	s_add_u32 s18, s18, 0x20080
	s_addc_u32 s19, s19, 0
	s_add_i32 s20, s20, s28
	v_lshl_add_u64 v[134:135], s[18:19], 0, v[184:185]
	s_mov_b32 m0, s20
	s_nop 0
	global_load_lds_dwordx4 v[134:135], off
	v_lshl_add_u64 v[134:135], s[18:19], 0, v[128:129]
	s_add_i32 m0, s20, 0x2000
	s_nop 0
	global_load_lds_dwordx4 v[134:135], off
	s_waitcnt vmcnt(6)
	s_setprio 1
	s_barrier
	v_mfma_f32_16x16x32_bf16 v[44:47], v[192:195], v[156:159], v[44:47]
	v_mfma_f32_16x16x32_bf16 v[12:15], v[206:209], v[156:159], v[12:15]
	v_mfma_f32_16x16x32_bf16 v[40:43], v[192:195], v[164:167], v[40:43]
	v_mfma_f32_16x16x32_bf16 v[8:11], v[206:209], v[164:167], v[8:11]
	v_mfma_f32_16x16x32_bf16 v[36:39], v[192:195], v[172:175], v[36:39]
	v_mfma_f32_16x16x32_bf16 v[4:7], v[206:209], v[172:175], v[4:7]
	v_mfma_f32_16x16x32_bf16 v[32:35], v[192:195], v[180:183], v[32:35]
	v_mfma_f32_16x16x32_bf16 v[0:3], v[206:209], v[180:183], v[0:3]
	v_mfma_f32_16x16x32_bf16 v[44:47], v[202:205], v[160:163], v[44:47]
	v_mfma_f32_16x16x32_bf16 v[12:15], v[210:213], v[160:163], v[12:15]
	v_mfma_f32_16x16x32_bf16 v[40:43], v[202:205], v[168:171], v[40:43]
	v_mfma_f32_16x16x32_bf16 v[8:11], v[210:213], v[168:171], v[8:11]
	v_mfma_f32_16x16x32_bf16 v[36:39], v[202:205], v[176:179], v[36:39]
	v_mfma_f32_16x16x32_bf16 v[4:7], v[210:213], v[176:179], v[4:7]
	v_mfma_f32_16x16x32_bf16 v[32:35], v[202:205], v[188:191], v[32:35]
	v_mfma_f32_16x16x32_bf16 v[0:3], v[210:213], v[188:191], v[0:3]
	s_barrier
	s_setprio 0
	s_add_i32 s43, s43, 2
	s_add_u32 s16, s16, 0x100
	s_addc_u32 s17, s17, 0
	s_add_u32 s41, s41, 0x100
	s_addc_u32 s42, s42, 0
	s_cmp_gt_u32 s43, 5
	s_cbranch_scc0 .LBB0_137
	s_lshl_b32 s0, s0, 8
	v_mov_b32_e32 v134, v145
	v_mov_b32_e32 v135, v144
	s_add_i32 s0, s0, s34
	s_mov_b32 s20, 0x3a0637bd
	v_add_u32_e32 v142, s0, v135
	s_lshl_b32 s0, s1, 8
	v_lshlrev_b32_e32 v135, 1, v134
	v_lshrrev_b32_e32 v136, 1, v134
	s_or_b32 s16, s0, s35
	v_and_or_b32 v135, v135, 2, v136
	v_lshl_add_u32 v134, v134, 2, s16
	v_lshlrev_b32_e32 v136, 2, v135
	v_ashrrev_i32_e32 v135, 31, v134
	v_lshlrev_b64 v[138:139], 5, v[134:135]
	v_lshl_add_u64 v[156:157], s[4:5], 0, v[138:139]
	global_load_dwordx4 v[138:141], v[156:157], off offset:16
	global_load_dwordx4 v[148:151], v[156:157], off offset:48
	global_load_dwordx4 v[152:155], v[156:157], off
	s_nop 0
	global_load_dwordx4 v[156:159], v[156:157], off offset:32
	s_mov_b32 s40, 0x3b000000
	s_mov_b32 s18, 0x45800000
	v_ashrrev_i32_e32 v143, 31, v142
	v_ashrrev_i32_e32 v137, 31, v136
	s_ashr_i32 s17, s16, 31
	s_waitcnt vmcnt(0)
	v_mov_b32_e32 v160, v152
	v_mov_b32_e32 v161, v156
	v_mov_b32_e32 v156, v153
	v_pk_add_f32 v[152:153], v[160:161], v[156:157]
	v_mov_b32_e32 v156, v154
	v_mov_b32_e32 v157, v158
	v_pk_add_f32 v[152:153], v[156:157], v[152:153]
	v_mov_b32_e32 v158, v155
	v_pk_add_f32 v[152:153], v[158:159], v[152:153]
	v_mov_b32_e32 v154, v138
	v_mov_b32_e32 v155, v148
	v_pk_add_f32 v[152:153], v[154:155], v[152:153]
	v_mov_b32_e32 v148, v139
	v_pk_add_f32 v[138:139], v[148:149], v[152:153]
	v_mov_b32_e32 v148, v140
	v_mov_b32_e32 v149, v150
	v_pk_add_f32 v[138:139], v[148:149], v[138:139]
	v_mov_b32_e32 v150, v141
	v_pk_add_f32 v[138:139], v[150:151], v[138:139]
	s_nop 0
	v_pk_add_f32 v[138:139], v[138:139], s[20:21] op_sel_hi:[1,0]
	s_nop 0
	v_pk_mul_f32 v[138:139], v[138:139], s[40:41] op_sel_hi:[1,0]
	s_nop 0
	v_mul_f32_e32 v135, 0x4b800000, v138
	v_cmp_gt_f32_e64 s[0:1], s67, v138
	v_cmp_gt_f32_e32 vcc, s67, v139
	s_nop 0
	v_cndmask_b32_e64 v135, v138, v135, s[0:1]
	v_rsq_f32_e32 v138, v135
	v_mul_f32_e32 v135, 0x4b800000, v139
	v_cndmask_b32_e32 v135, v139, v135, vcc
	v_rsq_f32_e32 v139, v135
	s_nop 0
	v_pk_mul_f32 v[140:141], v[138:139], s[18:19] op_sel_hi:[1,0]
	s_nop 0
	v_cndmask_b32_e64 v138, v138, v140, s[0:1]
	v_or_b32_e32 v140, 2, v134
	v_cndmask_b32_e32 v139, v139, v141, vcc
	v_ashrrev_i32_e32 v141, 31, v140
	v_lshlrev_b64 v[140:141], 5, v[140:141]
	v_lshl_add_u64 v[140:141], s[4:5], 0, v[140:141]
	global_load_dwordx4 v[148:151], v[140:141], off offset:16
	global_load_dwordx4 v[152:155], v[140:141], off offset:48
	global_load_dwordx4 v[156:159], v[140:141], off
	global_load_dwordx4 v[160:163], v[140:141], off offset:32
	v_pk_mul_f32 v[124:125], v[124:125], v[138:139]
	v_pk_mul_f32 v[120:121], v[120:121], v[138:139]
	v_pk_mul_f32 v[116:117], v[116:117], v[138:139]
	v_pk_mul_f32 v[112:113], v[112:113], v[138:139]
	v_pk_mul_f32 v[108:109], v[108:109], v[138:139]
	v_pk_mul_f32 v[104:105], v[104:105], v[138:139]
	v_pk_mul_f32 v[100:101], v[100:101], v[138:139]
	v_pk_mul_f32 v[96:97], v[96:97], v[138:139]
	s_waitcnt vmcnt(0)
	v_mov_b32_e32 v140, v156
	v_mov_b32_e32 v141, v160
	v_mov_b32_e32 v160, v157
	v_pk_add_f32 v[140:141], v[140:141], v[160:161]
	v_mov_b32_e32 v156, v158
	v_mov_b32_e32 v157, v162
	v_pk_add_f32 v[140:141], v[156:157], v[140:141]
	v_mov_b32_e32 v162, v159
	v_pk_add_f32 v[140:141], v[162:163], v[140:141]
	v_mov_b32_e32 v156, v148
	v_mov_b32_e32 v157, v152
	v_pk_add_f32 v[140:141], v[156:157], v[140:141]
	v_mov_b32_e32 v152, v149
	v_pk_add_f32 v[140:141], v[152:153], v[140:141]
	v_mov_b32_e32 v148, v150
	v_mov_b32_e32 v149, v154
	v_pk_add_f32 v[140:141], v[148:149], v[140:141]
	v_mov_b32_e32 v154, v151
	v_pk_add_f32 v[140:141], v[154:155], v[140:141]
	v_cvt_pk_bf16_f32 v150, v124, v125
	v_lshlrev_b64 v[124:125], 16, v[142:143]
	v_pk_add_f32 v[140:141], v[140:141], s[20:21] op_sel_hi:[1,0]
	v_lshl_add_u64 v[124:125], s[2:3], 0, v[124:125]
	v_pk_mul_f32 v[140:141], v[140:141], s[40:41] op_sel_hi:[1,0]
	s_nop 0
	v_mul_f32_e32 v135, 0x4b800000, v140
	v_cmp_gt_f32_e64 s[0:1], s67, v140
	v_cmp_gt_f32_e32 vcc, s67, v141
	s_nop 0
	v_cndmask_b32_e64 v135, v140, v135, s[0:1]
	v_rsq_f32_e32 v140, v135
	v_mul_f32_e32 v135, 0x4b800000, v141
	v_cndmask_b32_e32 v135, v141, v135, vcc
	v_rsq_f32_e32 v141, v135
	s_nop 0
	v_pk_mul_f32 v[148:149], v[140:141], s[18:19] op_sel_hi:[1,0]
	s_nop 0
	v_cndmask_b32_e32 v141, v141, v149, vcc
	v_cndmask_b32_e64 v140, v140, v148, s[0:1]
	v_add_u32_e32 v148, s16, v136
	v_ashrrev_i32_e32 v149, 31, v148
	v_pk_mul_f32 v[126:127], v[126:127], v[140:141]
	s_mov_b64 s[0:1], 0x100000
	v_cvt_pk_bf16_f32 v151, v126, v127
	v_lshlrev_b64 v[126:127], 1, v[148:149]
	v_lshl_add_u64 v[142:143], v[124:125], 0, v[126:127]
	global_store_dwordx2 v[142:143], v[150:151], off
	v_pk_mul_f32 v[122:123], v[122:123], v[140:141]
	v_cvt_pk_bf16_f32 v142, v120, v121
	v_lshl_add_u64 v[120:121], v[124:125], 0, s[0:1]
	v_cvt_pk_bf16_f32 v143, v122, v123
	v_lshl_add_u64 v[122:123], v[120:121], 0, v[126:127]
	s_mov_b64 s[0:1], 0x200000
	global_store_dwordx2 v[122:123], v[142:143], off
	v_pk_mul_f32 v[118:119], v[118:119], v[140:141]
	v_cvt_pk_bf16_f32 v122, v116, v117
	v_lshl_add_u64 v[116:117], v[124:125], 0, s[0:1]
	v_cvt_pk_bf16_f32 v123, v118, v119
	v_lshl_add_u64 v[118:119], v[116:117], 0, v[126:127]
	s_mov_b64 s[0:1], 0x300000
	global_store_dwordx2 v[118:119], v[122:123], off
	v_pk_mul_f32 v[114:115], v[114:115], v[140:141]
	v_cvt_pk_bf16_f32 v118, v112, v113
	v_lshl_add_u64 v[112:113], v[124:125], 0, s[0:1]
	v_cvt_pk_bf16_f32 v119, v114, v115
	v_lshl_add_u64 v[114:115], v[112:113], 0, v[126:127]
	s_mov_b64 s[0:1], 0x800000
	global_store_dwordx2 v[114:115], v[118:119], off
	v_pk_mul_f32 v[110:111], v[110:111], v[140:141]
	v_cvt_pk_bf16_f32 v114, v108, v109
	v_lshl_add_u64 v[108:109], v[124:125], 0, s[0:1]
	v_cvt_pk_bf16_f32 v115, v110, v111
	v_lshl_add_u64 v[110:111], v[108:109], 0, v[126:127]
	s_mov_b64 s[0:1], 0x900000
	global_store_dwordx2 v[110:111], v[114:115], off
	v_pk_mul_f32 v[106:107], v[106:107], v[140:141]
	v_cvt_pk_bf16_f32 v110, v104, v105
	v_lshl_add_u64 v[104:105], v[124:125], 0, s[0:1]
	v_cvt_pk_bf16_f32 v111, v106, v107
	v_lshl_add_u64 v[106:107], v[104:105], 0, v[126:127]
	s_mov_b64 s[0:1], 0xa00000
	global_store_dwordx2 v[106:107], v[110:111], off
	v_pk_mul_f32 v[102:103], v[102:103], v[140:141]
	v_cvt_pk_bf16_f32 v106, v100, v101
	v_lshl_add_u64 v[100:101], v[124:125], 0, s[0:1]
	v_cvt_pk_bf16_f32 v107, v102, v103
	v_lshl_add_u64 v[102:103], v[100:101], 0, v[126:127]
	s_mov_b64 s[0:1], 0xb00000
	global_store_dwordx2 v[102:103], v[106:107], off
	v_pk_mul_f32 v[98:99], v[98:99], v[140:141]
	v_cvt_pk_bf16_f32 v102, v96, v97
	v_lshl_add_u64 v[96:97], v[124:125], 0, s[0:1]
	v_cvt_pk_bf16_f32 v103, v98, v99
	v_lshl_add_u64 v[98:99], v[96:97], 0, v[126:127]
	global_store_dwordx2 v[98:99], v[102:103], off
	v_add_u32_e32 v98, 16, v134
	v_ashrrev_i32_e32 v99, 31, v98
	v_lshlrev_b64 v[98:99], 5, v[98:99]
	v_lshl_add_u64 v[98:99], s[4:5], 0, v[98:99]
	global_load_dwordx4 v[138:141], v[98:99], off offset:16
	global_load_dwordx4 v[148:151], v[98:99], off offset:48
	global_load_dwordx4 v[152:155], v[98:99], off
	global_load_dwordx4 v[156:159], v[98:99], off offset:32
	s_waitcnt vmcnt(0)
	v_mov_b32_e32 v98, v152
	v_mov_b32_e32 v99, v156
	v_mov_b32_e32 v156, v153
	v_pk_add_f32 v[98:99], v[98:99], v[156:157]
	v_mov_b32_e32 v102, v154
	v_mov_b32_e32 v103, v158
	v_pk_add_f32 v[98:99], v[102:103], v[98:99]
	v_mov_b32_e32 v158, v155
	v_pk_add_f32 v[98:99], v[158:159], v[98:99]
	v_mov_b32_e32 v102, v138
	v_mov_b32_e32 v103, v148
	v_pk_add_f32 v[98:99], v[102:103], v[98:99]
	v_mov_b32_e32 v148, v139
	v_pk_add_f32 v[98:99], v[148:149], v[98:99]
	v_mov_b32_e32 v102, v140
	v_mov_b32_e32 v103, v150
	v_pk_add_f32 v[98:99], v[102:103], v[98:99]
	v_mov_b32_e32 v150, v141
	v_pk_add_f32 v[98:99], v[150:151], v[98:99]
	s_nop 0
	v_pk_add_f32 v[98:99], v[98:99], s[20:21] op_sel_hi:[1,0]
	s_nop 0
	v_pk_mul_f32 v[98:99], v[98:99], s[40:41] op_sel_hi:[1,0]
	s_nop 0
	v_mul_f32_e32 v102, 0x4b800000, v98
	v_cmp_gt_f32_e64 s[0:1], s67, v98
	v_cmp_gt_f32_e32 vcc, s67, v99
	s_nop 0
	v_cndmask_b32_e64 v98, v98, v102, s[0:1]
	v_mul_f32_e32 v102, 0x4b800000, v99
	v_cndmask_b32_e32 v99, v99, v102, vcc
	v_rsq_f32_e32 v98, v98
	v_rsq_f32_e32 v99, v99
	s_nop 0
	v_pk_mul_f32 v[102:103], v[98:99], s[18:19] op_sel_hi:[1,0]
	s_nop 0
	v_cndmask_b32_e64 v98, v98, v102, s[0:1]
	v_add_u32_e32 v102, 18, v134
	v_cndmask_b32_e32 v99, v99, v103, vcc
	v_ashrrev_i32_e32 v103, 31, v102
	v_lshlrev_b64 v[102:103], 5, v[102:103]
	v_lshl_add_u64 v[102:103], s[4:5], 0, v[102:103]
	global_load_dwordx4 v[138:141], v[102:103], off offset:16
	global_load_dwordx4 v[148:151], v[102:103], off offset:48
	global_load_dwordx4 v[152:155], v[102:103], off
	global_load_dwordx4 v[156:159], v[102:103], off offset:32
	v_pk_mul_f32 v[92:93], v[92:93], v[98:99]
	v_pk_mul_f32 v[88:89], v[88:89], v[98:99]
	v_pk_mul_f32 v[84:85], v[84:85], v[98:99]
	v_pk_mul_f32 v[80:81], v[80:81], v[98:99]
	v_pk_mul_f32 v[76:77], v[76:77], v[98:99]
	v_pk_mul_f32 v[72:73], v[72:73], v[98:99]
	v_pk_mul_f32 v[68:69], v[68:69], v[98:99]
	v_pk_mul_f32 v[64:65], v[64:65], v[98:99]
	s_waitcnt vmcnt(0)
	v_mov_b32_e32 v102, v152
	v_mov_b32_e32 v103, v156
	v_mov_b32_e32 v156, v153
	v_pk_add_f32 v[102:103], v[102:103], v[156:157]
	v_mov_b32_e32 v106, v154
	v_mov_b32_e32 v107, v158
	v_pk_add_f32 v[102:103], v[106:107], v[102:103]
	v_mov_b32_e32 v158, v155
	v_pk_add_f32 v[102:103], v[158:159], v[102:103]
	v_mov_b32_e32 v106, v138
	v_mov_b32_e32 v107, v148
	v_pk_add_f32 v[102:103], v[106:107], v[102:103]
	v_mov_b32_e32 v148, v139
	v_pk_add_f32 v[102:103], v[148:149], v[102:103]
	v_mov_b32_e32 v106, v140
	v_mov_b32_e32 v107, v150
	v_pk_add_f32 v[102:103], v[106:107], v[102:103]
	v_mov_b32_e32 v150, v141
	v_pk_add_f32 v[102:103], v[150:151], v[102:103]
	s_nop 0
	v_pk_add_f32 v[102:103], v[102:103], s[20:21] op_sel_hi:[1,0]
	s_nop 0
	v_pk_mul_f32 v[102:103], v[102:103], s[40:41] op_sel_hi:[1,0]
	s_nop 0
	v_mul_f32_e32 v106, 0x4b800000, v102
	v_cmp_gt_f32_e64 s[0:1], s67, v102
	v_cmp_gt_f32_e32 vcc, s67, v103
	s_nop 0
	v_cndmask_b32_e64 v102, v102, v106, s[0:1]
	v_mul_f32_e32 v106, 0x4b800000, v103
	v_cndmask_b32_e32 v103, v103, v106, vcc
	v_rsq_f32_e32 v102, v102
	v_rsq_f32_e32 v103, v103
	s_nop 0
	v_pk_mul_f32 v[106:107], v[102:103], s[18:19] op_sel_hi:[1,0]
	s_nop 0
	v_cndmask_b32_e32 v103, v103, v107, vcc
	v_cndmask_b32_e64 v102, v102, v106, s[0:1]
	v_pk_mul_f32 v[94:95], v[94:95], v[102:103]
	v_cvt_pk_bf16_f32 v106, v92, v93
	v_lshl_add_u64 v[92:93], v[136:137], 0, s[16:17]
	v_cvt_pk_bf16_f32 v107, v94, v95
	v_lshlrev_b64 v[94:95], 1, v[92:93]
	v_lshl_add_u64 v[92:93], v[124:125], 0, v[94:95]
	global_store_dwordx2 v[92:93], v[106:107], off offset:32
	v_pk_mul_f32 v[90:91], v[90:91], v[102:103]
	v_cvt_pk_bf16_f32 v106, v88, v89
	v_lshl_add_u64 v[88:89], v[120:121], 0, v[94:95]
	v_cvt_pk_bf16_f32 v107, v90, v91
	global_store_dwordx2 v[88:89], v[106:107], off offset:32
	v_pk_mul_f32 v[86:87], v[86:87], v[102:103]
	v_cvt_pk_bf16_f32 v90, v84, v85
	v_lshl_add_u64 v[84:85], v[116:117], 0, v[94:95]
	v_cvt_pk_bf16_f32 v91, v86, v87
	global_store_dwordx2 v[84:85], v[90:91], off offset:32
	v_pk_mul_f32 v[82:83], v[82:83], v[102:103]
	v_cvt_pk_bf16_f32 v86, v80, v81
	v_lshl_add_u64 v[80:81], v[112:113], 0, v[94:95]
	v_cvt_pk_bf16_f32 v87, v82, v83
	global_store_dwordx2 v[80:81], v[86:87], off offset:32
	v_pk_mul_f32 v[78:79], v[78:79], v[102:103]
	v_cvt_pk_bf16_f32 v82, v76, v77
	v_lshl_add_u64 v[76:77], v[108:109], 0, v[94:95]
	v_cvt_pk_bf16_f32 v83, v78, v79
	global_store_dwordx2 v[76:77], v[82:83], off offset:32
	v_pk_mul_f32 v[74:75], v[74:75], v[102:103]
	v_cvt_pk_bf16_f32 v78, v72, v73
	v_lshl_add_u64 v[72:73], v[104:105], 0, v[94:95]
	v_cvt_pk_bf16_f32 v79, v74, v75
	global_store_dwordx2 v[72:73], v[78:79], off offset:32
	v_pk_mul_f32 v[70:71], v[70:71], v[102:103]
	v_cvt_pk_bf16_f32 v74, v68, v69
	v_lshl_add_u64 v[68:69], v[100:101], 0, v[94:95]
	v_pk_mul_f32 v[66:67], v[66:67], v[102:103]
	v_cvt_pk_bf16_f32 v75, v70, v71
	global_store_dwordx2 v[68:69], v[74:75], off offset:32
	v_cvt_pk_bf16_f32 v70, v64, v65
	v_cvt_pk_bf16_f32 v71, v66, v67
	v_add_u32_e32 v66, 0x80, v134
	v_ashrrev_i32_e32 v67, 31, v66
	v_lshl_add_u64 v[64:65], v[96:97], 0, v[94:95]
	v_lshlrev_b64 v[66:67], 5, v[66:67]
	global_store_dwordx2 v[64:65], v[70:71], off offset:32
	v_lshl_add_u64 v[66:67], s[4:5], 0, v[66:67]
	global_load_dwordx4 v[94:97], v[66:67], off offset:16
	global_load_dwordx4 v[98:101], v[66:67], off offset:48
	global_load_dwordx4 v[102:105], v[66:67], off
	global_load_dwordx4 v[106:109], v[66:67], off offset:32
	s_mov_b64 s[16:17], s[12:13]
	s_waitcnt vmcnt(0)
	v_mov_b32_e32 v66, v102
	v_mov_b32_e32 v67, v106
	v_mov_b32_e32 v106, v103
	v_pk_add_f32 v[66:67], v[66:67], v[106:107]
	v_mov_b32_e32 v70, v104
	v_mov_b32_e32 v71, v108
	v_pk_add_f32 v[66:67], v[70:71], v[66:67]
	v_mov_b32_e32 v108, v105
	v_pk_add_f32 v[66:67], v[108:109], v[66:67]
	v_mov_b32_e32 v70, v94
	v_mov_b32_e32 v71, v98
	v_pk_add_f32 v[66:67], v[70:71], v[66:67]
	v_mov_b32_e32 v98, v95
	v_pk_add_f32 v[66:67], v[98:99], v[66:67]
	v_mov_b32_e32 v70, v96
	v_mov_b32_e32 v71, v100
	v_pk_add_f32 v[66:67], v[70:71], v[66:67]
	v_mov_b32_e32 v100, v97
	v_pk_add_f32 v[66:67], v[100:101], v[66:67]
	s_nop 0
	v_pk_add_f32 v[66:67], v[66:67], s[20:21] op_sel_hi:[1,0]
	s_nop 0
	v_pk_mul_f32 v[66:67], v[66:67], s[40:41] op_sel_hi:[1,0]
	s_nop 0
	v_mul_f32_e32 v70, 0x4b800000, v66
	v_cmp_gt_f32_e64 s[0:1], s67, v66
	v_cmp_gt_f32_e32 vcc, s67, v67
	s_nop 0
	v_cndmask_b32_e64 v66, v66, v70, s[0:1]
	v_mul_f32_e32 v70, 0x4b800000, v67
	v_cndmask_b32_e32 v67, v67, v70, vcc
	v_rsq_f32_e32 v66, v66
	v_rsq_f32_e32 v67, v67
	s_nop 0
	v_pk_mul_f32 v[70:71], v[66:67], s[18:19] op_sel_hi:[1,0]
	s_nop 0
	v_cndmask_b32_e64 v66, v66, v70, s[0:1]
	v_add_u32_e32 v70, 0x82, v134
	v_cndmask_b32_e32 v67, v67, v71, vcc
	v_ashrrev_i32_e32 v71, 31, v70
	v_lshlrev_b64 v[70:71], 5, v[70:71]
	v_lshl_add_u64 v[70:71], s[4:5], 0, v[70:71]
	global_load_dwordx4 v[94:97], v[70:71], off offset:16
	global_load_dwordx4 v[98:101], v[70:71], off offset:48
	global_load_dwordx4 v[102:105], v[70:71], off
	global_load_dwordx4 v[106:109], v[70:71], off offset:32
	v_pk_mul_f32 v[60:61], v[60:61], v[66:67]
	v_pk_mul_f32 v[56:57], v[56:57], v[66:67]
	v_pk_mul_f32 v[52:53], v[52:53], v[66:67]
	v_pk_mul_f32 v[48:49], v[48:49], v[66:67]
	v_pk_mul_f32 v[44:45], v[44:45], v[66:67]
	v_pk_mul_f32 v[40:41], v[40:41], v[66:67]
	v_pk_mul_f32 v[36:37], v[36:37], v[66:67]
	v_pk_mul_f32 v[32:33], v[32:33], v[66:67]
	v_cvt_pk_bf16_f32 v60, v60, v61
	s_waitcnt vmcnt(0)
	v_mov_b32_e32 v70, v102
	v_mov_b32_e32 v71, v106
	v_mov_b32_e32 v106, v103
	v_pk_add_f32 v[70:71], v[70:71], v[106:107]
	v_mov_b32_e32 v74, v104
	v_mov_b32_e32 v75, v108
	v_pk_add_f32 v[70:71], v[74:75], v[70:71]
	v_mov_b32_e32 v108, v105
	v_pk_add_f32 v[70:71], v[108:109], v[70:71]
	v_mov_b32_e32 v74, v94
	v_mov_b32_e32 v75, v98
	v_pk_add_f32 v[70:71], v[74:75], v[70:71]
	v_mov_b32_e32 v98, v95
	v_pk_add_f32 v[70:71], v[98:99], v[70:71]
	v_mov_b32_e32 v74, v96
	v_mov_b32_e32 v75, v100
	v_pk_add_f32 v[70:71], v[74:75], v[70:71]
	v_mov_b32_e32 v100, v97
	v_pk_add_f32 v[70:71], v[100:101], v[70:71]
	s_nop 0
	v_pk_add_f32 v[70:71], v[70:71], s[20:21] op_sel_hi:[1,0]
	s_nop 0
	v_pk_mul_f32 v[70:71], v[70:71], s[40:41] op_sel_hi:[1,0]
	s_nop 0
	v_mul_f32_e32 v74, 0x4b800000, v70
	v_cmp_gt_f32_e64 s[0:1], s67, v70
	v_cmp_gt_f32_e32 vcc, s67, v71
	s_nop 0
	v_cndmask_b32_e64 v70, v70, v74, s[0:1]
	v_mul_f32_e32 v74, 0x4b800000, v71
	v_cndmask_b32_e32 v71, v71, v74, vcc
	v_rsq_f32_e32 v70, v70
	v_rsq_f32_e32 v71, v71
	s_nop 0
	v_pk_mul_f32 v[74:75], v[70:71], s[18:19] op_sel_hi:[1,0]
	s_nop 0
	v_cndmask_b32_e32 v71, v71, v75, vcc
	v_cndmask_b32_e64 v70, v70, v74, s[0:1]
	v_pk_mul_f32 v[62:63], v[62:63], v[70:71]
	v_pk_mul_f32 v[58:59], v[58:59], v[70:71]
	v_cvt_pk_bf16_f32 v61, v62, v63
	global_store_dwordx2 v[92:93], v[60:61], off offset:256
	v_cvt_pk_bf16_f32 v56, v56, v57
	v_cvt_pk_bf16_f32 v57, v58, v59
	global_store_dwordx2 v[88:89], v[56:57], off offset:256
	v_pk_mul_f32 v[54:55], v[54:55], v[70:71]
	v_cvt_pk_bf16_f32 v52, v52, v53
	v_pk_mul_f32 v[50:51], v[50:51], v[70:71]
	v_cvt_pk_bf16_f32 v53, v54, v55
	global_store_dwordx2 v[84:85], v[52:53], off offset:256
	v_cvt_pk_bf16_f32 v48, v48, v49
	v_cvt_pk_bf16_f32 v49, v50, v51
	global_store_dwordx2 v[80:81], v[48:49], off offset:256
	v_pk_mul_f32 v[46:47], v[46:47], v[70:71]
	v_cvt_pk_bf16_f32 v44, v44, v45
	v_pk_mul_f32 v[42:43], v[42:43], v[70:71]
	v_cvt_pk_bf16_f32 v45, v46, v47
	global_store_dwordx2 v[76:77], v[44:45], off offset:256
	v_cvt_pk_bf16_f32 v40, v40, v41
	v_cvt_pk_bf16_f32 v41, v42, v43
	global_store_dwordx2 v[72:73], v[40:41], off offset:256
	v_pk_mul_f32 v[38:39], v[38:39], v[70:71]
	v_cvt_pk_bf16_f32 v36, v36, v37
	v_pk_mul_f32 v[34:35], v[34:35], v[70:71]
	v_cvt_pk_bf16_f32 v37, v38, v39
	global_store_dwordx2 v[68:69], v[36:37], off offset:256
	v_cvt_pk_bf16_f32 v32, v32, v33
	v_cvt_pk_bf16_f32 v33, v34, v35
	global_store_dwordx2 v[64:65], v[32:33], off offset:256
	v_add_u32_e32 v32, 0x90, v134
	v_ashrrev_i32_e32 v33, 31, v32
	v_lshlrev_b64 v[32:33], 5, v[32:33]
	v_lshl_add_u64 v[44:45], s[4:5], 0, v[32:33]
	global_load_dwordx4 v[32:35], v[44:45], off offset:16
	global_load_dwordx4 v[36:39], v[44:45], off offset:48
	global_load_dwordx4 v[40:43], v[44:45], off
	s_nop 0
	global_load_dwordx4 v[44:47], v[44:45], off offset:32
	s_waitcnt vmcnt(0)
	v_mov_b32_e32 v48, v40
	v_mov_b32_e32 v49, v44
	v_mov_b32_e32 v44, v41
	v_pk_add_f32 v[40:41], v[48:49], v[44:45]
	v_mov_b32_e32 v44, v42
	v_mov_b32_e32 v45, v46
	v_pk_add_f32 v[40:41], v[44:45], v[40:41]
	v_mov_b32_e32 v46, v43
	v_pk_add_f32 v[40:41], v[46:47], v[40:41]
	v_mov_b32_e32 v42, v32
	v_mov_b32_e32 v43, v36
	v_pk_add_f32 v[40:41], v[42:43], v[40:41]
	v_mov_b32_e32 v36, v33
	v_pk_add_f32 v[32:33], v[36:37], v[40:41]
	v_mov_b32_e32 v36, v34
	v_mov_b32_e32 v37, v38
	v_pk_add_f32 v[32:33], v[36:37], v[32:33]
	v_mov_b32_e32 v38, v35
	v_pk_add_f32 v[32:33], v[38:39], v[32:33]
	s_nop 0
	v_pk_add_f32 v[32:33], v[32:33], s[20:21] op_sel_hi:[1,0]
	s_nop 0
	v_pk_mul_f32 v[32:33], v[32:33], s[40:41] op_sel_hi:[1,0]
	s_nop 0
	v_mul_f32_e32 v34, 0x4b800000, v32
	v_cmp_gt_f32_e64 s[0:1], s67, v32
	v_cmp_gt_f32_e32 vcc, s67, v33
	s_nop 0
	v_cndmask_b32_e64 v32, v32, v34, s[0:1]
	v_mul_f32_e32 v34, 0x4b800000, v33
	v_cndmask_b32_e32 v33, v33, v34, vcc
	v_rsq_f32_e32 v32, v32
	v_rsq_f32_e32 v33, v33
	s_nop 0
	v_pk_mul_f32 v[34:35], v[32:33], s[18:19] op_sel_hi:[1,0]
	s_nop 0
	v_cndmask_b32_e64 v32, v32, v34, s[0:1]
	v_add_u32_e32 v34, 0x92, v134
	v_cndmask_b32_e32 v33, v33, v35, vcc
	v_ashrrev_i32_e32 v35, 31, v34
	v_lshlrev_b64 v[34:35], 5, v[34:35]
	v_lshl_add_u64 v[46:47], s[4:5], 0, v[34:35]
	global_load_dwordx4 v[34:37], v[46:47], off offset:16
	global_load_dwordx4 v[38:41], v[46:47], off offset:48
	global_load_dwordx4 v[42:45], v[46:47], off
	s_nop 0
	global_load_dwordx4 v[46:49], v[46:47], off offset:32
	v_pk_mul_f32 v[28:29], v[28:29], v[32:33]
	v_pk_mul_f32 v[24:25], v[24:25], v[32:33]
	v_pk_mul_f32 v[20:21], v[20:21], v[32:33]
	v_pk_mul_f32 v[16:17], v[16:17], v[32:33]
	v_pk_mul_f32 v[12:13], v[12:13], v[32:33]
	v_pk_mul_f32 v[8:9], v[8:9], v[32:33]
	v_pk_mul_f32 v[4:5], v[4:5], v[32:33]
	v_pk_mul_f32 v[0:1], v[0:1], v[32:33]
	v_cvt_pk_bf16_f32 v28, v28, v29
	s_waitcnt vmcnt(0)
	v_mov_b32_e32 v50, v42
	v_mov_b32_e32 v51, v46
	v_mov_b32_e32 v46, v43
	v_pk_add_f32 v[42:43], v[50:51], v[46:47]
	v_mov_b32_e32 v46, v44
	v_mov_b32_e32 v47, v48
	v_pk_add_f32 v[42:43], v[46:47], v[42:43]
	v_mov_b32_e32 v48, v45
	v_pk_add_f32 v[42:43], v[48:49], v[42:43]
	v_mov_b32_e32 v44, v34
	v_mov_b32_e32 v45, v38
	v_pk_add_f32 v[42:43], v[44:45], v[42:43]
	v_mov_b32_e32 v38, v35
	v_pk_add_f32 v[34:35], v[38:39], v[42:43]
	v_mov_b32_e32 v38, v36
	v_mov_b32_e32 v39, v40
	v_pk_add_f32 v[34:35], v[38:39], v[34:35]
	v_mov_b32_e32 v40, v37
	v_pk_add_f32 v[34:35], v[40:41], v[34:35]
	s_nop 0
	v_pk_add_f32 v[34:35], v[34:35], s[20:21] op_sel_hi:[1,0]
	s_nop 0
	v_pk_mul_f32 v[34:35], v[34:35], s[40:41] op_sel_hi:[1,0]
	v_readlane_b32 s40, v244, 49
	v_mul_f32_e32 v36, 0x4b800000, v34
	v_cmp_gt_f32_e64 s[0:1], s67, v34
	v_cmp_gt_f32_e32 vcc, s67, v35
	v_readlane_b32 s41, v244, 50
	v_cndmask_b32_e64 v34, v34, v36, s[0:1]
	v_mul_f32_e32 v36, 0x4b800000, v35
	v_cndmask_b32_e32 v35, v35, v36, vcc
	v_rsq_f32_e32 v34, v34
	v_rsq_f32_e32 v35, v35
	v_readlane_b32 s46, v244, 55
	v_readlane_b32 s47, v244, 56
	v_readlane_b32 s48, v244, 57
	v_pk_mul_f32 v[36:37], v[34:35], s[18:19] op_sel_hi:[1,0]
	s_mov_b64 s[18:19], s[14:15]
	v_cndmask_b32_e32 v35, v35, v37, vcc
	v_cndmask_b32_e64 v34, v34, v36, s[0:1]
	s_and_b64 vcc, exec, s[6:7]
	s_mov_b32 s1, s10
	s_mov_b32 s0, s8
	v_readlane_b32 s49, v244, 58
	v_readlane_b32 s50, v244, 59
	v_readlane_b32 s51, v244, 60
	v_pk_mul_f32 v[30:31], v[30:31], v[34:35]
	v_pk_mul_f32 v[26:27], v[26:27], v[34:35]
	v_cvt_pk_bf16_f32 v29, v30, v31
	global_store_dwordx2 v[92:93], v[28:29], off offset:288
	v_cvt_pk_bf16_f32 v24, v24, v25
	v_cvt_pk_bf16_f32 v25, v26, v27
	global_store_dwordx2 v[88:89], v[24:25], off offset:288
	v_pk_mul_f32 v[22:23], v[22:23], v[34:35]
	v_cvt_pk_bf16_f32 v20, v20, v21
	v_pk_mul_f32 v[18:19], v[18:19], v[34:35]
	v_cvt_pk_bf16_f32 v21, v22, v23
	global_store_dwordx2 v[84:85], v[20:21], off offset:288
	v_cvt_pk_bf16_f32 v16, v16, v17
	v_cvt_pk_bf16_f32 v17, v18, v19
	global_store_dwordx2 v[80:81], v[16:17], off offset:288
	v_pk_mul_f32 v[14:15], v[14:15], v[34:35]
	v_cvt_pk_bf16_f32 v12, v12, v13
	v_pk_mul_f32 v[10:11], v[10:11], v[34:35]
	v_cvt_pk_bf16_f32 v13, v14, v15
	global_store_dwordx2 v[76:77], v[12:13], off offset:288
	v_cvt_pk_bf16_f32 v8, v8, v9
	v_cvt_pk_bf16_f32 v9, v10, v11
	global_store_dwordx2 v[72:73], v[8:9], off offset:288
	v_pk_mul_f32 v[6:7], v[6:7], v[34:35]
	v_cvt_pk_bf16_f32 v4, v4, v5
	v_pk_mul_f32 v[2:3], v[2:3], v[34:35]
	v_cvt_pk_bf16_f32 v5, v6, v7
	global_store_dwordx2 v[68:69], v[4:5], off offset:288
	v_cvt_pk_bf16_f32 v0, v0, v1
	v_cvt_pk_bf16_f32 v1, v2, v3
	global_store_dwordx2 v[64:65], v[0:1], off offset:288
	v_readlane_b32 s42, v244, 51
	v_readlane_b32 s43, v244, 52
	v_readlane_b32 s44, v244, 53
	v_readlane_b32 s45, v244, 54
	v_readlane_b32 s52, v244, 61
	v_readlane_b32 s53, v244, 62
	v_readlane_b32 s54, v244, 63
	v_readlane_b32 s55, v243, 0
	s_cbranch_vccz .LBB0_130
	s_waitcnt vmcnt(0)
	s_cmpk_gt_u32 s22, 0xff
	s_cbranch_scc1 .LBB0_141
	s_barrier

.LBB0_152:
	s_add_u32 s20, s18, 0xfffe0080
	s_addc_u32 s21, s19, -1
	s_add_i32 s45, 0, 0x10000
	v_add_u32_e32 v138, s45, v142
	ds_read_b128 v[144:147], v138
	ds_read_b128 v[148:151], v138 offset:1024
	ds_read_b128 v[152:155], v138 offset:2048
	ds_read_b128 v[156:159], v138 offset:3072
	s_cmp_eq_u32 s44, 4
	s_cselect_b32 s23, s9, s21
	s_cselect_b32 s22, s40, s20
	s_cselect_b32 s21, s7, s43
	s_cselect_b32 s20, s41, s42
	v_lshl_add_u64 v[138:139], s[18:19], 0, v[134:135]
	s_add_i32 m0, s17, 0xc000
	ds_read_b128 v[160:163], v143
	ds_read_b128 v[164:167], v143 offset:1024
	ds_read_b128 v[168:171], v143 offset:2048
	ds_read_b128 v[172:175], v143 offset:3072
	ds_read_b128 v[176:179], v143 offset:4096
	ds_read_b128 v[180:183], v143 offset:5120
	ds_read_b128 v[188:191], v143 offset:6144
	ds_read_b128 v[192:195], v143 offset:7168
	global_load_lds_dwordx4 v[138:139], off
	v_lshl_add_u64 v[138:139], s[18:19], 0, v[136:137]
	s_add_i32 m0, s17, 0xe000
	s_nop 0
	global_load_lds_dwordx4 v[138:139], off
	s_waitcnt lgkmcnt(8)
	s_setprio 1
	s_barrier
	s_waitcnt lgkmcnt(0)
	v_mfma_f32_16x16x32_bf16 v[124:127], v[144:147], v[160:163], v[124:127]
	v_mfma_f32_16x16x32_bf16 v[120:123], v[152:155], v[160:163], v[120:123]
	v_mfma_f32_16x16x32_bf16 v[108:111], v[144:147], v[168:171], v[108:111]
	v_mfma_f32_16x16x32_bf16 v[104:107], v[152:155], v[168:171], v[104:107]
	v_mfma_f32_16x16x32_bf16 v[92:95], v[144:147], v[176:179], v[92:95]
	v_mfma_f32_16x16x32_bf16 v[88:91], v[152:155], v[176:179], v[88:91]
	v_mfma_f32_16x16x32_bf16 v[76:79], v[144:147], v[188:191], v[76:79]
	v_mfma_f32_16x16x32_bf16 v[72:75], v[152:155], v[188:191], v[72:75]
	v_mfma_f32_16x16x32_bf16 v[124:127], v[148:151], v[164:167], v[124:127]
	v_mfma_f32_16x16x32_bf16 v[120:123], v[156:159], v[164:167], v[120:123]
	v_mfma_f32_16x16x32_bf16 v[108:111], v[148:151], v[172:175], v[108:111]
	v_mfma_f32_16x16x32_bf16 v[104:107], v[156:159], v[172:175], v[104:107]
	v_mfma_f32_16x16x32_bf16 v[92:95], v[148:151], v[180:183], v[92:95]
	v_mfma_f32_16x16x32_bf16 v[88:91], v[156:159], v[180:183], v[88:91]
	v_mfma_f32_16x16x32_bf16 v[76:79], v[148:151], v[192:195], v[76:79]
	v_mfma_f32_16x16x32_bf16 v[72:75], v[156:159], v[192:195], v[72:75]
	s_barrier
	s_setprio 0
	s_add_i32 s48, 0, 0x14000
	v_add_u32_e32 v138, s48, v142
	s_add_i32 s45, s45, s29
	ds_read_b128 v[202:205], v138
	ds_read_b128 v[206:209], v138 offset:1024
	ds_read_b128 v[210:213], v138 offset:2048
	ds_read_b128 v[214:217], v138 offset:3072
	v_lshl_add_u64 v[138:139], s[20:21], 0, v[184:185]
	s_mov_b32 m0, s45
	v_lshl_add_u64 v[196:197], s[20:21], 0, v[128:129]
	global_load_lds_dwordx4 v[138:139], off
	s_add_i32 m0, s45, 0x2000
	s_nop 0
	global_load_lds_dwordx4 v[196:197], off
	s_setprio 1
	s_barrier
	s_waitcnt lgkmcnt(0)
	v_mfma_f32_16x16x32_bf16 v[116:119], v[202:205], v[160:163], v[116:119]
	v_mfma_f32_16x16x32_bf16 v[112:115], v[210:213], v[160:163], v[112:115]
	v_mfma_f32_16x16x32_bf16 v[100:103], v[202:205], v[168:171], v[100:103]
	v_mfma_f32_16x16x32_bf16 v[96:99], v[210:213], v[168:171], v[96:99]
	v_mfma_f32_16x16x32_bf16 v[84:87], v[202:205], v[176:179], v[84:87]
	v_mfma_f32_16x16x32_bf16 v[80:83], v[210:213], v[176:179], v[80:83]
	v_mfma_f32_16x16x32_bf16 v[68:71], v[202:205], v[188:191], v[68:71]
	v_mfma_f32_16x16x32_bf16 v[64:67], v[210:213], v[188:191], v[64:67]
	v_mfma_f32_16x16x32_bf16 v[116:119], v[206:209], v[164:167], v[116:119]
	v_mfma_f32_16x16x32_bf16 v[112:115], v[214:217], v[164:167], v[112:115]
	v_mfma_f32_16x16x32_bf16 v[100:103], v[206:209], v[172:175], v[100:103]
	v_mfma_f32_16x16x32_bf16 v[96:99], v[214:217], v[172:175], v[96:99]
	v_mfma_f32_16x16x32_bf16 v[84:87], v[206:209], v[180:183], v[84:87]
	v_mfma_f32_16x16x32_bf16 v[80:83], v[214:217], v[180:183], v[80:83]
	v_mfma_f32_16x16x32_bf16 v[68:71], v[206:209], v[192:195], v[68:71]
	v_mfma_f32_16x16x32_bf16 v[64:67], v[214:217], v[192:195], v[64:67]
	s_barrier
	s_setprio 0
	s_mov_b32 m0, s17
	v_lshl_add_u64 v[218:219], s[22:23], 0, v[132:133]
	ds_read_b128 v[160:163], v143 offset:16384
	ds_read_b128 v[164:167], v143 offset:17408
	ds_read_b128 v[168:171], v143 offset:18432
	ds_read_b128 v[172:175], v143 offset:19456
	ds_read_b128 v[176:179], v143 offset:20480
	ds_read_b128 v[180:183], v143 offset:21504
	ds_read_b128 v[188:191], v143 offset:22528
	ds_read_b128 v[192:195], v143 offset:23552
	global_load_lds_dwordx4 v[218:219], off
	v_lshl_add_u64 v[220:221], s[22:23], 0, v[130:131]
	s_mov_b32 m0, s30
	s_nop 0
	global_load_lds_dwordx4 v[220:221], off
	s_setprio 1
	s_barrier
	s_waitcnt lgkmcnt(0)
	v_mfma_f32_16x16x32_bf16 v[60:63], v[144:147], v[160:163], v[60:63]
	v_mfma_f32_16x16x32_bf16 v[56:59], v[152:155], v[160:163], v[56:59]
	v_mfma_f32_16x16x32_bf16 v[44:47], v[144:147], v[168:171], v[44:47]
	v_mfma_f32_16x16x32_bf16 v[40:43], v[152:155], v[168:171], v[40:43]
	v_mfma_f32_16x16x32_bf16 v[28:31], v[144:147], v[176:179], v[28:31]
	v_mfma_f32_16x16x32_bf16 v[24:27], v[152:155], v[176:179], v[24:27]
	v_mfma_f32_16x16x32_bf16 v[12:15], v[144:147], v[188:191], v[12:15]
	v_mfma_f32_16x16x32_bf16 v[8:11], v[152:155], v[188:191], v[8:11]
	v_mfma_f32_16x16x32_bf16 v[60:63], v[148:151], v[164:167], v[60:63]
	v_mfma_f32_16x16x32_bf16 v[56:59], v[156:159], v[164:167], v[56:59]
	v_mfma_f32_16x16x32_bf16 v[44:47], v[148:151], v[172:175], v[44:47]
	v_mfma_f32_16x16x32_bf16 v[40:43], v[156:159], v[172:175], v[40:43]
	v_mfma_f32_16x16x32_bf16 v[28:31], v[148:151], v[180:183], v[28:31]
	v_mfma_f32_16x16x32_bf16 v[24:27], v[156:159], v[180:183], v[24:27]
	v_mfma_f32_16x16x32_bf16 v[12:15], v[148:151], v[192:195], v[12:15]
	v_mfma_f32_16x16x32_bf16 v[8:11], v[156:159], v[192:195], v[8:11]
	s_barrier
	s_setprio 0
	s_add_u32 s46, s20, 0x20000
	s_addc_u32 s47, s21, 0
	s_add_i32 s45, s48, s29
	v_lshl_add_u64 v[144:145], s[46:47], 0, v[184:185]
	s_mov_b32 m0, s45
	s_nop 0
	global_load_lds_dwordx4 v[144:145], off
	v_lshl_add_u64 v[144:145], s[46:47], 0, v[128:129]
	s_add_i32 m0, s45, 0x2000
	s_nop 0
	global_load_lds_dwordx4 v[144:145], off
	s_waitcnt vmcnt(6)
	s_setprio 1
	s_barrier
	v_mfma_f32_16x16x32_bf16 v[52:55], v[202:205], v[160:163], v[52:55]
	v_mfma_f32_16x16x32_bf16 v[48:51], v[210:213], v[160:163], v[48:51]
	v_mfma_f32_16x16x32_bf16 v[36:39], v[202:205], v[168:171], v[36:39]
	v_mfma_f32_16x16x32_bf16 v[32:35], v[210:213], v[168:171], v[32:35]
	v_mfma_f32_16x16x32_bf16 v[20:23], v[202:205], v[176:179], v[20:23]
	v_mfma_f32_16x16x32_bf16 v[16:19], v[210:213], v[176:179], v[16:19]
	v_mfma_f32_16x16x32_bf16 v[4:7], v[202:205], v[188:191], v[4:7]
	v_mfma_f32_16x16x32_bf16 v[0:3], v[210:213], v[188:191], v[0:3]
	v_mfma_f32_16x16x32_bf16 v[52:55], v[206:209], v[164:167], v[52:55]
	v_mfma_f32_16x16x32_bf16 v[48:51], v[214:217], v[164:167], v[48:51]
	v_mfma_f32_16x16x32_bf16 v[36:39], v[206:209], v[172:175], v[36:39]
	v_mfma_f32_16x16x32_bf16 v[32:35], v[214:217], v[172:175], v[32:35]
	v_mfma_f32_16x16x32_bf16 v[20:23], v[206:209], v[180:183], v[20:23]
	v_mfma_f32_16x16x32_bf16 v[16:19], v[214:217], v[180:183], v[16:19]
	v_mfma_f32_16x16x32_bf16 v[4:7], v[206:209], v[192:195], v[4:7]
	v_mfma_f32_16x16x32_bf16 v[0:3], v[214:217], v[192:195], v[0:3]
	s_barrier
	s_setprio 0
	s_add_i32 s45, 0, 0x18000
	v_add_u32_e32 v156, s45, v142
	ds_read_b128 v[144:147], v156
	ds_read_b128 v[148:151], v156 offset:1024
	ds_read_b128 v[152:155], v156 offset:2048
	ds_read_b128 v[156:159], v156 offset:3072
	s_add_u32 s22, s22, 0x20000
	s_addc_u32 s23, s23, 0
	s_mov_b32 m0, s31
	v_lshl_add_u64 v[202:203], s[22:23], 0, v[132:133]
	ds_read_b128 v[160:163], v143 offset:32768
	ds_read_b128 v[164:167], v143 offset:33792
	ds_read_b128 v[168:171], v143 offset:34816
	ds_read_b128 v[172:175], v143 offset:35840
	ds_read_b128 v[176:179], v143 offset:36864
	ds_read_b128 v[180:183], v143 offset:37888
	ds_read_b128 v[188:191], v143 offset:38912
	ds_read_b128 v[192:195], v143 offset:39936
	global_load_lds_dwordx4 v[202:203], off
	v_lshl_add_u64 v[202:203], s[22:23], 0, v[130:131]
	s_mov_b32 m0, s33
	s_nop 0
	global_load_lds_dwordx4 v[202:203], off
	s_waitcnt lgkmcnt(8)
	s_setprio 1
	s_barrier
	s_waitcnt lgkmcnt(0)
	v_mfma_f32_16x16x32_bf16 v[124:127], v[144:147], v[160:163], v[124:127]
	v_mfma_f32_16x16x32_bf16 v[120:123], v[152:155], v[160:163], v[120:123]
	v_mfma_f32_16x16x32_bf16 v[108:111], v[144:147], v[168:171], v[108:111]
	v_mfma_f32_16x16x32_bf16 v[104:107], v[152:155], v[168:171], v[104:107]
	v_mfma_f32_16x16x32_bf16 v[92:95], v[144:147], v[176:179], v[92:95]
	v_mfma_f32_16x16x32_bf16 v[88:91], v[152:155], v[176:179], v[88:91]
	v_mfma_f32_16x16x32_bf16 v[76:79], v[144:147], v[188:191], v[76:79]
	v_mfma_f32_16x16x32_bf16 v[72:75], v[152:155], v[188:191], v[72:75]
	v_mfma_f32_16x16x32_bf16 v[124:127], v[148:151], v[164:167], v[124:127]
	v_mfma_f32_16x16x32_bf16 v[120:123], v[156:159], v[164:167], v[120:123]
	v_mfma_f32_16x16x32_bf16 v[108:111], v[148:151], v[172:175], v[108:111]
	v_mfma_f32_16x16x32_bf16 v[104:107], v[156:159], v[172:175], v[104:107]
	v_mfma_f32_16x16x32_bf16 v[92:95], v[148:151], v[180:183], v[92:95]
	v_mfma_f32_16x16x32_bf16 v[88:91], v[156:159], v[180:183], v[88:91]
	v_mfma_f32_16x16x32_bf16 v[76:79], v[148:151], v[192:195], v[76:79]
	v_mfma_f32_16x16x32_bf16 v[72:75], v[156:159], v[192:195], v[72:75]
	s_barrier
	s_setprio 0
	s_add_i32 s22, 0, 0x1c000
	s_add_i32 s23, s45, s29
	v_add_u32_e32 v187, s22, v142
	v_lshl_add_u64 v[138:139], v[138:139], 0, s[50:51]
	s_mov_b32 m0, s23
	ds_read_b128 v[202:205], v187
	ds_read_b128 v[206:209], v187 offset:1024
	ds_read_b128 v[210:213], v187 offset:2048
	ds_read_b128 v[214:217], v187 offset:3072
	global_load_lds_dwordx4 v[138:139], off
	v_lshl_add_u64 v[138:139], v[196:197], 0, s[50:51]
	s_add_i32 m0, s23, 0x2000
	s_nop 0
	global_load_lds_dwordx4 v[138:139], off
	s_setprio 1
	s_barrier
	s_waitcnt lgkmcnt(0)
	v_mfma_f32_16x16x32_bf16 v[116:119], v[202:205], v[160:163], v[116:119]
	v_mfma_f32_16x16x32_bf16 v[112:115], v[210:213], v[160:163], v[112:115]
	v_mfma_f32_16x16x32_bf16 v[100:103], v[202:205], v[168:171], v[100:103]
	v_mfma_f32_16x16x32_bf16 v[96:99], v[210:213], v[168:171], v[96:99]
	v_mfma_f32_16x16x32_bf16 v[84:87], v[202:205], v[176:179], v[84:87]
	v_mfma_f32_16x16x32_bf16 v[80:83], v[210:213], v[176:179], v[80:83]
	v_mfma_f32_16x16x32_bf16 v[68:71], v[202:205], v[188:191], v[68:71]
	v_mfma_f32_16x16x32_bf16 v[64:67], v[210:213], v[188:191], v[64:67]
	v_mfma_f32_16x16x32_bf16 v[116:119], v[206:209], v[164:167], v[116:119]
	v_mfma_f32_16x16x32_bf16 v[112:115], v[214:217], v[164:167], v[112:115]
	v_mfma_f32_16x16x32_bf16 v[100:103], v[206:209], v[172:175], v[100:103]
	v_mfma_f32_16x16x32_bf16 v[96:99], v[214:217], v[172:175], v[96:99]
	v_mfma_f32_16x16x32_bf16 v[84:87], v[206:209], v[180:183], v[84:87]
	v_mfma_f32_16x16x32_bf16 v[80:83], v[214:217], v[180:183], v[80:83]
	v_mfma_f32_16x16x32_bf16 v[68:71], v[206:209], v[192:195], v[68:71]
	v_mfma_f32_16x16x32_bf16 v[64:67], v[214:217], v[192:195], v[64:67]
	s_barrier
	s_setprio 0
	s_mov_b32 m0, s36
	v_lshl_add_u64 v[138:139], v[218:219], 0, s[50:51]
	ds_read_b128 v[160:163], v143 offset:49152
	ds_read_b128 v[164:167], v143 offset:50176
	ds_read_b128 v[168:171], v143 offset:51200
	ds_read_b128 v[172:175], v143 offset:52224
	ds_read_b128 v[176:179], v143 offset:53248
	ds_read_b128 v[180:183], v143 offset:54272
	ds_read_b128 v[188:191], v143 offset:55296
	ds_read_b128 v[192:195], v143 offset:56320
	global_load_lds_dwordx4 v[138:139], off
	v_lshl_add_u64 v[138:139], v[220:221], 0, s[50:51]
	s_mov_b32 m0, s37
	s_nop 0
	global_load_lds_dwordx4 v[138:139], off
	s_setprio 1
	s_barrier
	s_waitcnt lgkmcnt(0)
	v_mfma_f32_16x16x32_bf16 v[60:63], v[144:147], v[160:163], v[60:63]
	v_mfma_f32_16x16x32_bf16 v[56:59], v[152:155], v[160:163], v[56:59]
	v_mfma_f32_16x16x32_bf16 v[44:47], v[144:147], v[168:171], v[44:47]
	v_mfma_f32_16x16x32_bf16 v[40:43], v[152:155], v[168:171], v[40:43]
	v_mfma_f32_16x16x32_bf16 v[28:31], v[144:147], v[176:179], v[28:31]
	v_mfma_f32_16x16x32_bf16 v[24:27], v[152:155], v[176:179], v[24:27]
	v_mfma_f32_16x16x32_bf16 v[12:15], v[144:147], v[188:191], v[12:15]
	v_mfma_f32_16x16x32_bf16 v[8:11], v[152:155], v[188:191], v[8:11]
	v_mfma_f32_16x16x32_bf16 v[60:63], v[148:151], v[164:167], v[60:63]
	v_mfma_f32_16x16x32_bf16 v[56:59], v[156:159], v[164:167], v[56:59]
	v_mfma_f32_16x16x32_bf16 v[44:47], v[148:151], v[172:175], v[44:47]
	v_mfma_f32_16x16x32_bf16 v[40:43], v[156:159], v[172:175], v[40:43]
	v_mfma_f32_16x16x32_bf16 v[28:31], v[148:151], v[180:183], v[28:31]
	v_mfma_f32_16x16x32_bf16 v[24:27], v[156:159], v[180:183], v[24:27]
	v_mfma_f32_16x16x32_bf16 v[12:15], v[148:151], v[192:195], v[12:15]
	v_mfma_f32_16x16x32_bf16 v[8:11], v[156:159], v[192:195], v[8:11]
	s_barrier
	s_setprio 0
	s_add_u32 s20, s20, 0x20080
	s_addc_u32 s21, s21, 0
	s_add_i32 s22, s22, s29
	v_lshl_add_u64 v[138:139], s[20:21], 0, v[184:185]
	s_mov_b32 m0, s22
	s_nop 0
	global_load_lds_dwordx4 v[138:139], off
	v_lshl_add_u64 v[138:139], s[20:21], 0, v[128:129]
	s_add_i32 m0, s22, 0x2000
	s_nop 0
	global_load_lds_dwordx4 v[138:139], off
	s_waitcnt vmcnt(6)
	s_setprio 1
	s_barrier
	v_mfma_f32_16x16x32_bf16 v[52:55], v[202:205], v[160:163], v[52:55]
	v_mfma_f32_16x16x32_bf16 v[48:51], v[210:213], v[160:163], v[48:51]
	v_mfma_f32_16x16x32_bf16 v[36:39], v[202:205], v[168:171], v[36:39]
	v_mfma_f32_16x16x32_bf16 v[32:35], v[210:213], v[168:171], v[32:35]
	v_mfma_f32_16x16x32_bf16 v[20:23], v[202:205], v[176:179], v[20:23]
	v_mfma_f32_16x16x32_bf16 v[16:19], v[210:213], v[176:179], v[16:19]
	v_mfma_f32_16x16x32_bf16 v[4:7], v[202:205], v[188:191], v[4:7]
	v_mfma_f32_16x16x32_bf16 v[0:3], v[210:213], v[188:191], v[0:3]
	v_mfma_f32_16x16x32_bf16 v[52:55], v[206:209], v[164:167], v[52:55]
	v_mfma_f32_16x16x32_bf16 v[48:51], v[214:217], v[164:167], v[48:51]
	v_mfma_f32_16x16x32_bf16 v[36:39], v[206:209], v[172:175], v[36:39]
	v_mfma_f32_16x16x32_bf16 v[32:35], v[214:217], v[172:175], v[32:35]
	v_mfma_f32_16x16x32_bf16 v[20:23], v[206:209], v[180:183], v[20:23]
	v_mfma_f32_16x16x32_bf16 v[16:19], v[214:217], v[180:183], v[16:19]
	v_mfma_f32_16x16x32_bf16 v[4:7], v[206:209], v[192:195], v[4:7]
	v_mfma_f32_16x16x32_bf16 v[0:3], v[214:217], v[192:195], v[0:3]
	s_barrier
	s_setprio 0
	s_add_i32 s44, s44, 2
	s_add_u32 s18, s18, 0x100
	s_addc_u32 s19, s19, 0
	s_add_u32 s42, s42, 0x100
	s_addc_u32 s43, s43, 0
	s_cmp_gt_u32 s44, 5
	s_cbranch_scc0 .LBB0_152
	v_mov_b32_e32 v139, v141
	v_mov_b32_e32 v138, v140
	s_lshl_b32 s7, s16, 8
	s_add_i32 s7, s7, s34
	v_add_u32_e32 v138, s7, v138
	s_lshl_b32 s7, s39, 8
	s_or_b32 s7, s7, s35
	v_lshl_add_u32 v152, v139, 3, s7
	v_ashrrev_i32_e32 v139, 31, v138
	v_lshlrev_b64 v[144:145], 5, v[138:139]
	v_lshl_add_u64 v[148:149], s[4:5], 0, v[144:145]
	global_load_dwordx4 v[144:147], v[148:149], off offset:16
	s_nop 0
	global_load_dwordx4 v[148:151], v[148:149], off
	s_movk_i32 s7, 0x1800
	v_ashrrev_i32_e32 v153, 31, v152
	s_mov_b32 s39, s6
	s_mov_b32 s16, s8
	s_mov_b64 s[20:21], s[14:15]
	s_waitcnt vmcnt(0)
	v_add_f32_e32 v139, v148, v149
	v_add_f32_e32 v139, v150, v139
	v_add_f32_e32 v139, v151, v139
	v_add_f32_e32 v139, v144, v139
	v_add_f32_e32 v139, v145, v139
	v_add_f32_e32 v139, v146, v139
	v_add_f32_e32 v139, v147, v139
	v_add_f32_e32 v139, 0x3a0637bd, v139
	v_mul_f32_e32 v139, 0x3b000000, v139
	v_cmp_gt_f32_e32 vcc, s67, v139
	v_mul_f32_e32 v144, 0x4b800000, v139
	s_nop 0
	v_cndmask_b32_e32 v139, v139, v144, vcc
	v_rsq_f32_e32 v139, v139
	s_nop 0
	v_mul_f32_e32 v144, 0x45800000, v139
	v_cndmask_b32_e32 v139, v139, v144, vcc
	v_mul_f32_e32 v124, v124, v139
	v_mul_f32_e32 v125, v125, v139
	v_mul_f32_e32 v126, v126, v139
	v_mul_f32_e32 v120, v120, v139
	v_mul_f32_e32 v121, v121, v139
	v_mul_f32_e32 v127, v127, v139
	v_mul_f32_e32 v122, v122, v139
	v_mul_f32_e32 v123, v123, v139
	v_cvt_pk_bf16_f32 v124, v124, v125
	v_cvt_pk_bf16_f32 v125, v126, v127
	v_cvt_pk_bf16_f32 v126, v120, v121
	v_mov_b64_e32 v[120:121], s[2:3]
	v_cvt_pk_bf16_f32 v127, v122, v123
	v_mad_i64_i32 v[144:145], s[18:19], v138, s7, v[120:121]
	v_lshlrev_b64 v[122:123], 1, v[152:153]
	v_lshl_add_u64 v[144:145], v[144:145], 0, v[122:123]
	global_store_dwordx4 v[144:145], v[124:127], off
	v_mul_f32_e32 v116, v116, v139
	v_mul_f32_e32 v117, v117, v139
	v_mul_f32_e32 v124, v112, v139
	v_mul_f32_e32 v118, v118, v139
	v_mul_f32_e32 v119, v119, v139
	v_mul_f32_e32 v125, v113, v139
	v_mul_f32_e32 v126, v114, v139
	v_cvt_pk_bf16_f32 v112, v116, v117
	v_cvt_pk_bf16_f32 v113, v118, v119
	v_cvt_pk_bf16_f32 v114, v124, v125
	v_add_u32_e32 v124, 16, v138
	v_mul_f32_e32 v115, v115, v139
	v_ashrrev_i32_e32 v125, 31, v124
	v_cvt_pk_bf16_f32 v115, v126, v115
	global_store_dwordx4 v[144:145], v[112:115], off offset:256
	s_nop 1
	v_lshlrev_b64 v[112:113], 5, v[124:125]
	v_lshl_add_u64 v[116:117], s[4:5], 0, v[112:113]
	global_load_dwordx4 v[112:115], v[116:117], off offset:16
	s_nop 0
	global_load_dwordx4 v[116:119], v[116:117], off
	s_waitcnt vmcnt(0)
	v_add_f32_e32 v116, v116, v117
	v_add_f32_e32 v116, v118, v116
	v_add_f32_e32 v116, v119, v116
	v_add_f32_e32 v112, v112, v116
	v_add_f32_e32 v112, v113, v112
	v_add_f32_e32 v112, v114, v112
	v_add_f32_e32 v112, v115, v112
	v_add_f32_e32 v112, 0x3a0637bd, v112
	v_mul_f32_e32 v112, 0x3b000000, v112
	v_cmp_gt_f32_e32 vcc, s67, v112
	v_mul_f32_e32 v113, 0x4b800000, v112
	s_nop 0
	v_cndmask_b32_e32 v112, v112, v113, vcc
	v_rsq_f32_e32 v112, v112
	s_nop 0
	v_mul_f32_e32 v113, 0x45800000, v112
	v_cndmask_b32_e32 v112, v112, v113, vcc
	v_mul_f32_e32 v108, v108, v112
	v_mul_f32_e32 v109, v109, v112
	v_mul_f32_e32 v113, v104, v112
	v_cvt_pk_bf16_f32 v104, v108, v109
	v_mad_i64_i32 v[108:109], s[18:19], v124, s7, v[120:121]
	v_mul_f32_e32 v107, v107, v112
	v_lshl_add_u64 v[108:109], v[108:109], 0, v[122:123]
	v_mul_f32_e32 v110, v110, v112
	v_mul_f32_e32 v111, v111, v112
	v_mul_f32_e32 v114, v105, v112
	v_mul_f32_e32 v115, v106, v112
	v_cvt_pk_bf16_f32 v105, v110, v111
	v_cvt_pk_bf16_f32 v106, v113, v114
	v_cvt_pk_bf16_f32 v107, v115, v107
	global_store_dwordx4 v[108:109], v[104:107], off
	v_mul_f32_e32 v100, v100, v112
	v_mul_f32_e32 v101, v101, v112
	v_mul_f32_e32 v104, v96, v112
	v_mul_f32_e32 v102, v102, v112
	v_mul_f32_e32 v103, v103, v112
	v_mul_f32_e32 v105, v97, v112
	v_mul_f32_e32 v106, v98, v112
	v_cvt_pk_bf16_f32 v96, v100, v101
	v_cvt_pk_bf16_f32 v97, v102, v103
	v_cvt_pk_bf16_f32 v98, v104, v105
	v_add_u32_e32 v104, 32, v138
	v_mul_f32_e32 v99, v99, v112
	v_ashrrev_i32_e32 v105, 31, v104
	v_cvt_pk_bf16_f32 v99, v106, v99
	global_store_dwordx4 v[108:109], v[96:99], off offset:256
	s_nop 1
	v_lshlrev_b64 v[96:97], 5, v[104:105]
	v_lshl_add_u64 v[100:101], s[4:5], 0, v[96:97]
	global_load_dwordx4 v[96:99], v[100:101], off offset:16
	s_nop 0
	global_load_dwordx4 v[100:103], v[100:101], off
	s_waitcnt vmcnt(0)
	v_add_f32_e32 v100, v100, v101
	v_add_f32_e32 v100, v102, v100
	v_add_f32_e32 v100, v103, v100
	v_add_f32_e32 v96, v96, v100
	v_add_f32_e32 v96, v97, v96
	v_add_f32_e32 v96, v98, v96
	v_add_f32_e32 v96, v99, v96
	v_add_f32_e32 v96, 0x3a0637bd, v96
	v_mul_f32_e32 v96, 0x3b000000, v96
	v_cmp_gt_f32_e32 vcc, s67, v96
	v_mul_f32_e32 v97, 0x4b800000, v96
	s_nop 0
	v_cndmask_b32_e32 v96, v96, v97, vcc
	v_rsq_f32_e32 v96, v96
	s_nop 0
	v_mul_f32_e32 v97, 0x45800000, v96
	v_cndmask_b32_e32 v96, v96, v97, vcc
	v_mul_f32_e32 v92, v92, v96
	v_mul_f32_e32 v93, v93, v96
	v_mul_f32_e32 v97, v88, v96
	v_cvt_pk_bf16_f32 v88, v92, v93
	v_mad_i64_i32 v[92:93], s[18:19], v104, s7, v[120:121]
	v_mul_f32_e32 v91, v91, v96
	v_lshl_add_u64 v[92:93], v[92:93], 0, v[122:123]
	v_mul_f32_e32 v94, v94, v96
	v_mul_f32_e32 v95, v95, v96
	v_mul_f32_e32 v98, v89, v96
	v_mul_f32_e32 v99, v90, v96
	v_cvt_pk_bf16_f32 v89, v94, v95
	v_cvt_pk_bf16_f32 v90, v97, v98
	v_cvt_pk_bf16_f32 v91, v99, v91
	global_store_dwordx4 v[92:93], v[88:91], off
	v_mul_f32_e32 v84, v84, v96
	v_mul_f32_e32 v85, v85, v96
	v_mul_f32_e32 v88, v80, v96
	v_mul_f32_e32 v86, v86, v96
	v_mul_f32_e32 v87, v87, v96
	v_mul_f32_e32 v89, v81, v96
	v_mul_f32_e32 v90, v82, v96
	v_cvt_pk_bf16_f32 v80, v84, v85
	v_cvt_pk_bf16_f32 v81, v86, v87
	v_cvt_pk_bf16_f32 v82, v88, v89
	v_add_u32_e32 v88, 48, v138
	v_mul_f32_e32 v83, v83, v96
	v_ashrrev_i32_e32 v89, 31, v88
	v_cvt_pk_bf16_f32 v83, v90, v83
	global_store_dwordx4 v[92:93], v[80:83], off offset:256
	s_nop 1
	v_lshlrev_b64 v[80:81], 5, v[88:89]
	v_lshl_add_u64 v[84:85], s[4:5], 0, v[80:81]
	global_load_dwordx4 v[80:83], v[84:85], off offset:16
	s_nop 0
	global_load_dwordx4 v[84:87], v[84:85], off
	s_waitcnt vmcnt(0)
	v_add_f32_e32 v84, v84, v85
	v_add_f32_e32 v84, v86, v84
	v_add_f32_e32 v84, v87, v84
	v_add_f32_e32 v80, v80, v84
	v_add_f32_e32 v80, v81, v80
	v_add_f32_e32 v80, v82, v80
	v_add_f32_e32 v80, v83, v80
	v_add_f32_e32 v80, 0x3a0637bd, v80
	v_mul_f32_e32 v80, 0x3b000000, v80
	v_cmp_gt_f32_e32 vcc, s67, v80
	v_mul_f32_e32 v81, 0x4b800000, v80
	s_nop 0
	v_cndmask_b32_e32 v80, v80, v81, vcc
	v_rsq_f32_e32 v80, v80
	s_nop 0
	v_mul_f32_e32 v81, 0x45800000, v80
	v_cndmask_b32_e32 v80, v80, v81, vcc
	v_mul_f32_e32 v76, v76, v80
	v_mul_f32_e32 v77, v77, v80
	v_mul_f32_e32 v81, v72, v80
	v_cvt_pk_bf16_f32 v72, v76, v77
	v_mad_i64_i32 v[76:77], s[18:19], v88, s7, v[120:121]
	v_mul_f32_e32 v75, v75, v80
	v_lshl_add_u64 v[76:77], v[76:77], 0, v[122:123]
	v_mul_f32_e32 v78, v78, v80
	v_mul_f32_e32 v79, v79, v80
	v_mul_f32_e32 v82, v73, v80
	v_mul_f32_e32 v83, v74, v80
	v_cvt_pk_bf16_f32 v73, v78, v79
	v_cvt_pk_bf16_f32 v74, v81, v82
	v_cvt_pk_bf16_f32 v75, v83, v75
	global_store_dwordx4 v[76:77], v[72:75], off
	v_mul_f32_e32 v68, v68, v80
	v_mul_f32_e32 v69, v69, v80
	v_mul_f32_e32 v72, v64, v80
	v_mul_f32_e32 v70, v70, v80
	v_mul_f32_e32 v71, v71, v80
	v_mul_f32_e32 v73, v65, v80
	v_mul_f32_e32 v74, v66, v80
	v_cvt_pk_bf16_f32 v64, v68, v69
	v_cvt_pk_bf16_f32 v65, v70, v71
	v_cvt_pk_bf16_f32 v66, v72, v73
	v_add_u32_e32 v72, 0x80, v138
	v_mul_f32_e32 v67, v67, v80
	v_ashrrev_i32_e32 v73, 31, v72
	v_cvt_pk_bf16_f32 v67, v74, v67
	global_store_dwordx4 v[76:77], v[64:67], off offset:256
	s_nop 1
	v_lshlrev_b64 v[64:65], 5, v[72:73]
	v_lshl_add_u64 v[68:69], s[4:5], 0, v[64:65]
	global_load_dwordx4 v[64:67], v[68:69], off offset:16
	s_nop 0
	global_load_dwordx4 v[68:71], v[68:69], off
	s_waitcnt vmcnt(0)
	v_add_f32_e32 v68, v68, v69
	v_add_f32_e32 v68, v70, v68
	v_add_f32_e32 v68, v71, v68
	v_add_f32_e32 v64, v64, v68
	v_add_f32_e32 v64, v65, v64
	v_add_f32_e32 v64, v66, v64
	v_add_f32_e32 v64, v67, v64
	v_add_f32_e32 v64, 0x3a0637bd, v64
	v_mul_f32_e32 v64, 0x3b000000, v64
	v_cmp_gt_f32_e32 vcc, s67, v64
	v_mul_f32_e32 v65, 0x4b800000, v64
	s_nop 0
	v_cndmask_b32_e32 v64, v64, v65, vcc
	v_rsq_f32_e32 v64, v64
	s_nop 0
	v_mul_f32_e32 v65, 0x45800000, v64
	v_cndmask_b32_e32 v64, v64, v65, vcc
	v_mul_f32_e32 v60, v60, v64
	v_mul_f32_e32 v61, v61, v64
	v_mul_f32_e32 v65, v56, v64
	v_cvt_pk_bf16_f32 v56, v60, v61
	v_mad_i64_i32 v[60:61], s[18:19], v72, s7, v[120:121]
	v_mul_f32_e32 v59, v59, v64
	v_lshl_add_u64 v[60:61], v[60:61], 0, v[122:123]
	v_mul_f32_e32 v62, v62, v64
	v_mul_f32_e32 v63, v63, v64
	v_mul_f32_e32 v66, v57, v64
	v_mul_f32_e32 v67, v58, v64
	v_cvt_pk_bf16_f32 v57, v62, v63
	v_cvt_pk_bf16_f32 v58, v65, v66
	v_cvt_pk_bf16_f32 v59, v67, v59
	global_store_dwordx4 v[60:61], v[56:59], off
	v_mul_f32_e32 v52, v52, v64
	v_mul_f32_e32 v53, v53, v64
	v_mul_f32_e32 v56, v48, v64
	v_mul_f32_e32 v54, v54, v64
	v_mul_f32_e32 v55, v55, v64
	v_mul_f32_e32 v57, v49, v64
	v_mul_f32_e32 v58, v50, v64
	v_cvt_pk_bf16_f32 v48, v52, v53
	v_cvt_pk_bf16_f32 v49, v54, v55
	v_cvt_pk_bf16_f32 v50, v56, v57
	v_add_u32_e32 v56, 0x90, v138
	v_mul_f32_e32 v51, v51, v64
	v_ashrrev_i32_e32 v57, 31, v56
	v_cvt_pk_bf16_f32 v51, v58, v51
	global_store_dwordx4 v[60:61], v[48:51], off offset:256
	s_nop 1
	v_lshlrev_b64 v[48:49], 5, v[56:57]
	v_lshl_add_u64 v[52:53], s[4:5], 0, v[48:49]
	global_load_dwordx4 v[48:51], v[52:53], off offset:16
	s_nop 0
	global_load_dwordx4 v[52:55], v[52:53], off
	s_waitcnt vmcnt(0)
	v_add_f32_e32 v52, v52, v53
	v_add_f32_e32 v52, v54, v52
	v_add_f32_e32 v52, v55, v52
	v_add_f32_e32 v48, v48, v52
	v_add_f32_e32 v48, v49, v48
	v_add_f32_e32 v48, v50, v48
	v_add_f32_e32 v48, v51, v48
	v_add_f32_e32 v48, 0x3a0637bd, v48
	v_mul_f32_e32 v48, 0x3b000000, v48
	v_cmp_gt_f32_e32 vcc, s67, v48
	v_mul_f32_e32 v49, 0x4b800000, v48
	s_nop 0
	v_cndmask_b32_e32 v48, v48, v49, vcc
	v_rsq_f32_e32 v48, v48
	s_nop 0
	v_mul_f32_e32 v49, 0x45800000, v48
	v_cndmask_b32_e32 v48, v48, v49, vcc
	v_mul_f32_e32 v44, v44, v48
	v_mul_f32_e32 v45, v45, v48
	v_mul_f32_e32 v49, v40, v48
	v_cvt_pk_bf16_f32 v40, v44, v45
	v_mad_i64_i32 v[44:45], s[18:19], v56, s7, v[120:121]
	v_mul_f32_e32 v43, v43, v48
	v_lshl_add_u64 v[44:45], v[44:45], 0, v[122:123]
	v_mul_f32_e32 v46, v46, v48
	v_mul_f32_e32 v47, v47, v48
	v_mul_f32_e32 v50, v41, v48
	v_mul_f32_e32 v51, v42, v48
	v_cvt_pk_bf16_f32 v41, v46, v47
	v_cvt_pk_bf16_f32 v42, v49, v50
	v_cvt_pk_bf16_f32 v43, v51, v43
	global_store_dwordx4 v[44:45], v[40:43], off
	v_mul_f32_e32 v36, v36, v48
	v_mul_f32_e32 v37, v37, v48
	v_mul_f32_e32 v40, v32, v48
	v_mul_f32_e32 v38, v38, v48
	v_mul_f32_e32 v39, v39, v48
	v_mul_f32_e32 v41, v33, v48
	v_mul_f32_e32 v42, v34, v48
	v_cvt_pk_bf16_f32 v32, v36, v37
	v_cvt_pk_bf16_f32 v33, v38, v39
	v_cvt_pk_bf16_f32 v34, v40, v41
	v_add_u32_e32 v40, 0xa0, v138
	v_mul_f32_e32 v35, v35, v48
	v_ashrrev_i32_e32 v41, 31, v40
	v_cvt_pk_bf16_f32 v35, v42, v35
	global_store_dwordx4 v[44:45], v[32:35], off offset:256
	s_nop 1
	v_lshlrev_b64 v[32:33], 5, v[40:41]
	v_lshl_add_u64 v[36:37], s[4:5], 0, v[32:33]
	global_load_dwordx4 v[32:35], v[36:37], off offset:16
	s_nop 0
	global_load_dwordx4 v[36:39], v[36:37], off
	s_waitcnt vmcnt(0)
	v_add_f32_e32 v36, v36, v37
	v_add_f32_e32 v36, v38, v36
	v_add_f32_e32 v36, v39, v36
	v_add_f32_e32 v32, v32, v36
	v_add_f32_e32 v32, v33, v32
	v_add_f32_e32 v32, v34, v32
	v_add_f32_e32 v32, v35, v32
	v_add_f32_e32 v32, 0x3a0637bd, v32
	v_mul_f32_e32 v32, 0x3b000000, v32
	v_cmp_gt_f32_e32 vcc, s67, v32
	v_mul_f32_e32 v33, 0x4b800000, v32
	s_nop 0
	v_cndmask_b32_e32 v32, v32, v33, vcc
	v_rsq_f32_e32 v32, v32
	s_nop 0
	v_mul_f32_e32 v33, 0x45800000, v32
	v_cndmask_b32_e32 v32, v32, v33, vcc
	v_mul_f32_e32 v28, v28, v32
	v_mul_f32_e32 v29, v29, v32
	v_mul_f32_e32 v33, v24, v32
	v_cvt_pk_bf16_f32 v24, v28, v29
	v_mad_i64_i32 v[28:29], s[18:19], v40, s7, v[120:121]
	v_mul_f32_e32 v27, v27, v32
	v_lshl_add_u64 v[28:29], v[28:29], 0, v[122:123]
	v_mul_f32_e32 v30, v30, v32
	v_mul_f32_e32 v31, v31, v32
	v_mul_f32_e32 v34, v25, v32
	v_mul_f32_e32 v35, v26, v32
	v_cvt_pk_bf16_f32 v25, v30, v31
	v_cvt_pk_bf16_f32 v26, v33, v34
	v_cvt_pk_bf16_f32 v27, v35, v27
	global_store_dwordx4 v[28:29], v[24:27], off
	v_mul_f32_e32 v20, v20, v32
	v_mul_f32_e32 v21, v21, v32
	v_mul_f32_e32 v24, v16, v32
	v_mul_f32_e32 v22, v22, v32
	v_mul_f32_e32 v23, v23, v32
	v_mul_f32_e32 v25, v17, v32
	v_mul_f32_e32 v26, v18, v32
	v_cvt_pk_bf16_f32 v16, v20, v21
	v_cvt_pk_bf16_f32 v17, v22, v23
	v_cvt_pk_bf16_f32 v18, v24, v25
	v_add_u32_e32 v24, 0xb0, v138
	v_mul_f32_e32 v19, v19, v32
	v_ashrrev_i32_e32 v25, 31, v24
	v_cvt_pk_bf16_f32 v19, v26, v19
	global_store_dwordx4 v[28:29], v[16:19], off offset:256
	s_nop 1
	v_lshlrev_b64 v[16:17], 5, v[24:25]
	v_lshl_add_u64 v[20:21], s[4:5], 0, v[16:17]
	global_load_dwordx4 v[16:19], v[20:21], off offset:16
	s_nop 0
	global_load_dwordx4 v[20:23], v[20:21], off
	s_waitcnt vmcnt(0)
	v_add_f32_e32 v20, v20, v21
	v_add_f32_e32 v20, v22, v20
	v_add_f32_e32 v20, v23, v20
	v_add_f32_e32 v16, v16, v20
	v_add_f32_e32 v16, v17, v16
	v_add_f32_e32 v16, v18, v16
	v_add_f32_e32 v16, v19, v16
	v_add_f32_e32 v16, 0x3a0637bd, v16
	v_mul_f32_e32 v16, 0x3b000000, v16
	v_cmp_gt_f32_e32 vcc, s67, v16
	v_mul_f32_e32 v17, 0x4b800000, v16
	s_nop 0
	v_cndmask_b32_e32 v16, v16, v17, vcc
	v_rsq_f32_e32 v16, v16
	s_nop 0
	v_mul_f32_e32 v17, 0x45800000, v16
	v_cndmask_b32_e32 v16, v16, v17, vcc
	v_mul_f32_e32 v12, v12, v16
	v_mul_f32_e32 v13, v13, v16
	v_mul_f32_e32 v17, v8, v16
	v_cvt_pk_bf16_f32 v8, v12, v13
	v_mad_i64_i32 v[12:13], s[18:19], v24, s7, v[120:121]
	v_mul_f32_e32 v14, v14, v16
	v_mul_f32_e32 v15, v15, v16
	v_mul_f32_e32 v18, v9, v16
	v_mul_f32_e32 v19, v10, v16
	v_mul_f32_e32 v11, v11, v16
	v_cvt_pk_bf16_f32 v9, v14, v15
	v_cvt_pk_bf16_f32 v10, v17, v18
	v_lshl_add_u64 v[12:13], v[12:13], 0, v[122:123]
	v_mul_f32_e32 v3, v3, v16
	s_and_b64 vcc, exec, s[10:11]
	s_mov_b64 s[18:19], s[12:13]
	v_cvt_pk_bf16_f32 v11, v19, v11
	global_store_dwordx4 v[12:13], v[8:11], off
	v_mul_f32_e32 v4, v4, v16
	v_mul_f32_e32 v5, v5, v16
	v_mul_f32_e32 v6, v6, v16
	v_mul_f32_e32 v7, v7, v16
	v_mul_f32_e32 v8, v0, v16
	v_mul_f32_e32 v9, v1, v16
	v_mul_f32_e32 v10, v2, v16
	v_cvt_pk_bf16_f32 v0, v4, v5
	v_cvt_pk_bf16_f32 v1, v6, v7
	v_cvt_pk_bf16_f32 v2, v8, v9
	v_cvt_pk_bf16_f32 v3, v10, v3
	global_store_dwordx4 v[12:13], v[0:3], off offset:256
	s_cbranch_vccz .LBB0_149
	s_waitcnt vmcnt(0)
	s_cmpk_gt_u32 s24, 0xff
	s_cbranch_scc1 .LBB0_156
	s_barrier

.LBB0_169:
	s_add_u32 s24, s22, 0xfff80080
	s_addc_u32 s25, s23, -1
	s_add_i32 s48, 0, 0x10000
	v_add_u32_e32 v154, s48, v144
	ds_read_b128 v[138:141], v154
	ds_read_b128 v[146:149], v154 offset:1024
	ds_read_b128 v[150:153], v154 offset:2048
	ds_read_b128 v[154:157], v154 offset:3072
	s_cmp_eq_u32 s47, 28
	s_cselect_b32 s27, s1, s25
	s_cselect_b32 s26, s11, s24
	s_cselect_b32 s25, s13, s46
	s_cselect_b32 s24, s21, s45
	v_lshl_add_u64 v[182:183], s[22:23], 0, v[134:135]
	s_add_i32 m0, s35, 0xc000
	ds_read_b128 v[158:161], v145
	ds_read_b128 v[162:165], v145 offset:1024
	ds_read_b128 v[166:169], v145 offset:2048
	ds_read_b128 v[170:173], v145 offset:3072
	ds_read_b128 v[174:177], v145 offset:4096
	ds_read_b128 v[178:181], v145 offset:5120
	ds_read_b128 v[188:191], v145 offset:6144
	ds_read_b128 v[192:195], v145 offset:7168
	global_load_lds_dwordx4 v[182:183], off
	v_lshl_add_u64 v[182:183], s[22:23], 0, v[136:137]
	s_add_i32 m0, s35, 0xe000
	s_nop 0
	global_load_lds_dwordx4 v[182:183], off
	s_waitcnt lgkmcnt(8)
	s_setprio 1
	s_barrier
	s_waitcnt lgkmcnt(0)
	v_mfma_f32_16x16x32_bf16 v[124:127], v[138:141], v[158:161], v[124:127]
	v_mfma_f32_16x16x32_bf16 v[120:123], v[150:153], v[158:161], v[120:123]
	v_mfma_f32_16x16x32_bf16 v[108:111], v[138:141], v[166:169], v[108:111]
	v_mfma_f32_16x16x32_bf16 v[104:107], v[150:153], v[166:169], v[104:107]
	v_mfma_f32_16x16x32_bf16 v[92:95], v[138:141], v[174:177], v[92:95]
	v_mfma_f32_16x16x32_bf16 v[88:91], v[150:153], v[174:177], v[88:91]
	v_mfma_f32_16x16x32_bf16 v[76:79], v[138:141], v[188:191], v[76:79]
	v_mfma_f32_16x16x32_bf16 v[72:75], v[150:153], v[188:191], v[72:75]
	v_mfma_f32_16x16x32_bf16 v[124:127], v[146:149], v[162:165], v[124:127]
	v_mfma_f32_16x16x32_bf16 v[120:123], v[154:157], v[162:165], v[120:123]
	v_mfma_f32_16x16x32_bf16 v[108:111], v[146:149], v[170:173], v[108:111]
	v_mfma_f32_16x16x32_bf16 v[104:107], v[154:157], v[170:173], v[104:107]
	v_mfma_f32_16x16x32_bf16 v[92:95], v[146:149], v[178:181], v[92:95]
	v_mfma_f32_16x16x32_bf16 v[88:91], v[154:157], v[178:181], v[88:91]
	v_mfma_f32_16x16x32_bf16 v[76:79], v[146:149], v[192:195], v[76:79]
	v_mfma_f32_16x16x32_bf16 v[72:75], v[154:157], v[192:195], v[72:75]
	s_barrier
	s_setprio 0
	s_add_i32 s50, 0, 0x14000
	v_add_u32_e32 v182, s50, v144
	s_add_i32 s48, s48, s34
	ds_read_b128 v[202:205], v182
	ds_read_b128 v[206:209], v182 offset:1024
	ds_read_b128 v[210:213], v182 offset:2048
	ds_read_b128 v[214:217], v182 offset:3072
	v_lshl_add_u64 v[182:183], s[24:25], 0, v[184:185]
	s_mov_b32 m0, s48
	v_lshl_add_u64 v[196:197], s[24:25], 0, v[132:133]
	global_load_lds_dwordx4 v[182:183], off
	s_add_i32 m0, s48, 0x2000
	s_nop 0
	global_load_lds_dwordx4 v[196:197], off
	s_setprio 1
	s_barrier
	s_waitcnt lgkmcnt(0)
	v_mfma_f32_16x16x32_bf16 v[116:119], v[202:205], v[158:161], v[116:119]
	v_mfma_f32_16x16x32_bf16 v[112:115], v[210:213], v[158:161], v[112:115]
	v_mfma_f32_16x16x32_bf16 v[100:103], v[202:205], v[166:169], v[100:103]
	v_mfma_f32_16x16x32_bf16 v[96:99], v[210:213], v[166:169], v[96:99]
	v_mfma_f32_16x16x32_bf16 v[84:87], v[202:205], v[174:177], v[84:87]
	v_mfma_f32_16x16x32_bf16 v[80:83], v[210:213], v[174:177], v[80:83]
	v_mfma_f32_16x16x32_bf16 v[68:71], v[202:205], v[188:191], v[68:71]
	v_mfma_f32_16x16x32_bf16 v[64:67], v[210:213], v[188:191], v[64:67]
	v_mfma_f32_16x16x32_bf16 v[116:119], v[206:209], v[162:165], v[116:119]
	v_mfma_f32_16x16x32_bf16 v[112:115], v[214:217], v[162:165], v[112:115]
	v_mfma_f32_16x16x32_bf16 v[100:103], v[206:209], v[170:173], v[100:103]
	v_mfma_f32_16x16x32_bf16 v[96:99], v[214:217], v[170:173], v[96:99]
	v_mfma_f32_16x16x32_bf16 v[84:87], v[206:209], v[178:181], v[84:87]
	v_mfma_f32_16x16x32_bf16 v[80:83], v[214:217], v[178:181], v[80:83]
	v_mfma_f32_16x16x32_bf16 v[68:71], v[206:209], v[192:195], v[68:71]
	v_mfma_f32_16x16x32_bf16 v[64:67], v[214:217], v[192:195], v[64:67]
	s_barrier
	s_setprio 0
	s_mov_b32 m0, s35
	v_lshl_add_u64 v[218:219], s[26:27], 0, v[128:129]
	ds_read_b128 v[158:161], v145 offset:16384
	ds_read_b128 v[162:165], v145 offset:17408
	ds_read_b128 v[166:169], v145 offset:18432
	ds_read_b128 v[170:173], v145 offset:19456
	ds_read_b128 v[174:177], v145 offset:20480
	ds_read_b128 v[178:181], v145 offset:21504
	ds_read_b128 v[188:191], v145 offset:22528
	ds_read_b128 v[192:195], v145 offset:23552
	global_load_lds_dwordx4 v[218:219], off
	v_lshl_add_u64 v[220:221], s[26:27], 0, v[130:131]
	s_mov_b32 m0, s36
	s_nop 0
	global_load_lds_dwordx4 v[220:221], off
	s_setprio 1
	s_barrier
	s_waitcnt lgkmcnt(0)
	v_mfma_f32_16x16x32_bf16 v[60:63], v[138:141], v[158:161], v[60:63]
	v_mfma_f32_16x16x32_bf16 v[56:59], v[150:153], v[158:161], v[56:59]
	v_mfma_f32_16x16x32_bf16 v[44:47], v[138:141], v[166:169], v[44:47]
	v_mfma_f32_16x16x32_bf16 v[40:43], v[150:153], v[166:169], v[40:43]
	v_mfma_f32_16x16x32_bf16 v[28:31], v[138:141], v[174:177], v[28:31]
	v_mfma_f32_16x16x32_bf16 v[24:27], v[150:153], v[174:177], v[24:27]
	v_mfma_f32_16x16x32_bf16 v[12:15], v[138:141], v[188:191], v[12:15]
	v_mfma_f32_16x16x32_bf16 v[8:11], v[150:153], v[188:191], v[8:11]
	v_mfma_f32_16x16x32_bf16 v[60:63], v[146:149], v[162:165], v[60:63]
	v_mfma_f32_16x16x32_bf16 v[56:59], v[154:157], v[162:165], v[56:59]
	v_mfma_f32_16x16x32_bf16 v[44:47], v[146:149], v[170:173], v[44:47]
	v_mfma_f32_16x16x32_bf16 v[40:43], v[154:157], v[170:173], v[40:43]
	v_mfma_f32_16x16x32_bf16 v[28:31], v[146:149], v[178:181], v[28:31]
	v_mfma_f32_16x16x32_bf16 v[24:27], v[154:157], v[178:181], v[24:27]
	v_mfma_f32_16x16x32_bf16 v[12:15], v[146:149], v[192:195], v[12:15]
	v_mfma_f32_16x16x32_bf16 v[8:11], v[154:157], v[192:195], v[8:11]
	s_barrier
	s_setprio 0
	s_add_u32 s48, s24, 0x80000
	s_addc_u32 s49, s25, 0
	s_add_i32 s50, s50, s34
	v_lshl_add_u64 v[138:139], s[48:49], 0, v[184:185]
	s_mov_b32 m0, s50
	s_nop 0
	global_load_lds_dwordx4 v[138:139], off
	v_lshl_add_u64 v[138:139], s[48:49], 0, v[132:133]
	s_add_i32 m0, s50, 0x2000
	s_nop 0
	global_load_lds_dwordx4 v[138:139], off
	s_waitcnt vmcnt(6)
	s_setprio 1
	s_barrier
	v_mfma_f32_16x16x32_bf16 v[52:55], v[202:205], v[158:161], v[52:55]
	v_mfma_f32_16x16x32_bf16 v[48:51], v[210:213], v[158:161], v[48:51]
	v_mfma_f32_16x16x32_bf16 v[36:39], v[202:205], v[166:169], v[36:39]
	v_mfma_f32_16x16x32_bf16 v[32:35], v[210:213], v[166:169], v[32:35]
	v_mfma_f32_16x16x32_bf16 v[20:23], v[202:205], v[174:177], v[20:23]
	v_mfma_f32_16x16x32_bf16 v[16:19], v[210:213], v[174:177], v[16:19]
	v_mfma_f32_16x16x32_bf16 v[4:7], v[202:205], v[188:191], v[4:7]
	v_mfma_f32_16x16x32_bf16 v[0:3], v[210:213], v[188:191], v[0:3]
	v_mfma_f32_16x16x32_bf16 v[52:55], v[206:209], v[162:165], v[52:55]
	v_mfma_f32_16x16x32_bf16 v[48:51], v[214:217], v[162:165], v[48:51]
	v_mfma_f32_16x16x32_bf16 v[36:39], v[206:209], v[170:173], v[36:39]
	v_mfma_f32_16x16x32_bf16 v[32:35], v[214:217], v[170:173], v[32:35]
	v_mfma_f32_16x16x32_bf16 v[20:23], v[206:209], v[178:181], v[20:23]
	v_mfma_f32_16x16x32_bf16 v[16:19], v[214:217], v[178:181], v[16:19]
	v_mfma_f32_16x16x32_bf16 v[4:7], v[206:209], v[192:195], v[4:7]
	v_mfma_f32_16x16x32_bf16 v[0:3], v[214:217], v[192:195], v[0:3]
	s_barrier
	s_setprio 0
	s_add_i32 s48, 0, 0x18000
	v_add_u32_e32 v154, s48, v144
	ds_read_b128 v[138:141], v154
	ds_read_b128 v[146:149], v154 offset:1024
	ds_read_b128 v[150:153], v154 offset:2048
	ds_read_b128 v[154:157], v154 offset:3072
	s_add_u32 s26, s26, 0x80000
	s_addc_u32 s27, s27, 0
	s_mov_b32 m0, s37
	v_lshl_add_u64 v[202:203], s[26:27], 0, v[128:129]
	ds_read_b128 v[158:161], v145 offset:32768
	ds_read_b128 v[162:165], v145 offset:33792
	ds_read_b128 v[166:169], v145 offset:34816
	ds_read_b128 v[170:173], v145 offset:35840
	ds_read_b128 v[174:177], v145 offset:36864
	ds_read_b128 v[178:181], v145 offset:37888
	ds_read_b128 v[188:191], v145 offset:38912
	ds_read_b128 v[192:195], v145 offset:39936
	global_load_lds_dwordx4 v[202:203], off
	v_lshl_add_u64 v[202:203], s[26:27], 0, v[130:131]
	s_mov_b32 m0, s38
	s_nop 0
	global_load_lds_dwordx4 v[202:203], off
	s_waitcnt lgkmcnt(8)
	s_setprio 1
	s_barrier
	s_waitcnt lgkmcnt(0)
	v_mfma_f32_16x16x32_bf16 v[124:127], v[138:141], v[158:161], v[124:127]
	v_mfma_f32_16x16x32_bf16 v[120:123], v[150:153], v[158:161], v[120:123]
	v_mfma_f32_16x16x32_bf16 v[108:111], v[138:141], v[166:169], v[108:111]
	v_mfma_f32_16x16x32_bf16 v[104:107], v[150:153], v[166:169], v[104:107]
	v_mfma_f32_16x16x32_bf16 v[92:95], v[138:141], v[174:177], v[92:95]
	v_mfma_f32_16x16x32_bf16 v[88:91], v[150:153], v[174:177], v[88:91]
	v_mfma_f32_16x16x32_bf16 v[76:79], v[138:141], v[188:191], v[76:79]
	v_mfma_f32_16x16x32_bf16 v[72:75], v[150:153], v[188:191], v[72:75]
	v_mfma_f32_16x16x32_bf16 v[124:127], v[146:149], v[162:165], v[124:127]
	v_mfma_f32_16x16x32_bf16 v[120:123], v[154:157], v[162:165], v[120:123]
	v_mfma_f32_16x16x32_bf16 v[108:111], v[146:149], v[170:173], v[108:111]
	v_mfma_f32_16x16x32_bf16 v[104:107], v[154:157], v[170:173], v[104:107]
	v_mfma_f32_16x16x32_bf16 v[92:95], v[146:149], v[178:181], v[92:95]
	v_mfma_f32_16x16x32_bf16 v[88:91], v[154:157], v[178:181], v[88:91]
	v_mfma_f32_16x16x32_bf16 v[76:79], v[146:149], v[192:195], v[76:79]
	v_mfma_f32_16x16x32_bf16 v[72:75], v[154:157], v[192:195], v[72:75]
	s_barrier
	s_setprio 0
	s_add_i32 s26, 0, 0x1c000
	s_add_i32 s27, s48, s34
	v_add_u32_e32 v187, s26, v144
	v_lshl_add_u64 v[182:183], v[182:183], 0, s[52:53]
	s_mov_b32 m0, s27
	ds_read_b128 v[202:205], v187
	ds_read_b128 v[206:209], v187 offset:1024
	ds_read_b128 v[210:213], v187 offset:2048
	ds_read_b128 v[214:217], v187 offset:3072
	global_load_lds_dwordx4 v[182:183], off
	v_lshl_add_u64 v[182:183], v[196:197], 0, s[52:53]
	s_add_i32 m0, s27, 0x2000
	s_nop 0
	global_load_lds_dwordx4 v[182:183], off
	s_setprio 1
	s_barrier
	s_waitcnt lgkmcnt(0)
	v_mfma_f32_16x16x32_bf16 v[116:119], v[202:205], v[158:161], v[116:119]
	v_mfma_f32_16x16x32_bf16 v[112:115], v[210:213], v[158:161], v[112:115]
	v_mfma_f32_16x16x32_bf16 v[100:103], v[202:205], v[166:169], v[100:103]
	v_mfma_f32_16x16x32_bf16 v[96:99], v[210:213], v[166:169], v[96:99]
	v_mfma_f32_16x16x32_bf16 v[84:87], v[202:205], v[174:177], v[84:87]
	v_mfma_f32_16x16x32_bf16 v[80:83], v[210:213], v[174:177], v[80:83]
	v_mfma_f32_16x16x32_bf16 v[68:71], v[202:205], v[188:191], v[68:71]
	v_mfma_f32_16x16x32_bf16 v[64:67], v[210:213], v[188:191], v[64:67]
	v_mfma_f32_16x16x32_bf16 v[116:119], v[206:209], v[162:165], v[116:119]
	v_mfma_f32_16x16x32_bf16 v[112:115], v[214:217], v[162:165], v[112:115]
	v_mfma_f32_16x16x32_bf16 v[100:103], v[206:209], v[170:173], v[100:103]
	v_mfma_f32_16x16x32_bf16 v[96:99], v[214:217], v[170:173], v[96:99]
	v_mfma_f32_16x16x32_bf16 v[84:87], v[206:209], v[178:181], v[84:87]
	v_mfma_f32_16x16x32_bf16 v[80:83], v[214:217], v[178:181], v[80:83]
	v_mfma_f32_16x16x32_bf16 v[68:71], v[206:209], v[192:195], v[68:71]
	v_mfma_f32_16x16x32_bf16 v[64:67], v[214:217], v[192:195], v[64:67]
	s_barrier
	s_setprio 0
	s_mov_b32 m0, s42
	v_lshl_add_u64 v[182:183], v[218:219], 0, s[52:53]
	ds_read_b128 v[158:161], v145 offset:49152
	ds_read_b128 v[162:165], v145 offset:50176
	ds_read_b128 v[166:169], v145 offset:51200
	ds_read_b128 v[170:173], v145 offset:52224
	ds_read_b128 v[174:177], v145 offset:53248
	ds_read_b128 v[178:181], v145 offset:54272
	ds_read_b128 v[188:191], v145 offset:55296
	ds_read_b128 v[192:195], v145 offset:56320
	global_load_lds_dwordx4 v[182:183], off
	v_lshl_add_u64 v[182:183], v[220:221], 0, s[52:53]
	s_mov_b32 m0, s43
	s_nop 0
	global_load_lds_dwordx4 v[182:183], off
	s_setprio 1
	s_barrier
	s_waitcnt lgkmcnt(0)
	v_mfma_f32_16x16x32_bf16 v[60:63], v[138:141], v[158:161], v[60:63]
	v_mfma_f32_16x16x32_bf16 v[56:59], v[150:153], v[158:161], v[56:59]
	v_mfma_f32_16x16x32_bf16 v[44:47], v[138:141], v[166:169], v[44:47]
	v_mfma_f32_16x16x32_bf16 v[40:43], v[150:153], v[166:169], v[40:43]
	v_mfma_f32_16x16x32_bf16 v[28:31], v[138:141], v[174:177], v[28:31]
	v_mfma_f32_16x16x32_bf16 v[24:27], v[150:153], v[174:177], v[24:27]
	v_mfma_f32_16x16x32_bf16 v[12:15], v[138:141], v[188:191], v[12:15]
	v_mfma_f32_16x16x32_bf16 v[8:11], v[150:153], v[188:191], v[8:11]
	v_mfma_f32_16x16x32_bf16 v[60:63], v[146:149], v[162:165], v[60:63]
	v_mfma_f32_16x16x32_bf16 v[56:59], v[154:157], v[162:165], v[56:59]
	v_mfma_f32_16x16x32_bf16 v[44:47], v[146:149], v[170:173], v[44:47]
	v_mfma_f32_16x16x32_bf16 v[40:43], v[154:157], v[170:173], v[40:43]
	v_mfma_f32_16x16x32_bf16 v[28:31], v[146:149], v[178:181], v[28:31]
	v_mfma_f32_16x16x32_bf16 v[24:27], v[154:157], v[178:181], v[24:27]
	v_mfma_f32_16x16x32_bf16 v[12:15], v[146:149], v[192:195], v[12:15]
	v_mfma_f32_16x16x32_bf16 v[8:11], v[154:157], v[192:195], v[8:11]
	s_barrier
	s_setprio 0
	s_add_u32 s24, s24, 0x80080
	s_addc_u32 s25, s25, 0
	s_add_i32 s26, s26, s34
	v_lshl_add_u64 v[138:139], s[24:25], 0, v[184:185]
	s_mov_b32 m0, s26
	s_nop 0
	global_load_lds_dwordx4 v[138:139], off
	v_lshl_add_u64 v[138:139], s[24:25], 0, v[132:133]
	s_add_i32 m0, s26, 0x2000
	s_nop 0
	global_load_lds_dwordx4 v[138:139], off
	s_waitcnt vmcnt(6)
	s_setprio 1
	s_barrier
	v_mfma_f32_16x16x32_bf16 v[52:55], v[202:205], v[158:161], v[52:55]
	v_mfma_f32_16x16x32_bf16 v[48:51], v[210:213], v[158:161], v[48:51]
	v_mfma_f32_16x16x32_bf16 v[36:39], v[202:205], v[166:169], v[36:39]
	v_mfma_f32_16x16x32_bf16 v[32:35], v[210:213], v[166:169], v[32:35]
	v_mfma_f32_16x16x32_bf16 v[20:23], v[202:205], v[174:177], v[20:23]
	v_mfma_f32_16x16x32_bf16 v[16:19], v[210:213], v[174:177], v[16:19]
	v_mfma_f32_16x16x32_bf16 v[4:7], v[202:205], v[188:191], v[4:7]
	v_mfma_f32_16x16x32_bf16 v[0:3], v[210:213], v[188:191], v[0:3]
	v_mfma_f32_16x16x32_bf16 v[52:55], v[206:209], v[162:165], v[52:55]
	v_mfma_f32_16x16x32_bf16 v[48:51], v[214:217], v[162:165], v[48:51]
	v_mfma_f32_16x16x32_bf16 v[36:39], v[206:209], v[170:173], v[36:39]
	v_mfma_f32_16x16x32_bf16 v[32:35], v[214:217], v[170:173], v[32:35]
	v_mfma_f32_16x16x32_bf16 v[20:23], v[206:209], v[178:181], v[20:23]
	v_mfma_f32_16x16x32_bf16 v[16:19], v[214:217], v[178:181], v[16:19]
	v_mfma_f32_16x16x32_bf16 v[4:7], v[206:209], v[192:195], v[4:7]
	v_mfma_f32_16x16x32_bf16 v[0:3], v[214:217], v[192:195], v[0:3]
	s_barrier
	s_setprio 0
	s_add_i32 s47, s47, 2
	s_add_u32 s22, s22, 0x100
	s_addc_u32 s23, s23, 0
	s_add_u32 s45, s45, 0x100
	s_addc_u32 s46, s46, 0
	s_cmp_gt_u32 s47, 29
	s_cbranch_scc0 .LBB0_169
	v_mov_b32_e32 v141, v143
	v_mov_b32_e32 v138, v142
	s_lshl_b32 s1, s20, 8
	s_add_i32 s1, s1, s40
	v_add_u32_e32 v138, s1, v138
	s_cmp_gt_i32 s0, 1
	s_mov_b64 s[20:21], -1
	s_cbranch_scc0 .LBB0_174
	s_andn2_b64 vcc, exec, s[6:7]
	s_cbranch_vccnz .LBB0_173
	v_ashrrev_i32_e32 v139, 31, v138
	v_lshlrev_b32_e32 v146, 3, v141
	v_lshlrev_b64 v[148:149], 8, v[138:139]
	v_ashrrev_i32_e32 v147, 31, v146
	v_lshl_add_u64 v[148:149], s[8:9], 0, v[148:149]
	v_lshl_add_u64 v[146:147], v[146:147], 2, v[148:149]
	v_add_co_u32_e32 v150, vcc, 0x1000, v146
	s_mov_b64 s[20:21], 0x1000
	s_nop 0
	v_addc_co_u32_e32 v151, vcc, 0, v147, vcc
	s_movk_i32 s1, 0x2000
	global_store_dwordx4 v[146:147], v[124:127], off
	global_store_dwordx4 v[146:147], v[120:123], off offset:16
	v_lshl_add_u64 v[148:149], v[146:147], 0, s[20:21]
	global_store_dwordx4 v[150:151], v[108:111], off
	global_store_dwordx4 v[148:149], v[104:107], off offset:16
	v_add_co_u32_e32 v150, vcc, s1, v146
	v_lshl_add_u64 v[148:149], v[146:147], 0, s[82:83]
	s_nop 0
	v_addc_co_u32_e32 v151, vcc, 0, v147, vcc
	global_store_dwordx4 v[150:151], v[92:95], off
	global_store_dwordx4 v[148:149], v[88:91], off offset:16
	v_add_co_u32_e32 v150, vcc, 0x3000, v146
	s_mov_b64 s[20:21], 0x3000
	s_nop 0
	v_addc_co_u32_e32 v151, vcc, 0, v147, vcc
	s_mov_b32 s1, 0x8000
	v_lshl_add_u64 v[148:149], v[146:147], 0, s[20:21]
	global_store_dwordx4 v[150:151], v[76:79], off
	global_store_dwordx4 v[148:149], v[72:75], off offset:16
	v_add_co_u32_e32 v150, vcc, s1, v146
	v_lshl_add_u64 v[148:149], v[146:147], 0, s[84:85]
	s_nop 0
	v_addc_co_u32_e32 v151, vcc, 0, v147, vcc
	global_store_dwordx4 v[150:151], v[60:63], off
	global_store_dwordx4 v[148:149], v[56:59], off offset:16
	v_add_co_u32_e32 v150, vcc, 0x9000, v146
	s_mov_b64 s[20:21], 0x9000
	s_nop 0
	v_addc_co_u32_e32 v151, vcc, 0, v147, vcc
	v_lshl_add_u64 v[148:149], v[146:147], 0, s[20:21]
	global_store_dwordx4 v[150:151], v[44:47], off
	global_store_dwordx4 v[148:149], v[40:43], off offset:16
	s_mov_b64 s[20:21], 0xa000
	v_add_co_u32_e32 v150, vcc, 0xa000, v146
	v_lshl_add_u64 v[148:149], v[146:147], 0, s[20:21]
	s_nop 0
	v_addc_co_u32_e32 v151, vcc, 0, v147, vcc
	s_mov_b64 s[20:21], 0xb000
	global_store_dwordx4 v[150:151], v[28:31], off
	global_store_dwordx4 v[148:149], v[24:27], off offset:16
	v_lshl_add_u64 v[148:149], v[146:147], 0, s[20:21]
	v_add_co_u32_e32 v146, vcc, 0xb000, v146
	s_nop 1
	v_addc_co_u32_e32 v147, vcc, 0, v147, vcc
	global_store_dwordx4 v[146:147], v[12:15], off
	global_store_dwordx4 v[148:149], v[8:11], off offset:16

.LBB0_207:
	s_add_u32 s22, s20, 0xfff80080
	s_addc_u32 s23, s21, -1
	s_add_i32 s47, 0, 0x10000
	v_add_u32_e32 v154, s47, v144
	ds_read_b128 v[138:141], v154
	ds_read_b128 v[146:149], v154 offset:1024
	ds_read_b128 v[150:153], v154 offset:2048
	ds_read_b128 v[154:157], v154 offset:3072
	s_cmp_eq_u32 s46, 28
	s_cselect_b32 s25, s1, s23
	s_cselect_b32 s24, s9, s22
	s_cselect_b32 s23, s11, s45
	s_cselect_b32 s22, s19, s44
	v_lshl_add_u64 v[182:183], s[20:21], 0, v[134:135]
	s_add_i32 m0, s33, 0xc000
	ds_read_b128 v[158:161], v145
	ds_read_b128 v[162:165], v145 offset:1024
	ds_read_b128 v[166:169], v145 offset:2048
	ds_read_b128 v[170:173], v145 offset:3072
	ds_read_b128 v[174:177], v145 offset:4096
	ds_read_b128 v[178:181], v145 offset:5120
	ds_read_b128 v[188:191], v145 offset:6144
	ds_read_b128 v[192:195], v145 offset:7168
	global_load_lds_dwordx4 v[182:183], off
	v_lshl_add_u64 v[182:183], s[20:21], 0, v[136:137]
	s_add_i32 m0, s33, 0xe000
	s_nop 0
	global_load_lds_dwordx4 v[182:183], off
	s_waitcnt lgkmcnt(8)
	s_setprio 1
	s_barrier
	s_waitcnt lgkmcnt(0)
	v_mfma_f32_16x16x32_bf16 v[124:127], v[138:141], v[158:161], v[124:127]
	v_mfma_f32_16x16x32_bf16 v[120:123], v[150:153], v[158:161], v[120:123]
	v_mfma_f32_16x16x32_bf16 v[108:111], v[138:141], v[166:169], v[108:111]
	v_mfma_f32_16x16x32_bf16 v[104:107], v[150:153], v[166:169], v[104:107]
	v_mfma_f32_16x16x32_bf16 v[92:95], v[138:141], v[174:177], v[92:95]
	v_mfma_f32_16x16x32_bf16 v[88:91], v[150:153], v[174:177], v[88:91]
	v_mfma_f32_16x16x32_bf16 v[76:79], v[138:141], v[188:191], v[76:79]
	v_mfma_f32_16x16x32_bf16 v[72:75], v[150:153], v[188:191], v[72:75]
	v_mfma_f32_16x16x32_bf16 v[124:127], v[146:149], v[162:165], v[124:127]
	v_mfma_f32_16x16x32_bf16 v[120:123], v[154:157], v[162:165], v[120:123]
	v_mfma_f32_16x16x32_bf16 v[108:111], v[146:149], v[170:173], v[108:111]
	v_mfma_f32_16x16x32_bf16 v[104:107], v[154:157], v[170:173], v[104:107]
	v_mfma_f32_16x16x32_bf16 v[92:95], v[146:149], v[178:181], v[92:95]
	v_mfma_f32_16x16x32_bf16 v[88:91], v[154:157], v[178:181], v[88:91]
	v_mfma_f32_16x16x32_bf16 v[76:79], v[146:149], v[192:195], v[76:79]
	v_mfma_f32_16x16x32_bf16 v[72:75], v[154:157], v[192:195], v[72:75]
	s_barrier
	s_setprio 0
	s_add_i32 s50, 0, 0x14000
	v_add_u32_e32 v182, s50, v144
	s_add_i32 s47, s47, s31
	ds_read_b128 v[202:205], v182
	ds_read_b128 v[206:209], v182 offset:1024
	ds_read_b128 v[210:213], v182 offset:2048
	ds_read_b128 v[214:217], v182 offset:3072
	v_lshl_add_u64 v[182:183], s[22:23], 0, v[184:185]
	s_mov_b32 m0, s47
	v_lshl_add_u64 v[196:197], s[22:23], 0, v[132:133]
	global_load_lds_dwordx4 v[182:183], off
	s_add_i32 m0, s47, 0x2000
	s_nop 0
	global_load_lds_dwordx4 v[196:197], off
	s_setprio 1
	s_barrier
	s_waitcnt lgkmcnt(0)
	v_mfma_f32_16x16x32_bf16 v[116:119], v[202:205], v[158:161], v[116:119]
	v_mfma_f32_16x16x32_bf16 v[112:115], v[210:213], v[158:161], v[112:115]
	v_mfma_f32_16x16x32_bf16 v[100:103], v[202:205], v[166:169], v[100:103]
	v_mfma_f32_16x16x32_bf16 v[96:99], v[210:213], v[166:169], v[96:99]
	v_mfma_f32_16x16x32_bf16 v[84:87], v[202:205], v[174:177], v[84:87]
	v_mfma_f32_16x16x32_bf16 v[80:83], v[210:213], v[174:177], v[80:83]
	v_mfma_f32_16x16x32_bf16 v[68:71], v[202:205], v[188:191], v[68:71]
	v_mfma_f32_16x16x32_bf16 v[64:67], v[210:213], v[188:191], v[64:67]
	v_mfma_f32_16x16x32_bf16 v[116:119], v[206:209], v[162:165], v[116:119]
	v_mfma_f32_16x16x32_bf16 v[112:115], v[214:217], v[162:165], v[112:115]
	v_mfma_f32_16x16x32_bf16 v[100:103], v[206:209], v[170:173], v[100:103]
	v_mfma_f32_16x16x32_bf16 v[96:99], v[214:217], v[170:173], v[96:99]
	v_mfma_f32_16x16x32_bf16 v[84:87], v[206:209], v[178:181], v[84:87]
	v_mfma_f32_16x16x32_bf16 v[80:83], v[214:217], v[178:181], v[80:83]
	v_mfma_f32_16x16x32_bf16 v[68:71], v[206:209], v[192:195], v[68:71]
	v_mfma_f32_16x16x32_bf16 v[64:67], v[214:217], v[192:195], v[64:67]
	s_barrier
	s_setprio 0
	s_mov_b32 m0, s33
	v_lshl_add_u64 v[218:219], s[24:25], 0, v[128:129]
	ds_read_b128 v[158:161], v145 offset:16384
	ds_read_b128 v[162:165], v145 offset:17408
	ds_read_b128 v[166:169], v145 offset:18432
	ds_read_b128 v[170:173], v145 offset:19456
	ds_read_b128 v[174:177], v145 offset:20480
	ds_read_b128 v[178:181], v145 offset:21504
	ds_read_b128 v[188:191], v145 offset:22528
	ds_read_b128 v[192:195], v145 offset:23552
	global_load_lds_dwordx4 v[218:219], off
	v_lshl_add_u64 v[220:221], s[24:25], 0, v[130:131]
	s_mov_b32 m0, s34
	s_nop 0
	global_load_lds_dwordx4 v[220:221], off
	s_setprio 1
	s_barrier
	s_waitcnt lgkmcnt(0)
	v_mfma_f32_16x16x32_bf16 v[60:63], v[138:141], v[158:161], v[60:63]
	v_mfma_f32_16x16x32_bf16 v[56:59], v[150:153], v[158:161], v[56:59]
	v_mfma_f32_16x16x32_bf16 v[44:47], v[138:141], v[166:169], v[44:47]
	v_mfma_f32_16x16x32_bf16 v[40:43], v[150:153], v[166:169], v[40:43]
	v_mfma_f32_16x16x32_bf16 v[28:31], v[138:141], v[174:177], v[28:31]
	v_mfma_f32_16x16x32_bf16 v[24:27], v[150:153], v[174:177], v[24:27]
	v_mfma_f32_16x16x32_bf16 v[12:15], v[138:141], v[188:191], v[12:15]
	v_mfma_f32_16x16x32_bf16 v[8:11], v[150:153], v[188:191], v[8:11]
	v_mfma_f32_16x16x32_bf16 v[60:63], v[146:149], v[162:165], v[60:63]
	v_mfma_f32_16x16x32_bf16 v[56:59], v[154:157], v[162:165], v[56:59]
	v_mfma_f32_16x16x32_bf16 v[44:47], v[146:149], v[170:173], v[44:47]
	v_mfma_f32_16x16x32_bf16 v[40:43], v[154:157], v[170:173], v[40:43]
	v_mfma_f32_16x16x32_bf16 v[28:31], v[146:149], v[178:181], v[28:31]
	v_mfma_f32_16x16x32_bf16 v[24:27], v[154:157], v[178:181], v[24:27]
	v_mfma_f32_16x16x32_bf16 v[12:15], v[146:149], v[192:195], v[12:15]
	v_mfma_f32_16x16x32_bf16 v[8:11], v[154:157], v[192:195], v[8:11]
	s_barrier
	s_setprio 0
	s_add_u32 s48, s22, 0x80000
	s_addc_u32 s49, s23, 0
	s_add_i32 s47, s50, s31
	v_lshl_add_u64 v[138:139], s[48:49], 0, v[184:185]
	s_mov_b32 m0, s47
	s_nop 0
	global_load_lds_dwordx4 v[138:139], off
	v_lshl_add_u64 v[138:139], s[48:49], 0, v[132:133]
	s_add_i32 m0, s47, 0x2000
	s_nop 0
	global_load_lds_dwordx4 v[138:139], off
	s_waitcnt vmcnt(6)
	s_setprio 1
	s_barrier
	v_mfma_f32_16x16x32_bf16 v[52:55], v[202:205], v[158:161], v[52:55]
	v_mfma_f32_16x16x32_bf16 v[48:51], v[210:213], v[158:161], v[48:51]
	v_mfma_f32_16x16x32_bf16 v[36:39], v[202:205], v[166:169], v[36:39]
	v_mfma_f32_16x16x32_bf16 v[32:35], v[210:213], v[166:169], v[32:35]
	v_mfma_f32_16x16x32_bf16 v[20:23], v[202:205], v[174:177], v[20:23]
	v_mfma_f32_16x16x32_bf16 v[16:19], v[210:213], v[174:177], v[16:19]
	v_mfma_f32_16x16x32_bf16 v[4:7], v[202:205], v[188:191], v[4:7]
	v_mfma_f32_16x16x32_bf16 v[0:3], v[210:213], v[188:191], v[0:3]
	v_mfma_f32_16x16x32_bf16 v[52:55], v[206:209], v[162:165], v[52:55]
	v_mfma_f32_16x16x32_bf16 v[48:51], v[214:217], v[162:165], v[48:51]
	v_mfma_f32_16x16x32_bf16 v[36:39], v[206:209], v[170:173], v[36:39]
	v_mfma_f32_16x16x32_bf16 v[32:35], v[214:217], v[170:173], v[32:35]
	v_mfma_f32_16x16x32_bf16 v[20:23], v[206:209], v[178:181], v[20:23]
	v_mfma_f32_16x16x32_bf16 v[16:19], v[214:217], v[178:181], v[16:19]
	v_mfma_f32_16x16x32_bf16 v[4:7], v[206:209], v[192:195], v[4:7]
	v_mfma_f32_16x16x32_bf16 v[0:3], v[214:217], v[192:195], v[0:3]
	s_barrier
	s_setprio 0
	s_add_i32 s47, 0, 0x18000
	v_add_u32_e32 v154, s47, v144
	ds_read_b128 v[138:141], v154
	ds_read_b128 v[146:149], v154 offset:1024
	ds_read_b128 v[150:153], v154 offset:2048
	ds_read_b128 v[154:157], v154 offset:3072
	s_add_u32 s24, s24, 0x80000
	s_addc_u32 s25, s25, 0
	s_mov_b32 m0, s35
	v_lshl_add_u64 v[202:203], s[24:25], 0, v[128:129]
	ds_read_b128 v[158:161], v145 offset:32768
	ds_read_b128 v[162:165], v145 offset:33792
	ds_read_b128 v[166:169], v145 offset:34816
	ds_read_b128 v[170:173], v145 offset:35840
	ds_read_b128 v[174:177], v145 offset:36864
	ds_read_b128 v[178:181], v145 offset:37888
	ds_read_b128 v[188:191], v145 offset:38912
	ds_read_b128 v[192:195], v145 offset:39936
	global_load_lds_dwordx4 v[202:203], off
	v_lshl_add_u64 v[202:203], s[24:25], 0, v[130:131]
	s_mov_b32 m0, s36
	s_nop 0
	global_load_lds_dwordx4 v[202:203], off
	s_waitcnt lgkmcnt(8)
	s_setprio 1
	s_barrier
	s_waitcnt lgkmcnt(0)
	v_mfma_f32_16x16x32_bf16 v[124:127], v[138:141], v[158:161], v[124:127]
	v_mfma_f32_16x16x32_bf16 v[120:123], v[150:153], v[158:161], v[120:123]
	v_mfma_f32_16x16x32_bf16 v[108:111], v[138:141], v[166:169], v[108:111]
	v_mfma_f32_16x16x32_bf16 v[104:107], v[150:153], v[166:169], v[104:107]
	v_mfma_f32_16x16x32_bf16 v[92:95], v[138:141], v[174:177], v[92:95]
	v_mfma_f32_16x16x32_bf16 v[88:91], v[150:153], v[174:177], v[88:91]
	v_mfma_f32_16x16x32_bf16 v[76:79], v[138:141], v[188:191], v[76:79]
	v_mfma_f32_16x16x32_bf16 v[72:75], v[150:153], v[188:191], v[72:75]
	v_mfma_f32_16x16x32_bf16 v[124:127], v[146:149], v[162:165], v[124:127]
	v_mfma_f32_16x16x32_bf16 v[120:123], v[154:157], v[162:165], v[120:123]
	v_mfma_f32_16x16x32_bf16 v[108:111], v[146:149], v[170:173], v[108:111]
	v_mfma_f32_16x16x32_bf16 v[104:107], v[154:157], v[170:173], v[104:107]
	v_mfma_f32_16x16x32_bf16 v[92:95], v[146:149], v[178:181], v[92:95]
	v_mfma_f32_16x16x32_bf16 v[88:91], v[154:157], v[178:181], v[88:91]
	v_mfma_f32_16x16x32_bf16 v[76:79], v[146:149], v[192:195], v[76:79]
	v_mfma_f32_16x16x32_bf16 v[72:75], v[154:157], v[192:195], v[72:75]
	s_barrier
	s_setprio 0
	s_add_i32 s24, 0, 0x1c000
	s_add_i32 s25, s47, s31
	v_add_u32_e32 v187, s24, v144
	v_lshl_add_u64 v[182:183], v[182:183], 0, s[52:53]
	s_mov_b32 m0, s25
	ds_read_b128 v[202:205], v187
	ds_read_b128 v[206:209], v187 offset:1024
	ds_read_b128 v[210:213], v187 offset:2048
	ds_read_b128 v[214:217], v187 offset:3072
	global_load_lds_dwordx4 v[182:183], off
	v_lshl_add_u64 v[182:183], v[196:197], 0, s[52:53]
	s_add_i32 m0, s25, 0x2000
	s_nop 0
	global_load_lds_dwordx4 v[182:183], off
	s_setprio 1
	s_barrier
	s_waitcnt lgkmcnt(0)
	v_mfma_f32_16x16x32_bf16 v[116:119], v[202:205], v[158:161], v[116:119]
	v_mfma_f32_16x16x32_bf16 v[112:115], v[210:213], v[158:161], v[112:115]
	v_mfma_f32_16x16x32_bf16 v[100:103], v[202:205], v[166:169], v[100:103]
	v_mfma_f32_16x16x32_bf16 v[96:99], v[210:213], v[166:169], v[96:99]
	v_mfma_f32_16x16x32_bf16 v[84:87], v[202:205], v[174:177], v[84:87]
	v_mfma_f32_16x16x32_bf16 v[80:83], v[210:213], v[174:177], v[80:83]
	v_mfma_f32_16x16x32_bf16 v[68:71], v[202:205], v[188:191], v[68:71]
	v_mfma_f32_16x16x32_bf16 v[64:67], v[210:213], v[188:191], v[64:67]
	v_mfma_f32_16x16x32_bf16 v[116:119], v[206:209], v[162:165], v[116:119]
	v_mfma_f32_16x16x32_bf16 v[112:115], v[214:217], v[162:165], v[112:115]
	v_mfma_f32_16x16x32_bf16 v[100:103], v[206:209], v[170:173], v[100:103]
	v_mfma_f32_16x16x32_bf16 v[96:99], v[214:217], v[170:173], v[96:99]
	v_mfma_f32_16x16x32_bf16 v[84:87], v[206:209], v[178:181], v[84:87]
	v_mfma_f32_16x16x32_bf16 v[80:83], v[214:217], v[178:181], v[80:83]
	v_mfma_f32_16x16x32_bf16 v[68:71], v[206:209], v[192:195], v[68:71]
	v_mfma_f32_16x16x32_bf16 v[64:67], v[214:217], v[192:195], v[64:67]
	s_barrier
	s_setprio 0
	s_mov_b32 m0, s40
	v_lshl_add_u64 v[182:183], v[218:219], 0, s[52:53]
	ds_read_b128 v[158:161], v145 offset:49152
	ds_read_b128 v[162:165], v145 offset:50176
	ds_read_b128 v[166:169], v145 offset:51200
	ds_read_b128 v[170:173], v145 offset:52224
	ds_read_b128 v[174:177], v145 offset:53248
	ds_read_b128 v[178:181], v145 offset:54272
	ds_read_b128 v[188:191], v145 offset:55296
	ds_read_b128 v[192:195], v145 offset:56320
	global_load_lds_dwordx4 v[182:183], off
	v_lshl_add_u64 v[182:183], v[220:221], 0, s[52:53]
	s_mov_b32 m0, s41
	s_nop 0
	global_load_lds_dwordx4 v[182:183], off
	s_setprio 1
	s_barrier
	s_waitcnt lgkmcnt(0)
	v_mfma_f32_16x16x32_bf16 v[60:63], v[138:141], v[158:161], v[60:63]
	v_mfma_f32_16x16x32_bf16 v[56:59], v[150:153], v[158:161], v[56:59]
	v_mfma_f32_16x16x32_bf16 v[44:47], v[138:141], v[166:169], v[44:47]
	v_mfma_f32_16x16x32_bf16 v[40:43], v[150:153], v[166:169], v[40:43]
	v_mfma_f32_16x16x32_bf16 v[28:31], v[138:141], v[174:177], v[28:31]
	v_mfma_f32_16x16x32_bf16 v[24:27], v[150:153], v[174:177], v[24:27]
	v_mfma_f32_16x16x32_bf16 v[12:15], v[138:141], v[188:191], v[12:15]
	v_mfma_f32_16x16x32_bf16 v[8:11], v[150:153], v[188:191], v[8:11]
	v_mfma_f32_16x16x32_bf16 v[60:63], v[146:149], v[162:165], v[60:63]
	v_mfma_f32_16x16x32_bf16 v[56:59], v[154:157], v[162:165], v[56:59]
	v_mfma_f32_16x16x32_bf16 v[44:47], v[146:149], v[170:173], v[44:47]
	v_mfma_f32_16x16x32_bf16 v[40:43], v[154:157], v[170:173], v[40:43]
	v_mfma_f32_16x16x32_bf16 v[28:31], v[146:149], v[178:181], v[28:31]
	v_mfma_f32_16x16x32_bf16 v[24:27], v[154:157], v[178:181], v[24:27]
	v_mfma_f32_16x16x32_bf16 v[12:15], v[146:149], v[192:195], v[12:15]
	v_mfma_f32_16x16x32_bf16 v[8:11], v[154:157], v[192:195], v[8:11]
	s_barrier
	s_setprio 0
	s_add_u32 s22, s22, 0x80080
	s_addc_u32 s23, s23, 0
	s_add_i32 s24, s24, s31
	v_lshl_add_u64 v[138:139], s[22:23], 0, v[184:185]
	s_mov_b32 m0, s24
	s_nop 0
	global_load_lds_dwordx4 v[138:139], off
	v_lshl_add_u64 v[138:139], s[22:23], 0, v[132:133]
	s_add_i32 m0, s24, 0x2000
	s_nop 0
	global_load_lds_dwordx4 v[138:139], off
	s_waitcnt vmcnt(6)
	s_setprio 1
	s_barrier
	v_mfma_f32_16x16x32_bf16 v[52:55], v[202:205], v[158:161], v[52:55]
	v_mfma_f32_16x16x32_bf16 v[48:51], v[210:213], v[158:161], v[48:51]
	v_mfma_f32_16x16x32_bf16 v[36:39], v[202:205], v[166:169], v[36:39]
	v_mfma_f32_16x16x32_bf16 v[32:35], v[210:213], v[166:169], v[32:35]
	v_mfma_f32_16x16x32_bf16 v[20:23], v[202:205], v[174:177], v[20:23]
	v_mfma_f32_16x16x32_bf16 v[16:19], v[210:213], v[174:177], v[16:19]
	v_mfma_f32_16x16x32_bf16 v[4:7], v[202:205], v[188:191], v[4:7]
	v_mfma_f32_16x16x32_bf16 v[0:3], v[210:213], v[188:191], v[0:3]
	v_mfma_f32_16x16x32_bf16 v[52:55], v[206:209], v[162:165], v[52:55]
	v_mfma_f32_16x16x32_bf16 v[48:51], v[214:217], v[162:165], v[48:51]
	v_mfma_f32_16x16x32_bf16 v[36:39], v[206:209], v[170:173], v[36:39]
	v_mfma_f32_16x16x32_bf16 v[32:35], v[214:217], v[170:173], v[32:35]
	v_mfma_f32_16x16x32_bf16 v[20:23], v[206:209], v[178:181], v[20:23]
	v_mfma_f32_16x16x32_bf16 v[16:19], v[214:217], v[178:181], v[16:19]
	v_mfma_f32_16x16x32_bf16 v[4:7], v[206:209], v[192:195], v[4:7]
	v_mfma_f32_16x16x32_bf16 v[0:3], v[214:217], v[192:195], v[0:3]
	s_barrier
	s_setprio 0
	s_add_i32 s46, s46, 2
	s_add_u32 s20, s20, 0x100
	s_addc_u32 s21, s21, 0
	s_add_u32 s44, s44, 0x100
	s_addc_u32 s45, s45, 0
	s_cmp_gt_u32 s46, 29
	s_cbranch_scc0 .LBB0_207
	v_mov_b32_e32 v138, v142
	v_mov_b32_e32 v146, v143
	s_lshl_b32 s1, s18, 8
	s_add_i32 s1, s1, s38
	v_add_u32_e32 v138, s1, v138
	s_lshl_b32 s1, s0, 8
	s_cmp_lt_i32 s0, 2
	v_lshlrev_b32_e32 v147, 3, v146
	s_mov_b64 s[18:19], -1
	v_ashrrev_i32_e32 v139, 31, v138
	s_cbranch_scc1 .LBB0_210
	v_mul_f32_e32 v140, 0xbfb8aa3b, v124
	v_mul_f32_e32 v149, 0xbfb8aa3b, v125
	v_mul_f32_e32 v150, 0xbfb8aa3b, v126
	v_mul_f32_e32 v153, 0xbfb8aa3b, v120
	v_exp_f32_e32 v148, v140
	v_exp_f32_e32 v149, v149
	v_exp_f32_e32 v150, v150
	v_mul_f32_e32 v151, 0xbfb8aa3b, v127
	v_exp_f32_e32 v153, v153
	v_mul_f32_e32 v154, 0xbfb8aa3b, v121
	v_exp_f32_e32 v151, v151
	v_exp_f32_e32 v154, v154
	v_mul_f32_e32 v155, 0xbfb8aa3b, v122
	v_mul_f32_e32 v156, 0xbfb8aa3b, v123
	v_add_f32_e32 v148, 1.0, v148
	v_add_f32_e32 v149, 1.0, v149
	v_add_f32_e32 v150, 1.0, v150
	v_add_f32_e32 v153, 1.0, v153
	v_exp_f32_e32 v155, v155
	v_exp_f32_e32 v156, v156
	v_rcp_f32_e32 v148, v148
	v_rcp_f32_e32 v149, v149
	v_rcp_f32_e32 v150, v150
	v_add_f32_e32 v151, 1.0, v151
	v_rcp_f32_e32 v153, v153
	v_add_f32_e32 v154, 1.0, v154
	v_rcp_f32_e32 v151, v151
	v_rcp_f32_e32 v154, v154
	v_add_f32_e32 v155, 1.0, v155
	v_add_f32_e32 v156, 1.0, v156
	s_add_i32 s9, s42, s1
	v_mul_f32_e32 v148, v124, v148
	v_mul_f32_e32 v149, v125, v149
	v_mul_f32_e32 v150, v126, v150
	v_rcp_f32_e32 v155, v155
	v_rcp_f32_e32 v156, v156
	v_mul_f32_e32 v153, v120, v153
	v_lshlrev_b64 v[140:141], 12, v[138:139]
	v_add_u32_e32 v152, s9, v147
	v_mul_f32_e32 v151, v127, v151
	v_mul_f32_e32 v154, v121, v154
	v_cvt_pk_bf16_f32 v148, v148, v149
	v_cvt_pk_bf16_f32 v149, v150, v151
	v_cvt_pk_bf16_f32 v150, v153, v154
	v_mul_f32_e32 v153, 0xbfb8aa3b, v116
	v_lshl_add_u64 v[140:141], s[6:7], 0, v[140:141]
	v_exp_f32_e32 v154, v153
	v_ashrrev_i32_e32 v153, 31, v152
	v_lshl_add_u64 v[140:141], v[152:153], 1, v[140:141]
	v_mul_f32_e32 v155, v122, v155
	v_mul_f32_e32 v156, v123, v156
	v_cvt_pk_bf16_f32 v151, v155, v156
	global_store_dwordx4 v[140:141], v[148:151], off
	v_mul_f32_e32 v152, 0xbfb8aa3b, v112
	v_mul_f32_e32 v153, 0xbfb8aa3b, v113
	v_mul_f32_e32 v149, 0xbfb8aa3b, v117
	v_mul_f32_e32 v150, 0xbfb8aa3b, v118
	v_exp_f32_e32 v149, v149
	v_exp_f32_e32 v150, v150
	v_mul_f32_e32 v151, 0xbfb8aa3b, v119
	v_add_f32_e32 v148, 1.0, v154
	v_exp_f32_e32 v151, v151
	v_mul_f32_e32 v154, 0xbfb8aa3b, v114
	v_mul_f32_e32 v155, 0xbfb8aa3b, v115
	v_exp_f32_e32 v152, v152
	v_exp_f32_e32 v153, v153
	v_exp_f32_e32 v154, v154
	v_exp_f32_e32 v155, v155
	v_add_f32_e32 v149, 1.0, v149
	v_add_f32_e32 v150, 1.0, v150
	v_rcp_f32_e32 v148, v148
	v_rcp_f32_e32 v149, v149
	v_rcp_f32_e32 v150, v150
	v_add_f32_e32 v151, 1.0, v151
	v_rcp_f32_e32 v151, v151
	v_add_f32_e32 v152, 1.0, v152
	v_add_f32_e32 v153, 1.0, v153
	v_add_f32_e32 v154, 1.0, v154
	v_add_f32_e32 v155, 1.0, v155
	v_rcp_f32_e32 v152, v152
	v_rcp_f32_e32 v153, v153
	v_rcp_f32_e32 v154, v154
	v_rcp_f32_e32 v155, v155
	v_mul_f32_e32 v148, v116, v148
	v_mul_f32_e32 v149, v117, v149
	v_mul_f32_e32 v150, v118, v150
	v_mul_f32_e32 v151, v119, v151
	v_cvt_pk_bf16_f32 v148, v148, v149
	v_cvt_pk_bf16_f32 v149, v150, v151
	v_mul_f32_e32 v150, 0xbfb8aa3b, v108
	v_mul_f32_e32 v152, v112, v152
	v_mul_f32_e32 v153, v113, v153
	v_mul_f32_e32 v154, v114, v154
	v_mul_f32_e32 v155, v115, v155
	v_exp_f32_e32 v156, v150
	v_cvt_pk_bf16_f32 v150, v152, v153
	v_cvt_pk_bf16_f32 v151, v154, v155
	global_store_dwordx4 v[140:141], v[148:151], off offset:256
	v_mul_f32_e32 v154, 0xbfb8aa3b, v106
	v_mul_f32_e32 v152, 0xbfb8aa3b, v104
	v_mul_f32_e32 v149, 0xbfb8aa3b, v109
	v_mul_f32_e32 v150, 0xbfb8aa3b, v110
	v_mul_f32_e32 v151, 0xbfb8aa3b, v111
	v_exp_f32_e32 v149, v149
	v_exp_f32_e32 v150, v150
	v_exp_f32_e32 v151, v151
	v_mul_f32_e32 v153, 0xbfb8aa3b, v105
	v_exp_f32_e32 v154, v154
	v_mul_f32_e32 v155, 0xbfb8aa3b, v107
	v_exp_f32_e32 v152, v152
	v_exp_f32_e32 v153, v153
	v_exp_f32_e32 v155, v155
	v_add_f32_e32 v148, 1.0, v156
	v_add_f32_e32 v149, 1.0, v149
	v_add_f32_e32 v150, 1.0, v150
	v_add_f32_e32 v151, 1.0, v151
	v_add_f32_e32 v154, 1.0, v154
	v_rcp_f32_e32 v148, v148
	v_rcp_f32_e32 v149, v149
	v_rcp_f32_e32 v150, v150
	v_rcp_f32_e32 v151, v151
	v_add_f32_e32 v152, 1.0, v152
	v_add_f32_e32 v153, 1.0, v153
	v_rcp_f32_e32 v154, v154
	v_add_f32_e32 v155, 1.0, v155
	v_rcp_f32_e32 v152, v152
	v_rcp_f32_e32 v153, v153
	v_rcp_f32_e32 v155, v155
	v_mul_f32_e32 v148, v108, v148
	v_mul_f32_e32 v149, v109, v149
	v_mul_f32_e32 v150, v110, v150
	v_mul_f32_e32 v151, v111, v151
	v_mul_f32_e32 v154, v106, v154
	v_mul_f32_e32 v152, v104, v152
	v_mul_f32_e32 v153, v105, v153
	v_mul_f32_e32 v155, v107, v155
	v_cvt_pk_bf16_f32 v148, v148, v149
	v_cvt_pk_bf16_f32 v149, v150, v151
	v_cvt_pk_bf16_f32 v150, v152, v153
	v_cvt_pk_bf16_f32 v151, v154, v155
	v_mul_f32_e32 v154, 0xbfb8aa3b, v100
	s_mov_b32 s9, 0x10000
	v_exp_f32_e32 v156, v154
	v_add_co_u32_e32 v154, vcc, s9, v140
	v_mul_f32_e32 v157, 0xbfb8aa3b, v99
	s_nop 0
	v_addc_co_u32_e32 v155, vcc, 0, v141, vcc
	global_store_dwordx4 v[154:155], v[148:151], off
	v_mul_f32_e32 v154, 0xbfb8aa3b, v96
	v_mul_f32_e32 v155, 0xbfb8aa3b, v97
	v_mul_f32_e32 v149, 0xbfb8aa3b, v101
	v_mul_f32_e32 v150, 0xbfb8aa3b, v102
	v_exp_f32_e32 v149, v149
	v_exp_f32_e32 v150, v150
	v_mul_f32_e32 v151, 0xbfb8aa3b, v103
	v_add_f32_e32 v148, 1.0, v156
	v_exp_f32_e32 v151, v151
	v_mul_f32_e32 v156, 0xbfb8aa3b, v98
	v_exp_f32_e32 v154, v154
	v_exp_f32_e32 v155, v155
	v_exp_f32_e32 v156, v156
	v_exp_f32_e32 v157, v157
	v_add_f32_e32 v149, 1.0, v149
	v_add_f32_e32 v150, 1.0, v150
	v_rcp_f32_e32 v148, v148
	v_rcp_f32_e32 v149, v149
	v_rcp_f32_e32 v150, v150
	v_add_f32_e32 v151, 1.0, v151
	v_rcp_f32_e32 v151, v151
	v_add_f32_e32 v154, 1.0, v154
	v_add_f32_e32 v155, 1.0, v155
	v_add_f32_e32 v156, 1.0, v156
	v_add_f32_e32 v157, 1.0, v157
	v_rcp_f32_e32 v154, v154
	v_rcp_f32_e32 v155, v155
	v_rcp_f32_e32 v156, v156
	v_rcp_f32_e32 v157, v157
	v_mul_f32_e32 v148, v100, v148
	v_mul_f32_e32 v149, v101, v149
	v_mul_f32_e32 v150, v102, v150
	s_mov_b64 s[18:19], 0x10000
	v_mul_f32_e32 v151, v103, v151
	v_cvt_pk_bf16_f32 v148, v148, v149
	v_cvt_pk_bf16_f32 v149, v150, v151
	v_mul_f32_e32 v150, 0xbfb8aa3b, v92
	v_lshl_add_u64 v[152:153], v[140:141], 0, s[18:19]
	v_mul_f32_e32 v154, v96, v154
	v_mul_f32_e32 v155, v97, v155
	v_mul_f32_e32 v156, v98, v156
	v_mul_f32_e32 v157, v99, v157
	v_exp_f32_e32 v158, v150
	v_cvt_pk_bf16_f32 v150, v154, v155
	v_cvt_pk_bf16_f32 v151, v156, v157
	global_store_dwordx4 v[152:153], v[148:151], off offset:256
	v_mul_f32_e32 v154, 0xbfb8aa3b, v90
	v_mul_f32_e32 v152, 0xbfb8aa3b, v88
	v_mul_f32_e32 v149, 0xbfb8aa3b, v93
	v_mul_f32_e32 v150, 0xbfb8aa3b, v94
	v_mul_f32_e32 v151, 0xbfb8aa3b, v95
	v_exp_f32_e32 v149, v149
	v_exp_f32_e32 v150, v150
	v_exp_f32_e32 v151, v151
	v_mul_f32_e32 v153, 0xbfb8aa3b, v89
	v_exp_f32_e32 v154, v154
	v_mul_f32_e32 v155, 0xbfb8aa3b, v91
	v_exp_f32_e32 v152, v152
	v_exp_f32_e32 v153, v153
	v_exp_f32_e32 v155, v155
	v_add_f32_e32 v148, 1.0, v158
	v_add_f32_e32 v149, 1.0, v149
	v_add_f32_e32 v150, 1.0, v150
	v_add_f32_e32 v151, 1.0, v151
	v_add_f32_e32 v154, 1.0, v154
	v_rcp_f32_e32 v148, v148
	v_rcp_f32_e32 v149, v149
	v_rcp_f32_e32 v150, v150
	v_rcp_f32_e32 v151, v151
	v_add_f32_e32 v152, 1.0, v152
	v_add_f32_e32 v153, 1.0, v153
	v_rcp_f32_e32 v154, v154
	v_add_f32_e32 v155, 1.0, v155
	v_rcp_f32_e32 v152, v152
	v_rcp_f32_e32 v153, v153
	v_rcp_f32_e32 v155, v155
	v_mul_f32_e32 v148, v92, v148
	v_mul_f32_e32 v149, v93, v149
	v_mul_f32_e32 v150, v94, v150
	v_mul_f32_e32 v151, v95, v151
	v_mul_f32_e32 v154, v90, v154
	v_mul_f32_e32 v152, v88, v152
	v_mul_f32_e32 v153, v89, v153
	v_mul_f32_e32 v155, v91, v155
	v_cvt_pk_bf16_f32 v148, v148, v149
	v_cvt_pk_bf16_f32 v149, v150, v151
	v_cvt_pk_bf16_f32 v150, v152, v153
	v_cvt_pk_bf16_f32 v151, v154, v155
	v_mul_f32_e32 v154, 0xbfb8aa3b, v84
	s_mov_b32 s9, 0x20000
	v_exp_f32_e32 v156, v154
	v_add_co_u32_e32 v154, vcc, s9, v140
	v_mul_f32_e32 v157, 0xbfb8aa3b, v83
	s_nop 0
	v_addc_co_u32_e32 v155, vcc, 0, v141, vcc
	global_store_dwordx4 v[154:155], v[148:151], off
	v_mul_f32_e32 v154, 0xbfb8aa3b, v80
	v_mul_f32_e32 v155, 0xbfb8aa3b, v81
	v_mul_f32_e32 v149, 0xbfb8aa3b, v85
	v_mul_f32_e32 v150, 0xbfb8aa3b, v86
	v_exp_f32_e32 v149, v149
	v_exp_f32_e32 v150, v150
	v_mul_f32_e32 v151, 0xbfb8aa3b, v87
	v_add_f32_e32 v148, 1.0, v156
	v_exp_f32_e32 v151, v151
	v_mul_f32_e32 v156, 0xbfb8aa3b, v82
	v_exp_f32_e32 v154, v154
	v_exp_f32_e32 v155, v155
	v_exp_f32_e32 v156, v156
	v_exp_f32_e32 v157, v157
	v_add_f32_e32 v149, 1.0, v149
	v_add_f32_e32 v150, 1.0, v150
	v_rcp_f32_e32 v148, v148
	v_rcp_f32_e32 v149, v149
	v_rcp_f32_e32 v150, v150
	v_add_f32_e32 v151, 1.0, v151
	v_rcp_f32_e32 v151, v151
	v_add_f32_e32 v154, 1.0, v154
	v_add_f32_e32 v155, 1.0, v155
	v_add_f32_e32 v156, 1.0, v156
	v_add_f32_e32 v157, 1.0, v157
	v_rcp_f32_e32 v154, v154
	v_rcp_f32_e32 v155, v155
	v_rcp_f32_e32 v156, v156
	v_rcp_f32_e32 v157, v157
	v_mul_f32_e32 v148, v84, v148
	v_mul_f32_e32 v149, v85, v149
	v_mul_f32_e32 v150, v86, v150
	s_mov_b64 s[18:19], 0x20000
	v_mul_f32_e32 v151, v87, v151
	v_cvt_pk_bf16_f32 v148, v148, v149
	v_cvt_pk_bf16_f32 v149, v150, v151
	v_mul_f32_e32 v150, 0xbfb8aa3b, v76
	v_lshl_add_u64 v[152:153], v[140:141], 0, s[18:19]
	v_mul_f32_e32 v154, v80, v154
	v_mul_f32_e32 v155, v81, v155
	v_mul_f32_e32 v156, v82, v156
	v_mul_f32_e32 v157, v83, v157
	v_exp_f32_e32 v158, v150
	v_cvt_pk_bf16_f32 v150, v154, v155
	v_cvt_pk_bf16_f32 v151, v156, v157
	global_store_dwordx4 v[152:153], v[148:151], off offset:256
	v_mul_f32_e32 v154, 0xbfb8aa3b, v74
	v_mul_f32_e32 v152, 0xbfb8aa3b, v72
	v_mul_f32_e32 v149, 0xbfb8aa3b, v77
	v_mul_f32_e32 v150, 0xbfb8aa3b, v78
	v_mul_f32_e32 v151, 0xbfb8aa3b, v79
	v_exp_f32_e32 v149, v149
	v_exp_f32_e32 v150, v150
	v_exp_f32_e32 v151, v151
	v_mul_f32_e32 v153, 0xbfb8aa3b, v73
	v_exp_f32_e32 v154, v154
	v_mul_f32_e32 v155, 0xbfb8aa3b, v75
	v_exp_f32_e32 v152, v152
	v_exp_f32_e32 v153, v153
	v_exp_f32_e32 v155, v155
	v_add_f32_e32 v148, 1.0, v158
	v_add_f32_e32 v149, 1.0, v149
	v_add_f32_e32 v150, 1.0, v150
	v_add_f32_e32 v151, 1.0, v151
	v_add_f32_e32 v154, 1.0, v154
	v_rcp_f32_e32 v148, v148
	v_rcp_f32_e32 v149, v149
	v_rcp_f32_e32 v150, v150
	v_rcp_f32_e32 v151, v151
	v_add_f32_e32 v152, 1.0, v152
	v_add_f32_e32 v153, 1.0, v153
	v_rcp_f32_e32 v154, v154
	v_add_f32_e32 v155, 1.0, v155
	v_rcp_f32_e32 v152, v152
	v_rcp_f32_e32 v153, v153
	v_rcp_f32_e32 v155, v155
	v_mul_f32_e32 v148, v76, v148
	v_mul_f32_e32 v149, v77, v149
	v_mul_f32_e32 v150, v78, v150
	v_mul_f32_e32 v151, v79, v151
	v_mul_f32_e32 v154, v74, v154
	v_mul_f32_e32 v152, v72, v152
	v_mul_f32_e32 v153, v73, v153
	v_mul_f32_e32 v155, v75, v155
	v_cvt_pk_bf16_f32 v148, v148, v149
	v_cvt_pk_bf16_f32 v149, v150, v151
	v_cvt_pk_bf16_f32 v150, v152, v153
	v_cvt_pk_bf16_f32 v151, v154, v155
	v_mul_f32_e32 v154, 0xbfb8aa3b, v68
	s_mov_b32 s9, 0x30000
	v_exp_f32_e32 v156, v154
	v_add_co_u32_e32 v154, vcc, s9, v140
	v_mul_f32_e32 v157, 0xbfb8aa3b, v67
	s_nop 0
	v_addc_co_u32_e32 v155, vcc, 0, v141, vcc
	global_store_dwordx4 v[154:155], v[148:151], off
	v_mul_f32_e32 v154, 0xbfb8aa3b, v64
	v_mul_f32_e32 v155, 0xbfb8aa3b, v65
	v_mul_f32_e32 v149, 0xbfb8aa3b, v69
	v_mul_f32_e32 v150, 0xbfb8aa3b, v70
	v_exp_f32_e32 v149, v149
	v_exp_f32_e32 v150, v150
	v_mul_f32_e32 v151, 0xbfb8aa3b, v71
	v_add_f32_e32 v148, 1.0, v156
	v_exp_f32_e32 v151, v151
	v_mul_f32_e32 v156, 0xbfb8aa3b, v66
	v_exp_f32_e32 v154, v154
	v_exp_f32_e32 v155, v155
	v_exp_f32_e32 v156, v156
	v_exp_f32_e32 v157, v157
	v_add_f32_e32 v149, 1.0, v149
	v_add_f32_e32 v150, 1.0, v150
	v_rcp_f32_e32 v148, v148
	v_rcp_f32_e32 v149, v149
	v_rcp_f32_e32 v150, v150
	v_add_f32_e32 v151, 1.0, v151
	v_rcp_f32_e32 v151, v151
	v_add_f32_e32 v154, 1.0, v154
	v_add_f32_e32 v155, 1.0, v155
	v_add_f32_e32 v156, 1.0, v156
	v_add_f32_e32 v157, 1.0, v157
	v_rcp_f32_e32 v154, v154
	v_rcp_f32_e32 v155, v155
	v_rcp_f32_e32 v156, v156
	v_rcp_f32_e32 v157, v157
	v_mul_f32_e32 v148, v68, v148
	v_mul_f32_e32 v149, v69, v149
	v_mul_f32_e32 v150, v70, v150
	s_mov_b64 s[18:19], 0x30000
	v_mul_f32_e32 v151, v71, v151
	v_cvt_pk_bf16_f32 v148, v148, v149
	v_cvt_pk_bf16_f32 v149, v150, v151
	v_mul_f32_e32 v150, 0xbfb8aa3b, v60
	v_lshl_add_u64 v[152:153], v[140:141], 0, s[18:19]
	v_mul_f32_e32 v154, v64, v154
	v_mul_f32_e32 v155, v65, v155
	v_mul_f32_e32 v156, v66, v156
	v_mul_f32_e32 v157, v67, v157
	v_exp_f32_e32 v158, v150
	v_cvt_pk_bf16_f32 v150, v154, v155
	v_cvt_pk_bf16_f32 v151, v156, v157
	global_store_dwordx4 v[152:153], v[148:151], off offset:256
	v_mul_f32_e32 v154, 0xbfb8aa3b, v58
	v_mul_f32_e32 v152, 0xbfb8aa3b, v56
	v_mul_f32_e32 v149, 0xbfb8aa3b, v61
	v_mul_f32_e32 v150, 0xbfb8aa3b, v62
	v_mul_f32_e32 v151, 0xbfb8aa3b, v63
	v_exp_f32_e32 v149, v149
	v_exp_f32_e32 v150, v150
	v_exp_f32_e32 v151, v151
	v_mul_f32_e32 v153, 0xbfb8aa3b, v57
	v_exp_f32_e32 v154, v154
	v_mul_f32_e32 v155, 0xbfb8aa3b, v59
	v_exp_f32_e32 v152, v152
	v_exp_f32_e32 v153, v153
	v_exp_f32_e32 v155, v155
	v_add_f32_e32 v148, 1.0, v158
	v_add_f32_e32 v149, 1.0, v149
	v_add_f32_e32 v150, 1.0, v150
	v_add_f32_e32 v151, 1.0, v151
	v_add_f32_e32 v154, 1.0, v154
	v_rcp_f32_e32 v148, v148
	v_rcp_f32_e32 v149, v149
	v_rcp_f32_e32 v150, v150
	v_rcp_f32_e32 v151, v151
	v_add_f32_e32 v152, 1.0, v152
	v_add_f32_e32 v153, 1.0, v153
	v_rcp_f32_e32 v154, v154
	v_add_f32_e32 v155, 1.0, v155
	v_rcp_f32_e32 v152, v152
	v_rcp_f32_e32 v153, v153
	v_rcp_f32_e32 v155, v155
	v_mul_f32_e32 v148, v60, v148
	v_mul_f32_e32 v149, v61, v149
	v_mul_f32_e32 v150, v62, v150
	v_mul_f32_e32 v151, v63, v151
	v_mul_f32_e32 v154, v58, v154
	v_mul_f32_e32 v152, v56, v152
	v_mul_f32_e32 v153, v57, v153
	v_mul_f32_e32 v155, v59, v155
	v_cvt_pk_bf16_f32 v148, v148, v149
	v_cvt_pk_bf16_f32 v149, v150, v151
	v_cvt_pk_bf16_f32 v150, v152, v153
	v_cvt_pk_bf16_f32 v151, v154, v155
	v_mul_f32_e32 v154, 0xbfb8aa3b, v52
	s_mov_b32 s9, 0x80000
	v_exp_f32_e32 v156, v154
	v_add_co_u32_e32 v154, vcc, s9, v140
	v_mul_f32_e32 v157, 0xbfb8aa3b, v51
	s_nop 0
	v_addc_co_u32_e32 v155, vcc, 0, v141, vcc
	global_store_dwordx4 v[154:155], v[148:151], off
	v_mul_f32_e32 v154, 0xbfb8aa3b, v48
	v_mul_f32_e32 v155, 0xbfb8aa3b, v49
	v_mul_f32_e32 v149, 0xbfb8aa3b, v53
	v_mul_f32_e32 v150, 0xbfb8aa3b, v54
	v_exp_f32_e32 v149, v149
	v_exp_f32_e32 v150, v150
	v_mul_f32_e32 v151, 0xbfb8aa3b, v55
	v_add_f32_e32 v148, 1.0, v156
	v_exp_f32_e32 v151, v151
	v_mul_f32_e32 v156, 0xbfb8aa3b, v50
	v_exp_f32_e32 v154, v154
	v_exp_f32_e32 v155, v155
	v_exp_f32_e32 v156, v156
	v_exp_f32_e32 v157, v157
	v_add_f32_e32 v149, 1.0, v149
	v_add_f32_e32 v150, 1.0, v150
	v_rcp_f32_e32 v148, v148
	v_rcp_f32_e32 v149, v149
	v_rcp_f32_e32 v150, v150
	v_add_f32_e32 v151, 1.0, v151
	v_rcp_f32_e32 v151, v151
	v_add_f32_e32 v154, 1.0, v154
	v_add_f32_e32 v155, 1.0, v155
	v_add_f32_e32 v156, 1.0, v156
	v_add_f32_e32 v157, 1.0, v157
	v_rcp_f32_e32 v154, v154
	v_rcp_f32_e32 v155, v155
	v_rcp_f32_e32 v156, v156
	v_rcp_f32_e32 v157, v157
	v_mul_f32_e32 v148, v52, v148
	v_mul_f32_e32 v149, v53, v149
	v_mul_f32_e32 v150, v54, v150
	s_mov_b64 s[18:19], 0x80000
	v_mul_f32_e32 v151, v55, v151
	v_cvt_pk_bf16_f32 v148, v148, v149
	v_cvt_pk_bf16_f32 v149, v150, v151
	v_mul_f32_e32 v150, 0xbfb8aa3b, v44
	v_lshl_add_u64 v[152:153], v[140:141], 0, s[18:19]
	v_mul_f32_e32 v154, v48, v154
	v_mul_f32_e32 v155, v49, v155
	v_mul_f32_e32 v156, v50, v156
	v_mul_f32_e32 v157, v51, v157
	v_exp_f32_e32 v158, v150
	v_cvt_pk_bf16_f32 v150, v154, v155
	v_cvt_pk_bf16_f32 v151, v156, v157
	global_store_dwordx4 v[152:153], v[148:151], off offset:256
	v_mul_f32_e32 v154, 0xbfb8aa3b, v42
	v_mul_f32_e32 v152, 0xbfb8aa3b, v40
	v_mul_f32_e32 v149, 0xbfb8aa3b, v45
	v_mul_f32_e32 v150, 0xbfb8aa3b, v46
	v_mul_f32_e32 v151, 0xbfb8aa3b, v47
	v_exp_f32_e32 v149, v149
	v_exp_f32_e32 v150, v150
	v_exp_f32_e32 v151, v151
	v_mul_f32_e32 v153, 0xbfb8aa3b, v41
	v_exp_f32_e32 v154, v154
	v_mul_f32_e32 v155, 0xbfb8aa3b, v43
	v_exp_f32_e32 v152, v152
	v_exp_f32_e32 v153, v153
	v_exp_f32_e32 v155, v155
	v_add_f32_e32 v148, 1.0, v158
	v_add_f32_e32 v149, 1.0, v149
	v_add_f32_e32 v150, 1.0, v150
	v_add_f32_e32 v151, 1.0, v151
	v_add_f32_e32 v154, 1.0, v154
	v_rcp_f32_e32 v148, v148
	v_rcp_f32_e32 v149, v149
	v_rcp_f32_e32 v150, v150
	v_rcp_f32_e32 v151, v151
	v_add_f32_e32 v152, 1.0, v152
	v_add_f32_e32 v153, 1.0, v153
	v_rcp_f32_e32 v154, v154
	v_add_f32_e32 v155, 1.0, v155
	v_rcp_f32_e32 v152, v152
	v_rcp_f32_e32 v153, v153
	v_rcp_f32_e32 v155, v155
	v_mul_f32_e32 v148, v44, v148
	v_mul_f32_e32 v149, v45, v149
	v_mul_f32_e32 v150, v46, v150
	v_mul_f32_e32 v151, v47, v151
	v_mul_f32_e32 v154, v42, v154
	v_mul_f32_e32 v152, v40, v152
	v_mul_f32_e32 v153, v41, v153
	v_mul_f32_e32 v155, v43, v155
	v_cvt_pk_bf16_f32 v148, v148, v149
	v_cvt_pk_bf16_f32 v149, v150, v151
	v_cvt_pk_bf16_f32 v150, v152, v153
	v_cvt_pk_bf16_f32 v151, v154, v155
	v_mul_f32_e32 v154, 0xbfb8aa3b, v36
	s_mov_b32 s9, 0x90000
	v_exp_f32_e32 v156, v154
	v_add_co_u32_e32 v154, vcc, s9, v140
	v_mul_f32_e32 v157, 0xbfb8aa3b, v35
	s_nop 0
	v_addc_co_u32_e32 v155, vcc, 0, v141, vcc
	global_store_dwordx4 v[154:155], v[148:151], off
	v_mul_f32_e32 v154, 0xbfb8aa3b, v32
	v_mul_f32_e32 v155, 0xbfb8aa3b, v33
	v_mul_f32_e32 v149, 0xbfb8aa3b, v37
	v_mul_f32_e32 v150, 0xbfb8aa3b, v38
	v_exp_f32_e32 v149, v149
	v_exp_f32_e32 v150, v150
	v_mul_f32_e32 v151, 0xbfb8aa3b, v39
	v_add_f32_e32 v148, 1.0, v156
	v_exp_f32_e32 v151, v151
	v_mul_f32_e32 v156, 0xbfb8aa3b, v34
	v_exp_f32_e32 v154, v154
	v_exp_f32_e32 v155, v155
	v_exp_f32_e32 v156, v156
	v_exp_f32_e32 v157, v157
	v_add_f32_e32 v149, 1.0, v149
	v_add_f32_e32 v150, 1.0, v150
	v_rcp_f32_e32 v148, v148
	v_rcp_f32_e32 v149, v149
	v_rcp_f32_e32 v150, v150
	v_add_f32_e32 v151, 1.0, v151
	v_rcp_f32_e32 v151, v151
	v_add_f32_e32 v154, 1.0, v154
	v_add_f32_e32 v155, 1.0, v155
	v_add_f32_e32 v156, 1.0, v156
	v_add_f32_e32 v157, 1.0, v157
	v_rcp_f32_e32 v154, v154
	v_rcp_f32_e32 v155, v155
	v_rcp_f32_e32 v156, v156
	v_rcp_f32_e32 v157, v157
	v_mul_f32_e32 v148, v36, v148
	v_mul_f32_e32 v149, v37, v149
	v_mul_f32_e32 v150, v38, v150
	s_mov_b64 s[18:19], 0x90000
	v_mul_f32_e32 v151, v39, v151
	v_cvt_pk_bf16_f32 v148, v148, v149
	v_cvt_pk_bf16_f32 v149, v150, v151
	v_mul_f32_e32 v150, 0xbfb8aa3b, v28
	v_lshl_add_u64 v[152:153], v[140:141], 0, s[18:19]
	v_mul_f32_e32 v154, v32, v154
	v_mul_f32_e32 v155, v33, v155
	v_mul_f32_e32 v156, v34, v156
	v_mul_f32_e32 v157, v35, v157
	v_exp_f32_e32 v158, v150
	v_cvt_pk_bf16_f32 v150, v154, v155
	v_cvt_pk_bf16_f32 v151, v156, v157
	global_store_dwordx4 v[152:153], v[148:151], off offset:256
	v_mul_f32_e32 v154, 0xbfb8aa3b, v26
	v_mul_f32_e32 v152, 0xbfb8aa3b, v24
	v_mul_f32_e32 v149, 0xbfb8aa3b, v29
	v_mul_f32_e32 v150, 0xbfb8aa3b, v30
	v_mul_f32_e32 v151, 0xbfb8aa3b, v31
	v_exp_f32_e32 v149, v149
	v_exp_f32_e32 v150, v150
	v_exp_f32_e32 v151, v151
	v_mul_f32_e32 v153, 0xbfb8aa3b, v25
	v_exp_f32_e32 v154, v154
	v_mul_f32_e32 v155, 0xbfb8aa3b, v27
	v_exp_f32_e32 v152, v152
	v_exp_f32_e32 v153, v153
	v_exp_f32_e32 v155, v155
	v_add_f32_e32 v148, 1.0, v158
	v_add_f32_e32 v149, 1.0, v149
	v_add_f32_e32 v150, 1.0, v150
	v_add_f32_e32 v151, 1.0, v151
	v_add_f32_e32 v154, 1.0, v154
	v_rcp_f32_e32 v148, v148
	v_rcp_f32_e32 v149, v149
	v_rcp_f32_e32 v150, v150
	v_rcp_f32_e32 v151, v151
	v_add_f32_e32 v152, 1.0, v152
	v_add_f32_e32 v153, 1.0, v153
	v_rcp_f32_e32 v154, v154
	v_add_f32_e32 v155, 1.0, v155
	v_rcp_f32_e32 v152, v152
	v_rcp_f32_e32 v153, v153
	v_rcp_f32_e32 v155, v155
	v_mul_f32_e32 v148, v28, v148
	v_mul_f32_e32 v149, v29, v149
	v_mul_f32_e32 v150, v30, v150
	v_mul_f32_e32 v151, v31, v151
	v_mul_f32_e32 v154, v26, v154
	v_mul_f32_e32 v152, v24, v152
	v_mul_f32_e32 v153, v25, v153
	v_mul_f32_e32 v155, v27, v155
	v_cvt_pk_bf16_f32 v148, v148, v149
	v_cvt_pk_bf16_f32 v149, v150, v151
	v_cvt_pk_bf16_f32 v150, v152, v153
	v_cvt_pk_bf16_f32 v151, v154, v155
	v_mul_f32_e32 v154, 0xbfb8aa3b, v20
	s_mov_b32 s9, 0xa0000
	v_exp_f32_e32 v156, v154
	v_add_co_u32_e32 v154, vcc, s9, v140
	v_mul_f32_e32 v157, 0xbfb8aa3b, v19
	s_nop 0
	v_addc_co_u32_e32 v155, vcc, 0, v141, vcc
	global_store_dwordx4 v[154:155], v[148:151], off
	v_mul_f32_e32 v154, 0xbfb8aa3b, v16
	v_mul_f32_e32 v155, 0xbfb8aa3b, v17
	v_mul_f32_e32 v149, 0xbfb8aa3b, v21
	v_mul_f32_e32 v150, 0xbfb8aa3b, v22
	v_exp_f32_e32 v149, v149
	v_exp_f32_e32 v150, v150
	v_mul_f32_e32 v151, 0xbfb8aa3b, v23
	v_exp_f32_e32 v151, v151
	v_add_f32_e32 v148, 1.0, v156
	v_exp_f32_e32 v154, v154
	v_exp_f32_e32 v155, v155
	v_mul_f32_e32 v156, 0xbfb8aa3b, v18
	v_exp_f32_e32 v156, v156
	v_exp_f32_e32 v157, v157
	v_add_f32_e32 v149, 1.0, v149
	v_add_f32_e32 v150, 1.0, v150
	v_rcp_f32_e32 v148, v148
	v_rcp_f32_e32 v149, v149
	v_rcp_f32_e32 v150, v150
	v_add_f32_e32 v151, 1.0, v151
	v_rcp_f32_e32 v151, v151
	v_add_f32_e32 v154, 1.0, v154
	v_add_f32_e32 v155, 1.0, v155
	v_rcp_f32_e32 v154, v154
	v_rcp_f32_e32 v155, v155
	v_add_f32_e32 v156, 1.0, v156
	v_add_f32_e32 v157, 1.0, v157
	v_rcp_f32_e32 v156, v156
	v_rcp_f32_e32 v157, v157
	v_mul_f32_e32 v148, v20, v148
	v_mul_f32_e32 v149, v21, v149
	v_mul_f32_e32 v150, v22, v150
	s_mov_b64 s[18:19], 0xa0000
	v_mul_f32_e32 v151, v23, v151
	v_cvt_pk_bf16_f32 v148, v148, v149
	v_cvt_pk_bf16_f32 v149, v150, v151
	v_mul_f32_e32 v150, 0xbfb8aa3b, v12
	v_lshl_add_u64 v[152:153], v[140:141], 0, s[18:19]
	v_mul_f32_e32 v154, v16, v154
	v_mul_f32_e32 v155, v17, v155
	v_exp_f32_e32 v158, v150
	v_cvt_pk_bf16_f32 v150, v154, v155
	v_mul_f32_e32 v156, v18, v156
	v_mul_f32_e32 v157, v19, v157
	v_cvt_pk_bf16_f32 v151, v156, v157
	global_store_dwordx4 v[152:153], v[148:151], off offset:256
	v_mul_f32_e32 v152, 0xbfb8aa3b, v8
	v_mul_f32_e32 v153, 0xbfb8aa3b, v9
	v_mul_f32_e32 v149, 0xbfb8aa3b, v13
	v_mul_f32_e32 v150, 0xbfb8aa3b, v14
	v_exp_f32_e32 v149, v149
	v_exp_f32_e32 v150, v150
	v_mul_f32_e32 v151, 0xbfb8aa3b, v15
	v_exp_f32_e32 v152, v152
	v_exp_f32_e32 v153, v153
	v_exp_f32_e32 v151, v151
	v_mul_f32_e32 v154, 0xbfb8aa3b, v10
	v_mul_f32_e32 v155, 0xbfb8aa3b, v11
	v_exp_f32_e32 v154, v154
	v_exp_f32_e32 v155, v155
	v_add_f32_e32 v148, 1.0, v158
	v_add_f32_e32 v149, 1.0, v149
	v_add_f32_e32 v150, 1.0, v150
	v_add_f32_e32 v152, 1.0, v152
	v_add_f32_e32 v153, 1.0, v153
	v_rcp_f32_e32 v148, v148
	v_rcp_f32_e32 v149, v149
	v_rcp_f32_e32 v150, v150
	v_add_f32_e32 v151, 1.0, v151
	v_rcp_f32_e32 v152, v152
	v_rcp_f32_e32 v153, v153
	v_rcp_f32_e32 v151, v151
	v_add_f32_e32 v154, 1.0, v154
	v_add_f32_e32 v155, 1.0, v155
	v_rcp_f32_e32 v154, v154
	v_rcp_f32_e32 v155, v155
	v_mul_f32_e32 v148, v12, v148
	v_mul_f32_e32 v149, v13, v149
	v_mul_f32_e32 v150, v14, v150
	v_mul_f32_e32 v152, v8, v152
	v_mul_f32_e32 v153, v9, v153
	s_mov_b64 s[18:19], 0xb0000
	s_mov_b32 s9, 0xb0000
	v_mul_f32_e32 v151, v15, v151
	v_cvt_pk_bf16_f32 v148, v148, v149
	v_cvt_pk_bf16_f32 v149, v150, v151
	v_cvt_pk_bf16_f32 v150, v152, v153
	v_lshl_add_u64 v[152:153], v[140:141], 0, s[18:19]
	v_add_co_u32_e32 v140, vcc, s9, v140
	v_mul_f32_e32 v154, v10, v154
	s_nop 0
	v_addc_co_u32_e32 v141, vcc, 0, v141, vcc
	v_mul_f32_e32 v155, v11, v155
	v_cvt_pk_bf16_f32 v151, v154, v155
	global_store_dwordx4 v[140:141], v[148:151], off
	v_mul_f32_e32 v154, 0xbfb8aa3b, v4
	v_exp_f32_e32 v154, v154
	v_mul_f32_e32 v148, 0xbfb8aa3b, v6
	v_exp_f32_e32 v148, v148
	v_mul_f32_e32 v149, 0xbfb8aa3b, v7
	v_exp_f32_e32 v149, v149
	v_mul_f32_e32 v151, 0xbfb8aa3b, v1
	v_add_f32_e32 v148, 1.0, v148
	v_rcp_f32_e32 v148, v148
	v_exp_f32_e32 v151, v151
	v_add_f32_e32 v140, 1.0, v154
	v_mul_f32_e32 v141, 0xbfb8aa3b, v5
	v_mul_f32_e32 v150, v6, v148
	v_add_f32_e32 v148, 1.0, v149
	v_mul_f32_e32 v149, 0xbfb8aa3b, v0
	v_rcp_f32_e32 v148, v148
	v_exp_f32_e32 v149, v149
	v_mul_f32_e32 v155, 0xbfb8aa3b, v3
	v_exp_f32_e32 v141, v141
	v_mul_f32_e32 v154, v7, v148
	v_add_f32_e32 v148, 1.0, v149
	v_add_f32_e32 v149, 1.0, v151
	v_mul_f32_e32 v151, 0xbfb8aa3b, v2
	v_exp_f32_e32 v151, v151
	v_exp_f32_e32 v155, v155
	v_add_f32_e32 v141, 1.0, v141
	v_rcp_f32_e32 v140, v140
	v_add_f32_e32 v151, 1.0, v151
	v_rcp_f32_e32 v151, v151
	v_add_f32_e32 v155, 1.0, v155
	v_rcp_f32_e32 v141, v141
	v_rcp_f32_e32 v148, v148
	v_rcp_f32_e32 v149, v149
	v_rcp_f32_e32 v155, v155
	v_mul_f32_e32 v151, v2, v151
	s_mov_b64 s[18:19], 0
	v_mul_f32_e32 v140, v4, v140
	v_mul_f32_e32 v141, v5, v141
	v_mul_f32_e32 v156, v0, v148
	v_mul_f32_e32 v157, v1, v149
	v_mul_f32_e32 v155, v3, v155
	v_cvt_pk_bf16_f32 v148, v140, v141
	v_cvt_pk_bf16_f32 v149, v150, v154
	v_cvt_pk_bf16_f32 v150, v156, v157
	v_cvt_pk_bf16_f32 v151, v151, v155
	global_store_dwordx4 v[152:153], v[148:151], off offset:256

.LBB0_284:
	s_add_u32 s20, s18, 1
	s_addc_u32 s21, s19, 0
	s_lshl_b64 s[58:59], s[20:21], s48
	s_add_u32 s20, s18, 2
	s_addc_u32 s21, s19, 0
	s_lshl_b64 s[22:23], s[20:21], s48
	s_add_u32 s19, s16, s22
	s_addc_u32 s22, s17, s23
	s_cmp_eq_u32 s49, s18
	s_cselect_b32 s23, s15, s22
	s_cselect_b32 s22, s14, s19
	s_cselect_b32 s24, s0, s56
	s_cselect_b32 s25, s1, s57
	s_add_u32 s18, s22, s4
	s_addc_u32 s19, s23, s5
	s_add_i32 s60, 0, 0x10000
	v_add_u32_e32 v140, s60, v154
	ds_read_b128 v[128:131], v140
	ds_read_b128 v[132:135], v140 offset:1024
	ds_read_b128 v[136:139], v140 offset:2048
	ds_read_b128 v[140:143], v140 offset:3072
	s_add_u32 s58, s54, s58
	s_addc_u32 s59, s55, s59
	v_lshl_add_u64 v[150:151], s[58:59], 0, v[144:145]
	s_add_i32 m0, s36, 0xc000
	ds_read_b128 v[156:159], v155
	ds_read_b128 v[160:163], v155 offset:1024
	ds_read_b128 v[164:167], v155 offset:2048
	ds_read_b128 v[168:171], v155 offset:3072
	ds_read_b128 v[172:175], v155 offset:4096
	ds_read_b128 v[176:179], v155 offset:5120
	ds_read_b128 v[180:183], v155 offset:6144
	ds_read_b128 v[188:191], v155 offset:7168
	global_load_lds_dwordx4 v[150:151], off
	v_lshl_add_u64 v[150:151], s[58:59], 0, v[146:147]
	s_add_i32 m0, s36, 0xe000
	s_nop 0
	global_load_lds_dwordx4 v[150:151], off
	s_waitcnt lgkmcnt(8)
	s_setprio 1
	s_barrier
	s_waitcnt lgkmcnt(0)
	v_mfma_f32_16x16x32_bf16 v[124:127], v[128:131], v[156:159], v[124:127]
	v_mfma_f32_16x16x32_bf16 v[120:123], v[136:139], v[156:159], v[120:123]
	v_mfma_f32_16x16x32_bf16 v[108:111], v[128:131], v[164:167], v[108:111]
	v_mfma_f32_16x16x32_bf16 v[104:107], v[136:139], v[164:167], v[104:107]
	v_mfma_f32_16x16x32_bf16 v[92:95], v[128:131], v[172:175], v[92:95]
	v_mfma_f32_16x16x32_bf16 v[88:91], v[136:139], v[172:175], v[88:91]
	v_mfma_f32_16x16x32_bf16 v[76:79], v[128:131], v[180:183], v[76:79]
	v_mfma_f32_16x16x32_bf16 v[72:75], v[136:139], v[180:183], v[72:75]
	v_mfma_f32_16x16x32_bf16 v[124:127], v[132:135], v[160:163], v[124:127]
	v_mfma_f32_16x16x32_bf16 v[120:123], v[140:143], v[160:163], v[120:123]
	v_mfma_f32_16x16x32_bf16 v[108:111], v[132:135], v[168:171], v[108:111]
	v_mfma_f32_16x16x32_bf16 v[104:107], v[140:143], v[168:171], v[104:107]
	v_mfma_f32_16x16x32_bf16 v[92:95], v[132:135], v[176:179], v[92:95]
	v_mfma_f32_16x16x32_bf16 v[88:91], v[140:143], v[176:179], v[88:91]
	v_mfma_f32_16x16x32_bf16 v[76:79], v[132:135], v[188:191], v[76:79]
	v_mfma_f32_16x16x32_bf16 v[72:75], v[140:143], v[188:191], v[72:75]
	s_barrier
	s_setprio 0
	s_add_i32 s58, 0, 0x14000
	v_add_u32_e32 v150, s58, v154
	s_add_i32 s59, s60, s33
	ds_read_b128 v[192:195], v150
	ds_read_b128 v[202:205], v150 offset:1024
	ds_read_b128 v[206:209], v150 offset:2048
	ds_read_b128 v[210:213], v150 offset:3072
	v_lshl_add_u64 v[150:151], s[24:25], 0, v[184:185]
	s_mov_b32 m0, s59
	v_lshl_add_u64 v[196:197], s[24:25], 0, v[148:149]
	global_load_lds_dwordx4 v[150:151], off
	s_add_i32 m0, s59, 0x2000
	s_nop 0
	global_load_lds_dwordx4 v[196:197], off
	s_setprio 1
	s_barrier
	s_waitcnt lgkmcnt(0)
	v_mfma_f32_16x16x32_bf16 v[116:119], v[192:195], v[156:159], v[116:119]
	v_mfma_f32_16x16x32_bf16 v[112:115], v[206:209], v[156:159], v[112:115]
	v_mfma_f32_16x16x32_bf16 v[100:103], v[192:195], v[164:167], v[100:103]
	v_mfma_f32_16x16x32_bf16 v[96:99], v[206:209], v[164:167], v[96:99]
	v_mfma_f32_16x16x32_bf16 v[84:87], v[192:195], v[172:175], v[84:87]
	v_mfma_f32_16x16x32_bf16 v[80:83], v[206:209], v[172:175], v[80:83]
	v_mfma_f32_16x16x32_bf16 v[68:71], v[192:195], v[180:183], v[68:71]
	v_mfma_f32_16x16x32_bf16 v[64:67], v[206:209], v[180:183], v[64:67]
	v_mfma_f32_16x16x32_bf16 v[116:119], v[202:205], v[160:163], v[116:119]
	v_mfma_f32_16x16x32_bf16 v[112:115], v[210:213], v[160:163], v[112:115]
	v_mfma_f32_16x16x32_bf16 v[100:103], v[202:205], v[168:171], v[100:103]
	v_mfma_f32_16x16x32_bf16 v[96:99], v[210:213], v[168:171], v[96:99]
	v_mfma_f32_16x16x32_bf16 v[84:87], v[202:205], v[176:179], v[84:87]
	v_mfma_f32_16x16x32_bf16 v[80:83], v[210:213], v[176:179], v[80:83]
	v_mfma_f32_16x16x32_bf16 v[68:71], v[202:205], v[188:191], v[68:71]
	v_mfma_f32_16x16x32_bf16 v[64:67], v[210:213], v[188:191], v[64:67]
	s_barrier
	s_setprio 0
	s_mov_b32 m0, s36
	v_lshl_add_u64 v[214:215], s[22:23], 0, v[144:145]
	ds_read_b128 v[156:159], v155 offset:16384
	ds_read_b128 v[160:163], v155 offset:17408
	ds_read_b128 v[164:167], v155 offset:18432
	ds_read_b128 v[168:171], v155 offset:19456
	ds_read_b128 v[172:175], v155 offset:20480
	ds_read_b128 v[176:179], v155 offset:21504
	ds_read_b128 v[180:183], v155 offset:22528
	ds_read_b128 v[188:191], v155 offset:23552
	global_load_lds_dwordx4 v[214:215], off
	v_lshl_add_u64 v[214:215], s[22:23], 0, v[146:147]
	s_mov_b32 m0, s37
	s_nop 0
	global_load_lds_dwordx4 v[214:215], off
	s_setprio 1
	s_barrier
	s_waitcnt lgkmcnt(0)
	v_mfma_f32_16x16x32_bf16 v[60:63], v[128:131], v[156:159], v[60:63]
	v_mfma_f32_16x16x32_bf16 v[56:59], v[136:139], v[156:159], v[56:59]
	v_mfma_f32_16x16x32_bf16 v[44:47], v[128:131], v[164:167], v[44:47]
	v_mfma_f32_16x16x32_bf16 v[40:43], v[136:139], v[164:167], v[40:43]
	v_mfma_f32_16x16x32_bf16 v[28:31], v[128:131], v[172:175], v[28:31]
	v_mfma_f32_16x16x32_bf16 v[24:27], v[136:139], v[172:175], v[24:27]
	v_mfma_f32_16x16x32_bf16 v[12:15], v[128:131], v[180:183], v[12:15]
	v_mfma_f32_16x16x32_bf16 v[8:11], v[136:139], v[180:183], v[8:11]
	v_mfma_f32_16x16x32_bf16 v[60:63], v[132:135], v[160:163], v[60:63]
	v_mfma_f32_16x16x32_bf16 v[56:59], v[140:143], v[160:163], v[56:59]
	v_mfma_f32_16x16x32_bf16 v[44:47], v[132:135], v[168:171], v[44:47]
	v_mfma_f32_16x16x32_bf16 v[40:43], v[140:143], v[168:171], v[40:43]
	v_mfma_f32_16x16x32_bf16 v[28:31], v[132:135], v[176:179], v[28:31]
	v_mfma_f32_16x16x32_bf16 v[24:27], v[140:143], v[176:179], v[24:27]
	v_mfma_f32_16x16x32_bf16 v[12:15], v[132:135], v[188:191], v[12:15]
	v_mfma_f32_16x16x32_bf16 v[8:11], v[140:143], v[188:191], v[8:11]
	s_barrier
	s_setprio 0
	s_add_u32 s24, s24, s28
	s_addc_u32 s25, s25, 0
	s_add_i32 s58, s58, s33
	v_lshl_add_u64 v[214:215], s[24:25], 0, v[184:185]
	s_mov_b32 m0, s58
	v_lshl_add_u64 v[216:217], s[24:25], 0, v[148:149]
	global_load_lds_dwordx4 v[214:215], off
	s_add_i32 m0, s58, 0x2000
	s_nop 0
	global_load_lds_dwordx4 v[216:217], off
	s_waitcnt vmcnt(6)
	s_setprio 1
	s_barrier
	v_mfma_f32_16x16x32_bf16 v[52:55], v[192:195], v[156:159], v[52:55]
	v_mfma_f32_16x16x32_bf16 v[48:51], v[206:209], v[156:159], v[48:51]
	v_mfma_f32_16x16x32_bf16 v[36:39], v[192:195], v[164:167], v[36:39]
	v_mfma_f32_16x16x32_bf16 v[32:35], v[206:209], v[164:167], v[32:35]
	v_mfma_f32_16x16x32_bf16 v[20:23], v[192:195], v[172:175], v[20:23]
	v_mfma_f32_16x16x32_bf16 v[16:19], v[206:209], v[172:175], v[16:19]
	v_mfma_f32_16x16x32_bf16 v[4:7], v[192:195], v[180:183], v[4:7]
	v_mfma_f32_16x16x32_bf16 v[0:3], v[206:209], v[180:183], v[0:3]
	v_mfma_f32_16x16x32_bf16 v[52:55], v[202:205], v[160:163], v[52:55]
	v_mfma_f32_16x16x32_bf16 v[48:51], v[210:213], v[160:163], v[48:51]
	v_mfma_f32_16x16x32_bf16 v[36:39], v[202:205], v[168:171], v[36:39]
	v_mfma_f32_16x16x32_bf16 v[32:35], v[210:213], v[168:171], v[32:35]
	v_mfma_f32_16x16x32_bf16 v[20:23], v[202:205], v[176:179], v[20:23]
	v_mfma_f32_16x16x32_bf16 v[16:19], v[210:213], v[176:179], v[16:19]
	v_mfma_f32_16x16x32_bf16 v[4:7], v[202:205], v[188:191], v[4:7]
	v_mfma_f32_16x16x32_bf16 v[0:3], v[210:213], v[188:191], v[0:3]
	s_barrier
	s_setprio 0
	s_add_i32 s24, 0, 0x18000
	v_add_u32_e32 v140, s24, v154
	ds_read_b128 v[128:131], v140
	ds_read_b128 v[132:135], v140 offset:1024
	ds_read_b128 v[136:139], v140 offset:2048
	ds_read_b128 v[140:143], v140 offset:3072
	s_add_u32 s22, s22, s29
	s_addc_u32 s23, s23, 0
	s_mov_b32 m0, s38
	v_lshl_add_u64 v[192:193], s[22:23], 0, v[144:145]
	ds_read_b128 v[156:159], v155 offset:32768
	ds_read_b128 v[160:163], v155 offset:33792
	ds_read_b128 v[164:167], v155 offset:34816
	ds_read_b128 v[168:171], v155 offset:35840
	ds_read_b128 v[172:175], v155 offset:36864
	ds_read_b128 v[176:179], v155 offset:37888
	ds_read_b128 v[180:183], v155 offset:38912
	ds_read_b128 v[188:191], v155 offset:39936
	global_load_lds_dwordx4 v[192:193], off
	v_lshl_add_u64 v[192:193], s[22:23], 0, v[146:147]
	s_mov_b32 m0, s39
	s_nop 0
	global_load_lds_dwordx4 v[192:193], off
	s_waitcnt lgkmcnt(8)
	s_setprio 1
	s_barrier
	s_waitcnt lgkmcnt(0)
	v_mfma_f32_16x16x32_bf16 v[124:127], v[128:131], v[156:159], v[124:127]
	v_mfma_f32_16x16x32_bf16 v[120:123], v[136:139], v[156:159], v[120:123]
	v_mfma_f32_16x16x32_bf16 v[108:111], v[128:131], v[164:167], v[108:111]
	v_mfma_f32_16x16x32_bf16 v[104:107], v[136:139], v[164:167], v[104:107]
	v_mfma_f32_16x16x32_bf16 v[92:95], v[128:131], v[172:175], v[92:95]
	v_mfma_f32_16x16x32_bf16 v[88:91], v[136:139], v[172:175], v[88:91]
	v_mfma_f32_16x16x32_bf16 v[76:79], v[128:131], v[180:183], v[76:79]
	v_mfma_f32_16x16x32_bf16 v[72:75], v[136:139], v[180:183], v[72:75]
	v_mfma_f32_16x16x32_bf16 v[124:127], v[132:135], v[160:163], v[124:127]
	v_mfma_f32_16x16x32_bf16 v[120:123], v[140:143], v[160:163], v[120:123]
	v_mfma_f32_16x16x32_bf16 v[108:111], v[132:135], v[168:171], v[108:111]
	v_mfma_f32_16x16x32_bf16 v[104:107], v[140:143], v[168:171], v[104:107]
	v_mfma_f32_16x16x32_bf16 v[92:95], v[132:135], v[176:179], v[92:95]
	v_mfma_f32_16x16x32_bf16 v[88:91], v[140:143], v[176:179], v[88:91]
	v_mfma_f32_16x16x32_bf16 v[76:79], v[132:135], v[188:191], v[76:79]
	v_mfma_f32_16x16x32_bf16 v[72:75], v[140:143], v[188:191], v[72:75]
	s_barrier
	s_setprio 0
	s_add_i32 s22, 0, 0x1c000
	s_add_i32 s23, s24, s33
	v_add_u32_e32 v187, s22, v154
	v_lshl_add_u64 v[150:151], v[150:151], 0, s[78:79]
	s_mov_b32 m0, s23
	ds_read_b128 v[192:195], v187
	ds_read_b128 v[202:205], v187 offset:1024
	ds_read_b128 v[206:209], v187 offset:2048
	ds_read_b128 v[210:213], v187 offset:3072
	global_load_lds_dwordx4 v[150:151], off
	v_lshl_add_u64 v[150:151], v[196:197], 0, s[78:79]
	s_add_i32 m0, s23, 0x2000
	s_nop 0
	global_load_lds_dwordx4 v[150:151], off
	s_setprio 1
	s_barrier
	s_waitcnt lgkmcnt(0)
	v_mfma_f32_16x16x32_bf16 v[116:119], v[192:195], v[156:159], v[116:119]
	v_mfma_f32_16x16x32_bf16 v[112:115], v[206:209], v[156:159], v[112:115]
	v_mfma_f32_16x16x32_bf16 v[100:103], v[192:195], v[164:167], v[100:103]
	v_mfma_f32_16x16x32_bf16 v[96:99], v[206:209], v[164:167], v[96:99]
	v_mfma_f32_16x16x32_bf16 v[84:87], v[192:195], v[172:175], v[84:87]
	v_mfma_f32_16x16x32_bf16 v[80:83], v[206:209], v[172:175], v[80:83]
	v_mfma_f32_16x16x32_bf16 v[68:71], v[192:195], v[180:183], v[68:71]
	v_mfma_f32_16x16x32_bf16 v[64:67], v[206:209], v[180:183], v[64:67]
	v_mfma_f32_16x16x32_bf16 v[116:119], v[202:205], v[160:163], v[116:119]
	v_mfma_f32_16x16x32_bf16 v[112:115], v[210:213], v[160:163], v[112:115]
	v_mfma_f32_16x16x32_bf16 v[100:103], v[202:205], v[168:171], v[100:103]
	v_mfma_f32_16x16x32_bf16 v[96:99], v[210:213], v[168:171], v[96:99]
	v_mfma_f32_16x16x32_bf16 v[84:87], v[202:205], v[176:179], v[84:87]
	v_mfma_f32_16x16x32_bf16 v[80:83], v[210:213], v[176:179], v[80:83]
	v_mfma_f32_16x16x32_bf16 v[68:71], v[202:205], v[188:191], v[68:71]
	v_mfma_f32_16x16x32_bf16 v[64:67], v[210:213], v[188:191], v[64:67]
	s_barrier
	s_setprio 0
	s_mov_b32 m0, s46
	v_lshl_add_u64 v[150:151], s[18:19], 0, v[144:145]
	ds_read_b128 v[156:159], v155 offset:49152
	ds_read_b128 v[160:163], v155 offset:50176
	ds_read_b128 v[164:167], v155 offset:51200
	ds_read_b128 v[168:171], v155 offset:52224
	ds_read_b128 v[172:175], v155 offset:53248
	ds_read_b128 v[176:179], v155 offset:54272
	ds_read_b128 v[180:183], v155 offset:55296
	ds_read_b128 v[188:191], v155 offset:56320
	global_load_lds_dwordx4 v[150:151], off
	v_lshl_add_u64 v[150:151], s[18:19], 0, v[146:147]
	s_mov_b32 m0, s47
	s_nop 0
	global_load_lds_dwordx4 v[150:151], off
	s_setprio 1
	s_barrier
	s_waitcnt lgkmcnt(0)
	v_mfma_f32_16x16x32_bf16 v[60:63], v[128:131], v[156:159], v[60:63]
	v_mfma_f32_16x16x32_bf16 v[56:59], v[136:139], v[156:159], v[56:59]
	v_mfma_f32_16x16x32_bf16 v[44:47], v[128:131], v[164:167], v[44:47]
	v_mfma_f32_16x16x32_bf16 v[40:43], v[136:139], v[164:167], v[40:43]
	v_mfma_f32_16x16x32_bf16 v[28:31], v[128:131], v[172:175], v[28:31]
	v_mfma_f32_16x16x32_bf16 v[24:27], v[136:139], v[172:175], v[24:27]
	v_mfma_f32_16x16x32_bf16 v[12:15], v[128:131], v[180:183], v[12:15]
	v_mfma_f32_16x16x32_bf16 v[8:11], v[136:139], v[180:183], v[8:11]
	v_mfma_f32_16x16x32_bf16 v[60:63], v[132:135], v[160:163], v[60:63]
	v_mfma_f32_16x16x32_bf16 v[56:59], v[140:143], v[160:163], v[56:59]
	v_mfma_f32_16x16x32_bf16 v[44:47], v[132:135], v[168:171], v[44:47]
	v_mfma_f32_16x16x32_bf16 v[40:43], v[140:143], v[168:171], v[40:43]
	v_mfma_f32_16x16x32_bf16 v[28:31], v[132:135], v[176:179], v[28:31]
	v_mfma_f32_16x16x32_bf16 v[24:27], v[140:143], v[176:179], v[24:27]
	v_mfma_f32_16x16x32_bf16 v[12:15], v[132:135], v[188:191], v[12:15]
	v_mfma_f32_16x16x32_bf16 v[8:11], v[140:143], v[188:191], v[8:11]
	s_barrier
	s_setprio 0
	s_add_i32 s18, s22, s33
	v_lshl_add_u64 v[128:129], v[214:215], 0, s[78:79]
	s_mov_b32 m0, s18
	s_nop 0
	global_load_lds_dwordx4 v[128:129], off
	v_lshl_add_u64 v[128:129], v[216:217], 0, s[78:79]
	s_add_i32 m0, s18, 0x2000
	s_nop 0
	global_load_lds_dwordx4 v[128:129], off
	s_waitcnt vmcnt(6)
	s_setprio 1
	s_barrier
	v_mfma_f32_16x16x32_bf16 v[52:55], v[192:195], v[156:159], v[52:55]
	v_mfma_f32_16x16x32_bf16 v[48:51], v[206:209], v[156:159], v[48:51]
	v_mfma_f32_16x16x32_bf16 v[36:39], v[192:195], v[164:167], v[36:39]
	v_mfma_f32_16x16x32_bf16 v[32:35], v[206:209], v[164:167], v[32:35]
	v_mfma_f32_16x16x32_bf16 v[20:23], v[192:195], v[172:175], v[20:23]
	v_mfma_f32_16x16x32_bf16 v[16:19], v[206:209], v[172:175], v[16:19]
	v_mfma_f32_16x16x32_bf16 v[4:7], v[192:195], v[180:183], v[4:7]
	v_mfma_f32_16x16x32_bf16 v[0:3], v[206:209], v[180:183], v[0:3]
	v_mfma_f32_16x16x32_bf16 v[52:55], v[202:205], v[160:163], v[52:55]
	v_mfma_f32_16x16x32_bf16 v[48:51], v[210:213], v[160:163], v[48:51]
	v_mfma_f32_16x16x32_bf16 v[36:39], v[202:205], v[168:171], v[36:39]
	v_mfma_f32_16x16x32_bf16 v[32:35], v[210:213], v[168:171], v[32:35]
	v_mfma_f32_16x16x32_bf16 v[20:23], v[202:205], v[176:179], v[20:23]
	v_mfma_f32_16x16x32_bf16 v[16:19], v[210:213], v[176:179], v[16:19]
	v_mfma_f32_16x16x32_bf16 v[4:7], v[202:205], v[188:191], v[4:7]
	v_mfma_f32_16x16x32_bf16 v[0:3], v[210:213], v[188:191], v[0:3]
	s_barrier
	s_setprio 0
	s_add_u32 s56, s56, 0x100
	s_addc_u32 s57, s57, 0
	s_cmp_ge_u32 s20, s40
	s_mov_b64 s[18:19], s[20:21]
	s_cbranch_scc0 .LBB0_284
	s_lshl_b32 s16, s52, 8
	s_add_i32 s18, s16, s41
	s_lshl_b32 s16, s53, 8
	v_mov_b32_e32 v156, v153
	v_mov_b32_e32 v128, v152
	s_or_b32 s16, s16, s42
	s_mov_b32 s53, s51
	v_lshl_add_u32 v150, v128, 2, s16
	s_ashr_i32 s16, s52, 5
	s_mul_hi_i32 s17, s16, 0x6000
	s_mulk_i32 s16, 0x6000
	v_add_u32_e32 v156, s18, v156
	s_add_u32 s16, s44, s16
	v_ashrrev_i32_e32 v157, 31, v156
	s_addc_u32 s17, s45, s17
	v_ashrrev_i32_e32 v151, 31, v150
	v_lshlrev_b64 v[156:157], 11, v[156:157]
	v_lshl_add_u64 v[128:129], v[150:151], 2, s[16:17]
	v_lshl_add_u64 v[150:151], v[156:157], 0, v[150:151]
	v_lshlrev_b64 v[150:151], 2, v[150:151]
	global_load_dwordx4 v[140:143], v[128:129], off
	global_load_dwordx4 v[136:139], v[128:129], off offset:64
	global_load_dwordx4 v[132:135], v[128:129], off offset:512
	s_nop 0
	global_load_dwordx4 v[128:131], v[128:129], off offset:576
	v_readlane_b32 s18, v244, 20
	v_readlane_b32 s19, v244, 21
	s_and_b64 vcc, exec, s[12:13]
	s_mov_b32 s52, s50
	s_add_u32 s16, s8, 0x0
	s_addc_u32 s17, s9, 0
	global_load_dwordx4 v[156:159], v150, s[16:17]
	global_load_dwordx4 v[160:163], v150, s[16:17] offset:64
	global_load_dwordx4 v[164:167], v150, s[16:17] offset:512
	global_load_dwordx4 v[168:171], v150, s[16:17] offset:576
	s_add_u32 s16, s8, 0x20000
	s_addc_u32 s17, s9, 0
	global_load_dwordx4 v[172:175], v150, s[16:17]
	global_load_dwordx4 v[176:179], v150, s[16:17] offset:64
	global_load_dwordx4 v[180:183], v150, s[16:17] offset:512
	global_load_dwordx4 v[188:191], v150, s[16:17] offset:576
	s_add_u32 s16, s8, 0x40000
	s_addc_u32 s17, s9, 0
	global_load_dwordx4 v[192:195], v150, s[16:17]
	global_load_dwordx4 v[202:205], v150, s[16:17] offset:64
	global_load_dwordx4 v[206:209], v150, s[16:17] offset:512
	global_load_dwordx4 v[210:213], v150, s[16:17] offset:576
	s_waitcnt vmcnt(8)
	v_pk_fma_f32 v[158:159], v[126:127], v[142:143], v[158:159]
	v_pk_fma_f32 v[156:157], v[124:125], v[140:141], v[156:157]
	v_pk_fma_f32 v[162:163], v[122:123], v[138:139], v[162:163]
	v_pk_fma_f32 v[160:161], v[120:121], v[136:137], v[160:161]
	v_pk_fma_f32 v[166:167], v[118:119], v[134:135], v[166:167]
	v_pk_fma_f32 v[164:165], v[116:117], v[132:133], v[164:165]
	v_pk_fma_f32 v[170:171], v[114:115], v[130:131], v[170:171]
	v_pk_fma_f32 v[168:169], v[112:113], v[128:129], v[168:169]
	s_add_u32 s16, s18, 0x0
	s_addc_u32 s17, s19, 0
	global_store_dwordx4 v150, v[156:159], s[16:17]
	global_store_dwordx4 v150, v[160:163], s[16:17] offset:64
	global_store_dwordx4 v150, v[164:167], s[16:17] offset:512
	global_store_dwordx4 v150, v[168:171], s[16:17] offset:576
	s_add_u32 s16, s8, 0x60000
	s_addc_u32 s17, s9, 0
	global_load_dwordx4 v[124:127], v150, s[16:17]
	global_load_dwordx4 v[120:123], v150, s[16:17] offset:64
	global_load_dwordx4 v[116:119], v150, s[16:17] offset:512
	global_load_dwordx4 v[112:115], v150, s[16:17] offset:576
	s_waitcnt vmcnt(12)
	v_pk_fma_f32 v[174:175], v[110:111], v[142:143], v[174:175]
	v_pk_fma_f32 v[172:173], v[108:109], v[140:141], v[172:173]
	v_pk_fma_f32 v[178:179], v[106:107], v[138:139], v[178:179]
	v_pk_fma_f32 v[176:177], v[104:105], v[136:137], v[176:177]
	v_pk_fma_f32 v[182:183], v[102:103], v[134:135], v[182:183]
	v_pk_fma_f32 v[180:181], v[100:101], v[132:133], v[180:181]
	v_pk_fma_f32 v[190:191], v[98:99], v[130:131], v[190:191]
	v_pk_fma_f32 v[188:189], v[96:97], v[128:129], v[188:189]
	s_add_u32 s16, s18, 0x20000
	s_addc_u32 s17, s19, 0
	global_store_dwordx4 v150, v[172:175], s[16:17]
	global_store_dwordx4 v150, v[176:179], s[16:17] offset:64
	global_store_dwordx4 v150, v[180:183], s[16:17] offset:512
	global_store_dwordx4 v150, v[188:191], s[16:17] offset:576
	s_add_u32 s16, s8, 0x100000
	s_addc_u32 s17, s9, 0
	global_load_dwordx4 v[108:111], v150, s[16:17]
	global_load_dwordx4 v[104:107], v150, s[16:17] offset:64
	global_load_dwordx4 v[100:103], v150, s[16:17] offset:512
	global_load_dwordx4 v[96:99], v150, s[16:17] offset:576
	s_waitcnt vmcnt(16)
	v_pk_fma_f32 v[194:195], v[94:95], v[142:143], v[194:195]
	v_pk_fma_f32 v[192:193], v[92:93], v[140:141], v[192:193]
	v_pk_fma_f32 v[204:205], v[90:91], v[138:139], v[204:205]
	v_pk_fma_f32 v[202:203], v[88:89], v[136:137], v[202:203]
	v_pk_fma_f32 v[208:209], v[86:87], v[134:135], v[208:209]
	v_pk_fma_f32 v[206:207], v[84:85], v[132:133], v[206:207]
	v_pk_fma_f32 v[212:213], v[82:83], v[130:131], v[212:213]
	v_pk_fma_f32 v[210:211], v[80:81], v[128:129], v[210:211]
	s_add_u32 s16, s18, 0x40000
	s_addc_u32 s17, s19, 0
	global_store_dwordx4 v150, v[192:195], s[16:17]
	global_store_dwordx4 v150, v[202:205], s[16:17] offset:64
	global_store_dwordx4 v150, v[206:209], s[16:17] offset:512
	global_store_dwordx4 v150, v[210:213], s[16:17] offset:576
	s_add_u32 s16, s8, 0x120000
	s_addc_u32 s17, s9, 0
	global_load_dwordx4 v[92:95], v150, s[16:17]
	global_load_dwordx4 v[88:91], v150, s[16:17] offset:64
	global_load_dwordx4 v[84:87], v150, s[16:17] offset:512
	global_load_dwordx4 v[80:83], v150, s[16:17] offset:576
	s_waitcnt vmcnt(16)
	v_pk_fma_f32 v[126:127], v[78:79], v[142:143], v[126:127]
	v_pk_fma_f32 v[124:125], v[76:77], v[140:141], v[124:125]
	v_pk_fma_f32 v[122:123], v[74:75], v[138:139], v[122:123]
	v_pk_fma_f32 v[120:121], v[72:73], v[136:137], v[120:121]
	v_pk_fma_f32 v[118:119], v[70:71], v[134:135], v[118:119]
	v_pk_fma_f32 v[116:117], v[68:69], v[132:133], v[116:117]
	v_pk_fma_f32 v[114:115], v[66:67], v[130:131], v[114:115]
	v_pk_fma_f32 v[112:113], v[64:65], v[128:129], v[112:113]
	s_add_u32 s16, s18, 0x60000
	s_addc_u32 s17, s19, 0
	global_store_dwordx4 v150, v[124:127], s[16:17]
	global_store_dwordx4 v150, v[120:123], s[16:17] offset:64
	global_store_dwordx4 v150, v[116:119], s[16:17] offset:512
	global_store_dwordx4 v150, v[112:115], s[16:17] offset:576
	s_add_u32 s16, s8, 0x140000
	s_addc_u32 s17, s9, 0
	global_load_dwordx4 v[76:79], v150, s[16:17]
	global_load_dwordx4 v[72:75], v150, s[16:17] offset:64
	global_load_dwordx4 v[68:71], v150, s[16:17] offset:512
	global_load_dwordx4 v[64:67], v150, s[16:17] offset:576
	s_waitcnt vmcnt(16)
	v_pk_fma_f32 v[110:111], v[62:63], v[142:143], v[110:111]
	v_pk_fma_f32 v[108:109], v[60:61], v[140:141], v[108:109]
	v_pk_fma_f32 v[106:107], v[58:59], v[138:139], v[106:107]
	v_pk_fma_f32 v[104:105], v[56:57], v[136:137], v[104:105]
	v_pk_fma_f32 v[102:103], v[54:55], v[134:135], v[102:103]
	v_pk_fma_f32 v[100:101], v[52:53], v[132:133], v[100:101]
	v_pk_fma_f32 v[98:99], v[50:51], v[130:131], v[98:99]
	v_pk_fma_f32 v[96:97], v[48:49], v[128:129], v[96:97]
	s_add_u32 s16, s18, 0x100000
	s_addc_u32 s17, s19, 0
	global_store_dwordx4 v150, v[108:111], s[16:17]
	global_store_dwordx4 v150, v[104:107], s[16:17] offset:64
	global_store_dwordx4 v150, v[100:103], s[16:17] offset:512
	global_store_dwordx4 v150, v[96:99], s[16:17] offset:576
	s_add_u32 s16, s8, 0x160000
	s_addc_u32 s17, s9, 0
	global_load_dwordx4 v[60:63], v150, s[16:17]
	global_load_dwordx4 v[56:59], v150, s[16:17] offset:64
	global_load_dwordx4 v[52:55], v150, s[16:17] offset:512
	global_load_dwordx4 v[48:51], v150, s[16:17] offset:576
	s_waitcnt vmcnt(16)
	v_pk_fma_f32 v[94:95], v[46:47], v[142:143], v[94:95]
	v_pk_fma_f32 v[92:93], v[44:45], v[140:141], v[92:93]
	v_pk_fma_f32 v[90:91], v[42:43], v[138:139], v[90:91]
	v_pk_fma_f32 v[88:89], v[40:41], v[136:137], v[88:89]
	v_pk_fma_f32 v[86:87], v[38:39], v[134:135], v[86:87]
	v_pk_fma_f32 v[84:85], v[36:37], v[132:133], v[84:85]
	v_pk_fma_f32 v[82:83], v[34:35], v[130:131], v[82:83]
	v_pk_fma_f32 v[80:81], v[32:33], v[128:129], v[80:81]
	s_add_u32 s16, s18, 0x120000
	s_addc_u32 s17, s19, 0
	global_store_dwordx4 v150, v[92:95], s[16:17]
	global_store_dwordx4 v150, v[88:91], s[16:17] offset:64
	global_store_dwordx4 v150, v[84:87], s[16:17] offset:512
	global_store_dwordx4 v150, v[80:83], s[16:17] offset:576
	s_waitcnt vmcnt(12)
	v_pk_fma_f32 v[78:79], v[30:31], v[142:143], v[78:79]
	v_pk_fma_f32 v[76:77], v[28:29], v[140:141], v[76:77]
	v_pk_fma_f32 v[74:75], v[26:27], v[138:139], v[74:75]
	v_pk_fma_f32 v[72:73], v[24:25], v[136:137], v[72:73]
	v_pk_fma_f32 v[70:71], v[22:23], v[134:135], v[70:71]
	v_pk_fma_f32 v[68:69], v[20:21], v[132:133], v[68:69]
	v_pk_fma_f32 v[66:67], v[18:19], v[130:131], v[66:67]
	v_pk_fma_f32 v[64:65], v[16:17], v[128:129], v[64:65]
	s_add_u32 s16, s18, 0x140000
	s_addc_u32 s17, s19, 0
	global_store_dwordx4 v150, v[76:79], s[16:17]
	global_store_dwordx4 v150, v[72:75], s[16:17] offset:64
	global_store_dwordx4 v150, v[68:71], s[16:17] offset:512
	global_store_dwordx4 v150, v[64:67], s[16:17] offset:576
	s_waitcnt vmcnt(8)
	v_pk_fma_f32 v[62:63], v[14:15], v[142:143], v[62:63]
	v_pk_fma_f32 v[60:61], v[12:13], v[140:141], v[60:61]
	v_pk_fma_f32 v[58:59], v[10:11], v[138:139], v[58:59]
	v_pk_fma_f32 v[56:57], v[8:9], v[136:137], v[56:57]
	v_pk_fma_f32 v[54:55], v[6:7], v[134:135], v[54:55]
	v_pk_fma_f32 v[52:53], v[4:5], v[132:133], v[52:53]
	v_pk_fma_f32 v[50:51], v[2:3], v[130:131], v[50:51]
	v_pk_fma_f32 v[48:49], v[0:1], v[128:129], v[48:49]
	s_add_u32 s16, s18, 0x160000
	s_addc_u32 s17, s19, 0
	global_store_dwordx4 v150, v[60:63], s[16:17]
	global_store_dwordx4 v150, v[56:59], s[16:17] offset:64
	global_store_dwordx4 v150, v[52:55], s[16:17] offset:512
	global_store_dwordx4 v150, v[48:51], s[16:17] offset:576
	s_mov_b64 s[16:17], s[14:15]
	s_mov_b64 s[18:19], s[0:1]
	s_cbranch_vccz .LBB0_273
	s_waitcnt vmcnt(0)
	s_cmpk_gt_u32 s27, 0xff
	s_cbranch_scc1 .LBB0_288
	s_barrier

.LBB0_314:
	s_add_u32 s20, s18, 0xfff80080
	s_addc_u32 s21, s19, -1
	s_add_i32 s47, 0, 0x10000
	v_add_u32_e32 v156, s47, v142
	ds_read_b128 v[144:147], v156
	ds_read_b128 v[148:151], v156 offset:1024
	ds_read_b128 v[152:155], v156 offset:2048
	ds_read_b128 v[156:159], v156 offset:3072
	s_cmp_eq_u32 s46, 28
	s_cselect_b32 s23, s5, s21
	s_cselect_b32 s22, s42, s20
	s_cselect_b32 s21, s9, s45
	s_cselect_b32 s20, s43, s44
	v_lshl_add_u64 v[196:197], s[18:19], 0, v[136:137]
	s_add_i32 m0, s17, 0xc000
	ds_read_b128 v[160:163], v143
	ds_read_b128 v[164:167], v143 offset:1024
	ds_read_b128 v[168:171], v143 offset:2048
	ds_read_b128 v[172:175], v143 offset:3072
	ds_read_b128 v[176:179], v143 offset:4096
	ds_read_b128 v[180:183], v143 offset:5120
	ds_read_b128 v[188:191], v143 offset:6144
	ds_read_b128 v[192:195], v143 offset:7168
	global_load_lds_dwordx4 v[196:197], off
	v_lshl_add_u64 v[196:197], s[18:19], 0, v[138:139]
	s_add_i32 m0, s17, 0xe000
	s_nop 0
	global_load_lds_dwordx4 v[196:197], off
	s_waitcnt lgkmcnt(8)
	s_setprio 1
	s_barrier
	s_waitcnt lgkmcnt(0)
	v_mfma_f32_16x16x32_bf16 v[124:127], v[144:147], v[160:163], v[124:127]
	v_mfma_f32_16x16x32_bf16 v[116:119], v[152:155], v[160:163], v[116:119]
	v_mfma_f32_16x16x32_bf16 v[108:111], v[144:147], v[168:171], v[108:111]
	v_mfma_f32_16x16x32_bf16 v[100:103], v[152:155], v[168:171], v[100:103]
	v_mfma_f32_16x16x32_bf16 v[92:95], v[144:147], v[176:179], v[92:95]
	v_mfma_f32_16x16x32_bf16 v[84:87], v[152:155], v[176:179], v[84:87]
	v_mfma_f32_16x16x32_bf16 v[76:79], v[144:147], v[188:191], v[76:79]
	v_mfma_f32_16x16x32_bf16 v[68:71], v[152:155], v[188:191], v[68:71]
	v_mfma_f32_16x16x32_bf16 v[124:127], v[148:151], v[164:167], v[124:127]
	v_mfma_f32_16x16x32_bf16 v[116:119], v[156:159], v[164:167], v[116:119]
	v_mfma_f32_16x16x32_bf16 v[108:111], v[148:151], v[172:175], v[108:111]
	v_mfma_f32_16x16x32_bf16 v[100:103], v[156:159], v[172:175], v[100:103]
	v_mfma_f32_16x16x32_bf16 v[92:95], v[148:151], v[180:183], v[92:95]
	v_mfma_f32_16x16x32_bf16 v[84:87], v[156:159], v[180:183], v[84:87]
	v_mfma_f32_16x16x32_bf16 v[76:79], v[148:151], v[192:195], v[76:79]
	v_mfma_f32_16x16x32_bf16 v[68:71], v[156:159], v[192:195], v[68:71]
	s_barrier
	s_setprio 0
	s_add_i32 s50, 0, 0x14000
	s_add_i32 s47, s47, s31
	v_add_u32_e32 v184, s50, v142
	v_lshl_add_u64 v[196:197], s[20:21], 0, v[130:131]
	s_mov_b32 m0, s47
	ds_read_b128 v[202:205], v184
	ds_read_b128 v[206:209], v184 offset:1024
	ds_read_b128 v[210:213], v184 offset:2048
	ds_read_b128 v[214:217], v184 offset:3072
	global_load_lds_dwordx4 v[196:197], off
	v_lshl_add_u64 v[218:219], s[20:21], 0, v[134:135]
	s_add_i32 m0, s47, 0x2000
	s_nop 0
	global_load_lds_dwordx4 v[218:219], off
	s_setprio 1
	s_barrier
	s_waitcnt lgkmcnt(0)
	v_mfma_f32_16x16x32_bf16 v[120:123], v[202:205], v[160:163], v[120:123]
	v_mfma_f32_16x16x32_bf16 v[112:115], v[210:213], v[160:163], v[112:115]
	v_mfma_f32_16x16x32_bf16 v[104:107], v[202:205], v[168:171], v[104:107]
	v_mfma_f32_16x16x32_bf16 v[96:99], v[210:213], v[168:171], v[96:99]
	v_mfma_f32_16x16x32_bf16 v[88:91], v[202:205], v[176:179], v[88:91]
	v_mfma_f32_16x16x32_bf16 v[80:83], v[210:213], v[176:179], v[80:83]
	v_mfma_f32_16x16x32_bf16 v[72:75], v[202:205], v[188:191], v[72:75]
	v_mfma_f32_16x16x32_bf16 v[64:67], v[210:213], v[188:191], v[64:67]
	v_mfma_f32_16x16x32_bf16 v[120:123], v[206:209], v[164:167], v[120:123]
	v_mfma_f32_16x16x32_bf16 v[112:115], v[214:217], v[164:167], v[112:115]
	v_mfma_f32_16x16x32_bf16 v[104:107], v[206:209], v[172:175], v[104:107]
	v_mfma_f32_16x16x32_bf16 v[96:99], v[214:217], v[172:175], v[96:99]
	v_mfma_f32_16x16x32_bf16 v[88:91], v[206:209], v[180:183], v[88:91]
	v_mfma_f32_16x16x32_bf16 v[80:83], v[214:217], v[180:183], v[80:83]
	v_mfma_f32_16x16x32_bf16 v[72:75], v[206:209], v[192:195], v[72:75]
	v_mfma_f32_16x16x32_bf16 v[64:67], v[214:217], v[192:195], v[64:67]
	s_barrier
	s_setprio 0
	s_mov_b32 m0, s17
	v_lshl_add_u64 v[220:221], s[22:23], 0, v[128:129]
	ds_read_b128 v[160:163], v143 offset:16384
	ds_read_b128 v[164:167], v143 offset:17408
	ds_read_b128 v[168:171], v143 offset:18432
	ds_read_b128 v[172:175], v143 offset:19456
	ds_read_b128 v[176:179], v143 offset:20480
	ds_read_b128 v[180:183], v143 offset:21504
	ds_read_b128 v[188:191], v143 offset:22528
	ds_read_b128 v[192:195], v143 offset:23552
	global_load_lds_dwordx4 v[220:221], off
	v_lshl_add_u64 v[222:223], s[22:23], 0, v[132:133]
	s_mov_b32 m0, s33
	s_nop 0
	global_load_lds_dwordx4 v[222:223], off
	s_setprio 1
	s_barrier
	s_waitcnt lgkmcnt(0)
	v_mfma_f32_16x16x32_bf16 v[60:63], v[144:147], v[160:163], v[60:63]
	v_mfma_f32_16x16x32_bf16 v[52:55], v[152:155], v[160:163], v[52:55]
	v_mfma_f32_16x16x32_bf16 v[44:47], v[144:147], v[168:171], v[44:47]
	v_mfma_f32_16x16x32_bf16 v[36:39], v[152:155], v[168:171], v[36:39]
	v_mfma_f32_16x16x32_bf16 v[28:31], v[144:147], v[176:179], v[28:31]
	v_mfma_f32_16x16x32_bf16 v[20:23], v[152:155], v[176:179], v[20:23]
	v_mfma_f32_16x16x32_bf16 v[12:15], v[144:147], v[188:191], v[12:15]
	v_mfma_f32_16x16x32_bf16 v[4:7], v[152:155], v[188:191], v[4:7]
	v_mfma_f32_16x16x32_bf16 v[60:63], v[148:151], v[164:167], v[60:63]
	v_mfma_f32_16x16x32_bf16 v[52:55], v[156:159], v[164:167], v[52:55]
	v_mfma_f32_16x16x32_bf16 v[44:47], v[148:151], v[172:175], v[44:47]
	v_mfma_f32_16x16x32_bf16 v[36:39], v[156:159], v[172:175], v[36:39]
	v_mfma_f32_16x16x32_bf16 v[28:31], v[148:151], v[180:183], v[28:31]
	v_mfma_f32_16x16x32_bf16 v[20:23], v[156:159], v[180:183], v[20:23]
	v_mfma_f32_16x16x32_bf16 v[12:15], v[148:151], v[192:195], v[12:15]
	v_mfma_f32_16x16x32_bf16 v[4:7], v[156:159], v[192:195], v[4:7]
	s_barrier
	s_setprio 0
	s_add_u32 s48, s20, 0x80000
	s_addc_u32 s49, s21, 0
	s_add_i32 s47, s50, s31
	v_lshl_add_u64 v[144:145], s[48:49], 0, v[130:131]
	s_mov_b32 m0, s47
	s_nop 0
	global_load_lds_dwordx4 v[144:145], off
	v_lshl_add_u64 v[144:145], s[48:49], 0, v[134:135]
	s_add_i32 m0, s47, 0x2000
	s_nop 0
	global_load_lds_dwordx4 v[144:145], off
	s_waitcnt vmcnt(6)
	s_setprio 1
	s_barrier
	v_mfma_f32_16x16x32_bf16 v[56:59], v[202:205], v[160:163], v[56:59]
	v_mfma_f32_16x16x32_bf16 v[48:51], v[210:213], v[160:163], v[48:51]
	v_mfma_f32_16x16x32_bf16 v[40:43], v[202:205], v[168:171], v[40:43]
	v_mfma_f32_16x16x32_bf16 v[32:35], v[210:213], v[168:171], v[32:35]
	v_mfma_f32_16x16x32_bf16 v[24:27], v[202:205], v[176:179], v[24:27]
	v_mfma_f32_16x16x32_bf16 v[16:19], v[210:213], v[176:179], v[16:19]
	v_mfma_f32_16x16x32_bf16 v[8:11], v[202:205], v[188:191], v[8:11]
	v_mfma_f32_16x16x32_bf16 v[0:3], v[210:213], v[188:191], v[0:3]
	v_mfma_f32_16x16x32_bf16 v[56:59], v[206:209], v[164:167], v[56:59]
	v_mfma_f32_16x16x32_bf16 v[48:51], v[214:217], v[164:167], v[48:51]
	v_mfma_f32_16x16x32_bf16 v[40:43], v[206:209], v[172:175], v[40:43]
	v_mfma_f32_16x16x32_bf16 v[32:35], v[214:217], v[172:175], v[32:35]
	v_mfma_f32_16x16x32_bf16 v[24:27], v[206:209], v[180:183], v[24:27]
	v_mfma_f32_16x16x32_bf16 v[16:19], v[214:217], v[180:183], v[16:19]
	v_mfma_f32_16x16x32_bf16 v[8:11], v[206:209], v[192:195], v[8:11]
	v_mfma_f32_16x16x32_bf16 v[0:3], v[214:217], v[192:195], v[0:3]
	s_barrier
	s_setprio 0
	s_add_i32 s47, 0, 0x18000
	v_add_u32_e32 v156, s47, v142
	ds_read_b128 v[144:147], v156
	ds_read_b128 v[148:151], v156 offset:1024
	ds_read_b128 v[152:155], v156 offset:2048
	ds_read_b128 v[156:159], v156 offset:3072
	s_add_u32 s22, s22, 0x80000
	s_addc_u32 s23, s23, 0
	s_mov_b32 m0, s34
	v_lshl_add_u64 v[202:203], s[22:23], 0, v[128:129]
	ds_read_b128 v[160:163], v143 offset:32768
	ds_read_b128 v[164:167], v143 offset:33792
	ds_read_b128 v[168:171], v143 offset:34816
	ds_read_b128 v[172:175], v143 offset:35840
	ds_read_b128 v[176:179], v143 offset:36864
	ds_read_b128 v[180:183], v143 offset:37888
	ds_read_b128 v[188:191], v143 offset:38912
	ds_read_b128 v[192:195], v143 offset:39936
	global_load_lds_dwordx4 v[202:203], off
	v_lshl_add_u64 v[202:203], s[22:23], 0, v[132:133]
	s_mov_b32 m0, s35
	s_nop 0
	global_load_lds_dwordx4 v[202:203], off
	s_waitcnt lgkmcnt(8)
	s_setprio 1
	s_barrier
	s_waitcnt lgkmcnt(0)
	v_mfma_f32_16x16x32_bf16 v[124:127], v[144:147], v[160:163], v[124:127]
	v_mfma_f32_16x16x32_bf16 v[116:119], v[152:155], v[160:163], v[116:119]
	v_mfma_f32_16x16x32_bf16 v[108:111], v[144:147], v[168:171], v[108:111]
	v_mfma_f32_16x16x32_bf16 v[100:103], v[152:155], v[168:171], v[100:103]
	v_mfma_f32_16x16x32_bf16 v[92:95], v[144:147], v[176:179], v[92:95]
	v_mfma_f32_16x16x32_bf16 v[84:87], v[152:155], v[176:179], v[84:87]
	v_mfma_f32_16x16x32_bf16 v[76:79], v[144:147], v[188:191], v[76:79]
	v_mfma_f32_16x16x32_bf16 v[68:71], v[152:155], v[188:191], v[68:71]
	v_mfma_f32_16x16x32_bf16 v[124:127], v[148:151], v[164:167], v[124:127]
	v_mfma_f32_16x16x32_bf16 v[116:119], v[156:159], v[164:167], v[116:119]
	v_mfma_f32_16x16x32_bf16 v[108:111], v[148:151], v[172:175], v[108:111]
	v_mfma_f32_16x16x32_bf16 v[100:103], v[156:159], v[172:175], v[100:103]
	v_mfma_f32_16x16x32_bf16 v[92:95], v[148:151], v[180:183], v[92:95]
	v_mfma_f32_16x16x32_bf16 v[84:87], v[156:159], v[180:183], v[84:87]
	v_mfma_f32_16x16x32_bf16 v[76:79], v[148:151], v[192:195], v[76:79]
	v_mfma_f32_16x16x32_bf16 v[68:71], v[156:159], v[192:195], v[68:71]
	s_barrier
	s_setprio 0
	s_add_i32 s22, 0, 0x1c000
	s_add_i32 s23, s47, s31
	v_add_u32_e32 v184, s22, v142
	v_lshl_add_u64 v[196:197], v[196:197], 0, s[52:53]
	s_mov_b32 m0, s23
	ds_read_b128 v[202:205], v184
	ds_read_b128 v[206:209], v184 offset:1024
	ds_read_b128 v[210:213], v184 offset:2048
	ds_read_b128 v[214:217], v184 offset:3072
	global_load_lds_dwordx4 v[196:197], off
	v_lshl_add_u64 v[196:197], v[218:219], 0, s[52:53]
	s_add_i32 m0, s23, 0x2000
	s_nop 0
	global_load_lds_dwordx4 v[196:197], off
	s_setprio 1
	s_barrier
	s_waitcnt lgkmcnt(0)
	v_mfma_f32_16x16x32_bf16 v[120:123], v[202:205], v[160:163], v[120:123]
	v_mfma_f32_16x16x32_bf16 v[112:115], v[210:213], v[160:163], v[112:115]
	v_mfma_f32_16x16x32_bf16 v[104:107], v[202:205], v[168:171], v[104:107]
	v_mfma_f32_16x16x32_bf16 v[96:99], v[210:213], v[168:171], v[96:99]
	v_mfma_f32_16x16x32_bf16 v[88:91], v[202:205], v[176:179], v[88:91]
	v_mfma_f32_16x16x32_bf16 v[80:83], v[210:213], v[176:179], v[80:83]
	v_mfma_f32_16x16x32_bf16 v[72:75], v[202:205], v[188:191], v[72:75]
	v_mfma_f32_16x16x32_bf16 v[64:67], v[210:213], v[188:191], v[64:67]
	v_mfma_f32_16x16x32_bf16 v[120:123], v[206:209], v[164:167], v[120:123]
	v_mfma_f32_16x16x32_bf16 v[112:115], v[214:217], v[164:167], v[112:115]
	v_mfma_f32_16x16x32_bf16 v[104:107], v[206:209], v[172:175], v[104:107]
	v_mfma_f32_16x16x32_bf16 v[96:99], v[214:217], v[172:175], v[96:99]
	v_mfma_f32_16x16x32_bf16 v[88:91], v[206:209], v[180:183], v[88:91]
	v_mfma_f32_16x16x32_bf16 v[80:83], v[214:217], v[180:183], v[80:83]
	v_mfma_f32_16x16x32_bf16 v[72:75], v[206:209], v[192:195], v[72:75]
	v_mfma_f32_16x16x32_bf16 v[64:67], v[214:217], v[192:195], v[64:67]
	s_barrier
	s_setprio 0
	s_mov_b32 m0, s38
	v_lshl_add_u64 v[196:197], v[220:221], 0, s[52:53]
	ds_read_b128 v[160:163], v143 offset:49152
	ds_read_b128 v[164:167], v143 offset:50176
	ds_read_b128 v[168:171], v143 offset:51200
	ds_read_b128 v[172:175], v143 offset:52224
	ds_read_b128 v[176:179], v143 offset:53248
	ds_read_b128 v[180:183], v143 offset:54272
	ds_read_b128 v[188:191], v143 offset:55296
	ds_read_b128 v[192:195], v143 offset:56320
	global_load_lds_dwordx4 v[196:197], off
	v_lshl_add_u64 v[196:197], v[222:223], 0, s[52:53]
	s_mov_b32 m0, s39
	s_nop 0
	global_load_lds_dwordx4 v[196:197], off
	s_setprio 1
	s_barrier
	s_waitcnt lgkmcnt(0)
	v_mfma_f32_16x16x32_bf16 v[60:63], v[144:147], v[160:163], v[60:63]
	v_mfma_f32_16x16x32_bf16 v[52:55], v[152:155], v[160:163], v[52:55]
	v_mfma_f32_16x16x32_bf16 v[44:47], v[144:147], v[168:171], v[44:47]
	v_mfma_f32_16x16x32_bf16 v[36:39], v[152:155], v[168:171], v[36:39]
	v_mfma_f32_16x16x32_bf16 v[28:31], v[144:147], v[176:179], v[28:31]
	v_mfma_f32_16x16x32_bf16 v[20:23], v[152:155], v[176:179], v[20:23]
	v_mfma_f32_16x16x32_bf16 v[12:15], v[144:147], v[188:191], v[12:15]
	v_mfma_f32_16x16x32_bf16 v[4:7], v[152:155], v[188:191], v[4:7]
	v_mfma_f32_16x16x32_bf16 v[60:63], v[148:151], v[164:167], v[60:63]
	v_mfma_f32_16x16x32_bf16 v[52:55], v[156:159], v[164:167], v[52:55]
	v_mfma_f32_16x16x32_bf16 v[44:47], v[148:151], v[172:175], v[44:47]
	v_mfma_f32_16x16x32_bf16 v[36:39], v[156:159], v[172:175], v[36:39]
	v_mfma_f32_16x16x32_bf16 v[28:31], v[148:151], v[180:183], v[28:31]
	v_mfma_f32_16x16x32_bf16 v[20:23], v[156:159], v[180:183], v[20:23]
	v_mfma_f32_16x16x32_bf16 v[12:15], v[148:151], v[192:195], v[12:15]
	v_mfma_f32_16x16x32_bf16 v[4:7], v[156:159], v[192:195], v[4:7]
	s_barrier
	s_setprio 0
	s_add_u32 s20, s20, 0x80080
	s_addc_u32 s21, s21, 0
	s_add_i32 s22, s22, s31
	v_lshl_add_u64 v[144:145], s[20:21], 0, v[130:131]
	s_mov_b32 m0, s22
	s_nop 0
	global_load_lds_dwordx4 v[144:145], off
	v_lshl_add_u64 v[144:145], s[20:21], 0, v[134:135]
	s_add_i32 m0, s22, 0x2000
	s_nop 0
	global_load_lds_dwordx4 v[144:145], off
	s_waitcnt vmcnt(6)
	s_setprio 1
	s_barrier
	v_mfma_f32_16x16x32_bf16 v[56:59], v[202:205], v[160:163], v[56:59]
	v_mfma_f32_16x16x32_bf16 v[48:51], v[210:213], v[160:163], v[48:51]
	v_mfma_f32_16x16x32_bf16 v[40:43], v[202:205], v[168:171], v[40:43]
	v_mfma_f32_16x16x32_bf16 v[32:35], v[210:213], v[168:171], v[32:35]
	v_mfma_f32_16x16x32_bf16 v[24:27], v[202:205], v[176:179], v[24:27]
	v_mfma_f32_16x16x32_bf16 v[16:19], v[210:213], v[176:179], v[16:19]
	v_mfma_f32_16x16x32_bf16 v[8:11], v[202:205], v[188:191], v[8:11]
	v_mfma_f32_16x16x32_bf16 v[0:3], v[210:213], v[188:191], v[0:3]
	v_mfma_f32_16x16x32_bf16 v[56:59], v[206:209], v[164:167], v[56:59]
	v_mfma_f32_16x16x32_bf16 v[48:51], v[214:217], v[164:167], v[48:51]
	v_mfma_f32_16x16x32_bf16 v[40:43], v[206:209], v[172:175], v[40:43]
	v_mfma_f32_16x16x32_bf16 v[32:35], v[214:217], v[172:175], v[32:35]
	v_mfma_f32_16x16x32_bf16 v[24:27], v[206:209], v[180:183], v[24:27]
	v_mfma_f32_16x16x32_bf16 v[16:19], v[214:217], v[180:183], v[16:19]
	v_mfma_f32_16x16x32_bf16 v[8:11], v[206:209], v[192:195], v[8:11]
	v_mfma_f32_16x16x32_bf16 v[0:3], v[214:217], v[192:195], v[0:3]
	s_barrier
	s_setprio 0
	s_add_i32 s46, s46, 2
	s_add_u32 s18, s18, 0x100
	s_addc_u32 s19, s19, 0
	s_add_u32 s44, s44, 0x100
	s_addc_u32 s45, s45, 0
	s_cmp_gt_u32 s46, 29
	s_cbranch_scc0 .LBB0_314
	v_mov_b32_e32 v144, v140
	v_mov_b32_e32 v145, v141
	s_lshl_b32 s5, s16, 8
	s_add_i32 s5, s5, s36
	v_add_u32_e32 v144, s5, v144
	s_lshl_b32 s5, s41, 7
	s_or_b32 s5, s5, s37
	v_lshl_add_u32 v145, v145, 3, s5
	v_ashrrev_i32_e32 v146, 6, v145
	v_and_b32_e32 v152, 56, v145
	v_mul_f32_e32 v145, 0x3d372713, v124
	v_fma_f32 v145, v124, v145, 1.0
	v_mul_f32_e32 v145, v124, v145
	v_mul_f32_e32 v145, 0xc0135761, v145
	v_exp_f32_e32 v148, v145
	v_mul_f32_e32 v145, 0xbfb8aa3b, v120
	v_exp_f32_e32 v149, v145
	v_mul_f32_e32 v145, 0x3d372713, v125
	v_fma_f32 v145, v125, v145, 1.0
	v_mul_f32_e32 v145, v125, v145
	v_mul_f32_e32 v145, 0xc0135761, v145
	v_exp_f32_e32 v150, v145
	v_mul_f32_e32 v145, 0xbfb8aa3b, v121
	v_exp_f32_e32 v151, v145
	v_pk_add_f32 v[148:149], v[148:149], 1.0 op_sel_hi:[1,0]
	v_mul_f32_e32 v120, v124, v120
	v_mul_f32_e32 v145, v148, v149
	v_pk_add_f32 v[148:149], v[150:151], 1.0 op_sel_hi:[1,0]
	v_rcp_f32_e32 v145, v145
	v_mul_f32_e32 v148, v148, v149
	v_rcp_f32_e32 v148, v148
	v_mul_f32_e32 v124, 0x3d372713, v127
	v_mul_f32_e32 v149, v120, v145
	v_mul_f32_e32 v120, v125, v121
	v_mul_f32_e32 v148, v120, v148
	v_mul_f32_e32 v120, 0x3d372713, v126
	v_fma_f32 v120, v126, v120, 1.0
	v_mul_f32_e32 v120, v126, v120
	v_mul_f32_e32 v120, 0xc0135761, v120
	v_mul_f32_e32 v121, 0xbfb8aa3b, v122
	v_fma_f32 v124, v127, v124, 1.0
	v_exp_f32_e32 v120, v120
	v_exp_f32_e32 v121, v121
	v_mul_f32_e32 v124, v127, v124
	v_mul_f32_e32 v124, 0xc0135761, v124
	v_mul_f32_e32 v125, 0xbfb8aa3b, v123
	v_exp_f32_e32 v124, v124
	v_exp_f32_e32 v125, v125
	v_pk_add_f32 v[120:121], v[120:121], 1.0 op_sel_hi:[1,0]
	v_ashrrev_i32_e32 v147, 31, v146
	v_mul_f32_e32 v120, v120, v121
	v_rcp_f32_e32 v145, v120
	v_pk_add_f32 v[120:121], v[124:125], 1.0 op_sel_hi:[1,0]
	v_lshlrev_b64 v[146:147], 22, v[146:147]
	v_mul_f32_e32 v120, v120, v121
	v_rcp_f32_e32 v120, v120
	v_mul_f32_e32 v121, v126, v122
	v_mul_f32_e32 v124, v121, v145
	v_mul_f32_e32 v121, v127, v123
	v_mul_f32_e32 v125, v121, v120
	v_mul_f32_e32 v120, 0x3d372713, v116
	v_fma_f32 v120, v116, v120, 1.0
	v_mul_f32_e32 v120, v116, v120
	v_mul_f32_e32 v122, 0x3d372713, v117
	v_mul_f32_e32 v120, 0xc0135761, v120
	v_mul_f32_e32 v121, 0xbfb8aa3b, v112
	v_fma_f32 v122, v117, v122, 1.0
	v_exp_f32_e32 v120, v120
	v_exp_f32_e32 v121, v121
	v_mul_f32_e32 v122, v117, v122
	v_mul_f32_e32 v122, 0xc0135761, v122
	v_mul_f32_e32 v123, 0xbfb8aa3b, v113
	v_exp_f32_e32 v122, v122
	v_exp_f32_e32 v123, v123
	v_pk_add_f32 v[120:121], v[120:121], 1.0 op_sel_hi:[1,0]
	v_mul_f32_e32 v112, v116, v112
	v_mul_f32_e32 v120, v120, v121
	v_rcp_f32_e32 v126, v120
	v_pk_add_f32 v[120:121], v[122:123], 1.0 op_sel_hi:[1,0]
	v_mul_f32_e32 v116, 0x3d372713, v119
	v_mul_f32_e32 v120, v120, v121
	v_rcp_f32_e32 v120, v120
	v_mul_f32_e32 v121, v112, v126
	v_mul_f32_e32 v112, v117, v113
	v_mul_f32_e32 v113, 0xbfb8aa3b, v114
	v_mul_f32_e32 v120, v112, v120
	v_mul_f32_e32 v112, 0x3d372713, v118
	v_fma_f32 v112, v118, v112, 1.0
	v_mul_f32_e32 v112, v118, v112
	v_mul_f32_e32 v112, 0xc0135761, v112
	v_fma_f32 v116, v119, v116, 1.0
	v_exp_f32_e32 v112, v112
	v_exp_f32_e32 v113, v113
	v_mul_f32_e32 v116, v119, v116
	v_mul_f32_e32 v116, 0xc0135761, v116
	v_mul_f32_e32 v117, 0xbfb8aa3b, v115
	v_exp_f32_e32 v116, v116
	v_exp_f32_e32 v117, v117
	v_pk_add_f32 v[112:113], v[112:113], 1.0 op_sel_hi:[1,0]
	v_ashrrev_i32_e32 v145, 31, v144
	v_mul_f32_e32 v112, v112, v113
	v_rcp_f32_e32 v122, v112
	v_pk_add_f32 v[112:113], v[116:117], 1.0 op_sel_hi:[1,0]
	v_lshlrev_b32_e32 v184, 1, v152
	v_mul_f32_e32 v112, v112, v113
	v_rcp_f32_e32 v112, v112
	v_mul_f32_e32 v113, v118, v114
	v_mul_f32_e32 v114, v119, v115
	v_mul_f32_e32 v113, v113, v122
	v_mul_f32_e32 v112, v114, v112
	v_cvt_pk_bf16_f32 v114, v149, v148
	v_cvt_pk_bf16_f32 v115, v124, v125
	v_cvt_pk_bf16_f32 v116, v121, v120
	v_cvt_pk_bf16_f32 v117, v113, v112
	v_lshl_add_u64 v[112:113], s[0:1], 0, v[146:147]
	v_lshlrev_b64 v[118:119], 7, v[144:145]
	v_lshl_add_u64 v[112:113], v[112:113], 0, v[118:119]
	v_lshl_add_u64 v[112:113], v[112:113], 0, v[184:185]
	global_store_dwordx4 v[112:113], v[114:117], off
	s_movk_i32 s5, 0x1000
	s_mov_b32 s41, s8
	v_mul_f32_e32 v114, 0x3d372713, v108
	v_fma_f32 v114, v108, v114, 1.0
	v_mul_f32_e32 v114, v108, v114
	v_mul_f32_e32 v116, 0x3d372713, v109
	v_mul_f32_e32 v114, 0xc0135761, v114
	v_mul_f32_e32 v115, 0xbfb8aa3b, v104
	v_fma_f32 v116, v109, v116, 1.0
	v_exp_f32_e32 v114, v114
	v_exp_f32_e32 v115, v115
	v_mul_f32_e32 v116, v109, v116
	v_mul_f32_e32 v116, 0xc0135761, v116
	v_mul_f32_e32 v117, 0xbfb8aa3b, v105
	v_exp_f32_e32 v116, v116
	v_exp_f32_e32 v117, v117
	v_pk_add_f32 v[114:115], v[114:115], 1.0 op_sel_hi:[1,0]
	v_mul_f32_e32 v104, v108, v104
	v_mul_f32_e32 v114, v114, v115
	v_rcp_f32_e32 v118, v114
	v_pk_add_f32 v[114:115], v[116:117], 1.0 op_sel_hi:[1,0]
	v_mul_f32_e32 v108, 0x3d372713, v111
	v_mul_f32_e32 v114, v114, v115
	v_rcp_f32_e32 v114, v114
	v_mul_f32_e32 v115, v104, v118
	v_mul_f32_e32 v104, v109, v105
	v_mul_f32_e32 v105, 0xbfb8aa3b, v106
	v_mul_f32_e32 v114, v104, v114
	v_mul_f32_e32 v104, 0x3d372713, v110
	v_fma_f32 v104, v110, v104, 1.0
	v_mul_f32_e32 v104, v110, v104
	v_mul_f32_e32 v104, 0xc0135761, v104
	v_fma_f32 v108, v111, v108, 1.0
	v_exp_f32_e32 v104, v104
	v_exp_f32_e32 v105, v105
	v_mul_f32_e32 v108, v111, v108
	v_mul_f32_e32 v108, 0xc0135761, v108
	v_mul_f32_e32 v109, 0xbfb8aa3b, v107
	v_exp_f32_e32 v108, v108
	v_exp_f32_e32 v109, v109
	v_pk_add_f32 v[104:105], v[104:105], 1.0 op_sel_hi:[1,0]
	s_mov_b32 s16, s4
	v_mul_f32_e32 v104, v104, v105
	v_rcp_f32_e32 v116, v104
	v_pk_add_f32 v[104:105], v[108:109], 1.0 op_sel_hi:[1,0]
	s_mov_b64 s[20:21], s[14:15]
	v_mul_f32_e32 v104, v104, v105
	v_rcp_f32_e32 v104, v104
	v_mul_f32_e32 v105, v110, v106
	v_mul_f32_e32 v108, v105, v116
	v_mul_f32_e32 v105, v111, v107
	v_mul_f32_e32 v109, v105, v104
	v_mul_f32_e32 v104, 0x3d372713, v100
	v_fma_f32 v104, v100, v104, 1.0
	v_mul_f32_e32 v104, v100, v104
	v_mul_f32_e32 v106, 0x3d372713, v101
	v_mul_f32_e32 v104, 0xc0135761, v104
	v_mul_f32_e32 v105, 0xbfb8aa3b, v96
	v_fma_f32 v106, v101, v106, 1.0
	v_exp_f32_e32 v104, v104
	v_exp_f32_e32 v105, v105
	v_mul_f32_e32 v106, v101, v106
	v_mul_f32_e32 v106, 0xc0135761, v106
	v_mul_f32_e32 v107, 0xbfb8aa3b, v97
	v_exp_f32_e32 v106, v106
	v_exp_f32_e32 v107, v107
	v_pk_add_f32 v[104:105], v[104:105], 1.0 op_sel_hi:[1,0]
	v_mul_f32_e32 v96, v100, v96
	v_mul_f32_e32 v104, v104, v105
	v_rcp_f32_e32 v110, v104
	v_pk_add_f32 v[104:105], v[106:107], 1.0 op_sel_hi:[1,0]
	v_mul_f32_e32 v100, 0x3d372713, v103
	v_mul_f32_e32 v104, v104, v105
	v_rcp_f32_e32 v104, v104
	v_mul_f32_e32 v105, v96, v110
	v_mul_f32_e32 v96, v101, v97
	v_mul_f32_e32 v97, 0xbfb8aa3b, v98
	v_mul_f32_e32 v104, v96, v104
	v_mul_f32_e32 v96, 0x3d372713, v102
	v_fma_f32 v96, v102, v96, 1.0
	v_mul_f32_e32 v96, v102, v96
	v_mul_f32_e32 v96, 0xc0135761, v96
	v_fma_f32 v100, v103, v100, 1.0
	v_exp_f32_e32 v96, v96
	v_exp_f32_e32 v97, v97
	v_mul_f32_e32 v100, v103, v100
	v_mul_f32_e32 v100, 0xc0135761, v100
	v_mul_f32_e32 v101, 0xbfb8aa3b, v99
	v_exp_f32_e32 v100, v100
	v_exp_f32_e32 v101, v101
	v_pk_add_f32 v[96:97], v[96:97], 1.0 op_sel_hi:[1,0]
	s_mov_b64 s[18:19], s[12:13]
	v_mul_f32_e32 v96, v96, v97
	v_rcp_f32_e32 v106, v96
	v_pk_add_f32 v[96:97], v[100:101], 1.0 op_sel_hi:[1,0]
	s_nop 0
	v_mul_f32_e32 v96, v96, v97
	v_rcp_f32_e32 v96, v96
	v_mul_f32_e32 v97, v102, v98
	v_mul_f32_e32 v100, v97, v106
	v_mul_f32_e32 v97, v103, v99
	v_mul_f32_e32 v99, v97, v96
	v_cvt_pk_bf16_f32 v96, v115, v114
	v_cvt_pk_bf16_f32 v97, v108, v109
	v_cvt_pk_bf16_f32 v98, v105, v104
	v_cvt_pk_bf16_f32 v99, v100, v99
	global_store_dwordx4 v[112:113], v[96:99], off offset:2048
	s_nop 1
	v_mul_f32_e32 v96, 0x3d372713, v92
	v_fma_f32 v96, v92, v96, 1.0
	v_mul_f32_e32 v96, v92, v96
	v_mul_f32_e32 v98, 0x3d372713, v93
	v_mul_f32_e32 v96, 0xc0135761, v96
	v_mul_f32_e32 v97, 0xbfb8aa3b, v88
	v_fma_f32 v98, v93, v98, 1.0
	v_exp_f32_e32 v96, v96
	v_exp_f32_e32 v97, v97
	v_mul_f32_e32 v98, v93, v98
	v_mul_f32_e32 v98, 0xc0135761, v98
	v_mul_f32_e32 v99, 0xbfb8aa3b, v89
	v_exp_f32_e32 v98, v98
	v_exp_f32_e32 v99, v99
	v_pk_add_f32 v[96:97], v[96:97], 1.0 op_sel_hi:[1,0]
	v_mul_f32_e32 v88, v92, v88
	v_mul_f32_e32 v96, v96, v97
	v_rcp_f32_e32 v100, v96
	v_pk_add_f32 v[96:97], v[98:99], 1.0 op_sel_hi:[1,0]
	v_mul_f32_e32 v92, 0x3d372713, v95
	v_mul_f32_e32 v96, v96, v97
	v_rcp_f32_e32 v96, v96
	v_mul_f32_e32 v97, v88, v100
	v_mul_f32_e32 v88, v93, v89
	v_mul_f32_e32 v89, 0xbfb8aa3b, v90
	v_mul_f32_e32 v96, v88, v96
	v_mul_f32_e32 v88, 0x3d372713, v94
	v_fma_f32 v88, v94, v88, 1.0
	v_mul_f32_e32 v88, v94, v88
	v_mul_f32_e32 v88, 0xc0135761, v88
	v_fma_f32 v92, v95, v92, 1.0
	v_exp_f32_e32 v88, v88
	v_exp_f32_e32 v89, v89
	v_mul_f32_e32 v92, v95, v92
	v_mul_f32_e32 v92, 0xc0135761, v92
	v_mul_f32_e32 v93, 0xbfb8aa3b, v91
	v_exp_f32_e32 v92, v92
	v_exp_f32_e32 v93, v93
	v_pk_add_f32 v[88:89], v[88:89], 1.0 op_sel_hi:[1,0]
	s_nop 0
	v_mul_f32_e32 v88, v88, v89
	v_rcp_f32_e32 v98, v88
	v_pk_add_f32 v[88:89], v[92:93], 1.0 op_sel_hi:[1,0]
	s_nop 0
	v_mul_f32_e32 v88, v88, v89
	v_rcp_f32_e32 v88, v88
	v_mul_f32_e32 v89, v94, v90
	v_mul_f32_e32 v92, v89, v98
	v_mul_f32_e32 v89, v95, v91
	v_mul_f32_e32 v93, v89, v88
	v_mul_f32_e32 v88, 0x3d372713, v84
	v_fma_f32 v88, v84, v88, 1.0
	v_mul_f32_e32 v88, v84, v88
	v_mul_f32_e32 v90, 0x3d372713, v85
	v_mul_f32_e32 v88, 0xc0135761, v88
	v_mul_f32_e32 v89, 0xbfb8aa3b, v80
	v_fma_f32 v90, v85, v90, 1.0
	v_exp_f32_e32 v88, v88
	v_exp_f32_e32 v89, v89
	v_mul_f32_e32 v90, v85, v90
	v_mul_f32_e32 v90, 0xc0135761, v90
	v_mul_f32_e32 v91, 0xbfb8aa3b, v81
	v_exp_f32_e32 v90, v90
	v_exp_f32_e32 v91, v91
	v_pk_add_f32 v[88:89], v[88:89], 1.0 op_sel_hi:[1,0]
	v_mul_f32_e32 v80, v84, v80
	v_mul_f32_e32 v88, v88, v89
	v_rcp_f32_e32 v94, v88
	v_pk_add_f32 v[88:89], v[90:91], 1.0 op_sel_hi:[1,0]
	v_mul_f32_e32 v84, 0x3d372713, v87
	v_mul_f32_e32 v88, v88, v89
	v_rcp_f32_e32 v88, v88
	v_mul_f32_e32 v89, v80, v94
	v_mul_f32_e32 v80, v85, v81
	v_mul_f32_e32 v81, 0xbfb8aa3b, v82
	v_mul_f32_e32 v88, v80, v88
	v_mul_f32_e32 v80, 0x3d372713, v86
	v_fma_f32 v80, v86, v80, 1.0
	v_mul_f32_e32 v80, v86, v80
	v_mul_f32_e32 v80, 0xc0135761, v80
	v_fma_f32 v84, v87, v84, 1.0
	v_exp_f32_e32 v80, v80
	v_exp_f32_e32 v81, v81
	v_mul_f32_e32 v84, v87, v84
	v_mul_f32_e32 v84, 0xc0135761, v84
	v_mul_f32_e32 v85, 0xbfb8aa3b, v83
	v_exp_f32_e32 v84, v84
	v_exp_f32_e32 v85, v85
	v_pk_add_f32 v[80:81], v[80:81], 1.0 op_sel_hi:[1,0]
	s_nop 0
	v_mul_f32_e32 v80, v80, v81
	v_rcp_f32_e32 v90, v80
	v_pk_add_f32 v[80:81], v[84:85], 1.0 op_sel_hi:[1,0]
	s_nop 0
	v_mul_f32_e32 v80, v80, v81
	v_rcp_f32_e32 v80, v80
	v_mul_f32_e32 v81, v86, v82
	v_mul_f32_e32 v84, v81, v90
	v_mul_f32_e32 v81, v87, v83
	v_mul_f32_e32 v83, v81, v80
	v_cvt_pk_bf16_f32 v80, v97, v96
	v_cvt_pk_bf16_f32 v81, v92, v93
	v_cvt_pk_bf16_f32 v82, v89, v88
	v_cvt_pk_bf16_f32 v83, v84, v83
	v_add_co_u32_e32 v84, vcc, s5, v112
	s_movk_i32 s5, 0x4000
	s_nop 0
	v_addc_co_u32_e32 v85, vcc, 0, v113, vcc
	global_store_dwordx4 v[84:85], v[80:83], off
	s_nop 1
	v_mul_f32_e32 v80, 0x3d372713, v76
	v_fma_f32 v80, v76, v80, 1.0
	v_mul_f32_e32 v80, v76, v80
	v_mul_f32_e32 v82, 0x3d372713, v77
	v_mul_f32_e32 v80, 0xc0135761, v80
	v_mul_f32_e32 v81, 0xbfb8aa3b, v72
	v_fma_f32 v82, v77, v82, 1.0
	v_exp_f32_e32 v80, v80
	v_exp_f32_e32 v81, v81
	v_mul_f32_e32 v82, v77, v82
	v_mul_f32_e32 v82, 0xc0135761, v82
	v_mul_f32_e32 v83, 0xbfb8aa3b, v73
	v_exp_f32_e32 v82, v82
	v_exp_f32_e32 v83, v83
	v_pk_add_f32 v[80:81], v[80:81], 1.0 op_sel_hi:[1,0]
	v_mul_f32_e32 v72, v76, v72
	v_mul_f32_e32 v80, v80, v81
	v_rcp_f32_e32 v86, v80
	v_pk_add_f32 v[80:81], v[82:83], 1.0 op_sel_hi:[1,0]
	v_mul_f32_e32 v76, 0x3d372713, v79
	v_mul_f32_e32 v80, v80, v81
	v_rcp_f32_e32 v80, v80
	v_mul_f32_e32 v81, v72, v86
	v_mul_f32_e32 v72, v77, v73
	v_mul_f32_e32 v73, 0xbfb8aa3b, v74
	v_mul_f32_e32 v80, v72, v80
	v_mul_f32_e32 v72, 0x3d372713, v78
	v_fma_f32 v72, v78, v72, 1.0
	v_mul_f32_e32 v72, v78, v72
	v_mul_f32_e32 v72, 0xc0135761, v72
	v_fma_f32 v76, v79, v76, 1.0
	v_exp_f32_e32 v72, v72
	v_exp_f32_e32 v73, v73
	v_mul_f32_e32 v76, v79, v76
	v_mul_f32_e32 v76, 0xc0135761, v76
	v_mul_f32_e32 v77, 0xbfb8aa3b, v75
	v_exp_f32_e32 v76, v76
	v_exp_f32_e32 v77, v77
	v_pk_add_f32 v[72:73], v[72:73], 1.0 op_sel_hi:[1,0]
	s_nop 0
	v_mul_f32_e32 v72, v72, v73
	v_rcp_f32_e32 v82, v72
	v_pk_add_f32 v[72:73], v[76:77], 1.0 op_sel_hi:[1,0]
	s_nop 0
	v_mul_f32_e32 v72, v72, v73
	v_rcp_f32_e32 v72, v72
	v_mul_f32_e32 v73, v78, v74
	v_mul_f32_e32 v76, v73, v82
	v_mul_f32_e32 v73, v79, v75
	v_mul_f32_e32 v77, v73, v72
	v_mul_f32_e32 v72, 0x3d372713, v68
	v_fma_f32 v72, v68, v72, 1.0
	v_mul_f32_e32 v72, v68, v72
	v_mul_f32_e32 v74, 0x3d372713, v69
	v_mul_f32_e32 v72, 0xc0135761, v72
	v_mul_f32_e32 v73, 0xbfb8aa3b, v64
	v_fma_f32 v74, v69, v74, 1.0
	v_exp_f32_e32 v72, v72
	v_exp_f32_e32 v73, v73
	v_mul_f32_e32 v74, v69, v74
	v_mul_f32_e32 v74, 0xc0135761, v74
	v_mul_f32_e32 v75, 0xbfb8aa3b, v65
	v_exp_f32_e32 v74, v74
	v_exp_f32_e32 v75, v75
	v_pk_add_f32 v[72:73], v[72:73], 1.0 op_sel_hi:[1,0]
	v_mul_f32_e32 v64, v68, v64
	v_mul_f32_e32 v72, v72, v73
	v_rcp_f32_e32 v78, v72
	v_pk_add_f32 v[72:73], v[74:75], 1.0 op_sel_hi:[1,0]
	v_mul_f32_e32 v68, 0x3d372713, v71
	v_mul_f32_e32 v72, v72, v73
	v_rcp_f32_e32 v72, v72
	v_mul_f32_e32 v73, v64, v78
	v_mul_f32_e32 v64, v69, v65
	v_mul_f32_e32 v65, 0xbfb8aa3b, v66
	v_mul_f32_e32 v72, v64, v72
	v_mul_f32_e32 v64, 0x3d372713, v70
	v_fma_f32 v64, v70, v64, 1.0
	v_mul_f32_e32 v64, v70, v64
	v_mul_f32_e32 v64, 0xc0135761, v64
	v_fma_f32 v68, v71, v68, 1.0
	v_exp_f32_e32 v64, v64
	v_exp_f32_e32 v65, v65
	v_mul_f32_e32 v68, v71, v68
	v_mul_f32_e32 v68, 0xc0135761, v68
	v_mul_f32_e32 v69, 0xbfb8aa3b, v67
	v_exp_f32_e32 v68, v68
	v_exp_f32_e32 v69, v69
	v_pk_add_f32 v[64:65], v[64:65], 1.0 op_sel_hi:[1,0]
	s_nop 0
	v_mul_f32_e32 v64, v64, v65
	v_rcp_f32_e32 v74, v64
	v_pk_add_f32 v[64:65], v[68:69], 1.0 op_sel_hi:[1,0]
	s_nop 0
	v_mul_f32_e32 v64, v64, v65
	v_rcp_f32_e32 v64, v64
	v_mul_f32_e32 v65, v70, v66
	v_mul_f32_e32 v68, v65, v74
	v_mul_f32_e32 v65, v71, v67
	v_mul_f32_e32 v67, v65, v64
	v_cvt_pk_bf16_f32 v64, v81, v80
	v_cvt_pk_bf16_f32 v65, v76, v77
	v_cvt_pk_bf16_f32 v66, v73, v72
	v_cvt_pk_bf16_f32 v67, v68, v67
	global_store_dwordx4 v[84:85], v[64:67], off offset:2048
	s_nop 1
	v_mul_f32_e32 v64, 0x3d372713, v60
	v_fma_f32 v64, v60, v64, 1.0
	v_mul_f32_e32 v64, v60, v64
	v_mul_f32_e32 v66, 0x3d372713, v61
	v_mul_f32_e32 v64, 0xc0135761, v64
	v_mul_f32_e32 v65, 0xbfb8aa3b, v56
	v_fma_f32 v66, v61, v66, 1.0
	v_exp_f32_e32 v64, v64
	v_exp_f32_e32 v65, v65
	v_mul_f32_e32 v66, v61, v66
	v_mul_f32_e32 v66, 0xc0135761, v66
	v_mul_f32_e32 v67, 0xbfb8aa3b, v57
	v_exp_f32_e32 v66, v66
	v_exp_f32_e32 v67, v67
	v_pk_add_f32 v[64:65], v[64:65], 1.0 op_sel_hi:[1,0]
	v_mul_f32_e32 v56, v60, v56
	v_mul_f32_e32 v64, v64, v65
	v_rcp_f32_e32 v68, v64
	v_pk_add_f32 v[64:65], v[66:67], 1.0 op_sel_hi:[1,0]
	v_mul_f32_e32 v60, 0x3d372713, v63
	v_mul_f32_e32 v64, v64, v65
	v_rcp_f32_e32 v64, v64
	v_mul_f32_e32 v65, v56, v68
	v_mul_f32_e32 v56, v61, v57
	v_mul_f32_e32 v57, 0xbfb8aa3b, v58
	v_mul_f32_e32 v64, v56, v64
	v_mul_f32_e32 v56, 0x3d372713, v62
	v_fma_f32 v56, v62, v56, 1.0
	v_mul_f32_e32 v56, v62, v56
	v_mul_f32_e32 v56, 0xc0135761, v56
	v_fma_f32 v60, v63, v60, 1.0
	v_exp_f32_e32 v56, v56
	v_exp_f32_e32 v57, v57
	v_mul_f32_e32 v60, v63, v60
	v_mul_f32_e32 v60, 0xc0135761, v60
	v_mul_f32_e32 v61, 0xbfb8aa3b, v59
	v_exp_f32_e32 v60, v60
	v_exp_f32_e32 v61, v61
	v_pk_add_f32 v[56:57], v[56:57], 1.0 op_sel_hi:[1,0]
	s_nop 0
	v_mul_f32_e32 v56, v56, v57
	v_rcp_f32_e32 v66, v56
	v_pk_add_f32 v[56:57], v[60:61], 1.0 op_sel_hi:[1,0]
	s_nop 0
	v_mul_f32_e32 v56, v56, v57
	v_rcp_f32_e32 v56, v56
	v_mul_f32_e32 v57, v62, v58
	v_mul_f32_e32 v60, v57, v66
	v_mul_f32_e32 v57, v63, v59
	v_mul_f32_e32 v61, v57, v56
	v_mul_f32_e32 v56, 0x3d372713, v52
	v_fma_f32 v56, v52, v56, 1.0
	v_mul_f32_e32 v56, v52, v56
	v_mul_f32_e32 v58, 0x3d372713, v53
	v_mul_f32_e32 v56, 0xc0135761, v56
	v_mul_f32_e32 v57, 0xbfb8aa3b, v48
	v_fma_f32 v58, v53, v58, 1.0
	v_exp_f32_e32 v56, v56
	v_exp_f32_e32 v57, v57
	v_mul_f32_e32 v58, v53, v58
	v_mul_f32_e32 v58, 0xc0135761, v58
	v_mul_f32_e32 v59, 0xbfb8aa3b, v49
	v_exp_f32_e32 v58, v58
	v_exp_f32_e32 v59, v59
	v_pk_add_f32 v[56:57], v[56:57], 1.0 op_sel_hi:[1,0]
	v_mul_f32_e32 v48, v52, v48
	v_mul_f32_e32 v56, v56, v57
	v_rcp_f32_e32 v62, v56
	v_pk_add_f32 v[56:57], v[58:59], 1.0 op_sel_hi:[1,0]
	v_mul_f32_e32 v52, 0x3d372713, v55
	v_mul_f32_e32 v56, v56, v57
	v_rcp_f32_e32 v56, v56
	v_mul_f32_e32 v57, v48, v62
	v_mul_f32_e32 v48, v53, v49
	v_mul_f32_e32 v49, 0xbfb8aa3b, v50
	v_mul_f32_e32 v56, v48, v56
	v_mul_f32_e32 v48, 0x3d372713, v54
	v_fma_f32 v48, v54, v48, 1.0
	v_mul_f32_e32 v48, v54, v48
	v_mul_f32_e32 v48, 0xc0135761, v48
	v_fma_f32 v52, v55, v52, 1.0
	v_exp_f32_e32 v48, v48
	v_exp_f32_e32 v49, v49
	v_mul_f32_e32 v52, v55, v52
	v_mul_f32_e32 v52, 0xc0135761, v52
	v_mul_f32_e32 v53, 0xbfb8aa3b, v51
	v_exp_f32_e32 v52, v52
	v_exp_f32_e32 v53, v53
	v_pk_add_f32 v[48:49], v[48:49], 1.0 op_sel_hi:[1,0]
	s_nop 0
	v_mul_f32_e32 v48, v48, v49
	v_rcp_f32_e32 v58, v48
	v_pk_add_f32 v[48:49], v[52:53], 1.0 op_sel_hi:[1,0]
	s_nop 0
	v_mul_f32_e32 v48, v48, v49
	v_rcp_f32_e32 v48, v48
	v_mul_f32_e32 v49, v54, v50
	v_mul_f32_e32 v50, v55, v51
	v_add_co_u32_e32 v54, vcc, s5, v112
	v_mul_f32_e32 v48, v50, v48
	s_nop 0
	v_addc_co_u32_e32 v55, vcc, 0, v113, vcc
	s_movk_i32 s5, 0x5000
	v_mul_f32_e32 v49, v49, v58
	v_cvt_pk_bf16_f32 v50, v65, v64
	v_cvt_pk_bf16_f32 v51, v60, v61
	v_cvt_pk_bf16_f32 v52, v57, v56
	v_cvt_pk_bf16_f32 v53, v49, v48
	v_add_co_u32_e32 v48, vcc, s5, v112
	s_nop 1
	v_addc_co_u32_e32 v49, vcc, 0, v113, vcc
	global_store_dwordx4 v[48:49], v[50:53], off offset:-4096
	s_and_b64 vcc, exec, s[2:3]
	s_nop 0
	v_mul_f32_e32 v50, 0x3d372713, v44
	v_fma_f32 v50, v44, v50, 1.0
	v_mul_f32_e32 v50, v44, v50
	v_mul_f32_e32 v52, 0x3d372713, v45
	v_mul_f32_e32 v50, 0xc0135761, v50
	v_mul_f32_e32 v51, 0xbfb8aa3b, v40
	v_fma_f32 v52, v45, v52, 1.0
	v_exp_f32_e32 v50, v50
	v_exp_f32_e32 v51, v51
	v_mul_f32_e32 v52, v45, v52
	v_mul_f32_e32 v52, 0xc0135761, v52
	v_mul_f32_e32 v53, 0xbfb8aa3b, v41
	v_exp_f32_e32 v52, v52
	v_exp_f32_e32 v53, v53
	v_pk_add_f32 v[50:51], v[50:51], 1.0 op_sel_hi:[1,0]
	v_mul_f32_e32 v40, v44, v40
	v_mul_f32_e32 v50, v50, v51
	v_rcp_f32_e32 v56, v50
	v_pk_add_f32 v[50:51], v[52:53], 1.0 op_sel_hi:[1,0]
	v_mul_f32_e32 v44, 0x3d372713, v47
	v_mul_f32_e32 v50, v50, v51
	v_rcp_f32_e32 v50, v50
	v_mul_f32_e32 v51, v40, v56
	v_mul_f32_e32 v40, v45, v41
	v_mul_f32_e32 v41, 0xbfb8aa3b, v42
	v_mul_f32_e32 v50, v40, v50
	v_mul_f32_e32 v40, 0x3d372713, v46
	v_fma_f32 v40, v46, v40, 1.0
	v_mul_f32_e32 v40, v46, v40
	v_mul_f32_e32 v40, 0xc0135761, v40
	v_fma_f32 v44, v47, v44, 1.0
	v_exp_f32_e32 v40, v40
	v_exp_f32_e32 v41, v41
	v_mul_f32_e32 v44, v47, v44
	v_mul_f32_e32 v44, 0xc0135761, v44
	v_mul_f32_e32 v45, 0xbfb8aa3b, v43
	v_exp_f32_e32 v44, v44
	v_exp_f32_e32 v45, v45
	v_pk_add_f32 v[40:41], v[40:41], 1.0 op_sel_hi:[1,0]
	s_nop 0
	v_mul_f32_e32 v40, v40, v41
	v_rcp_f32_e32 v52, v40
	v_pk_add_f32 v[40:41], v[44:45], 1.0 op_sel_hi:[1,0]
	s_nop 0
	v_mul_f32_e32 v40, v40, v41
	v_rcp_f32_e32 v40, v40
	v_mul_f32_e32 v41, v46, v42
	v_mul_f32_e32 v44, v41, v52
	v_mul_f32_e32 v41, v47, v43
	v_mul_f32_e32 v45, v41, v40
	v_mul_f32_e32 v40, 0x3d372713, v36
	v_fma_f32 v40, v36, v40, 1.0
	v_mul_f32_e32 v40, v36, v40
	v_mul_f32_e32 v42, 0x3d372713, v37
	v_mul_f32_e32 v40, 0xc0135761, v40
	v_mul_f32_e32 v41, 0xbfb8aa3b, v32
	v_fma_f32 v42, v37, v42, 1.0
	v_exp_f32_e32 v40, v40
	v_exp_f32_e32 v41, v41
	v_mul_f32_e32 v42, v37, v42
	v_mul_f32_e32 v42, 0xc0135761, v42
	v_mul_f32_e32 v43, 0xbfb8aa3b, v33
	v_exp_f32_e32 v42, v42
	v_exp_f32_e32 v43, v43
	v_pk_add_f32 v[40:41], v[40:41], 1.0 op_sel_hi:[1,0]
	v_mul_f32_e32 v32, v36, v32
	v_mul_f32_e32 v40, v40, v41
	v_rcp_f32_e32 v46, v40
	v_pk_add_f32 v[40:41], v[42:43], 1.0 op_sel_hi:[1,0]
	v_mul_f32_e32 v36, 0x3d372713, v39
	v_mul_f32_e32 v40, v40, v41
	v_rcp_f32_e32 v40, v40
	v_mul_f32_e32 v41, v32, v46
	v_mul_f32_e32 v32, v37, v33
	v_mul_f32_e32 v33, 0xbfb8aa3b, v34
	v_mul_f32_e32 v40, v32, v40
	v_mul_f32_e32 v32, 0x3d372713, v38
	v_fma_f32 v32, v38, v32, 1.0
	v_mul_f32_e32 v32, v38, v32
	v_mul_f32_e32 v32, 0xc0135761, v32
	v_fma_f32 v36, v39, v36, 1.0
	v_exp_f32_e32 v32, v32
	v_exp_f32_e32 v33, v33
	v_mul_f32_e32 v36, v39, v36
	v_mul_f32_e32 v36, 0xc0135761, v36
	v_mul_f32_e32 v37, 0xbfb8aa3b, v35
	v_exp_f32_e32 v36, v36
	v_exp_f32_e32 v37, v37
	v_pk_add_f32 v[32:33], v[32:33], 1.0 op_sel_hi:[1,0]
	s_nop 0
	v_mul_f32_e32 v32, v32, v33
	v_rcp_f32_e32 v42, v32
	v_pk_add_f32 v[32:33], v[36:37], 1.0 op_sel_hi:[1,0]
	s_nop 0
	v_mul_f32_e32 v32, v32, v33
	v_rcp_f32_e32 v32, v32
	v_mul_f32_e32 v33, v38, v34
	v_mul_f32_e32 v36, v33, v42
	v_mul_f32_e32 v33, v39, v35
	v_mul_f32_e32 v35, v33, v32
	v_cvt_pk_bf16_f32 v32, v51, v50
	v_cvt_pk_bf16_f32 v33, v44, v45
	v_cvt_pk_bf16_f32 v34, v41, v40
	v_cvt_pk_bf16_f32 v35, v36, v35
	global_store_dwordx4 v[54:55], v[32:35], off offset:2048
	s_nop 1
	v_mul_f32_e32 v32, 0x3d372713, v28
	v_fma_f32 v32, v28, v32, 1.0
	v_mul_f32_e32 v32, v28, v32
	v_mul_f32_e32 v34, 0x3d372713, v29
	v_mul_f32_e32 v32, 0xc0135761, v32
	v_mul_f32_e32 v33, 0xbfb8aa3b, v24
	v_fma_f32 v34, v29, v34, 1.0
	v_exp_f32_e32 v32, v32
	v_exp_f32_e32 v33, v33
	v_mul_f32_e32 v34, v29, v34
	v_mul_f32_e32 v34, 0xc0135761, v34
	v_mul_f32_e32 v35, 0xbfb8aa3b, v25
	v_exp_f32_e32 v34, v34
	v_exp_f32_e32 v35, v35
	v_pk_add_f32 v[32:33], v[32:33], 1.0 op_sel_hi:[1,0]
	v_mul_f32_e32 v24, v28, v24
	v_mul_f32_e32 v32, v32, v33
	v_rcp_f32_e32 v36, v32
	v_pk_add_f32 v[32:33], v[34:35], 1.0 op_sel_hi:[1,0]
	v_mul_f32_e32 v28, 0x3d372713, v31
	v_mul_f32_e32 v32, v32, v33
	v_rcp_f32_e32 v32, v32
	v_mul_f32_e32 v33, v24, v36
	v_mul_f32_e32 v24, v29, v25
	v_mul_f32_e32 v25, 0xbfb8aa3b, v26
	v_mul_f32_e32 v32, v24, v32
	v_mul_f32_e32 v24, 0x3d372713, v30
	v_fma_f32 v24, v30, v24, 1.0
	v_mul_f32_e32 v24, v30, v24
	v_mul_f32_e32 v24, 0xc0135761, v24
	v_fma_f32 v28, v31, v28, 1.0
	v_exp_f32_e32 v24, v24
	v_exp_f32_e32 v25, v25
	v_mul_f32_e32 v28, v31, v28
	v_mul_f32_e32 v28, 0xc0135761, v28
	v_mul_f32_e32 v29, 0xbfb8aa3b, v27
	v_exp_f32_e32 v28, v28
	v_exp_f32_e32 v29, v29
	v_pk_add_f32 v[24:25], v[24:25], 1.0 op_sel_hi:[1,0]
	s_nop 0
	v_mul_f32_e32 v24, v24, v25
	v_rcp_f32_e32 v34, v24
	v_pk_add_f32 v[24:25], v[28:29], 1.0 op_sel_hi:[1,0]
	s_nop 0
	v_mul_f32_e32 v24, v24, v25
	v_rcp_f32_e32 v24, v24
	v_mul_f32_e32 v25, v30, v26
	v_mul_f32_e32 v28, v25, v34
	v_mul_f32_e32 v25, v31, v27
	v_mul_f32_e32 v29, v25, v24
	v_mul_f32_e32 v24, 0x3d372713, v20
	v_fma_f32 v24, v20, v24, 1.0
	v_mul_f32_e32 v24, v20, v24
	v_mul_f32_e32 v26, 0x3d372713, v21
	v_mul_f32_e32 v24, 0xc0135761, v24
	v_mul_f32_e32 v25, 0xbfb8aa3b, v16
	v_fma_f32 v26, v21, v26, 1.0
	v_exp_f32_e32 v24, v24
	v_exp_f32_e32 v25, v25
	v_mul_f32_e32 v26, v21, v26
	v_mul_f32_e32 v26, 0xc0135761, v26
	v_mul_f32_e32 v27, 0xbfb8aa3b, v17
	v_exp_f32_e32 v26, v26
	v_exp_f32_e32 v27, v27
	v_pk_add_f32 v[24:25], v[24:25], 1.0 op_sel_hi:[1,0]
	v_mul_f32_e32 v16, v20, v16
	v_mul_f32_e32 v24, v24, v25
	v_rcp_f32_e32 v30, v24
	v_pk_add_f32 v[24:25], v[26:27], 1.0 op_sel_hi:[1,0]
	v_mul_f32_e32 v20, 0x3d372713, v23
	v_mul_f32_e32 v24, v24, v25
	v_rcp_f32_e32 v24, v24
	v_mul_f32_e32 v25, v16, v30
	v_mul_f32_e32 v16, v21, v17
	v_mul_f32_e32 v17, 0xbfb8aa3b, v18
	v_mul_f32_e32 v24, v16, v24
	v_mul_f32_e32 v16, 0x3d372713, v22
	v_fma_f32 v16, v22, v16, 1.0
	v_mul_f32_e32 v16, v22, v16
	v_mul_f32_e32 v16, 0xc0135761, v16
	v_fma_f32 v20, v23, v20, 1.0
	v_exp_f32_e32 v16, v16
	v_exp_f32_e32 v17, v17
	v_mul_f32_e32 v20, v23, v20
	v_mul_f32_e32 v20, 0xc0135761, v20
	v_mul_f32_e32 v21, 0xbfb8aa3b, v19
	v_exp_f32_e32 v20, v20
	v_exp_f32_e32 v21, v21
	v_pk_add_f32 v[16:17], v[16:17], 1.0 op_sel_hi:[1,0]
	s_nop 0
	v_mul_f32_e32 v16, v16, v17
	v_rcp_f32_e32 v26, v16
	v_pk_add_f32 v[16:17], v[20:21], 1.0 op_sel_hi:[1,0]
	s_nop 0
	v_mul_f32_e32 v16, v16, v17
	v_rcp_f32_e32 v16, v16
	v_mul_f32_e32 v17, v22, v18
	v_mul_f32_e32 v20, v17, v26
	v_mul_f32_e32 v17, v23, v19
	v_mul_f32_e32 v19, v17, v16
	v_cvt_pk_bf16_f32 v16, v33, v32
	v_cvt_pk_bf16_f32 v17, v28, v29
	v_cvt_pk_bf16_f32 v18, v25, v24
	v_cvt_pk_bf16_f32 v19, v20, v19
	global_store_dwordx4 v[48:49], v[16:19], off
	s_nop 1
	v_mul_f32_e32 v16, 0x3d372713, v12
	v_fma_f32 v16, v12, v16, 1.0
	v_mul_f32_e32 v16, v12, v16
	v_mul_f32_e32 v18, 0x3d372713, v13
	v_mul_f32_e32 v16, 0xc0135761, v16
	v_mul_f32_e32 v17, 0xbfb8aa3b, v8
	v_fma_f32 v18, v13, v18, 1.0
	v_exp_f32_e32 v16, v16
	v_exp_f32_e32 v17, v17
	v_mul_f32_e32 v18, v13, v18
	v_mul_f32_e32 v18, 0xc0135761, v18
	v_mul_f32_e32 v19, 0xbfb8aa3b, v9
	v_exp_f32_e32 v18, v18
	v_exp_f32_e32 v19, v19
	v_pk_add_f32 v[16:17], v[16:17], 1.0 op_sel_hi:[1,0]
	v_mul_f32_e32 v8, v12, v8
	v_mul_f32_e32 v16, v16, v17
	v_rcp_f32_e32 v20, v16
	v_pk_add_f32 v[16:17], v[18:19], 1.0 op_sel_hi:[1,0]
	v_mul_f32_e32 v12, 0x3d372713, v15
	v_mul_f32_e32 v16, v16, v17
	v_rcp_f32_e32 v16, v16
	v_mul_f32_e32 v17, v8, v20
	v_mul_f32_e32 v8, v13, v9
	v_mul_f32_e32 v9, 0xbfb8aa3b, v10
	v_mul_f32_e32 v16, v8, v16
	v_mul_f32_e32 v8, 0x3d372713, v14
	v_fma_f32 v8, v14, v8, 1.0
	v_mul_f32_e32 v8, v14, v8
	v_mul_f32_e32 v8, 0xc0135761, v8
	v_fma_f32 v12, v15, v12, 1.0
	v_exp_f32_e32 v8, v8
	v_exp_f32_e32 v9, v9
	v_mul_f32_e32 v12, v15, v12
	v_mul_f32_e32 v12, 0xc0135761, v12
	v_mul_f32_e32 v13, 0xbfb8aa3b, v11
	v_exp_f32_e32 v12, v12
	v_exp_f32_e32 v13, v13
	v_pk_add_f32 v[8:9], v[8:9], 1.0 op_sel_hi:[1,0]
	s_nop 0
	v_mul_f32_e32 v8, v8, v9
	v_rcp_f32_e32 v18, v8
	v_pk_add_f32 v[8:9], v[12:13], 1.0 op_sel_hi:[1,0]
	s_nop 0
	v_mul_f32_e32 v8, v8, v9
	v_rcp_f32_e32 v8, v8
	v_mul_f32_e32 v9, v14, v10
	v_mul_f32_e32 v12, v9, v18
	v_mul_f32_e32 v9, v15, v11
	v_mul_f32_e32 v13, v9, v8
	v_mul_f32_e32 v8, 0x3d372713, v4
	v_fma_f32 v8, v4, v8, 1.0
	v_mul_f32_e32 v8, v4, v8
	v_mul_f32_e32 v10, 0x3d372713, v5
	v_mul_f32_e32 v8, 0xc0135761, v8
	v_mul_f32_e32 v9, 0xbfb8aa3b, v0
	v_fma_f32 v10, v5, v10, 1.0
	v_exp_f32_e32 v8, v8
	v_exp_f32_e32 v9, v9
	v_mul_f32_e32 v10, v5, v10
	v_mul_f32_e32 v10, 0xc0135761, v10
	v_mul_f32_e32 v11, 0xbfb8aa3b, v1
	v_exp_f32_e32 v10, v10
	v_exp_f32_e32 v11, v11
	v_pk_add_f32 v[8:9], v[8:9], 1.0 op_sel_hi:[1,0]
	v_mul_f32_e32 v0, v4, v0
	v_mul_f32_e32 v8, v8, v9
	v_rcp_f32_e32 v14, v8
	v_pk_add_f32 v[8:9], v[10:11], 1.0 op_sel_hi:[1,0]
	v_mul_f32_e32 v4, 0x3d372713, v7
	v_mul_f32_e32 v8, v8, v9
	v_rcp_f32_e32 v8, v8
	v_mul_f32_e32 v9, v0, v14
	v_mul_f32_e32 v0, v5, v1
	v_mul_f32_e32 v1, 0xbfb8aa3b, v2
	v_mul_f32_e32 v8, v0, v8
	v_mul_f32_e32 v0, 0x3d372713, v6
	v_fma_f32 v0, v6, v0, 1.0
	v_mul_f32_e32 v0, v6, v0
	v_mul_f32_e32 v0, 0xc0135761, v0
	v_fma_f32 v4, v7, v4, 1.0
	v_exp_f32_e32 v0, v0
	v_exp_f32_e32 v1, v1
	v_mul_f32_e32 v4, v7, v4
	v_mul_f32_e32 v4, 0xc0135761, v4
	v_mul_f32_e32 v5, 0xbfb8aa3b, v3
	v_exp_f32_e32 v4, v4
	v_exp_f32_e32 v5, v5
	v_pk_add_f32 v[0:1], v[0:1], 1.0 op_sel_hi:[1,0]
	s_nop 0
	v_mul_f32_e32 v0, v0, v1
	v_rcp_f32_e32 v10, v0
	v_pk_add_f32 v[0:1], v[4:5], 1.0 op_sel_hi:[1,0]
	s_nop 0
	v_mul_f32_e32 v0, v0, v1
	v_rcp_f32_e32 v0, v0
	v_mul_f32_e32 v1, v6, v2
	v_mul_f32_e32 v4, v1, v10
	v_mul_f32_e32 v1, v7, v3
	v_mul_f32_e32 v3, v1, v0
	v_cvt_pk_bf16_f32 v0, v17, v16
	v_cvt_pk_bf16_f32 v1, v12, v13
	v_cvt_pk_bf16_f32 v2, v9, v8
	v_cvt_pk_bf16_f32 v3, v4, v3
	global_store_dwordx4 v[48:49], v[0:3], off offset:2048
	s_cbranch_vccz .LBB0_307
	s_waitcnt vmcnt(0)
	s_cmpk_gt_u32 s30, 0xff
	s_cbranch_scc1 .LBB0_318
	s_barrier

.LBB0_334:
	s_add_u32 s4, s0, 0xfff80080
	s_addc_u32 s5, s1, -1
	s_add_i32 s51, 0, 0x10000
	v_add_u32_e32 v138, s51, v142
	ds_read_b128 v[144:147], v138
	ds_read_b128 v[148:151], v138 offset:1024
	ds_read_b128 v[152:155], v138 offset:2048
	ds_read_b128 v[156:159], v138 offset:3072
	s_cmp_eq_u32 s50, 28
	s_cselect_b32 s25, s17, s5
	s_cselect_b32 s24, s46, s4
	s_cselect_b32 s5, s19, s49
	s_cselect_b32 s4, s47, s48
	v_lshl_add_u64 v[138:139], s[0:1], 0, v[134:135]
	s_add_i32 m0, s3, 0xc000
	ds_read_b128 v[160:163], v143
	ds_read_b128 v[164:167], v143 offset:1024
	ds_read_b128 v[168:171], v143 offset:2048
	ds_read_b128 v[172:175], v143 offset:3072
	ds_read_b128 v[176:179], v143 offset:4096
	ds_read_b128 v[180:183], v143 offset:5120
	ds_read_b128 v[188:191], v143 offset:6144
	ds_read_b128 v[192:195], v143 offset:7168
	global_load_lds_dwordx4 v[138:139], off
	v_lshl_add_u64 v[138:139], s[0:1], 0, v[136:137]
	s_add_i32 m0, s3, 0xe000
	s_nop 0
	global_load_lds_dwordx4 v[138:139], off
	s_waitcnt lgkmcnt(8)
	s_setprio 1
	s_barrier
	s_waitcnt lgkmcnt(0)
	v_mfma_f32_16x16x32_bf16 v[124:127], v[144:147], v[160:163], v[124:127]
	v_mfma_f32_16x16x32_bf16 v[68:71], v[152:155], v[160:163], v[68:71]
	v_mfma_f32_16x16x32_bf16 v[116:119], v[144:147], v[168:171], v[116:119]
	v_mfma_f32_16x16x32_bf16 v[88:91], v[152:155], v[168:171], v[88:91]
	v_mfma_f32_16x16x32_bf16 v[108:111], v[144:147], v[176:179], v[108:111]
	v_mfma_f32_16x16x32_bf16 v[104:107], v[152:155], v[176:179], v[104:107]
	v_mfma_f32_16x16x32_bf16 v[92:95], v[144:147], v[188:191], v[92:95]
	v_mfma_f32_16x16x32_bf16 v[84:87], v[152:155], v[188:191], v[84:87]
	v_mfma_f32_16x16x32_bf16 v[124:127], v[148:151], v[164:167], v[124:127]
	v_mfma_f32_16x16x32_bf16 v[68:71], v[156:159], v[164:167], v[68:71]
	v_mfma_f32_16x16x32_bf16 v[116:119], v[148:151], v[172:175], v[116:119]
	v_mfma_f32_16x16x32_bf16 v[88:91], v[156:159], v[172:175], v[88:91]
	v_mfma_f32_16x16x32_bf16 v[108:111], v[148:151], v[180:183], v[108:111]
	v_mfma_f32_16x16x32_bf16 v[104:107], v[156:159], v[180:183], v[104:107]
	v_mfma_f32_16x16x32_bf16 v[92:95], v[148:151], v[192:195], v[92:95]
	v_mfma_f32_16x16x32_bf16 v[84:87], v[156:159], v[192:195], v[84:87]
	s_barrier
	s_setprio 0
	s_add_i32 s54, 0, 0x14000
	v_add_u32_e32 v138, s54, v142
	s_add_i32 s51, s51, s35
	ds_read_b128 v[202:205], v138
	ds_read_b128 v[206:209], v138 offset:1024
	ds_read_b128 v[210:213], v138 offset:2048
	ds_read_b128 v[214:217], v138 offset:3072
	v_lshl_add_u64 v[138:139], s[4:5], 0, v[184:185]
	s_mov_b32 m0, s51
	v_lshl_add_u64 v[196:197], s[4:5], 0, v[132:133]
	global_load_lds_dwordx4 v[138:139], off
	s_add_i32 m0, s51, 0x2000
	s_nop 0
	global_load_lds_dwordx4 v[196:197], off
	s_setprio 1
	s_barrier
	s_waitcnt lgkmcnt(0)
	v_mfma_f32_16x16x32_bf16 v[120:123], v[202:205], v[160:163], v[120:123]
	v_mfma_f32_16x16x32_bf16 v[56:59], v[210:213], v[160:163], v[56:59]
	v_mfma_f32_16x16x32_bf16 v[112:115], v[202:205], v[168:171], v[112:115]
	v_mfma_f32_16x16x32_bf16 v[80:83], v[210:213], v[168:171], v[80:83]
	v_mfma_f32_16x16x32_bf16 v[100:103], v[202:205], v[176:179], v[100:103]
	v_mfma_f32_16x16x32_bf16 v[96:99], v[210:213], v[176:179], v[96:99]
	v_mfma_f32_16x16x32_bf16 v[76:79], v[202:205], v[188:191], v[76:79]
	v_mfma_f32_16x16x32_bf16 v[72:75], v[210:213], v[188:191], v[72:75]
	v_mfma_f32_16x16x32_bf16 v[120:123], v[206:209], v[164:167], v[120:123]
	v_mfma_f32_16x16x32_bf16 v[56:59], v[214:217], v[164:167], v[56:59]
	v_mfma_f32_16x16x32_bf16 v[112:115], v[206:209], v[172:175], v[112:115]
	v_mfma_f32_16x16x32_bf16 v[80:83], v[214:217], v[172:175], v[80:83]
	v_mfma_f32_16x16x32_bf16 v[100:103], v[206:209], v[180:183], v[100:103]
	v_mfma_f32_16x16x32_bf16 v[96:99], v[214:217], v[180:183], v[96:99]
	v_mfma_f32_16x16x32_bf16 v[76:79], v[206:209], v[192:195], v[76:79]
	v_mfma_f32_16x16x32_bf16 v[72:75], v[214:217], v[192:195], v[72:75]
	s_barrier
	s_setprio 0
	s_mov_b32 m0, s3
	v_lshl_add_u64 v[218:219], s[24:25], 0, v[128:129]
	ds_read_b128 v[160:163], v143 offset:16384
	ds_read_b128 v[164:167], v143 offset:17408
	ds_read_b128 v[168:171], v143 offset:18432
	ds_read_b128 v[172:175], v143 offset:19456
	ds_read_b128 v[176:179], v143 offset:20480
	ds_read_b128 v[180:183], v143 offset:21504
	ds_read_b128 v[188:191], v143 offset:22528
	ds_read_b128 v[192:195], v143 offset:23552
	global_load_lds_dwordx4 v[218:219], off
	v_lshl_add_u64 v[220:221], s[24:25], 0, v[130:131]
	s_mov_b32 m0, s36
	s_nop 0
	global_load_lds_dwordx4 v[220:221], off
	s_setprio 1
	s_barrier
	s_waitcnt lgkmcnt(0)
	v_mfma_f32_16x16x32_bf16 v[64:67], v[144:147], v[160:163], v[64:67]
	v_mfma_f32_16x16x32_bf16 v[60:63], v[152:155], v[160:163], v[60:63]
	v_mfma_f32_16x16x32_bf16 v[44:47], v[144:147], v[168:171], v[44:47]
	v_mfma_f32_16x16x32_bf16 v[40:43], v[152:155], v[168:171], v[40:43]
	v_mfma_f32_16x16x32_bf16 v[28:31], v[144:147], v[176:179], v[28:31]
	v_mfma_f32_16x16x32_bf16 v[24:27], v[152:155], v[176:179], v[24:27]
	v_mfma_f32_16x16x32_bf16 v[12:15], v[144:147], v[188:191], v[12:15]
	v_mfma_f32_16x16x32_bf16 v[8:11], v[152:155], v[188:191], v[8:11]
	v_mfma_f32_16x16x32_bf16 v[64:67], v[148:151], v[164:167], v[64:67]
	v_mfma_f32_16x16x32_bf16 v[60:63], v[156:159], v[164:167], v[60:63]
	v_mfma_f32_16x16x32_bf16 v[44:47], v[148:151], v[172:175], v[44:47]
	v_mfma_f32_16x16x32_bf16 v[40:43], v[156:159], v[172:175], v[40:43]
	v_mfma_f32_16x16x32_bf16 v[28:31], v[148:151], v[180:183], v[28:31]
	v_mfma_f32_16x16x32_bf16 v[24:27], v[156:159], v[180:183], v[24:27]
	v_mfma_f32_16x16x32_bf16 v[12:15], v[148:151], v[192:195], v[12:15]
	v_mfma_f32_16x16x32_bf16 v[8:11], v[156:159], v[192:195], v[8:11]
	s_barrier
	s_setprio 0
	s_add_u32 s52, s4, 0x80000
	s_addc_u32 s53, s5, 0
	s_add_i32 s51, s54, s35
	v_lshl_add_u64 v[144:145], s[52:53], 0, v[184:185]
	s_mov_b32 m0, s51
	s_nop 0
	global_load_lds_dwordx4 v[144:145], off
	v_lshl_add_u64 v[144:145], s[52:53], 0, v[132:133]
	s_add_i32 m0, s51, 0x2000
	s_nop 0
	global_load_lds_dwordx4 v[144:145], off
	s_waitcnt vmcnt(6)
	s_setprio 1
	s_barrier
	v_mfma_f32_16x16x32_bf16 v[52:55], v[202:205], v[160:163], v[52:55]
	v_mfma_f32_16x16x32_bf16 v[48:51], v[210:213], v[160:163], v[48:51]
	v_mfma_f32_16x16x32_bf16 v[36:39], v[202:205], v[168:171], v[36:39]
	v_mfma_f32_16x16x32_bf16 v[32:35], v[210:213], v[168:171], v[32:35]
	v_mfma_f32_16x16x32_bf16 v[20:23], v[202:205], v[176:179], v[20:23]
	v_mfma_f32_16x16x32_bf16 v[16:19], v[210:213], v[176:179], v[16:19]
	v_mfma_f32_16x16x32_bf16 v[4:7], v[202:205], v[188:191], v[4:7]
	v_mfma_f32_16x16x32_bf16 v[0:3], v[210:213], v[188:191], v[0:3]
	v_mfma_f32_16x16x32_bf16 v[52:55], v[206:209], v[164:167], v[52:55]
	v_mfma_f32_16x16x32_bf16 v[48:51], v[214:217], v[164:167], v[48:51]
	v_mfma_f32_16x16x32_bf16 v[36:39], v[206:209], v[172:175], v[36:39]
	v_mfma_f32_16x16x32_bf16 v[32:35], v[214:217], v[172:175], v[32:35]
	v_mfma_f32_16x16x32_bf16 v[20:23], v[206:209], v[180:183], v[20:23]
	v_mfma_f32_16x16x32_bf16 v[16:19], v[214:217], v[180:183], v[16:19]
	v_mfma_f32_16x16x32_bf16 v[4:7], v[206:209], v[192:195], v[4:7]
	v_mfma_f32_16x16x32_bf16 v[0:3], v[214:217], v[192:195], v[0:3]
	s_barrier
	s_setprio 0
	s_add_i32 s51, 0, 0x18000
	v_add_u32_e32 v156, s51, v142
	ds_read_b128 v[144:147], v156
	ds_read_b128 v[148:151], v156 offset:1024
	ds_read_b128 v[152:155], v156 offset:2048
	ds_read_b128 v[156:159], v156 offset:3072
	s_add_u32 s24, s24, 0x80000
	s_addc_u32 s25, s25, 0
	s_mov_b32 m0, s37
	v_lshl_add_u64 v[202:203], s[24:25], 0, v[128:129]
	ds_read_b128 v[160:163], v143 offset:32768
	ds_read_b128 v[164:167], v143 offset:33792
	ds_read_b128 v[168:171], v143 offset:34816
	ds_read_b128 v[172:175], v143 offset:35840
	ds_read_b128 v[176:179], v143 offset:36864
	ds_read_b128 v[180:183], v143 offset:37888
	ds_read_b128 v[188:191], v143 offset:38912
	ds_read_b128 v[192:195], v143 offset:39936
	global_load_lds_dwordx4 v[202:203], off
	v_lshl_add_u64 v[202:203], s[24:25], 0, v[130:131]
	s_mov_b32 m0, s38
	s_nop 0
	global_load_lds_dwordx4 v[202:203], off
	s_waitcnt lgkmcnt(8)
	s_setprio 1
	s_barrier
	s_waitcnt lgkmcnt(0)
	v_mfma_f32_16x16x32_bf16 v[124:127], v[144:147], v[160:163], v[124:127]
	v_mfma_f32_16x16x32_bf16 v[68:71], v[152:155], v[160:163], v[68:71]
	v_mfma_f32_16x16x32_bf16 v[116:119], v[144:147], v[168:171], v[116:119]
	v_mfma_f32_16x16x32_bf16 v[88:91], v[152:155], v[168:171], v[88:91]
	v_mfma_f32_16x16x32_bf16 v[108:111], v[144:147], v[176:179], v[108:111]
	v_mfma_f32_16x16x32_bf16 v[104:107], v[152:155], v[176:179], v[104:107]
	v_mfma_f32_16x16x32_bf16 v[92:95], v[144:147], v[188:191], v[92:95]
	v_mfma_f32_16x16x32_bf16 v[84:87], v[152:155], v[188:191], v[84:87]
	v_mfma_f32_16x16x32_bf16 v[124:127], v[148:151], v[164:167], v[124:127]
	v_mfma_f32_16x16x32_bf16 v[68:71], v[156:159], v[164:167], v[68:71]
	v_mfma_f32_16x16x32_bf16 v[116:119], v[148:151], v[172:175], v[116:119]
	v_mfma_f32_16x16x32_bf16 v[88:91], v[156:159], v[172:175], v[88:91]
	v_mfma_f32_16x16x32_bf16 v[108:111], v[148:151], v[180:183], v[108:111]
	v_mfma_f32_16x16x32_bf16 v[104:107], v[156:159], v[180:183], v[104:107]
	v_mfma_f32_16x16x32_bf16 v[92:95], v[148:151], v[192:195], v[92:95]
	v_mfma_f32_16x16x32_bf16 v[84:87], v[156:159], v[192:195], v[84:87]
	s_barrier
	s_setprio 0
	s_add_i32 s24, 0, 0x1c000
	s_add_i32 s25, s51, s35
	v_add_u32_e32 v187, s24, v142
	v_lshl_add_u64 v[138:139], v[138:139], 0, s[56:57]
	s_mov_b32 m0, s25
	ds_read_b128 v[202:205], v187
	ds_read_b128 v[206:209], v187 offset:1024
	ds_read_b128 v[210:213], v187 offset:2048
	ds_read_b128 v[214:217], v187 offset:3072
	global_load_lds_dwordx4 v[138:139], off
	v_lshl_add_u64 v[138:139], v[196:197], 0, s[56:57]
	s_add_i32 m0, s25, 0x2000
	s_nop 0
	global_load_lds_dwordx4 v[138:139], off
	s_setprio 1
	s_barrier
	s_waitcnt lgkmcnt(0)
	v_mfma_f32_16x16x32_bf16 v[120:123], v[202:205], v[160:163], v[120:123]
	v_mfma_f32_16x16x32_bf16 v[56:59], v[210:213], v[160:163], v[56:59]
	v_mfma_f32_16x16x32_bf16 v[112:115], v[202:205], v[168:171], v[112:115]
	v_mfma_f32_16x16x32_bf16 v[80:83], v[210:213], v[168:171], v[80:83]
	v_mfma_f32_16x16x32_bf16 v[100:103], v[202:205], v[176:179], v[100:103]
	v_mfma_f32_16x16x32_bf16 v[96:99], v[210:213], v[176:179], v[96:99]
	v_mfma_f32_16x16x32_bf16 v[76:79], v[202:205], v[188:191], v[76:79]
	v_mfma_f32_16x16x32_bf16 v[72:75], v[210:213], v[188:191], v[72:75]
	v_mfma_f32_16x16x32_bf16 v[120:123], v[206:209], v[164:167], v[120:123]
	v_mfma_f32_16x16x32_bf16 v[56:59], v[214:217], v[164:167], v[56:59]
	v_mfma_f32_16x16x32_bf16 v[112:115], v[206:209], v[172:175], v[112:115]
	v_mfma_f32_16x16x32_bf16 v[80:83], v[214:217], v[172:175], v[80:83]
	v_mfma_f32_16x16x32_bf16 v[100:103], v[206:209], v[180:183], v[100:103]
	v_mfma_f32_16x16x32_bf16 v[96:99], v[214:217], v[180:183], v[96:99]
	v_mfma_f32_16x16x32_bf16 v[76:79], v[206:209], v[192:195], v[76:79]
	v_mfma_f32_16x16x32_bf16 v[72:75], v[214:217], v[192:195], v[72:75]
	s_barrier
	s_setprio 0
	s_mov_b32 m0, s41
	v_lshl_add_u64 v[138:139], v[218:219], 0, s[56:57]
	ds_read_b128 v[160:163], v143 offset:49152
	ds_read_b128 v[164:167], v143 offset:50176
	ds_read_b128 v[168:171], v143 offset:51200
	ds_read_b128 v[172:175], v143 offset:52224
	ds_read_b128 v[176:179], v143 offset:53248
	ds_read_b128 v[180:183], v143 offset:54272
	ds_read_b128 v[188:191], v143 offset:55296
	ds_read_b128 v[192:195], v143 offset:56320
	global_load_lds_dwordx4 v[138:139], off
	v_lshl_add_u64 v[138:139], v[220:221], 0, s[56:57]
	s_mov_b32 m0, s42
	s_nop 0
	global_load_lds_dwordx4 v[138:139], off
	s_setprio 1
	s_barrier
	s_waitcnt lgkmcnt(0)
	v_mfma_f32_16x16x32_bf16 v[64:67], v[144:147], v[160:163], v[64:67]
	v_mfma_f32_16x16x32_bf16 v[60:63], v[152:155], v[160:163], v[60:63]
	v_mfma_f32_16x16x32_bf16 v[44:47], v[144:147], v[168:171], v[44:47]
	v_mfma_f32_16x16x32_bf16 v[40:43], v[152:155], v[168:171], v[40:43]
	v_mfma_f32_16x16x32_bf16 v[28:31], v[144:147], v[176:179], v[28:31]
	v_mfma_f32_16x16x32_bf16 v[24:27], v[152:155], v[176:179], v[24:27]
	v_mfma_f32_16x16x32_bf16 v[12:15], v[144:147], v[188:191], v[12:15]
	v_mfma_f32_16x16x32_bf16 v[8:11], v[152:155], v[188:191], v[8:11]
	v_mfma_f32_16x16x32_bf16 v[64:67], v[148:151], v[164:167], v[64:67]
	v_mfma_f32_16x16x32_bf16 v[60:63], v[156:159], v[164:167], v[60:63]
	v_mfma_f32_16x16x32_bf16 v[44:47], v[148:151], v[172:175], v[44:47]
	v_mfma_f32_16x16x32_bf16 v[40:43], v[156:159], v[172:175], v[40:43]
	v_mfma_f32_16x16x32_bf16 v[28:31], v[148:151], v[180:183], v[28:31]
	v_mfma_f32_16x16x32_bf16 v[24:27], v[156:159], v[180:183], v[24:27]
	v_mfma_f32_16x16x32_bf16 v[12:15], v[148:151], v[192:195], v[12:15]
	v_mfma_f32_16x16x32_bf16 v[8:11], v[156:159], v[192:195], v[8:11]
	s_barrier
	s_setprio 0
	s_add_u32 s4, s4, 0x80080
	s_addc_u32 s5, s5, 0
	s_add_i32 s24, s24, s35
	v_lshl_add_u64 v[138:139], s[4:5], 0, v[184:185]
	s_mov_b32 m0, s24
	s_nop 0
	global_load_lds_dwordx4 v[138:139], off
	v_lshl_add_u64 v[138:139], s[4:5], 0, v[132:133]
	s_add_i32 m0, s24, 0x2000
	s_nop 0
	global_load_lds_dwordx4 v[138:139], off
	s_waitcnt vmcnt(6)
	s_setprio 1
	s_barrier
	v_mfma_f32_16x16x32_bf16 v[52:55], v[202:205], v[160:163], v[52:55]
	v_mfma_f32_16x16x32_bf16 v[48:51], v[210:213], v[160:163], v[48:51]
	v_mfma_f32_16x16x32_bf16 v[36:39], v[202:205], v[168:171], v[36:39]
	v_mfma_f32_16x16x32_bf16 v[32:35], v[210:213], v[168:171], v[32:35]
	v_mfma_f32_16x16x32_bf16 v[20:23], v[202:205], v[176:179], v[20:23]
	v_mfma_f32_16x16x32_bf16 v[16:19], v[210:213], v[176:179], v[16:19]
	v_mfma_f32_16x16x32_bf16 v[4:7], v[202:205], v[188:191], v[4:7]
	v_mfma_f32_16x16x32_bf16 v[0:3], v[210:213], v[188:191], v[0:3]
	v_mfma_f32_16x16x32_bf16 v[52:55], v[206:209], v[164:167], v[52:55]
	v_mfma_f32_16x16x32_bf16 v[48:51], v[214:217], v[164:167], v[48:51]
	v_mfma_f32_16x16x32_bf16 v[36:39], v[206:209], v[172:175], v[36:39]
	v_mfma_f32_16x16x32_bf16 v[32:35], v[214:217], v[172:175], v[32:35]
	v_mfma_f32_16x16x32_bf16 v[20:23], v[206:209], v[180:183], v[20:23]
	v_mfma_f32_16x16x32_bf16 v[16:19], v[214:217], v[180:183], v[16:19]
	v_mfma_f32_16x16x32_bf16 v[4:7], v[206:209], v[192:195], v[4:7]
	v_mfma_f32_16x16x32_bf16 v[0:3], v[214:217], v[192:195], v[0:3]
	s_barrier
	s_setprio 0
	s_add_i32 s50, s50, 2
	s_add_u32 s0, s0, 0x100
	s_addc_u32 s1, s1, 0
	s_add_u32 s48, s48, 0x100
	s_addc_u32 s49, s49, 0
	s_cmp_gt_u32 s50, 29
	s_cbranch_scc0 .LBB0_334
	v_mul_f32_e32 v148, 0x3d372713, v125
	v_fma_f32 v148, v125, v148, 1.0
	v_mul_f32_e32 v148, v125, v148
	v_mul_f32_e32 v139, 0x3d372713, v124
	v_mul_f32_e32 v148, 0xc0135761, v148
	v_fma_f32 v139, v124, v139, 1.0
	v_exp_f32_e32 v148, v148
	v_mul_f32_e32 v149, 0x3d372713, v126
	v_mul_f32_e32 v139, v124, v139
	v_fma_f32 v149, v126, v149, 1.0
	v_mul_f32_e32 v139, 0xc0135761, v139
	v_mul_f32_e32 v149, v126, v149
	v_exp_f32_e32 v145, v139
	v_mul_f32_e32 v149, 0xc0135761, v149
	v_exp_f32_e32 v149, v149
	v_add_f32_e32 v148, 1.0, v148
	v_mul_f32_e32 v150, 0x3d372713, v127
	v_rcp_f32_e32 v148, v148
	v_fma_f32 v150, v127, v150, 1.0
	v_mul_f32_e32 v150, v127, v150
	v_add_f32_e32 v145, 1.0, v145
	v_mul_f32_e32 v150, 0xc0135761, v150
	v_rcp_f32_e32 v145, v145
	v_add_f32_e32 v149, 1.0, v149
	v_exp_f32_e32 v150, v150
	v_rcp_f32_e32 v149, v149
	v_mul_f32_e32 v125, v125, v148
	v_mul_f32_e32 v148, 0x3d372713, v68
	v_fma_f32 v148, v68, v148, 1.0
	v_mul_f32_e32 v148, v68, v148
	v_mul_f32_e32 v124, v124, v145
	v_add_f32_e32 v145, 1.0, v150
	v_mul_f32_e32 v148, 0xc0135761, v148
	v_mul_f32_e32 v126, v126, v149
	v_rcp_f32_e32 v145, v145
	v_exp_f32_e32 v148, v148
	v_mul_f32_e32 v149, 0x3d372713, v69
	v_fma_f32 v149, v69, v149, 1.0
	v_mul_f32_e32 v149, v69, v149
	v_mul_f32_e32 v149, 0xc0135761, v149
	v_exp_f32_e32 v149, v149
	v_mul_f32_e32 v127, v127, v145
	v_add_f32_e32 v145, 1.0, v148
	v_rcp_f32_e32 v145, v145
	v_mov_b32_e32 v138, v141
	v_mov_b32_e32 v144, v140
	s_lshl_b32 s0, s2, 8
	v_add_f32_e32 v148, 1.0, v149
	s_add_i32 s0, s0, s39
	v_mul_f32_e32 v149, 0x3d372713, v70
	v_rcp_f32_e32 v148, v148
	v_mul_f32_e32 v145, v68, v145
	v_cvt_pk_bf16_f32 v68, v124, v125
	v_mul_f32_e32 v124, 0x3d372713, v120
	v_add_u32_e32 v146, s0, v144
	s_lshl_b32 s0, s45, 8
	v_fma_f32 v149, v70, v149, 1.0
	v_fma_f32 v124, v120, v124, 1.0
	s_or_b32 s0, s0, s40
	v_ashrrev_i32_e32 v147, 31, v146
	v_mul_f32_e32 v149, v70, v149
	v_mul_f32_e32 v124, v120, v124
	v_lshl_add_u32 v138, v138, 3, s0
	v_lshlrev_b64 v[146:147], 16, v[146:147]
	v_mul_f32_e32 v149, 0xc0135761, v149
	v_mul_f32_e32 v124, 0xc0135761, v124
	v_ashrrev_i32_e32 v139, 31, v138
	v_exp_f32_e32 v149, v149
	v_mul_f32_e32 v148, v69, v148
	v_cvt_pk_bf16_f32 v69, v126, v127
	v_exp_f32_e32 v126, v124
	v_lshl_add_u64 v[124:125], s[8:9], 0, v[146:147]
	v_lshl_add_u64 v[124:125], v[138:139], 1, v[124:125]
	v_mul_f32_e32 v127, 0x3d372713, v121
	v_mul_f32_e32 v139, 0x3d372713, v122
	v_fma_f32 v127, v121, v127, 1.0
	v_fma_f32 v139, v122, v139, 1.0
	v_mul_f32_e32 v127, v121, v127
	v_mul_f32_e32 v139, v122, v139
	v_add_f32_e32 v149, 1.0, v149
	v_mul_f32_e32 v127, 0xc0135761, v127
	v_mul_f32_e32 v139, 0xc0135761, v139
	v_rcp_f32_e32 v149, v149
	v_exp_f32_e32 v127, v127
	v_exp_f32_e32 v139, v139
	v_add_f32_e32 v126, 1.0, v126
	v_mul_f32_e32 v149, v70, v149
	v_cvt_pk_bf16_f32 v70, v145, v148
	v_add_f32_e32 v127, 1.0, v127
	v_add_f32_e32 v139, 1.0, v139
	v_mul_f32_e32 v145, 0x3d372713, v123
	v_rcp_f32_e32 v127, v127
	v_rcp_f32_e32 v139, v139
	v_fma_f32 v145, v123, v145, 1.0
	v_mul_f32_e32 v145, v123, v145
	v_mul_f32_e32 v145, 0xc0135761, v145
	v_rcp_f32_e32 v126, v126
	v_exp_f32_e32 v145, v145
	v_mul_f32_e32 v121, v121, v127
	v_mul_f32_e32 v122, v122, v139
	v_mul_f32_e32 v127, 0x3d372713, v56
	v_mul_f32_e32 v139, 0x3d372713, v57
	v_fma_f32 v127, v56, v127, 1.0
	v_fma_f32 v139, v57, v139, 1.0
	v_mul_f32_e32 v127, v56, v127
	v_mul_f32_e32 v139, v57, v139
	v_mul_f32_e32 v120, v120, v126
	v_add_f32_e32 v126, 1.0, v145
	v_mul_f32_e32 v127, 0xc0135761, v127
	v_mul_f32_e32 v139, 0xc0135761, v139
	v_mul_f32_e32 v150, 0x3d372713, v71
	v_rcp_f32_e32 v126, v126
	v_exp_f32_e32 v127, v127
	v_exp_f32_e32 v139, v139
	v_fma_f32 v150, v71, v150, 1.0
	v_mul_f32_e32 v150, v71, v150
	v_mul_f32_e32 v150, 0xc0135761, v150
	v_exp_f32_e32 v150, v150
	v_mul_f32_e32 v123, v123, v126
	v_add_f32_e32 v126, 1.0, v127
	v_add_f32_e32 v127, 1.0, v139
	v_mul_f32_e32 v139, 0x3d372713, v58
	v_fma_f32 v139, v58, v139, 1.0
	v_mul_f32_e32 v139, v58, v139
	v_mul_f32_e32 v139, 0xc0135761, v139
	v_add_f32_e32 v150, 1.0, v150
	v_exp_f32_e32 v139, v139
	v_rcp_f32_e32 v150, v150
	v_rcp_f32_e32 v126, v126
	v_rcp_f32_e32 v127, v127
	v_add_f32_e32 v139, 1.0, v139
	v_mul_f32_e32 v71, v71, v150
	v_rcp_f32_e32 v139, v139
	v_cvt_pk_bf16_f32 v71, v149, v71
	global_store_dwordx4 v[124:125], v[68:71], off
	v_mul_f32_e32 v126, v56, v126
	v_mul_f32_e32 v127, v57, v127
	v_cvt_pk_bf16_f32 v56, v120, v121
	v_cvt_pk_bf16_f32 v57, v122, v123
	v_mul_f32_e32 v121, 0x3d372713, v117
	v_mul_f32_e32 v122, 0x3d372713, v118
	v_fma_f32 v121, v117, v121, 1.0
	v_fma_f32 v122, v118, v122, 1.0
	v_mul_f32_e32 v121, v117, v121
	v_mul_f32_e32 v122, v118, v122
	v_mul_f32_e32 v139, v58, v139
	v_mul_f32_e32 v58, 0x3d372713, v116
	v_mul_f32_e32 v121, 0xc0135761, v121
	v_mul_f32_e32 v122, 0xc0135761, v122
	v_fma_f32 v58, v116, v58, 1.0
	v_exp_f32_e32 v121, v121
	v_exp_f32_e32 v122, v122
	v_mul_f32_e32 v58, v116, v58
	v_mul_f32_e32 v58, 0xc0135761, v58
	v_exp_f32_e32 v120, v58
	v_add_f32_e32 v121, 1.0, v121
	v_add_f32_e32 v122, 1.0, v122
	v_mul_f32_e32 v123, 0x3d372713, v119
	v_rcp_f32_e32 v121, v121
	v_rcp_f32_e32 v122, v122
	v_fma_f32 v123, v119, v123, 1.0
	v_mul_f32_e32 v123, v119, v123
	v_add_f32_e32 v120, 1.0, v120
	v_mul_f32_e32 v123, 0xc0135761, v123
	v_rcp_f32_e32 v120, v120
	v_exp_f32_e32 v123, v123
	v_mul_f32_e32 v117, v117, v121
	v_mul_f32_e32 v118, v118, v122
	v_mul_f32_e32 v121, 0x3d372713, v88
	v_mul_f32_e32 v122, 0x3d372713, v89
	v_fma_f32 v121, v88, v121, 1.0
	v_fma_f32 v122, v89, v122, 1.0
	v_mul_f32_e32 v121, v88, v121
	v_mul_f32_e32 v122, v89, v122
	v_mul_f32_e32 v145, 0x3d372713, v59
	v_mul_f32_e32 v116, v116, v120
	v_add_f32_e32 v120, 1.0, v123
	v_mul_f32_e32 v121, 0xc0135761, v121
	v_mul_f32_e32 v122, 0xc0135761, v122
	v_fma_f32 v145, v59, v145, 1.0
	v_rcp_f32_e32 v120, v120
	v_exp_f32_e32 v121, v121
	v_exp_f32_e32 v122, v122
	v_mul_f32_e32 v145, v59, v145
	v_mul_f32_e32 v145, 0xc0135761, v145
	v_exp_f32_e32 v145, v145
	v_mul_f32_e32 v119, v119, v120
	v_add_f32_e32 v120, 1.0, v121
	v_add_f32_e32 v121, 1.0, v122
	v_mul_f32_e32 v122, 0x3d372713, v90
	v_fma_f32 v122, v90, v122, 1.0
	v_mul_f32_e32 v122, v90, v122
	v_add_f32_e32 v145, 1.0, v145
	v_mul_f32_e32 v122, 0xc0135761, v122
	v_mul_f32_e32 v123, 0x3d372713, v91
	v_rcp_f32_e32 v145, v145
	v_exp_f32_e32 v122, v122
	v_fma_f32 v123, v91, v123, 1.0
	v_rcp_f32_e32 v120, v120
	v_mul_f32_e32 v123, v91, v123
	v_rcp_f32_e32 v121, v121
	v_mul_f32_e32 v123, 0xc0135761, v123
	v_exp_f32_e32 v123, v123
	v_mul_f32_e32 v59, v59, v145
	v_add_f32_e32 v122, 1.0, v122
	v_cvt_pk_bf16_f32 v58, v126, v127
	v_cvt_pk_bf16_f32 v59, v139, v59
	global_store_dwordx4 v[124:125], v[56:59], off offset:256
	v_rcp_f32_e32 v122, v122
	v_mul_f32_e32 v120, v88, v120
	v_mul_f32_e32 v121, v89, v121
	v_cvt_pk_bf16_f32 v88, v116, v117
	v_cvt_pk_bf16_f32 v89, v118, v119
	v_mul_f32_e32 v118, 0x3d372713, v112
	v_fma_f32 v118, v112, v118, 1.0
	v_add_f32_e32 v123, 1.0, v123
	v_mul_f32_e32 v118, v112, v118
	v_rcp_f32_e32 v123, v123
	v_mul_f32_e32 v118, 0xc0135761, v118
	v_mul_f32_e32 v122, v90, v122
	v_cvt_pk_bf16_f32 v90, v120, v121
	s_mov_b64 s[0:1], 0x100000
	v_exp_f32_e32 v120, v118
	v_lshl_add_u64 v[116:117], v[124:125], 0, s[0:1]
	s_mov_b32 s0, 0x100000
	v_add_co_u32_e32 v118, vcc, s0, v124
	v_mul_f32_e32 v91, v91, v123
	s_nop 0
	v_addc_co_u32_e32 v119, vcc, 0, v125, vcc
	v_cvt_pk_bf16_f32 v91, v122, v91
	global_store_dwordx4 v[118:119], v[88:91], off
	v_add_f32_e32 v118, 1.0, v120
	v_mul_f32_e32 v119, 0x3d372713, v113
	v_mul_f32_e32 v120, 0x3d372713, v114
	v_fma_f32 v119, v113, v119, 1.0
	v_fma_f32 v120, v114, v120, 1.0
	v_mul_f32_e32 v119, v113, v119
	v_mul_f32_e32 v120, v114, v120
	v_mul_f32_e32 v119, 0xc0135761, v119
	v_mul_f32_e32 v120, 0xc0135761, v120
	v_exp_f32_e32 v119, v119
	v_exp_f32_e32 v120, v120
	v_mul_f32_e32 v121, 0x3d372713, v115
	v_fma_f32 v121, v115, v121, 1.0
	v_add_f32_e32 v119, 1.0, v119
	v_add_f32_e32 v120, 1.0, v120
	v_rcp_f32_e32 v119, v119
	v_rcp_f32_e32 v120, v120
	v_mul_f32_e32 v121, v115, v121
	v_mul_f32_e32 v121, 0xc0135761, v121
	v_rcp_f32_e32 v118, v118
	v_exp_f32_e32 v121, v121
	v_mul_f32_e32 v113, v113, v119
	v_mul_f32_e32 v114, v114, v120
	v_mul_f32_e32 v119, 0x3d372713, v80
	v_mul_f32_e32 v120, 0x3d372713, v81
	v_fma_f32 v119, v80, v119, 1.0
	v_fma_f32 v120, v81, v120, 1.0
	v_mul_f32_e32 v119, v80, v119
	v_mul_f32_e32 v120, v81, v120
	v_mul_f32_e32 v112, v112, v118
	v_add_f32_e32 v118, 1.0, v121
	v_mul_f32_e32 v119, 0xc0135761, v119
	v_mul_f32_e32 v120, 0xc0135761, v120
	v_rcp_f32_e32 v118, v118
	v_exp_f32_e32 v119, v119
	v_exp_f32_e32 v120, v120
	v_mul_f32_e32 v121, 0x3d372713, v83
	v_mul_f32_e32 v115, v115, v118
	v_add_f32_e32 v118, 1.0, v119
	v_add_f32_e32 v119, 1.0, v120
	v_mul_f32_e32 v120, 0x3d372713, v82
	v_fma_f32 v120, v82, v120, 1.0
	v_mul_f32_e32 v120, v82, v120
	v_mul_f32_e32 v120, 0xc0135761, v120
	v_exp_f32_e32 v120, v120
	v_rcp_f32_e32 v118, v118
	v_rcp_f32_e32 v119, v119
	v_fma_f32 v121, v83, v121, 1.0
	v_add_f32_e32 v120, 1.0, v120
	v_rcp_f32_e32 v120, v120
	v_mul_f32_e32 v118, v80, v118
	v_mul_f32_e32 v119, v81, v119
	v_cvt_pk_bf16_f32 v80, v112, v113
	v_cvt_pk_bf16_f32 v81, v114, v115
	v_mul_f32_e32 v113, 0x3d372713, v109
	v_mul_f32_e32 v114, 0x3d372713, v110
	v_fma_f32 v113, v109, v113, 1.0
	v_fma_f32 v114, v110, v114, 1.0
	v_mul_f32_e32 v113, v109, v113
	v_mul_f32_e32 v114, v110, v114
	v_mul_f32_e32 v120, v82, v120
	v_mul_f32_e32 v82, 0x3d372713, v108
	v_mul_f32_e32 v113, 0xc0135761, v113
	v_mul_f32_e32 v114, 0xc0135761, v114
	v_fma_f32 v82, v108, v82, 1.0
	v_exp_f32_e32 v113, v113
	v_exp_f32_e32 v114, v114
	v_mul_f32_e32 v82, v108, v82
	v_mul_f32_e32 v82, 0xc0135761, v82
	v_exp_f32_e32 v112, v82
	v_add_f32_e32 v113, 1.0, v113
	v_add_f32_e32 v114, 1.0, v114
	v_mul_f32_e32 v115, 0x3d372713, v111
	v_rcp_f32_e32 v113, v113
	v_rcp_f32_e32 v114, v114
	v_fma_f32 v115, v111, v115, 1.0
	v_mul_f32_e32 v115, v111, v115
	v_add_f32_e32 v112, 1.0, v112
	v_mul_f32_e32 v115, 0xc0135761, v115
	v_rcp_f32_e32 v112, v112
	v_exp_f32_e32 v115, v115
	v_mul_f32_e32 v109, v109, v113
	v_mul_f32_e32 v110, v110, v114
	v_mul_f32_e32 v113, 0x3d372713, v104
	v_mul_f32_e32 v114, 0x3d372713, v105
	v_fma_f32 v113, v104, v113, 1.0
	v_fma_f32 v114, v105, v114, 1.0
	v_mul_f32_e32 v113, v104, v113
	v_mul_f32_e32 v114, v105, v114
	v_mul_f32_e32 v108, v108, v112
	v_add_f32_e32 v112, 1.0, v115
	v_mul_f32_e32 v113, 0xc0135761, v113
	v_mul_f32_e32 v114, 0xc0135761, v114
	v_rcp_f32_e32 v112, v112
	v_exp_f32_e32 v113, v113
	v_exp_f32_e32 v114, v114
	v_mul_f32_e32 v121, v83, v121
	v_mul_f32_e32 v121, 0xc0135761, v121
	v_exp_f32_e32 v121, v121
	v_mul_f32_e32 v111, v111, v112
	v_add_f32_e32 v112, 1.0, v113
	v_add_f32_e32 v113, 1.0, v114
	v_mul_f32_e32 v114, 0x3d372713, v106
	v_fma_f32 v114, v106, v114, 1.0
	v_mul_f32_e32 v114, v106, v114
	v_add_f32_e32 v121, 1.0, v121
	v_mul_f32_e32 v114, 0xc0135761, v114
	v_mul_f32_e32 v115, 0x3d372713, v107
	v_rcp_f32_e32 v121, v121
	v_exp_f32_e32 v114, v114
	v_fma_f32 v115, v107, v115, 1.0
	v_rcp_f32_e32 v112, v112
	v_mul_f32_e32 v115, v107, v115
	v_rcp_f32_e32 v113, v113
	v_mul_f32_e32 v115, 0xc0135761, v115
	v_exp_f32_e32 v115, v115
	v_mul_f32_e32 v83, v83, v121
	v_add_f32_e32 v114, 1.0, v114
	v_cvt_pk_bf16_f32 v82, v118, v119
	v_cvt_pk_bf16_f32 v83, v120, v83
	global_store_dwordx4 v[116:117], v[80:83], off offset:256
	v_rcp_f32_e32 v114, v114
	v_mul_f32_e32 v112, v104, v112
	v_mul_f32_e32 v113, v105, v113
	v_cvt_pk_bf16_f32 v104, v108, v109
	v_cvt_pk_bf16_f32 v105, v110, v111
	v_mul_f32_e32 v110, 0x3d372713, v100
	v_fma_f32 v110, v100, v110, 1.0
	v_add_f32_e32 v115, 1.0, v115
	v_mul_f32_e32 v110, v100, v110
	v_rcp_f32_e32 v115, v115
	v_mul_f32_e32 v110, 0xc0135761, v110
	v_mul_f32_e32 v114, v106, v114
	v_cvt_pk_bf16_f32 v106, v112, v113
	s_mov_b64 s[0:1], 0x200000
	v_exp_f32_e32 v112, v110
	v_lshl_add_u64 v[108:109], v[124:125], 0, s[0:1]
	s_mov_b32 s0, 0x200000
	v_add_co_u32_e32 v110, vcc, s0, v124
	v_mul_f32_e32 v107, v107, v115
	s_nop 0
	v_addc_co_u32_e32 v111, vcc, 0, v125, vcc
	v_cvt_pk_bf16_f32 v107, v114, v107
	global_store_dwordx4 v[110:111], v[104:107], off
	v_add_f32_e32 v110, 1.0, v112
	v_mul_f32_e32 v111, 0x3d372713, v101
	v_mul_f32_e32 v112, 0x3d372713, v102
	v_fma_f32 v111, v101, v111, 1.0
	v_fma_f32 v112, v102, v112, 1.0
	v_mul_f32_e32 v111, v101, v111
	v_mul_f32_e32 v112, v102, v112
	v_mul_f32_e32 v111, 0xc0135761, v111
	v_mul_f32_e32 v112, 0xc0135761, v112
	v_exp_f32_e32 v111, v111
	v_exp_f32_e32 v112, v112
	v_mul_f32_e32 v113, 0x3d372713, v103
	v_fma_f32 v113, v103, v113, 1.0
	v_add_f32_e32 v111, 1.0, v111
	v_add_f32_e32 v112, 1.0, v112
	v_rcp_f32_e32 v111, v111
	v_rcp_f32_e32 v112, v112
	v_mul_f32_e32 v113, v103, v113
	v_mul_f32_e32 v113, 0xc0135761, v113
	v_rcp_f32_e32 v110, v110
	v_exp_f32_e32 v113, v113
	v_mul_f32_e32 v101, v101, v111
	v_mul_f32_e32 v102, v102, v112
	v_mul_f32_e32 v111, 0x3d372713, v96
	v_mul_f32_e32 v112, 0x3d372713, v97
	v_fma_f32 v111, v96, v111, 1.0
	v_fma_f32 v112, v97, v112, 1.0
	v_mul_f32_e32 v111, v96, v111
	v_mul_f32_e32 v112, v97, v112
	v_mul_f32_e32 v100, v100, v110
	v_add_f32_e32 v110, 1.0, v113
	v_mul_f32_e32 v111, 0xc0135761, v111
	v_mul_f32_e32 v112, 0xc0135761, v112
	v_rcp_f32_e32 v110, v110
	v_exp_f32_e32 v111, v111
	v_exp_f32_e32 v112, v112
	v_mul_f32_e32 v113, 0x3d372713, v99
	v_mul_f32_e32 v103, v103, v110
	v_add_f32_e32 v110, 1.0, v111
	v_add_f32_e32 v111, 1.0, v112
	v_mul_f32_e32 v112, 0x3d372713, v98
	v_fma_f32 v112, v98, v112, 1.0
	v_mul_f32_e32 v112, v98, v112
	v_mul_f32_e32 v112, 0xc0135761, v112
	v_exp_f32_e32 v112, v112
	v_rcp_f32_e32 v110, v110
	v_rcp_f32_e32 v111, v111
	v_fma_f32 v113, v99, v113, 1.0
	v_add_f32_e32 v112, 1.0, v112
	v_rcp_f32_e32 v112, v112
	v_mul_f32_e32 v110, v96, v110
	v_mul_f32_e32 v111, v97, v111
	v_cvt_pk_bf16_f32 v96, v100, v101
	v_cvt_pk_bf16_f32 v97, v102, v103
	v_mul_f32_e32 v101, 0x3d372713, v93
	v_mul_f32_e32 v102, 0x3d372713, v94
	v_fma_f32 v101, v93, v101, 1.0
	v_fma_f32 v102, v94, v102, 1.0
	v_mul_f32_e32 v101, v93, v101
	v_mul_f32_e32 v102, v94, v102
	v_mul_f32_e32 v112, v98, v112
	v_mul_f32_e32 v98, 0x3d372713, v92
	v_mul_f32_e32 v101, 0xc0135761, v101
	v_mul_f32_e32 v102, 0xc0135761, v102
	v_fma_f32 v98, v92, v98, 1.0
	v_exp_f32_e32 v101, v101
	v_exp_f32_e32 v102, v102
	v_mul_f32_e32 v98, v92, v98
	v_mul_f32_e32 v98, 0xc0135761, v98
	v_exp_f32_e32 v100, v98
	v_add_f32_e32 v101, 1.0, v101
	v_add_f32_e32 v102, 1.0, v102
	v_mul_f32_e32 v103, 0x3d372713, v95
	v_rcp_f32_e32 v101, v101
	v_rcp_f32_e32 v102, v102
	v_fma_f32 v103, v95, v103, 1.0
	v_mul_f32_e32 v103, v95, v103
	v_add_f32_e32 v100, 1.0, v100
	v_mul_f32_e32 v103, 0xc0135761, v103
	v_rcp_f32_e32 v100, v100
	v_exp_f32_e32 v103, v103
	v_mul_f32_e32 v93, v93, v101
	v_mul_f32_e32 v94, v94, v102
	v_mul_f32_e32 v101, 0x3d372713, v84
	v_mul_f32_e32 v102, 0x3d372713, v85
	v_fma_f32 v101, v84, v101, 1.0
	v_fma_f32 v102, v85, v102, 1.0
	v_mul_f32_e32 v101, v84, v101
	v_mul_f32_e32 v102, v85, v102
	v_mul_f32_e32 v92, v92, v100
	v_add_f32_e32 v100, 1.0, v103
	v_mul_f32_e32 v101, 0xc0135761, v101
	v_mul_f32_e32 v102, 0xc0135761, v102
	v_rcp_f32_e32 v100, v100
	v_exp_f32_e32 v101, v101
	v_exp_f32_e32 v102, v102
	v_mul_f32_e32 v113, v99, v113
	v_mul_f32_e32 v113, 0xc0135761, v113
	v_exp_f32_e32 v113, v113
	v_mul_f32_e32 v95, v95, v100
	v_add_f32_e32 v100, 1.0, v101
	v_add_f32_e32 v101, 1.0, v102
	v_mul_f32_e32 v102, 0x3d372713, v86
	v_fma_f32 v102, v86, v102, 1.0
	v_mul_f32_e32 v102, v86, v102
	v_add_f32_e32 v113, 1.0, v113
	v_mul_f32_e32 v102, 0xc0135761, v102
	v_mul_f32_e32 v103, 0x3d372713, v87
	v_rcp_f32_e32 v113, v113
	v_exp_f32_e32 v102, v102
	v_fma_f32 v103, v87, v103, 1.0
	v_rcp_f32_e32 v100, v100
	v_mul_f32_e32 v103, v87, v103
	v_rcp_f32_e32 v101, v101
	v_mul_f32_e32 v103, 0xc0135761, v103
	v_exp_f32_e32 v103, v103
	v_mul_f32_e32 v99, v99, v113
	v_add_f32_e32 v102, 1.0, v102
	v_cvt_pk_bf16_f32 v98, v110, v111
	v_cvt_pk_bf16_f32 v99, v112, v99
	global_store_dwordx4 v[108:109], v[96:99], off offset:256
	v_rcp_f32_e32 v102, v102
	v_mul_f32_e32 v100, v84, v100
	v_mul_f32_e32 v101, v85, v101
	v_cvt_pk_bf16_f32 v84, v92, v93
	v_cvt_pk_bf16_f32 v85, v94, v95
	v_mul_f32_e32 v94, 0x3d372713, v76
	v_fma_f32 v94, v76, v94, 1.0
	v_add_f32_e32 v103, 1.0, v103
	v_mul_f32_e32 v94, v76, v94
	v_rcp_f32_e32 v103, v103
	v_mul_f32_e32 v94, 0xc0135761, v94
	v_mul_f32_e32 v102, v86, v102
	v_cvt_pk_bf16_f32 v86, v100, v101
	s_mov_b64 s[0:1], 0x300000
	v_exp_f32_e32 v100, v94
	v_lshl_add_u64 v[92:93], v[124:125], 0, s[0:1]
	s_mov_b32 s0, 0x300000
	v_add_co_u32_e32 v94, vcc, s0, v124
	v_mul_f32_e32 v87, v87, v103
	s_nop 0
	v_addc_co_u32_e32 v95, vcc, 0, v125, vcc
	v_cvt_pk_bf16_f32 v87, v102, v87
	global_store_dwordx4 v[94:95], v[84:87], off
	v_add_f32_e32 v94, 1.0, v100
	v_mul_f32_e32 v95, 0x3d372713, v77
	v_mul_f32_e32 v100, 0x3d372713, v78
	v_fma_f32 v95, v77, v95, 1.0
	v_fma_f32 v100, v78, v100, 1.0
	v_mul_f32_e32 v95, v77, v95
	v_mul_f32_e32 v100, v78, v100
	v_mul_f32_e32 v95, 0xc0135761, v95
	v_mul_f32_e32 v100, 0xc0135761, v100
	v_exp_f32_e32 v95, v95
	v_exp_f32_e32 v100, v100
	v_mul_f32_e32 v101, 0x3d372713, v79
	v_fma_f32 v101, v79, v101, 1.0
	v_add_f32_e32 v95, 1.0, v95
	v_add_f32_e32 v100, 1.0, v100
	v_rcp_f32_e32 v95, v95
	v_rcp_f32_e32 v100, v100
	v_mul_f32_e32 v101, v79, v101
	v_mul_f32_e32 v101, 0xc0135761, v101
	v_rcp_f32_e32 v94, v94
	v_exp_f32_e32 v101, v101
	v_mul_f32_e32 v77, v77, v95
	v_mul_f32_e32 v78, v78, v100
	v_mul_f32_e32 v95, 0x3d372713, v72
	v_mul_f32_e32 v100, 0x3d372713, v73
	v_fma_f32 v95, v72, v95, 1.0
	v_fma_f32 v100, v73, v100, 1.0
	v_mul_f32_e32 v95, v72, v95
	v_mul_f32_e32 v100, v73, v100
	v_mul_f32_e32 v76, v76, v94
	v_add_f32_e32 v94, 1.0, v101
	v_mul_f32_e32 v95, 0xc0135761, v95
	v_mul_f32_e32 v100, 0xc0135761, v100
	v_rcp_f32_e32 v94, v94
	v_exp_f32_e32 v95, v95
	v_exp_f32_e32 v100, v100
	v_mul_f32_e32 v101, 0x3d372713, v75
	v_mul_f32_e32 v79, v79, v94
	v_add_f32_e32 v94, 1.0, v95
	v_add_f32_e32 v95, 1.0, v100
	v_mul_f32_e32 v100, 0x3d372713, v74
	v_fma_f32 v100, v74, v100, 1.0
	v_mul_f32_e32 v100, v74, v100
	v_mul_f32_e32 v100, 0xc0135761, v100
	v_exp_f32_e32 v100, v100
	v_rcp_f32_e32 v94, v94
	v_rcp_f32_e32 v95, v95
	v_fma_f32 v101, v75, v101, 1.0
	v_add_f32_e32 v100, 1.0, v100
	v_rcp_f32_e32 v100, v100
	v_mul_f32_e32 v94, v72, v94
	v_mul_f32_e32 v95, v73, v95
	v_cvt_pk_bf16_f32 v72, v76, v77
	v_cvt_pk_bf16_f32 v73, v78, v79
	v_mul_f32_e32 v77, 0x3d372713, v65
	v_mul_f32_e32 v78, 0x3d372713, v66
	v_fma_f32 v77, v65, v77, 1.0
	v_fma_f32 v78, v66, v78, 1.0
	v_mul_f32_e32 v77, v65, v77
	v_mul_f32_e32 v78, v66, v78
	v_mul_f32_e32 v100, v74, v100
	v_mul_f32_e32 v74, 0x3d372713, v64
	v_mul_f32_e32 v77, 0xc0135761, v77
	v_mul_f32_e32 v78, 0xc0135761, v78
	v_fma_f32 v74, v64, v74, 1.0
	v_exp_f32_e32 v77, v77
	v_exp_f32_e32 v78, v78
	v_mul_f32_e32 v74, v64, v74
	v_mul_f32_e32 v74, 0xc0135761, v74
	v_exp_f32_e32 v76, v74
	v_add_f32_e32 v77, 1.0, v77
	v_add_f32_e32 v78, 1.0, v78
	v_mul_f32_e32 v79, 0x3d372713, v67
	v_rcp_f32_e32 v77, v77
	v_rcp_f32_e32 v78, v78
	v_fma_f32 v79, v67, v79, 1.0
	v_mul_f32_e32 v79, v67, v79
	v_add_f32_e32 v76, 1.0, v76
	v_mul_f32_e32 v79, 0xc0135761, v79
	v_rcp_f32_e32 v76, v76
	v_exp_f32_e32 v79, v79
	v_mul_f32_e32 v65, v65, v77
	v_mul_f32_e32 v66, v66, v78
	v_mul_f32_e32 v77, 0x3d372713, v60
	v_mul_f32_e32 v78, 0x3d372713, v61
	v_fma_f32 v77, v60, v77, 1.0
	v_fma_f32 v78, v61, v78, 1.0
	v_mul_f32_e32 v77, v60, v77
	v_mul_f32_e32 v78, v61, v78
	v_mul_f32_e32 v64, v64, v76
	v_add_f32_e32 v76, 1.0, v79
	v_mul_f32_e32 v77, 0xc0135761, v77
	v_mul_f32_e32 v78, 0xc0135761, v78
	v_rcp_f32_e32 v76, v76
	v_exp_f32_e32 v77, v77
	v_exp_f32_e32 v78, v78
	v_mul_f32_e32 v101, v75, v101
	v_mul_f32_e32 v101, 0xc0135761, v101
	v_exp_f32_e32 v101, v101
	v_mul_f32_e32 v67, v67, v76
	v_add_f32_e32 v76, 1.0, v77
	v_add_f32_e32 v77, 1.0, v78
	v_mul_f32_e32 v78, 0x3d372713, v62
	v_fma_f32 v78, v62, v78, 1.0
	v_mul_f32_e32 v78, v62, v78
	v_add_f32_e32 v101, 1.0, v101
	v_mul_f32_e32 v78, 0xc0135761, v78
	v_mul_f32_e32 v79, 0x3d372713, v63
	v_rcp_f32_e32 v101, v101
	v_exp_f32_e32 v78, v78
	v_fma_f32 v79, v63, v79, 1.0
	v_rcp_f32_e32 v76, v76
	v_mul_f32_e32 v79, v63, v79
	v_rcp_f32_e32 v77, v77
	v_mul_f32_e32 v79, 0xc0135761, v79
	v_exp_f32_e32 v79, v79
	v_mul_f32_e32 v75, v75, v101
	v_add_f32_e32 v78, 1.0, v78
	v_cvt_pk_bf16_f32 v74, v94, v95
	v_cvt_pk_bf16_f32 v75, v100, v75
	global_store_dwordx4 v[92:93], v[72:75], off offset:256
	v_rcp_f32_e32 v78, v78
	v_mul_f32_e32 v76, v60, v76
	v_mul_f32_e32 v77, v61, v77
	v_cvt_pk_bf16_f32 v60, v64, v65
	v_cvt_pk_bf16_f32 v61, v66, v67
	v_mul_f32_e32 v66, 0x3d372713, v52
	v_fma_f32 v66, v52, v66, 1.0
	v_add_f32_e32 v79, 1.0, v79
	v_mul_f32_e32 v66, v52, v66
	v_rcp_f32_e32 v79, v79
	v_mul_f32_e32 v66, 0xc0135761, v66
	v_mul_f32_e32 v78, v62, v78
	v_cvt_pk_bf16_f32 v62, v76, v77
	v_exp_f32_e32 v76, v66
	v_add_co_u32_e32 v66, vcc, s67, v124
	v_mul_f32_e32 v63, v63, v79
	s_nop 0
	v_addc_co_u32_e32 v67, vcc, 0, v125, vcc
	v_cvt_pk_bf16_f32 v63, v78, v63
	global_store_dwordx4 v[66:67], v[60:63], off
	v_add_f32_e32 v66, 1.0, v76
	v_mul_f32_e32 v67, 0x3d372713, v53
	v_mul_f32_e32 v76, 0x3d372713, v54
	v_fma_f32 v67, v53, v67, 1.0
	v_fma_f32 v76, v54, v76, 1.0
	v_mul_f32_e32 v67, v53, v67
	v_mul_f32_e32 v76, v54, v76
	v_mul_f32_e32 v67, 0xc0135761, v67
	v_mul_f32_e32 v76, 0xc0135761, v76
	v_exp_f32_e32 v67, v67
	v_exp_f32_e32 v76, v76
	v_mul_f32_e32 v77, 0x3d372713, v55
	v_fma_f32 v77, v55, v77, 1.0
	v_add_f32_e32 v67, 1.0, v67
	v_add_f32_e32 v76, 1.0, v76
	v_rcp_f32_e32 v67, v67
	v_rcp_f32_e32 v76, v76
	v_mul_f32_e32 v77, v55, v77
	v_mul_f32_e32 v77, 0xc0135761, v77
	v_rcp_f32_e32 v66, v66
	v_exp_f32_e32 v77, v77
	v_mul_f32_e32 v53, v53, v67
	v_mul_f32_e32 v54, v54, v76
	v_mul_f32_e32 v67, 0x3d372713, v48
	v_mul_f32_e32 v76, 0x3d372713, v49
	v_fma_f32 v67, v48, v67, 1.0
	v_fma_f32 v76, v49, v76, 1.0
	v_mul_f32_e32 v67, v48, v67
	v_mul_f32_e32 v76, v49, v76
	v_mul_f32_e32 v52, v52, v66
	v_add_f32_e32 v66, 1.0, v77
	v_mul_f32_e32 v67, 0xc0135761, v67
	v_mul_f32_e32 v76, 0xc0135761, v76
	v_rcp_f32_e32 v66, v66
	v_exp_f32_e32 v67, v67
	v_exp_f32_e32 v76, v76
	v_mul_f32_e32 v77, 0x3d372713, v51
	v_mul_f32_e32 v55, v55, v66
	v_add_f32_e32 v66, 1.0, v67
	v_add_f32_e32 v67, 1.0, v76
	v_mul_f32_e32 v76, 0x3d372713, v50
	v_fma_f32 v76, v50, v76, 1.0
	v_mul_f32_e32 v76, v50, v76
	v_mul_f32_e32 v76, 0xc0135761, v76
	v_exp_f32_e32 v76, v76
	v_rcp_f32_e32 v66, v66
	v_rcp_f32_e32 v67, v67
	v_fma_f32 v77, v51, v77, 1.0
	v_add_f32_e32 v76, 1.0, v76
	v_rcp_f32_e32 v76, v76
	v_mul_f32_e32 v66, v48, v66
	v_mul_f32_e32 v67, v49, v67
	v_cvt_pk_bf16_f32 v48, v52, v53
	v_cvt_pk_bf16_f32 v49, v54, v55
	v_mul_f32_e32 v53, 0x3d372713, v45
	v_mul_f32_e32 v54, 0x3d372713, v46
	v_fma_f32 v53, v45, v53, 1.0
	v_fma_f32 v54, v46, v54, 1.0
	v_mul_f32_e32 v53, v45, v53
	v_mul_f32_e32 v54, v46, v54
	v_mul_f32_e32 v76, v50, v76
	v_mul_f32_e32 v50, 0x3d372713, v44
	v_mul_f32_e32 v53, 0xc0135761, v53
	v_mul_f32_e32 v54, 0xc0135761, v54
	v_fma_f32 v50, v44, v50, 1.0
	v_exp_f32_e32 v53, v53
	v_exp_f32_e32 v54, v54
	v_mul_f32_e32 v50, v44, v50
	v_mul_f32_e32 v50, 0xc0135761, v50
	v_exp_f32_e32 v52, v50
	v_add_f32_e32 v53, 1.0, v53
	v_add_f32_e32 v54, 1.0, v54
	v_mul_f32_e32 v55, 0x3d372713, v47
	v_rcp_f32_e32 v53, v53
	v_rcp_f32_e32 v54, v54
	v_fma_f32 v55, v47, v55, 1.0
	v_mul_f32_e32 v55, v47, v55
	v_add_f32_e32 v52, 1.0, v52
	v_mul_f32_e32 v55, 0xc0135761, v55
	v_rcp_f32_e32 v52, v52
	v_exp_f32_e32 v55, v55
	v_mul_f32_e32 v45, v45, v53
	v_mul_f32_e32 v46, v46, v54
	v_mul_f32_e32 v53, 0x3d372713, v40
	v_mul_f32_e32 v54, 0x3d372713, v41
	v_fma_f32 v53, v40, v53, 1.0
	v_fma_f32 v54, v41, v54, 1.0
	v_mul_f32_e32 v53, v40, v53
	v_mul_f32_e32 v54, v41, v54
	v_mul_f32_e32 v44, v44, v52
	v_add_f32_e32 v52, 1.0, v55
	v_mul_f32_e32 v53, 0xc0135761, v53
	v_mul_f32_e32 v54, 0xc0135761, v54
	v_rcp_f32_e32 v52, v52
	v_exp_f32_e32 v53, v53
	v_exp_f32_e32 v54, v54
	v_mul_f32_e32 v77, v51, v77
	v_mul_f32_e32 v77, 0xc0135761, v77
	v_exp_f32_e32 v77, v77
	v_mul_f32_e32 v47, v47, v52
	v_add_f32_e32 v52, 1.0, v53
	v_add_f32_e32 v53, 1.0, v54
	v_mul_f32_e32 v54, 0x3d372713, v42
	v_fma_f32 v54, v42, v54, 1.0
	v_mul_f32_e32 v54, v42, v54
	v_add_f32_e32 v77, 1.0, v77
	v_mul_f32_e32 v54, 0xc0135761, v54
	v_mul_f32_e32 v55, 0x3d372713, v43
	v_rcp_f32_e32 v77, v77
	v_exp_f32_e32 v54, v54
	v_fma_f32 v55, v43, v55, 1.0
	v_rcp_f32_e32 v52, v52
	v_mul_f32_e32 v55, v43, v55
	v_rcp_f32_e32 v53, v53
	v_mul_f32_e32 v55, 0xc0135761, v55
	s_mov_b64 s[0:1], 0x800000
	v_exp_f32_e32 v55, v55
	v_lshl_add_u64 v[64:65], v[124:125], 0, s[0:1]
	v_mul_f32_e32 v51, v51, v77
	v_add_f32_e32 v54, 1.0, v54
	v_cvt_pk_bf16_f32 v50, v66, v67
	v_cvt_pk_bf16_f32 v51, v76, v51
	global_store_dwordx4 v[64:65], v[48:51], off offset:256
	v_rcp_f32_e32 v54, v54
	v_mul_f32_e32 v52, v40, v52
	v_mul_f32_e32 v53, v41, v53
	v_cvt_pk_bf16_f32 v40, v44, v45
	v_cvt_pk_bf16_f32 v41, v46, v47
	v_mul_f32_e32 v46, 0x3d372713, v36
	v_fma_f32 v46, v36, v46, 1.0
	v_add_f32_e32 v55, 1.0, v55
	v_mul_f32_e32 v46, v36, v46
	v_rcp_f32_e32 v55, v55
	v_mul_f32_e32 v46, 0xc0135761, v46
	v_mul_f32_e32 v54, v42, v54
	v_cvt_pk_bf16_f32 v42, v52, v53
	s_mov_b64 s[0:1], 0x900000
	v_exp_f32_e32 v52, v46
	v_lshl_add_u64 v[44:45], v[124:125], 0, s[0:1]
	s_mov_b32 s0, 0x900000
	v_add_co_u32_e32 v46, vcc, s0, v124
	v_mul_f32_e32 v43, v43, v55
	s_nop 0
	v_addc_co_u32_e32 v47, vcc, 0, v125, vcc
	v_cvt_pk_bf16_f32 v43, v54, v43
	global_store_dwordx4 v[46:47], v[40:43], off
	v_add_f32_e32 v46, 1.0, v52
	v_mul_f32_e32 v47, 0x3d372713, v37
	v_mul_f32_e32 v52, 0x3d372713, v38
	v_fma_f32 v47, v37, v47, 1.0
	v_fma_f32 v52, v38, v52, 1.0
	v_mul_f32_e32 v47, v37, v47
	v_mul_f32_e32 v52, v38, v52
	v_mul_f32_e32 v47, 0xc0135761, v47
	v_mul_f32_e32 v52, 0xc0135761, v52
	v_exp_f32_e32 v47, v47
	v_exp_f32_e32 v52, v52
	v_mul_f32_e32 v53, 0x3d372713, v39
	v_fma_f32 v53, v39, v53, 1.0
	v_add_f32_e32 v47, 1.0, v47
	v_add_f32_e32 v52, 1.0, v52
	v_rcp_f32_e32 v47, v47
	v_rcp_f32_e32 v52, v52
	v_mul_f32_e32 v53, v39, v53
	v_mul_f32_e32 v53, 0xc0135761, v53
	v_rcp_f32_e32 v46, v46
	v_exp_f32_e32 v53, v53
	v_mul_f32_e32 v37, v37, v47
	v_mul_f32_e32 v38, v38, v52
	v_mul_f32_e32 v47, 0x3d372713, v32
	v_mul_f32_e32 v52, 0x3d372713, v33
	v_fma_f32 v47, v32, v47, 1.0
	v_fma_f32 v52, v33, v52, 1.0
	v_mul_f32_e32 v47, v32, v47
	v_mul_f32_e32 v52, v33, v52
	v_mul_f32_e32 v36, v36, v46
	v_add_f32_e32 v46, 1.0, v53
	v_mul_f32_e32 v47, 0xc0135761, v47
	v_mul_f32_e32 v52, 0xc0135761, v52
	v_rcp_f32_e32 v46, v46
	v_exp_f32_e32 v47, v47
	v_exp_f32_e32 v52, v52
	v_mul_f32_e32 v53, 0x3d372713, v35
	v_mul_f32_e32 v39, v39, v46
	v_add_f32_e32 v46, 1.0, v47
	v_add_f32_e32 v47, 1.0, v52
	v_mul_f32_e32 v52, 0x3d372713, v34
	v_fma_f32 v52, v34, v52, 1.0
	v_mul_f32_e32 v52, v34, v52
	v_mul_f32_e32 v52, 0xc0135761, v52
	v_exp_f32_e32 v52, v52
	v_rcp_f32_e32 v46, v46
	v_rcp_f32_e32 v47, v47
	v_fma_f32 v53, v35, v53, 1.0
	v_add_f32_e32 v52, 1.0, v52
	v_rcp_f32_e32 v52, v52
	v_mul_f32_e32 v46, v32, v46
	v_mul_f32_e32 v47, v33, v47
	v_cvt_pk_bf16_f32 v32, v36, v37
	v_cvt_pk_bf16_f32 v33, v38, v39
	v_mul_f32_e32 v37, 0x3d372713, v29
	v_mul_f32_e32 v38, 0x3d372713, v30
	v_fma_f32 v37, v29, v37, 1.0
	v_fma_f32 v38, v30, v38, 1.0
	v_mul_f32_e32 v37, v29, v37
	v_mul_f32_e32 v38, v30, v38
	v_mul_f32_e32 v52, v34, v52
	v_mul_f32_e32 v34, 0x3d372713, v28
	v_mul_f32_e32 v37, 0xc0135761, v37
	v_mul_f32_e32 v38, 0xc0135761, v38
	v_fma_f32 v34, v28, v34, 1.0
	v_exp_f32_e32 v37, v37
	v_exp_f32_e32 v38, v38
	v_mul_f32_e32 v34, v28, v34
	v_mul_f32_e32 v34, 0xc0135761, v34
	v_exp_f32_e32 v36, v34
	v_add_f32_e32 v37, 1.0, v37
	v_add_f32_e32 v38, 1.0, v38
	v_mul_f32_e32 v39, 0x3d372713, v31
	v_rcp_f32_e32 v37, v37
	v_rcp_f32_e32 v38, v38
	v_fma_f32 v39, v31, v39, 1.0
	v_mul_f32_e32 v39, v31, v39
	v_add_f32_e32 v36, 1.0, v36
	v_mul_f32_e32 v39, 0xc0135761, v39
	v_rcp_f32_e32 v36, v36
	v_exp_f32_e32 v39, v39
	v_mul_f32_e32 v29, v29, v37
	v_mul_f32_e32 v30, v30, v38
	v_mul_f32_e32 v37, 0x3d372713, v24
	v_mul_f32_e32 v38, 0x3d372713, v25
	v_fma_f32 v37, v24, v37, 1.0
	v_fma_f32 v38, v25, v38, 1.0
	v_mul_f32_e32 v37, v24, v37
	v_mul_f32_e32 v38, v25, v38
	v_mul_f32_e32 v28, v28, v36
	v_add_f32_e32 v36, 1.0, v39
	v_mul_f32_e32 v37, 0xc0135761, v37
	v_mul_f32_e32 v38, 0xc0135761, v38
	v_rcp_f32_e32 v36, v36
	v_exp_f32_e32 v37, v37
	v_exp_f32_e32 v38, v38
	v_mul_f32_e32 v53, v35, v53
	v_mul_f32_e32 v53, 0xc0135761, v53
	v_exp_f32_e32 v53, v53
	v_mul_f32_e32 v31, v31, v36
	v_add_f32_e32 v36, 1.0, v37
	v_add_f32_e32 v37, 1.0, v38
	v_mul_f32_e32 v38, 0x3d372713, v26
	v_fma_f32 v38, v26, v38, 1.0
	v_mul_f32_e32 v38, v26, v38
	v_add_f32_e32 v53, 1.0, v53
	v_mul_f32_e32 v38, 0xc0135761, v38
	v_mul_f32_e32 v39, 0x3d372713, v27
	v_rcp_f32_e32 v53, v53
	v_exp_f32_e32 v38, v38
	v_fma_f32 v39, v27, v39, 1.0
	v_rcp_f32_e32 v36, v36
	v_mul_f32_e32 v39, v27, v39
	v_rcp_f32_e32 v37, v37
	v_mul_f32_e32 v39, 0xc0135761, v39
	v_exp_f32_e32 v39, v39
	v_mul_f32_e32 v35, v35, v53
	v_add_f32_e32 v38, 1.0, v38
	v_cvt_pk_bf16_f32 v34, v46, v47
	v_cvt_pk_bf16_f32 v35, v52, v35
	global_store_dwordx4 v[44:45], v[32:35], off offset:256
	v_rcp_f32_e32 v38, v38
	v_mul_f32_e32 v36, v24, v36
	v_mul_f32_e32 v37, v25, v37
	v_cvt_pk_bf16_f32 v24, v28, v29
	v_cvt_pk_bf16_f32 v25, v30, v31
	v_mul_f32_e32 v30, 0x3d372713, v20
	v_fma_f32 v30, v20, v30, 1.0
	v_add_f32_e32 v39, 1.0, v39
	v_mul_f32_e32 v30, v20, v30
	v_rcp_f32_e32 v39, v39
	v_mul_f32_e32 v30, 0xc0135761, v30
	v_mul_f32_e32 v38, v26, v38
	v_cvt_pk_bf16_f32 v26, v36, v37
	s_mov_b64 s[0:1], 0xa00000
	v_exp_f32_e32 v36, v30
	v_lshl_add_u64 v[28:29], v[124:125], 0, s[0:1]
	s_mov_b32 s0, 0xa00000
	v_add_co_u32_e32 v30, vcc, s0, v124
	v_mul_f32_e32 v27, v27, v39
	s_nop 0
	v_addc_co_u32_e32 v31, vcc, 0, v125, vcc
	v_cvt_pk_bf16_f32 v27, v38, v27
	global_store_dwordx4 v[30:31], v[24:27], off
	v_add_f32_e32 v30, 1.0, v36
	v_mul_f32_e32 v31, 0x3d372713, v21
	v_mul_f32_e32 v36, 0x3d372713, v22
	v_fma_f32 v31, v21, v31, 1.0
	v_fma_f32 v36, v22, v36, 1.0
	v_mul_f32_e32 v31, v21, v31
	v_mul_f32_e32 v36, v22, v36
	v_mul_f32_e32 v31, 0xc0135761, v31
	v_mul_f32_e32 v36, 0xc0135761, v36
	v_exp_f32_e32 v31, v31
	v_exp_f32_e32 v36, v36
	v_mul_f32_e32 v37, 0x3d372713, v23
	v_fma_f32 v37, v23, v37, 1.0
	v_add_f32_e32 v31, 1.0, v31
	v_add_f32_e32 v36, 1.0, v36
	v_rcp_f32_e32 v31, v31
	v_rcp_f32_e32 v36, v36
	v_mul_f32_e32 v37, v23, v37
	v_mul_f32_e32 v37, 0xc0135761, v37
	v_rcp_f32_e32 v30, v30
	v_exp_f32_e32 v37, v37
	v_mul_f32_e32 v21, v21, v31
	v_mul_f32_e32 v22, v22, v36
	v_mul_f32_e32 v31, 0x3d372713, v16
	v_mul_f32_e32 v36, 0x3d372713, v17
	v_fma_f32 v31, v16, v31, 1.0
	v_fma_f32 v36, v17, v36, 1.0
	v_mul_f32_e32 v31, v16, v31
	v_mul_f32_e32 v36, v17, v36
	v_mul_f32_e32 v20, v20, v30
	v_add_f32_e32 v30, 1.0, v37
	v_mul_f32_e32 v31, 0xc0135761, v31
	v_mul_f32_e32 v36, 0xc0135761, v36
	v_rcp_f32_e32 v30, v30
	v_exp_f32_e32 v31, v31
	v_exp_f32_e32 v36, v36
	v_mul_f32_e32 v37, 0x3d372713, v19
	v_mul_f32_e32 v23, v23, v30
	v_add_f32_e32 v30, 1.0, v31
	v_add_f32_e32 v31, 1.0, v36
	v_mul_f32_e32 v36, 0x3d372713, v18
	v_fma_f32 v36, v18, v36, 1.0
	v_mul_f32_e32 v36, v18, v36
	v_mul_f32_e32 v36, 0xc0135761, v36
	v_exp_f32_e32 v36, v36
	v_rcp_f32_e32 v30, v30
	v_rcp_f32_e32 v31, v31
	v_fma_f32 v37, v19, v37, 1.0
	v_add_f32_e32 v36, 1.0, v36
	v_rcp_f32_e32 v36, v36
	v_mul_f32_e32 v30, v16, v30
	v_mul_f32_e32 v31, v17, v31
	v_cvt_pk_bf16_f32 v16, v20, v21
	v_cvt_pk_bf16_f32 v17, v22, v23
	v_mul_f32_e32 v21, 0x3d372713, v13
	v_mul_f32_e32 v22, 0x3d372713, v14
	v_fma_f32 v21, v13, v21, 1.0
	v_fma_f32 v22, v14, v22, 1.0
	v_mul_f32_e32 v21, v13, v21
	v_mul_f32_e32 v22, v14, v22
	v_mul_f32_e32 v36, v18, v36
	v_mul_f32_e32 v18, 0x3d372713, v12
	v_mul_f32_e32 v21, 0xc0135761, v21
	v_mul_f32_e32 v22, 0xc0135761, v22
	v_fma_f32 v18, v12, v18, 1.0
	v_exp_f32_e32 v21, v21
	v_exp_f32_e32 v22, v22
	v_mul_f32_e32 v18, v12, v18
	v_mul_f32_e32 v18, 0xc0135761, v18
	v_exp_f32_e32 v20, v18
	v_add_f32_e32 v21, 1.0, v21
	v_add_f32_e32 v22, 1.0, v22
	v_mul_f32_e32 v23, 0x3d372713, v15
	v_rcp_f32_e32 v21, v21
	v_rcp_f32_e32 v22, v22
	v_fma_f32 v23, v15, v23, 1.0
	v_mul_f32_e32 v23, v15, v23
	v_add_f32_e32 v20, 1.0, v20
	v_mul_f32_e32 v23, 0xc0135761, v23
	v_rcp_f32_e32 v20, v20
	v_exp_f32_e32 v23, v23
	v_mul_f32_e32 v13, v13, v21
	v_mul_f32_e32 v14, v14, v22
	v_mul_f32_e32 v21, 0x3d372713, v8
	v_mul_f32_e32 v22, 0x3d372713, v9
	v_fma_f32 v21, v8, v21, 1.0
	v_fma_f32 v22, v9, v22, 1.0
	v_mul_f32_e32 v21, v8, v21
	v_mul_f32_e32 v22, v9, v22
	v_mul_f32_e32 v12, v12, v20
	v_add_f32_e32 v20, 1.0, v23
	v_mul_f32_e32 v21, 0xc0135761, v21
	v_mul_f32_e32 v22, 0xc0135761, v22
	v_rcp_f32_e32 v20, v20
	v_exp_f32_e32 v21, v21
	v_exp_f32_e32 v22, v22
	v_mul_f32_e32 v37, v19, v37
	v_mul_f32_e32 v37, 0xc0135761, v37
	v_exp_f32_e32 v37, v37
	v_mul_f32_e32 v15, v15, v20
	v_add_f32_e32 v20, 1.0, v21
	v_add_f32_e32 v21, 1.0, v22
	v_mul_f32_e32 v22, 0x3d372713, v10
	v_fma_f32 v22, v10, v22, 1.0
	v_mul_f32_e32 v22, v10, v22
	v_add_f32_e32 v37, 1.0, v37
	v_mul_f32_e32 v22, 0xc0135761, v22
	v_mul_f32_e32 v23, 0x3d372713, v11
	v_rcp_f32_e32 v37, v37
	v_exp_f32_e32 v22, v22
	v_fma_f32 v23, v11, v23, 1.0
	v_rcp_f32_e32 v20, v20
	v_mul_f32_e32 v23, v11, v23
	v_rcp_f32_e32 v21, v21
	v_mul_f32_e32 v23, 0xc0135761, v23
	v_exp_f32_e32 v23, v23
	v_mul_f32_e32 v19, v19, v37
	v_add_f32_e32 v22, 1.0, v22
	v_cvt_pk_bf16_f32 v18, v30, v31
	v_cvt_pk_bf16_f32 v19, v36, v19
	global_store_dwordx4 v[28:29], v[16:19], off offset:256
	v_rcp_f32_e32 v22, v22
	v_mul_f32_e32 v20, v8, v20
	v_mul_f32_e32 v21, v9, v21
	v_cvt_pk_bf16_f32 v8, v12, v13
	v_cvt_pk_bf16_f32 v9, v14, v15
	v_mul_f32_e32 v14, 0x3d372713, v4
	v_fma_f32 v14, v4, v14, 1.0
	v_add_f32_e32 v23, 1.0, v23
	v_mul_f32_e32 v14, v4, v14
	v_rcp_f32_e32 v23, v23
	v_mul_f32_e32 v14, 0xc0135761, v14
	v_mul_f32_e32 v22, v10, v22
	v_cvt_pk_bf16_f32 v10, v20, v21
	s_mov_b64 s[0:1], 0xb00000
	v_exp_f32_e32 v20, v14
	v_lshl_add_u64 v[12:13], v[124:125], 0, s[0:1]
	s_mov_b32 s0, 0xb00000
	v_add_co_u32_e32 v14, vcc, s0, v124
	v_mul_f32_e32 v11, v11, v23
	s_nop 0
	v_addc_co_u32_e32 v15, vcc, 0, v125, vcc
	v_cvt_pk_bf16_f32 v11, v22, v11
	global_store_dwordx4 v[14:15], v[8:11], off
	v_add_f32_e32 v14, 1.0, v20
	v_mul_f32_e32 v15, 0x3d372713, v5
	v_mul_f32_e32 v20, 0x3d372713, v6
	v_fma_f32 v15, v5, v15, 1.0
	v_fma_f32 v20, v6, v20, 1.0
	v_mul_f32_e32 v15, v5, v15
	v_mul_f32_e32 v20, v6, v20
	v_mul_f32_e32 v15, 0xc0135761, v15
	v_mul_f32_e32 v20, 0xc0135761, v20
	v_exp_f32_e32 v15, v15
	v_exp_f32_e32 v20, v20
	v_mul_f32_e32 v21, 0x3d372713, v7
	v_fma_f32 v21, v7, v21, 1.0
	v_add_f32_e32 v15, 1.0, v15
	v_add_f32_e32 v20, 1.0, v20
	v_rcp_f32_e32 v15, v15
	v_rcp_f32_e32 v20, v20
	v_mul_f32_e32 v21, v7, v21
	v_mul_f32_e32 v21, 0xc0135761, v21
	v_rcp_f32_e32 v14, v14
	v_exp_f32_e32 v21, v21
	v_mul_f32_e32 v5, v5, v15
	v_mul_f32_e32 v6, v6, v20
	v_mul_f32_e32 v15, 0x3d372713, v0
	v_mul_f32_e32 v20, 0x3d372713, v1
	v_fma_f32 v15, v0, v15, 1.0
	v_fma_f32 v20, v1, v20, 1.0
	v_mul_f32_e32 v15, v0, v15
	v_mul_f32_e32 v20, v1, v20
	v_mul_f32_e32 v4, v4, v14
	v_add_f32_e32 v14, 1.0, v21
	v_mul_f32_e32 v15, 0xc0135761, v15
	v_mul_f32_e32 v20, 0xc0135761, v20
	v_rcp_f32_e32 v14, v14
	v_exp_f32_e32 v15, v15
	v_exp_f32_e32 v20, v20
	v_mul_f32_e32 v21, 0x3d372713, v3
	v_mul_f32_e32 v7, v7, v14
	v_add_f32_e32 v14, 1.0, v15
	v_add_f32_e32 v15, 1.0, v20
	v_mul_f32_e32 v20, 0x3d372713, v2
	v_fma_f32 v21, v3, v21, 1.0
	v_fma_f32 v20, v2, v20, 1.0
	v_mul_f32_e32 v21, v3, v21
	v_mul_f32_e32 v20, v2, v20
	v_mul_f32_e32 v21, 0xc0135761, v21
	v_mul_f32_e32 v20, 0xc0135761, v20
	v_exp_f32_e32 v21, v21
	v_exp_f32_e32 v20, v20
	v_rcp_f32_e32 v14, v14
	v_rcp_f32_e32 v15, v15
	v_add_f32_e32 v21, 1.0, v21
	v_add_f32_e32 v20, 1.0, v20
	v_rcp_f32_e32 v21, v21
	v_rcp_f32_e32 v20, v20
	v_lshlrev_b32_e32 v46, 16, v88
	v_and_b32_e32 v47, 0xffff0000, v88
	v_mul_f32_e32 v14, v0, v14
	v_cvt_pk_bf16_f32 v0, v4, v5
	v_lshlrev_b32_e32 v64, 16, v68
	v_and_b32_e32 v65, 0xffff0000, v68
	v_pk_mul_f32 v[4:5], v[46:47], v[46:47]
	v_lshlrev_b32_e32 v52, 16, v104
	v_pk_fma_f32 v[4:5], v[64:65], v[64:65], v[4:5]
	v_and_b32_e32 v53, 0xffff0000, v104
	v_mul_f32_e32 v3, v3, v21
	v_pk_fma_f32 v[4:5], v[52:53], v[52:53], v[4:5]
	v_lshlrev_b32_e32 v44, 16, v84
	v_and_b32_e32 v45, 0xffff0000, v84
	v_mul_f32_e32 v15, v1, v15
	v_mul_f32_e32 v20, v2, v20
	v_cvt_pk_bf16_f32 v1, v6, v7
	v_cvt_pk_bf16_f32 v2, v14, v15
	v_cvt_pk_bf16_f32 v3, v20, v3
	global_store_dwordx4 v[12:13], v[0:3], off offset:256
	v_pk_fma_f32 v[12:13], v[44:45], v[44:45], v[4:5]
	v_and_b32_e32 v4, 0xffff0000, v60
	v_and_b32_e32 v5, 0xffff0000, v40
	v_pk_mul_f32 v[6:7], v[4:5], v[4:5]
	v_and_b32_e32 v28, 0xffff0000, v24
	v_and_b32_e32 v29, 0xffff0000, v8
	v_add_f32_e32 v6, v13, v6
	v_pk_mul_f32 v[30:31], v[28:29], v[28:29]
	v_add_f32_e32 v6, v6, v7
	v_add_f32_e32 v6, v6, v30
	v_lshlrev_b32_e32 v78, 16, v69
	v_and_b32_e32 v79, 0xffff0000, v69
	v_lshlrev_b32_e32 v68, 16, v89
	v_and_b32_e32 v69, 0xffff0000, v89
	v_add_f32_e32 v108, v6, v31
	v_pk_mul_f32 v[6:7], v[68:69], v[68:69]
	v_lshlrev_b32_e32 v76, 16, v105
	v_pk_fma_f32 v[6:7], v[78:79], v[78:79], v[6:7]
	v_and_b32_e32 v77, 0xffff0000, v105
	v_pk_fma_f32 v[6:7], v[76:77], v[76:77], v[6:7]
	v_lshlrev_b32_e32 v66, 16, v85
	v_and_b32_e32 v67, 0xffff0000, v85
	v_lshlrev_b32_e32 v38, 16, v61
	v_lshlrev_b32_e32 v39, 16, v41
	v_lshlrev_b32_e32 v20, 16, v40
	v_pk_fma_f32 v[54:55], v[66:67], v[66:67], v[6:7]
	v_and_b32_e32 v7, 0xffff0000, v41
	v_pk_mul_f32 v[40:41], v[38:39], v[38:39]
	v_and_b32_e32 v6, 0xffff0000, v61
	v_lshlrev_b32_e32 v36, 16, v25
	v_lshlrev_b32_e32 v37, 16, v9
	v_add_f32_e32 v13, v54, v40
	v_lshlrev_b32_e32 v14, 16, v60
	v_lshlrev_b32_e32 v22, 16, v24
	v_lshlrev_b32_e32 v24, 16, v8
	v_pk_mul_f32 v[60:61], v[6:7], v[6:7]
	v_and_b32_e32 v31, 0xffff0000, v9
	v_pk_mul_f32 v[8:9], v[36:37], v[36:37]
	v_add_f32_e32 v13, v13, v41
	v_and_b32_e32 v30, 0xffff0000, v25
	v_add_f32_e32 v8, v13, v8
	v_add_f32_e32 v13, v55, v60
	v_add_f32_e32 v105, v8, v9
	v_pk_mul_f32 v[8:9], v[30:31], v[30:31]
	v_add_f32_e32 v13, v13, v61
	v_add_f32_e32 v8, v13, v8
	v_lshlrev_b32_e32 v88, 16, v90
	v_and_b32_e32 v89, 0xffff0000, v90
	v_add_f32_e32 v104, v8, v9
	v_lshlrev_b32_e32 v94, 16, v70
	v_and_b32_e32 v95, 0xffff0000, v70
	v_pk_mul_f32 v[8:9], v[88:89], v[88:89]
	v_lshlrev_b32_e32 v92, 16, v106
	v_pk_fma_f32 v[8:9], v[94:95], v[94:95], v[8:9]
	v_and_b32_e32 v93, 0xffff0000, v106
	v_pk_fma_f32 v[8:9], v[92:93], v[92:93], v[8:9]
	v_lshlrev_b32_e32 v84, 16, v86
	v_and_b32_e32 v85, 0xffff0000, v86
	v_lshlrev_b32_e32 v60, 16, v62
	v_lshlrev_b32_e32 v61, 16, v42
	v_pk_fma_f32 v[110:111], v[84:85], v[84:85], v[8:9]
	v_pk_mul_f32 v[102:103], v[60:61], v[60:61]
	v_lshlrev_b32_e32 v54, 16, v26
	v_lshlrev_b32_e32 v55, 16, v10
	v_and_b32_e32 v41, 0xffff0000, v10
	v_add_f32_e32 v10, v110, v102
	v_and_b32_e32 v8, 0xffff0000, v62
	v_and_b32_e32 v9, 0xffff0000, v42
	v_pk_mul_f32 v[114:115], v[54:55], v[54:55]
	v_add_f32_e32 v10, v10, v103
	v_pk_mul_f32 v[112:113], v[8:9], v[8:9]
	v_add_f32_e32 v10, v10, v114
	v_add_f32_e32 v103, v10, v115
	v_add_f32_e32 v10, v111, v112
	v_and_b32_e32 v40, 0xffff0000, v26
	v_add_f32_e32 v10, v10, v113
	v_lshlrev_b32_e32 v112, 16, v91
	v_and_b32_e32 v113, 0xffff0000, v91
	v_pk_mul_f32 v[114:115], v[40:41], v[40:41]
	v_lshlrev_b32_e32 v110, 16, v71
	v_and_b32_e32 v111, 0xffff0000, v71
	v_pk_mul_f32 v[70:71], v[112:113], v[112:113]
	v_add_f32_e32 v10, v10, v114
	v_pk_fma_f32 v[70:71], v[110:111], v[110:111], v[70:71]
	v_lshlrev_b32_e32 v106, 16, v107
	v_and_b32_e32 v107, 0xffff0000, v107
	v_add_f32_e32 v102, v10, v115
	v_pk_fma_f32 v[70:71], v[106:107], v[106:107], v[70:71]
	v_lshlrev_b32_e32 v114, 16, v87
	v_and_b32_e32 v115, 0xffff0000, v87
	v_lshlrev_b32_e32 v86, 16, v63
	v_lshlrev_b32_e32 v87, 16, v43
	v_pk_fma_f32 v[90:91], v[114:115], v[114:115], v[70:71]
	v_and_b32_e32 v71, 0xffff0000, v43
	v_pk_mul_f32 v[42:43], v[86:87], v[86:87]
	v_lshlrev_b32_e32 v26, 16, v27
	v_and_b32_e32 v10, 0xffff0000, v27
	v_lshlrev_b32_e32 v27, 16, v11
	v_add_f32_e32 v13, v90, v42
	v_and_b32_e32 v70, 0xffff0000, v63
	v_pk_mul_f32 v[116:117], v[26:27], v[26:27]
	v_add_f32_e32 v13, v13, v43
	v_pk_mul_f32 v[62:63], v[70:71], v[70:71]
	v_add_f32_e32 v13, v13, v116
	v_and_b32_e32 v11, 0xffff0000, v11
	v_add_f32_e32 v101, v13, v117
	v_add_f32_e32 v13, v91, v62
	v_pk_mul_f32 v[42:43], v[10:11], v[10:11]
	v_add_f32_e32 v13, v13, v63
	v_add_f32_e32 v13, v13, v42
	v_lshlrev_b32_e32 v118, 16, v80
	v_and_b32_e32 v119, 0xffff0000, v80
	v_add_f32_e32 v13, v13, v43
	v_lshlrev_b32_e32 v116, 16, v56
	v_and_b32_e32 v117, 0xffff0000, v56
	v_pk_mul_f32 v[42:43], v[118:119], v[118:119]
	v_lshlrev_b32_e32 v120, 16, v96
	v_pk_fma_f32 v[42:43], v[116:117], v[116:117], v[42:43]
	v_and_b32_e32 v121, 0xffff0000, v96
	v_pk_fma_f32 v[42:43], v[120:121], v[120:121], v[42:43]
	v_lshlrev_b32_e32 v122, 16, v72
	v_and_b32_e32 v123, 0xffff0000, v72
	v_and_b32_e32 v124, 0xffff0000, v48
	v_and_b32_e32 v125, 0xffff0000, v32
	v_pk_fma_f32 v[42:43], v[122:123], v[122:123], v[42:43]
	v_pk_mul_f32 v[126:127], v[124:125], v[124:125]
	v_and_b32_e32 v90, 0xffff0000, v16
	v_lshlrev_b32_e32 v62, 16, v0
	v_and_b32_e32 v91, 0xffff0000, v0
	v_add_f32_e32 v0, v43, v126
	v_pk_mul_f32 v[146:147], v[90:91], v[90:91]
	v_add_f32_e32 v0, v0, v127
	v_add_f32_e32 v0, v0, v146
	v_lshlrev_b32_e32 v80, 16, v81
	v_and_b32_e32 v81, 0xffff0000, v81
	v_add_f32_e32 v109, v0, v147
	v_lshlrev_b32_e32 v126, 16, v57
	v_and_b32_e32 v127, 0xffff0000, v57
	v_pk_mul_f32 v[146:147], v[80:81], v[80:81]
	v_lshlrev_b32_e32 v96, 16, v97
	v_pk_fma_f32 v[146:147], v[126:127], v[126:127], v[146:147]
	v_and_b32_e32 v97, 0xffff0000, v97
	v_pk_fma_f32 v[146:147], v[96:97], v[96:97], v[146:147]
	v_lshlrev_b32_e32 v148, 16, v73
	v_and_b32_e32 v149, 0xffff0000, v73
	v_pk_fma_f32 v[72:73], v[148:149], v[148:149], v[146:147]
	v_lshlrev_b32_e32 v146, 16, v49
	v_lshlrev_b32_e32 v147, 16, v33
	v_pk_mul_f32 v[152:153], v[146:147], v[146:147]
	v_lshlrev_b32_e32 v56, 16, v48
	v_lshlrev_b32_e32 v48, 16, v32
	v_lshlrev_b32_e32 v32, 16, v16
	v_lshlrev_b32_e32 v16, 16, v17
	v_and_b32_e32 v0, 0xffff0000, v17
	v_lshlrev_b32_e32 v17, 16, v1
	v_add_f32_e32 v15, v72, v152
	v_and_b32_e32 v150, 0xffff0000, v49
	v_and_b32_e32 v151, 0xffff0000, v33
	v_pk_mul_f32 v[156:157], v[16:17], v[16:17]
	v_add_f32_e32 v15, v15, v153
	v_pk_mul_f32 v[154:155], v[150:151], v[150:151]
	v_add_f32_e32 v15, v15, v156
	v_and_b32_e32 v1, 0xffff0000, v1
	v_add_f32_e32 v139, v15, v157
	v_add_f32_e32 v15, v73, v154
	v_pk_mul_f32 v[152:153], v[0:1], v[0:1]
	v_add_f32_e32 v15, v15, v155
	v_add_f32_e32 v15, v15, v152
	v_lshlrev_b32_e32 v154, 16, v82
	v_and_b32_e32 v155, 0xffff0000, v82
	v_add_f32_e32 v72, v15, v153
	v_lshlrev_b32_e32 v152, 16, v58
	v_and_b32_e32 v153, 0xffff0000, v58
	v_pk_mul_f32 v[156:157], v[154:155], v[154:155]
	v_lshlrev_b32_e32 v158, 16, v98
	v_pk_fma_f32 v[156:157], v[152:153], v[152:153], v[156:157]
	v_and_b32_e32 v159, 0xffff0000, v98
	v_pk_fma_f32 v[156:157], v[158:159], v[158:159], v[156:157]
	v_lshlrev_b32_e32 v160, 16, v74
	v_and_b32_e32 v161, 0xffff0000, v74
	v_lshlrev_b32_e32 v162, 16, v50
	v_lshlrev_b32_e32 v163, 16, v34
	v_pk_fma_f32 v[156:157], v[160:161], v[160:161], v[156:157]
	v_pk_mul_f32 v[166:167], v[162:163], v[162:163]
	v_lshlrev_b32_e32 v170, 16, v18
	v_lshlrev_b32_e32 v171, 16, v2
	v_and_b32_e32 v173, 0xffff0000, v2
	v_add_f32_e32 v2, v156, v166
	v_and_b32_e32 v164, 0xffff0000, v50
	v_and_b32_e32 v165, 0xffff0000, v34
	v_pk_mul_f32 v[174:175], v[170:171], v[170:171]
	v_add_f32_e32 v2, v2, v167
	v_pk_mul_f32 v[168:169], v[164:165], v[164:165]
	v_add_f32_e32 v2, v2, v174
	v_and_b32_e32 v172, 0xffff0000, v18
	v_add_f32_e32 v50, v2, v175
	v_add_f32_e32 v2, v157, v168
	v_lshlrev_b32_e32 v82, 16, v83
	v_and_b32_e32 v83, 0xffff0000, v83
	v_pk_mul_f32 v[166:167], v[172:173], v[172:173]
	v_add_f32_e32 v2, v2, v169
	v_lshlrev_b32_e32 v58, 16, v59
	v_and_b32_e32 v59, 0xffff0000, v59
	v_pk_mul_f32 v[156:157], v[82:83], v[82:83]
	v_add_f32_e32 v2, v2, v166
	v_pk_fma_f32 v[156:157], v[58:59], v[58:59], v[156:157]
	v_lshlrev_b32_e32 v98, 16, v99
	v_and_b32_e32 v99, 0xffff0000, v99
	v_add_f32_e32 v43, v2, v167
	v_pk_fma_f32 v[156:157], v[98:99], v[98:99], v[156:157]
	v_lshlrev_b32_e32 v74, 16, v75
	v_and_b32_e32 v75, 0xffff0000, v75
	v_lshlrev_b32_e32 v166, 16, v51
	v_lshlrev_b32_e32 v167, 16, v35
	v_pk_fma_f32 v[156:157], v[74:75], v[74:75], v[156:157]
	v_and_b32_e32 v169, 0xffff0000, v35
	v_pk_mul_f32 v[34:35], v[166:167], v[166:167]
	v_lshlrev_b32_e32 v18, 16, v19
	v_and_b32_e32 v2, 0xffff0000, v19
	v_lshlrev_b32_e32 v19, 16, v3
	v_add_f32_e32 v15, v156, v34
	v_and_b32_e32 v168, 0xffff0000, v51
	v_pk_mul_f32 v[176:177], v[18:19], v[18:19]
	v_add_f32_e32 v15, v15, v35
	v_pk_mul_f32 v[174:175], v[168:169], v[168:169]
	v_add_f32_e32 v15, v15, v176
	v_and_b32_e32 v3, 0xffff0000, v3
	v_add_f32_e32 v35, v15, v177
	v_add_f32_e32 v15, v157, v174
	v_pk_add_f32 v[64:65], v[64:65], 0 op_sel_hi:[1,0]
	v_pk_mul_f32 v[176:177], v[2:3], v[2:3]
	v_add_f32_e32 v15, v15, v175
	v_pk_add_f32 v[78:79], v[78:79], 0 op_sel_hi:[1,0]
	v_pk_add_f32 v[46:47], v[64:65], v[46:47]
	v_add_f32_e32 v15, v15, v176
	v_pk_add_f32 v[94:95], v[94:95], 0 op_sel_hi:[1,0]
	v_pk_add_f32 v[68:69], v[78:79], v[68:69]
	v_pk_add_f32 v[46:47], v[46:47], v[52:53]
	v_add_f32_e32 v34, v15, v177
	v_pk_add_f32 v[110:111], v[110:111], 0 op_sel_hi:[1,0]
	v_pk_add_f32 v[88:89], v[94:95], v[88:89]
	v_pk_add_f32 v[52:53], v[68:69], v[76:77]
	v_pk_add_f32 v[44:45], v[46:47], v[44:45]
	v_mov_b32_e32 v15, v4
	v_pk_add_f32 v[116:117], v[116:117], 0 op_sel_hi:[1,0]
	v_pk_add_f32 v[126:127], v[126:127], 0 op_sel_hi:[1,0]
	v_pk_add_f32 v[110:111], v[110:111], v[112:113]
	v_pk_add_f32 v[64:65], v[88:89], v[92:93]
	v_pk_add_f32 v[52:53], v[52:53], v[66:67]
	v_pk_add_f32 v[44:45], v[44:45], v[14:15]
	v_mov_b32_e32 v46, v38
	v_mov_b32_e32 v47, v6
	v_mov_b32_e32 v21, v5
	v_pk_add_f32 v[80:81], v[126:127], v[80:81]
	v_pk_add_f32 v[116:117], v[116:117], v[118:119]
	v_pk_add_f32 v[68:69], v[110:111], v[106:107]
	v_pk_add_f32 v[64:65], v[64:65], v[84:85]
	v_pk_add_f32 v[46:47], v[52:53], v[46:47]
	v_mov_b32_e32 v52, v60
	v_mov_b32_e32 v53, v8
	v_mov_b32_e32 v6, v39
	v_pk_add_f32 v[4:5], v[44:45], v[20:21]
	v_mov_b32_e32 v23, v28
	v_pk_add_f32 v[76:77], v[116:117], v[120:121]
	v_pk_add_f32 v[78:79], v[80:81], v[96:97]
	v_pk_add_f32 v[68:69], v[68:69], v[114:115]
	v_pk_add_f32 v[52:53], v[64:65], v[52:53]
	v_mov_b32_e32 v64, v86
	v_mov_b32_e32 v65, v70
	v_mov_b32_e32 v8, v61
	v_pk_add_f32 v[6:7], v[46:47], v[6:7]
	v_pk_add_f32 v[38:39], v[4:5], v[22:23]
	v_mov_b32_e32 v4, v36
	v_mov_b32_e32 v5, v30
	v_pk_add_f32 v[78:79], v[78:79], v[148:149]
	v_pk_add_f32 v[76:77], v[76:77], v[122:123]
	v_pk_add_f32 v[64:65], v[68:69], v[64:65]
	v_mov_b32_e32 v57, v124
	v_mov_b32_e32 v68, v146
	v_mov_b32_e32 v69, v150
	v_mov_b32_e32 v70, v87
	v_pk_add_f32 v[8:9], v[52:53], v[8:9]
	v_pk_add_f32 v[44:45], v[6:7], v[4:5]
	v_mov_b32_e32 v4, v54
	v_mov_b32_e32 v5, v40
	v_pk_add_f32 v[66:67], v[76:77], v[56:57]
	v_pk_add_f32 v[68:69], v[78:79], v[68:69]
	v_mov_b32_e32 v150, v147
	v_mov_b32_e32 v49, v125
	v_pk_add_f32 v[64:65], v[64:65], v[70:71]
	v_pk_add_f32 v[46:47], v[8:9], v[4:5]
	v_mov_b32_e32 v4, v26
	v_mov_b32_e32 v5, v10
	v_mov_b32_e32 v57, v48
	v_pk_add_f32 v[68:69], v[68:69], v[150:151]
	v_pk_add_f32 v[66:67], v[66:67], v[48:49]
	v_pk_add_f32 v[52:53], v[64:65], v[4:5]
	v_mov_b32_e32 v33, v90
	v_mov_b32_e32 v4, v16
	v_mov_b32_e32 v5, v0
	v_mov_b32_e32 v25, v29
	v_pk_mul_f32 v[28:29], v[56:57], v[56:57]
	v_pk_add_f32 v[8:9], v[66:67], v[32:33]
	v_pk_add_f32 v[6:7], v[68:69], v[4:5]
	v_mov_b32_e32 v0, v17
	v_mov_b32_e32 v33, v62
	v_add_f32_e32 v15, v42, v28
	v_pk_add_f32 v[6:7], v[6:7], v[0:1]
	v_pk_mul_f32 v[0:1], v[32:33], v[32:33]
	v_add_f32_e32 v15, v15, v29
	v_add_f32_e32 v0, v15, v0
	v_mov_b32_e32 v15, v20
	v_pk_mul_f32 v[14:15], v[14:15], v[14:15]
	v_mov_b32_e32 v23, v24
	v_add_f32_e32 v12, v12, v14
	v_add_f32_e32 v21, v0, v1
	v_pk_mul_f32 v[0:1], v[22:23], v[22:23]
	v_add_f32_e32 v12, v12, v15
	v_add_f32_e32 v0, v12, v0
	v_add_f32_e32 v0, v0, v1
	v_bitop3_b32 v1, v144, 8, v144 bitop3:0xc
	v_mov_b32_e32 v10, v27
	v_mov_b32_e32 v30, v37
	v_pk_add_f32 v[26:27], v[38:39], v[24:25]
	v_cmp_eq_u32_e32 vcc, 1, v1
	v_mov_b32_e32 v60, v18
	v_mov_b32_e32 v61, v2
	v_mov_b32_e32 v2, v19
	v_pk_add_f32 v[18:19], v[44:45], v[30:31]
	v_cndmask_b32_e32 v12, v26, v27, vcc
	v_cmp_eq_u32_e32 vcc, 2, v1
	v_mov_b32_e32 v40, v55
	v_pk_add_f32 v[16:17], v[46:47], v[40:41]
	v_cndmask_b32_e32 v12, v12, v18, vcc
	v_cmp_eq_u32_e32 vcc, 3, v1
	v_pk_add_f32 v[152:153], v[152:153], 0 op_sel_hi:[1,0]
	v_pk_add_f32 v[58:59], v[58:59], 0 op_sel_hi:[1,0]
	v_cndmask_b32_e32 v12, v12, v19, vcc
	v_cmp_eq_u32_e32 vcc, 4, v1
	v_pk_add_f32 v[58:59], v[58:59], v[82:83]
	v_pk_add_f32 v[82:83], v[152:153], v[154:155]
	v_cndmask_b32_e32 v12, v12, v16, vcc
	v_cmp_eq_u32_e32 vcc, 5, v1
	v_pk_add_f32 v[10:11], v[52:53], v[10:11]
	v_pk_add_f32 v[80:81], v[82:83], v[158:159]
	v_cndmask_b32_e32 v12, v12, v17, vcc
	v_cmp_eq_u32_e32 vcc, 6, v1
	v_pk_add_f32 v[58:59], v[58:59], v[98:99]
	v_mov_b32_e32 v63, v91
	v_cndmask_b32_e32 v12, v12, v10, vcc
	v_cmp_eq_u32_e32 vcc, 7, v1
	v_pk_add_f32 v[58:59], v[58:59], v[74:75]
	v_pk_add_f32 v[74:75], v[80:81], v[160:161]
	v_mov_b32_e32 v76, v162
	v_mov_b32_e32 v77, v164
	v_pk_add_f32 v[8:9], v[8:9], v[62:63]
	v_cndmask_b32_e32 v12, v12, v11, vcc
	v_cmp_eq_u32_e32 vcc, 8, v1
	v_pk_add_f32 v[74:75], v[74:75], v[76:77]
	v_mov_b32_e32 v164, v163
	v_cndmask_b32_e32 v12, v12, v8, vcc
	v_cmp_eq_u32_e32 vcc, 9, v1
	v_mov_b32_e32 v76, v166
	v_mov_b32_e32 v77, v168
	v_pk_add_f32 v[74:75], v[74:75], v[164:165]
	v_mov_b32_e32 v4, v170
	v_mov_b32_e32 v5, v172
	v_cndmask_b32_e32 v12, v12, v9, vcc
	v_cmp_eq_u32_e32 vcc, 10, v1
	v_pk_add_f32 v[58:59], v[58:59], v[76:77]
	v_mov_b32_e32 v168, v167
	v_pk_add_f32 v[4:5], v[74:75], v[4:5]
	v_mov_b32_e32 v172, v171
	v_cndmask_b32_e32 v12, v12, v6, vcc
	v_cmp_eq_u32_e32 vcc, 11, v1
	v_pk_add_f32 v[58:59], v[58:59], v[168:169]
	v_pk_add_f32 v[4:5], v[4:5], v[172:173]
	v_cndmask_b32_e32 v12, v12, v7, vcc
	v_cmp_eq_u32_e32 vcc, 12, v1
	v_pk_add_f32 v[58:59], v[58:59], v[60:61]
	v_and_b32_e32 v100, 8, v144
	v_cndmask_b32_e32 v12, v12, v4, vcc
	v_cmp_eq_u32_e32 vcc, 13, v1
	v_pk_add_f32 v[2:3], v[58:59], v[2:3]
	v_xor_b32_e32 v20, 8, v199
	v_cndmask_b32_e32 v12, v12, v5, vcc
	v_cmp_eq_u32_e32 vcc, 14, v1
	s_mov_b32 s45, s18
	s_nop 0
	v_cndmask_b32_e32 v12, v12, v2, vcc
	v_cmp_eq_u32_e32 vcc, 15, v1
	s_nop 1
	v_cndmask_b32_e32 v12, v12, v3, vcc
	v_cmp_eq_u32_e32 vcc, 1, v100
	s_nop 1
	v_cndmask_b32_e32 v1, v26, v27, vcc
	v_cmp_eq_u32_e32 vcc, 2, v100
	s_nop 1
	v_cndmask_b32_e32 v1, v1, v18, vcc
	v_cmp_eq_u32_e32 vcc, 3, v100
	s_nop 1
	v_cndmask_b32_e32 v1, v1, v19, vcc
	v_cmp_eq_u32_e32 vcc, 4, v100
	s_nop 1
	v_cndmask_b32_e32 v1, v1, v16, vcc
	v_cmp_eq_u32_e32 vcc, 5, v100
	s_nop 1
	v_cndmask_b32_e32 v1, v1, v17, vcc
	v_cmp_eq_u32_e32 vcc, 6, v100
	s_nop 1
	v_cndmask_b32_e32 v1, v1, v10, vcc
	v_cmp_eq_u32_e32 vcc, 7, v100
	s_nop 1
	v_cndmask_b32_e32 v1, v1, v11, vcc
	v_cmp_ne_u32_e32 vcc, 0, v100
	s_nop 1
	v_cndmask_b32_e32 v1, v1, v8, vcc
	v_cmp_eq_u32_e32 vcc, 9, v100
	s_nop 1
	v_cndmask_b32_e32 v1, v1, v9, vcc
	v_cmp_eq_u32_e32 vcc, 10, v100
	s_nop 1
	v_cndmask_b32_e32 v1, v1, v6, vcc
	v_cmp_eq_u32_e32 vcc, 11, v100
	s_nop 1
	v_cndmask_b32_e32 v1, v1, v7, vcc
	v_cmp_eq_u32_e32 vcc, 12, v100
	s_nop 1
	v_cndmask_b32_e32 v1, v1, v4, vcc
	v_cmp_eq_u32_e32 vcc, 13, v100
	s_nop 1
	v_cndmask_b32_e32 v1, v1, v5, vcc
	v_cmp_eq_u32_e32 vcc, 14, v100
	s_nop 1
	v_cndmask_b32_e32 v14, v1, v2, vcc
	v_and_b32_e32 v1, 64, v199
	v_add_u32_e32 v1, 64, v1
	v_cmp_lt_i32_e64 s[0:1], v20, v1
	v_cmp_eq_u32_e32 vcc, 0, v100
	s_nop 0
	v_cndmask_b32_e64 v20, v199, v20, s[0:1]
	v_lshlrev_b32_e32 v24, 2, v20
	ds_bpermute_b32 v12, v24, v12
	v_cmp_eq_u32_e64 s[0:1], 15, v100
	v_cndmask_b32_e32 v15, v0, v21, vcc
	v_cndmask_b32_e32 v20, v21, v0, vcc
	v_cndmask_b32_e64 v14, v14, v3, s[0:1]
	s_waitcnt lgkmcnt(0)
	v_add_f32_e32 v0, v14, v12
	v_bitop3_b32 v12, v144, 9, 8 bitop3:0x6c
	v_cmp_eq_u32_e64 s[0:1], 1, v12
	ds_bpermute_b32 v15, v24, v15
	v_cndmask_b32_e32 v21, v108, v109, vcc
	v_cndmask_b32_e64 v14, v0, v27, s[0:1]
	v_cmp_eq_u32_e64 s[0:1], 2, v12
	ds_bpermute_b32 v21, v24, v21
	s_waitcnt lgkmcnt(0)
	v_add_f32_e32 v15, v20, v15
	v_cndmask_b32_e64 v14, v14, v18, s[0:1]
	v_cmp_eq_u32_e64 s[0:1], 3, v12
	s_nop 1
	v_cndmask_b32_e64 v14, v14, v19, s[0:1]
	v_cmp_eq_u32_e64 s[0:1], 4, v12
	s_nop 1
	v_cndmask_b32_e64 v14, v14, v16, s[0:1]
	v_cmp_eq_u32_e64 s[0:1], 5, v12
	s_nop 1
	v_cndmask_b32_e64 v14, v14, v17, s[0:1]
	v_cmp_eq_u32_e64 s[0:1], 6, v12
	s_nop 1
	v_cndmask_b32_e64 v14, v14, v10, s[0:1]
	v_cmp_eq_u32_e64 s[0:1], 7, v12
	s_nop 1
	v_cndmask_b32_e64 v14, v14, v11, s[0:1]
	v_cmp_eq_u32_e64 s[0:1], 8, v12
	s_nop 1
	v_cndmask_b32_e64 v14, v14, v8, s[0:1]
	v_cmp_eq_u32_e64 s[0:1], 9, v12
	s_nop 1
	v_cndmask_b32_e64 v14, v14, v9, s[0:1]
	v_cmp_eq_u32_e64 s[0:1], 10, v12
	s_nop 1
	v_cndmask_b32_e64 v14, v14, v6, s[0:1]
	v_cmp_eq_u32_e64 s[0:1], 11, v12
	s_nop 1
	v_cndmask_b32_e64 v14, v14, v7, s[0:1]
	v_cmp_eq_u32_e64 s[0:1], 12, v12
	s_nop 1
	v_cndmask_b32_e64 v14, v14, v4, s[0:1]
	v_cmp_eq_u32_e64 s[0:1], 13, v12
	s_nop 1
	v_cndmask_b32_e64 v14, v14, v5, s[0:1]
	v_cmp_eq_u32_e64 s[0:1], 14, v12
	s_nop 1
	v_cndmask_b32_e64 v14, v14, v2, s[0:1]
	v_cmp_eq_u32_e64 s[0:1], 15, v12
	s_nop 1
	v_cndmask_b32_e64 v12, v14, v3, s[0:1]
	v_or_b32_e32 v14, 1, v100
	v_cmp_eq_u32_e64 s[0:1], 1, v14
	ds_bpermute_b32 v12, v24, v12
	s_nop 0
	v_cndmask_b32_e64 v20, v0, v27, s[0:1]
	v_cmp_eq_u32_e64 s[0:1], 2, v14
	s_nop 1
	v_cndmask_b32_e64 v20, v20, v18, s[0:1]
	v_cmp_eq_u32_e64 s[0:1], 3, v14
	s_nop 1
	v_cndmask_b32_e64 v20, v20, v19, s[0:1]
	v_cmp_eq_u32_e64 s[0:1], 4, v14
	s_nop 1
	v_cndmask_b32_e64 v20, v20, v16, s[0:1]
	v_cmp_eq_u32_e64 s[0:1], 5, v14
	s_nop 1
	v_cndmask_b32_e64 v20, v20, v17, s[0:1]
	v_cmp_eq_u32_e64 s[0:1], 6, v14
	s_nop 1
	v_cndmask_b32_e64 v20, v20, v10, s[0:1]
	v_cmp_eq_u32_e64 s[0:1], 7, v14
	s_nop 1
	v_cndmask_b32_e64 v20, v20, v11, s[0:1]
	v_cmp_eq_u32_e64 s[0:1], 8, v14
	s_nop 1
	v_cndmask_b32_e64 v20, v20, v8, s[0:1]
	v_cmp_eq_u32_e64 s[0:1], 9, v14
	s_nop 1
	v_cndmask_b32_e64 v20, v20, v9, s[0:1]
	v_cmp_eq_u32_e64 s[0:1], 10, v14
	s_nop 1
	v_cndmask_b32_e64 v20, v20, v6, s[0:1]
	v_cmp_eq_u32_e64 s[0:1], 11, v14
	s_nop 1
	v_cndmask_b32_e64 v20, v20, v7, s[0:1]
	v_cmp_eq_u32_e64 s[0:1], 12, v14
	s_nop 1
	v_cndmask_b32_e64 v20, v20, v4, s[0:1]
	v_cmp_eq_u32_e64 s[0:1], 13, v14
	s_nop 1
	v_cndmask_b32_e64 v20, v20, v5, s[0:1]
	v_cmp_eq_u32_e64 s[0:1], 14, v14
	s_nop 1
	v_cndmask_b32_e64 v20, v20, v2, s[0:1]
	v_cmp_eq_u32_e64 s[0:1], 15, v14
	s_nop 1
	v_cndmask_b32_e64 v14, v20, v3, s[0:1]
	s_waitcnt lgkmcnt(0)
	v_add_f32_e32 v23, v14, v12
	v_bitop3_b32 v12, v144, 10, 8 bitop3:0x6c
	v_cmp_eq_u32_e64 s[0:1], 1, v12
	v_cndmask_b32_e32 v20, v109, v108, vcc
	v_add_f32_e32 v20, v20, v21
	v_cndmask_b32_e64 v14, v0, v23, s[0:1]
	v_cmp_eq_u32_e64 s[0:1], 2, v12
	s_nop 1
	v_cndmask_b32_e64 v14, v14, v18, s[0:1]
	v_cmp_eq_u32_e64 s[0:1], 3, v12
	s_nop 1
	v_cndmask_b32_e64 v14, v14, v19, s[0:1]
	v_cmp_eq_u32_e64 s[0:1], 4, v12
	s_nop 1
	v_cndmask_b32_e64 v14, v14, v16, s[0:1]
	v_cmp_eq_u32_e64 s[0:1], 5, v12
	s_nop 1
	v_cndmask_b32_e64 v14, v14, v17, s[0:1]
	v_cmp_eq_u32_e64 s[0:1], 6, v12
	s_nop 1
	v_cndmask_b32_e64 v14, v14, v10, s[0:1]
	v_cmp_eq_u32_e64 s[0:1], 7, v12
	s_nop 1
	v_cndmask_b32_e64 v14, v14, v11, s[0:1]
	v_cmp_eq_u32_e64 s[0:1], 8, v12
	s_nop 1
	v_cndmask_b32_e64 v14, v14, v8, s[0:1]
	v_cmp_eq_u32_e64 s[0:1], 9, v12
	s_nop 1
	v_cndmask_b32_e64 v14, v14, v9, s[0:1]
	v_cmp_eq_u32_e64 s[0:1], 10, v12
	s_nop 1
	v_cndmask_b32_e64 v14, v14, v6, s[0:1]
	v_cmp_eq_u32_e64 s[0:1], 11, v12
	s_nop 1
	v_cndmask_b32_e64 v14, v14, v7, s[0:1]
	v_cmp_eq_u32_e64 s[0:1], 12, v12
	s_nop 1
	v_cndmask_b32_e64 v14, v14, v4, s[0:1]
	v_cmp_eq_u32_e64 s[0:1], 13, v12
	s_nop 1
	v_cndmask_b32_e64 v14, v14, v5, s[0:1]
	v_cmp_eq_u32_e64 s[0:1], 14, v12
	s_nop 1
	v_cndmask_b32_e64 v14, v14, v2, s[0:1]
	v_cmp_eq_u32_e64 s[0:1], 15, v12
	s_nop 1
	v_cndmask_b32_e64 v12, v14, v3, s[0:1]
	v_or_b32_e32 v14, 2, v100
	v_cmp_eq_u32_e64 s[0:1], 1, v14
	ds_bpermute_b32 v12, v24, v12
	s_nop 0
	v_cndmask_b32_e64 v21, v0, v23, s[0:1]
	v_cmp_eq_u32_e64 s[0:1], 2, v14
	s_nop 1
	v_cndmask_b32_e64 v18, v21, v18, s[0:1]
	v_cmp_eq_u32_e64 s[0:1], 3, v14
	v_cndmask_b32_e32 v21, v105, v139, vcc
	ds_bpermute_b32 v21, v24, v21
	v_cndmask_b32_e64 v18, v18, v19, s[0:1]
	v_cmp_eq_u32_e64 s[0:1], 4, v14
	s_nop 1
	v_cndmask_b32_e64 v18, v18, v16, s[0:1]
	v_cmp_eq_u32_e64 s[0:1], 5, v14
	s_nop 1
	v_cndmask_b32_e64 v18, v18, v17, s[0:1]
	v_cmp_eq_u32_e64 s[0:1], 6, v14
	s_nop 1
	v_cndmask_b32_e64 v18, v18, v10, s[0:1]
	v_cmp_eq_u32_e64 s[0:1], 7, v14
	s_nop 1
	v_cndmask_b32_e64 v18, v18, v11, s[0:1]
	v_cmp_eq_u32_e64 s[0:1], 8, v14
	s_nop 1
	v_cndmask_b32_e64 v18, v18, v8, s[0:1]
	v_cmp_eq_u32_e64 s[0:1], 9, v14
	s_nop 1
	v_cndmask_b32_e64 v18, v18, v9, s[0:1]
	v_cmp_eq_u32_e64 s[0:1], 10, v14
	s_nop 1
	v_cndmask_b32_e64 v18, v18, v6, s[0:1]
	v_cmp_eq_u32_e64 s[0:1], 11, v14
	s_nop 1
	v_cndmask_b32_e64 v18, v18, v7, s[0:1]
	v_cmp_eq_u32_e64 s[0:1], 12, v14
	s_nop 1
	v_cndmask_b32_e64 v18, v18, v4, s[0:1]
	v_cmp_eq_u32_e64 s[0:1], 13, v14
	s_nop 1
	v_cndmask_b32_e64 v18, v18, v5, s[0:1]
	v_cmp_eq_u32_e64 s[0:1], 14, v14
	s_nop 1
	v_cndmask_b32_e64 v18, v18, v2, s[0:1]
	v_cmp_eq_u32_e64 s[0:1], 15, v14
	s_nop 1
	v_cndmask_b32_e64 v14, v18, v3, s[0:1]
	s_waitcnt lgkmcnt(0)
	v_add_f32_e32 v22, v14, v12
	v_bitop3_b32 v12, v144, 11, 8 bitop3:0x6c
	v_cmp_eq_u32_e64 s[0:1], 1, v12
	v_cndmask_b32_e32 v18, v139, v105, vcc
	v_add_f32_e32 v18, v18, v21
	v_cndmask_b32_e64 v14, v0, v23, s[0:1]
	v_cmp_eq_u32_e64 s[0:1], 2, v12
	s_nop 1
	v_cndmask_b32_e64 v14, v14, v22, s[0:1]
	v_cmp_eq_u32_e64 s[0:1], 3, v12
	s_nop 1
	v_cndmask_b32_e64 v14, v14, v19, s[0:1]
	v_cmp_eq_u32_e64 s[0:1], 4, v12
	s_nop 1
	v_cndmask_b32_e64 v14, v14, v16, s[0:1]
	v_cmp_eq_u32_e64 s[0:1], 5, v12
	s_nop 1
	v_cndmask_b32_e64 v14, v14, v17, s[0:1]
	v_cmp_eq_u32_e64 s[0:1], 6, v12
	s_nop 1
	v_cndmask_b32_e64 v14, v14, v10, s[0:1]
	v_cmp_eq_u32_e64 s[0:1], 7, v12
	s_nop 1
	v_cndmask_b32_e64 v14, v14, v11, s[0:1]
	v_cmp_eq_u32_e64 s[0:1], 8, v12
	s_nop 1
	v_cndmask_b32_e64 v14, v14, v8, s[0:1]
	v_cmp_eq_u32_e64 s[0:1], 9, v12
	s_nop 1
	v_cndmask_b32_e64 v14, v14, v9, s[0:1]
	v_cmp_eq_u32_e64 s[0:1], 10, v12
	s_nop 1
	v_cndmask_b32_e64 v14, v14, v6, s[0:1]
	v_cmp_eq_u32_e64 s[0:1], 11, v12
	s_nop 1
	v_cndmask_b32_e64 v14, v14, v7, s[0:1]
	v_cmp_eq_u32_e64 s[0:1], 12, v12
	s_nop 1
	v_cndmask_b32_e64 v14, v14, v4, s[0:1]
	v_cmp_eq_u32_e64 s[0:1], 13, v12
	s_nop 1
	v_cndmask_b32_e64 v14, v14, v5, s[0:1]
	v_cmp_eq_u32_e64 s[0:1], 14, v12
	s_nop 1
	v_cndmask_b32_e64 v14, v14, v2, s[0:1]
	v_cmp_eq_u32_e64 s[0:1], 15, v12
	s_nop 1
	v_cndmask_b32_e64 v12, v14, v3, s[0:1]
	v_or_b32_e32 v14, 3, v100
	v_cmp_eq_u32_e64 s[0:1], 1, v14
	ds_bpermute_b32 v12, v24, v12
	s_nop 0
	v_cndmask_b32_e64 v21, v0, v23, s[0:1]
	v_cmp_eq_u32_e64 s[0:1], 2, v14
	s_nop 1
	v_cndmask_b32_e64 v21, v21, v22, s[0:1]
	v_cmp_eq_u32_e64 s[0:1], 3, v14
	s_nop 1
	v_cndmask_b32_e64 v19, v21, v19, s[0:1]
	v_cmp_eq_u32_e64 s[0:1], 4, v14
	v_cndmask_b32_e32 v21, v104, v72, vcc
	ds_bpermute_b32 v25, v24, v21
	v_cndmask_b32_e64 v19, v19, v16, s[0:1]
	v_cmp_eq_u32_e64 s[0:1], 5, v14
	s_nop 1
	v_cndmask_b32_e64 v19, v19, v17, s[0:1]
	v_cmp_eq_u32_e64 s[0:1], 6, v14
	s_nop 1
	v_cndmask_b32_e64 v19, v19, v10, s[0:1]
	v_cmp_eq_u32_e64 s[0:1], 7, v14
	s_nop 1
	v_cndmask_b32_e64 v19, v19, v11, s[0:1]
	v_cmp_eq_u32_e64 s[0:1], 8, v14
	s_nop 1
	v_cndmask_b32_e64 v19, v19, v8, s[0:1]
	v_cmp_eq_u32_e64 s[0:1], 9, v14
	s_nop 1
	v_cndmask_b32_e64 v19, v19, v9, s[0:1]
	v_cmp_eq_u32_e64 s[0:1], 10, v14
	s_nop 1
	v_cndmask_b32_e64 v19, v19, v6, s[0:1]
	v_cmp_eq_u32_e64 s[0:1], 11, v14
	s_nop 1
	v_cndmask_b32_e64 v19, v19, v7, s[0:1]
	v_cmp_eq_u32_e64 s[0:1], 12, v14
	s_nop 1
	v_cndmask_b32_e64 v19, v19, v4, s[0:1]
	v_cmp_eq_u32_e64 s[0:1], 13, v14
	s_nop 1
	v_cndmask_b32_e64 v19, v19, v5, s[0:1]
	v_cmp_eq_u32_e64 s[0:1], 14, v14
	s_nop 1
	v_cndmask_b32_e64 v19, v19, v2, s[0:1]
	v_cmp_eq_u32_e64 s[0:1], 15, v14
	s_nop 1
	v_cndmask_b32_e64 v14, v19, v3, s[0:1]
	s_waitcnt lgkmcnt(0)
	v_add_f32_e32 v21, v14, v12
	v_bitop3_b32 v12, v144, 12, 8 bitop3:0x6c
	v_cmp_eq_u32_e64 s[0:1], 1, v12
	v_cndmask_b32_e32 v19, v72, v104, vcc
	v_add_f32_e32 v19, v19, v25
	v_cndmask_b32_e64 v14, v0, v23, s[0:1]
	v_cmp_eq_u32_e64 s[0:1], 2, v12
	s_nop 1
	v_cndmask_b32_e64 v14, v14, v22, s[0:1]
	v_cmp_eq_u32_e64 s[0:1], 3, v12
	s_nop 1
	v_cndmask_b32_e64 v14, v14, v21, s[0:1]
	v_cmp_eq_u32_e64 s[0:1], 4, v12
	s_nop 1
	v_cndmask_b32_e64 v14, v14, v16, s[0:1]
	v_cmp_eq_u32_e64 s[0:1], 5, v12
	s_nop 1
	v_cndmask_b32_e64 v14, v14, v17, s[0:1]
	v_cmp_eq_u32_e64 s[0:1], 6, v12
	s_nop 1
	v_cndmask_b32_e64 v14, v14, v10, s[0:1]
	v_cmp_eq_u32_e64 s[0:1], 7, v12
	s_nop 1
	v_cndmask_b32_e64 v14, v14, v11, s[0:1]
	v_cmp_eq_u32_e64 s[0:1], 8, v12
	s_nop 1
	v_cndmask_b32_e64 v14, v14, v8, s[0:1]
	v_cmp_eq_u32_e64 s[0:1], 9, v12
	s_nop 1
	v_cndmask_b32_e64 v14, v14, v9, s[0:1]
	v_cmp_eq_u32_e64 s[0:1], 10, v12
	s_nop 1
	v_cndmask_b32_e64 v14, v14, v6, s[0:1]
	v_cmp_eq_u32_e64 s[0:1], 11, v12
	s_nop 1
	v_cndmask_b32_e64 v14, v14, v7, s[0:1]
	v_cmp_eq_u32_e64 s[0:1], 12, v12
	s_nop 1
	v_cndmask_b32_e64 v14, v14, v4, s[0:1]
	v_cmp_eq_u32_e64 s[0:1], 13, v12
	s_nop 1
	v_cndmask_b32_e64 v14, v14, v5, s[0:1]
	v_cmp_eq_u32_e64 s[0:1], 14, v12
	s_nop 1
	v_cndmask_b32_e64 v14, v14, v2, s[0:1]
	v_cmp_eq_u32_e64 s[0:1], 15, v12
	s_nop 1
	v_cndmask_b32_e64 v12, v14, v3, s[0:1]
	v_or_b32_e32 v14, 4, v100
	v_cmp_eq_u32_e64 s[0:1], 1, v14
	ds_bpermute_b32 v12, v24, v12
	s_nop 0
	v_cndmask_b32_e64 v25, v0, v23, s[0:1]
	v_cmp_eq_u32_e64 s[0:1], 2, v14
	s_nop 1
	v_cndmask_b32_e64 v25, v25, v22, s[0:1]
	v_cmp_eq_u32_e64 s[0:1], 3, v14
	s_nop 1
	v_cndmask_b32_e64 v25, v25, v21, s[0:1]
	v_cmp_eq_u32_e64 s[0:1], 4, v14
	s_nop 1
	v_cndmask_b32_e64 v16, v25, v16, s[0:1]
	v_cmp_eq_u32_e64 s[0:1], 5, v14
	v_cndmask_b32_e32 v25, v103, v50, vcc
	ds_bpermute_b32 v25, v24, v25
	v_cndmask_b32_e64 v16, v16, v17, s[0:1]
	v_cmp_eq_u32_e64 s[0:1], 6, v14
	s_nop 1
	v_cndmask_b32_e64 v16, v16, v10, s[0:1]
	v_cmp_eq_u32_e64 s[0:1], 7, v14
	s_nop 1
	v_cndmask_b32_e64 v16, v16, v11, s[0:1]
	v_cmp_eq_u32_e64 s[0:1], 8, v14
	s_nop 1
	v_cndmask_b32_e64 v16, v16, v8, s[0:1]
	v_cmp_eq_u32_e64 s[0:1], 9, v14
	s_nop 1
	v_cndmask_b32_e64 v16, v16, v9, s[0:1]
	v_cmp_eq_u32_e64 s[0:1], 10, v14
	s_nop 1
	v_cndmask_b32_e64 v16, v16, v6, s[0:1]
	v_cmp_eq_u32_e64 s[0:1], 11, v14
	s_nop 1
	v_cndmask_b32_e64 v16, v16, v7, s[0:1]
	v_cmp_eq_u32_e64 s[0:1], 12, v14
	s_nop 1
	v_cndmask_b32_e64 v16, v16, v4, s[0:1]
	v_cmp_eq_u32_e64 s[0:1], 13, v14
	s_nop 1
	v_cndmask_b32_e64 v16, v16, v5, s[0:1]
	v_cmp_eq_u32_e64 s[0:1], 14, v14
	s_nop 1
	v_cndmask_b32_e64 v16, v16, v2, s[0:1]
	v_cmp_eq_u32_e64 s[0:1], 15, v14
	s_nop 1
	v_cndmask_b32_e64 v14, v16, v3, s[0:1]
	s_waitcnt lgkmcnt(0)
	v_add_f32_e32 v12, v14, v12
	v_bitop3_b32 v14, v144, 13, 8 bitop3:0x6c
	v_cndmask_b32_e32 v16, v50, v103, vcc
	v_cmp_eq_u32_e64 s[0:1], 1, v14
	v_add_f32_e32 v16, v16, v25
	s_nop 0
	v_cndmask_b32_e64 v25, v0, v23, s[0:1]
	v_cmp_eq_u32_e64 s[0:1], 2, v14
	s_nop 1
	v_cndmask_b32_e64 v25, v25, v22, s[0:1]
	v_cmp_eq_u32_e64 s[0:1], 3, v14
	s_nop 1
	v_cndmask_b32_e64 v25, v25, v21, s[0:1]
	v_cmp_eq_u32_e64 s[0:1], 4, v14
	s_nop 1
	v_cndmask_b32_e64 v25, v25, v12, s[0:1]
	v_cmp_eq_u32_e64 s[0:1], 5, v14
	s_nop 1
	v_cndmask_b32_e64 v25, v25, v17, s[0:1]
	v_cmp_eq_u32_e64 s[0:1], 6, v14
	s_nop 1
	v_cndmask_b32_e64 v25, v25, v10, s[0:1]
	v_cmp_eq_u32_e64 s[0:1], 7, v14
	s_nop 1
	v_cndmask_b32_e64 v25, v25, v11, s[0:1]
	v_cmp_eq_u32_e64 s[0:1], 8, v14
	s_nop 1
	v_cndmask_b32_e64 v25, v25, v8, s[0:1]
	v_cmp_eq_u32_e64 s[0:1], 9, v14
	s_nop 1
	v_cndmask_b32_e64 v25, v25, v9, s[0:1]
	v_cmp_eq_u32_e64 s[0:1], 10, v14
	s_nop 1
	v_cndmask_b32_e64 v25, v25, v6, s[0:1]
	v_cmp_eq_u32_e64 s[0:1], 11, v14
	s_nop 1
	v_cndmask_b32_e64 v25, v25, v7, s[0:1]
	v_cmp_eq_u32_e64 s[0:1], 12, v14
	s_nop 1
	v_cndmask_b32_e64 v25, v25, v4, s[0:1]
	v_cmp_eq_u32_e64 s[0:1], 13, v14
	s_nop 1
	v_cndmask_b32_e64 v25, v25, v5, s[0:1]
	v_cmp_eq_u32_e64 s[0:1], 14, v14
	s_nop 1
	v_cndmask_b32_e64 v25, v25, v2, s[0:1]
	v_cmp_eq_u32_e64 s[0:1], 15, v14
	s_nop 1
	v_cndmask_b32_e64 v14, v25, v3, s[0:1]
	v_or_b32_e32 v25, 5, v100
	v_cmp_eq_u32_e64 s[0:1], 1, v25
	ds_bpermute_b32 v14, v24, v14
	s_nop 0
	v_cndmask_b32_e64 v26, v0, v23, s[0:1]
	v_cmp_eq_u32_e64 s[0:1], 2, v25
	s_nop 1
	v_cndmask_b32_e64 v26, v26, v22, s[0:1]
	v_cmp_eq_u32_e64 s[0:1], 3, v25
	s_nop 1
	v_cndmask_b32_e64 v26, v26, v21, s[0:1]
	v_cmp_eq_u32_e64 s[0:1], 4, v25
	s_nop 1
	v_cndmask_b32_e64 v26, v26, v12, s[0:1]
	v_cmp_eq_u32_e64 s[0:1], 5, v25
	s_nop 1
	v_cndmask_b32_e64 v17, v26, v17, s[0:1]
	v_cmp_eq_u32_e64 s[0:1], 6, v25
	v_cndmask_b32_e32 v26, v102, v43, vcc
	ds_bpermute_b32 v26, v24, v26
	v_cndmask_b32_e64 v17, v17, v10, s[0:1]
	v_cmp_eq_u32_e64 s[0:1], 7, v25
	s_nop 1
	v_cndmask_b32_e64 v17, v17, v11, s[0:1]
	v_cmp_eq_u32_e64 s[0:1], 8, v25
	s_nop 1
	v_cndmask_b32_e64 v17, v17, v8, s[0:1]
	v_cmp_eq_u32_e64 s[0:1], 9, v25
	s_nop 1
	v_cndmask_b32_e64 v17, v17, v9, s[0:1]
	v_cmp_eq_u32_e64 s[0:1], 10, v25
	s_nop 1
	v_cndmask_b32_e64 v17, v17, v6, s[0:1]
	v_cmp_eq_u32_e64 s[0:1], 11, v25
	s_nop 1
	v_cndmask_b32_e64 v17, v17, v7, s[0:1]
	v_cmp_eq_u32_e64 s[0:1], 12, v25
	s_nop 1
	v_cndmask_b32_e64 v17, v17, v4, s[0:1]
	v_cmp_eq_u32_e64 s[0:1], 13, v25
	s_nop 1
	v_cndmask_b32_e64 v17, v17, v5, s[0:1]
	v_cmp_eq_u32_e64 s[0:1], 14, v25
	s_nop 1
	v_cndmask_b32_e64 v17, v17, v2, s[0:1]
	v_cmp_eq_u32_e64 s[0:1], 15, v25
	v_cndmask_b32_e32 v25, v43, v102, vcc
	s_nop 0
	v_cndmask_b32_e64 v17, v17, v3, s[0:1]
	s_waitcnt lgkmcnt(0)
	v_add_f32_e32 v14, v17, v14
	v_add_f32_e32 v17, v25, v26
	v_bitop3_b32 v25, v144, 14, 8 bitop3:0x6c
	v_cmp_eq_u32_e64 s[0:1], 1, v25
	s_nop 1
	v_cndmask_b32_e64 v26, v0, v23, s[0:1]
	v_cmp_eq_u32_e64 s[0:1], 2, v25
	s_nop 1
	v_cndmask_b32_e64 v26, v26, v22, s[0:1]
	v_cmp_eq_u32_e64 s[0:1], 3, v25
	s_nop 1
	v_cndmask_b32_e64 v26, v26, v21, s[0:1]
	v_cmp_eq_u32_e64 s[0:1], 4, v25
	s_nop 1
	v_cndmask_b32_e64 v26, v26, v12, s[0:1]
	v_cmp_eq_u32_e64 s[0:1], 5, v25
	s_nop 1
	v_cndmask_b32_e64 v26, v26, v14, s[0:1]
	v_cmp_eq_u32_e64 s[0:1], 6, v25
	s_nop 1
	v_cndmask_b32_e64 v26, v26, v10, s[0:1]
	v_cmp_eq_u32_e64 s[0:1], 7, v25
	s_nop 1
	v_cndmask_b32_e64 v26, v26, v11, s[0:1]
	v_cmp_eq_u32_e64 s[0:1], 8, v25
	s_nop 1
	v_cndmask_b32_e64 v26, v26, v8, s[0:1]
	v_cmp_eq_u32_e64 s[0:1], 9, v25
	s_nop 1
	v_cndmask_b32_e64 v26, v26, v9, s[0:1]
	v_cmp_eq_u32_e64 s[0:1], 10, v25
	s_nop 1
	v_cndmask_b32_e64 v26, v26, v6, s[0:1]
	v_cmp_eq_u32_e64 s[0:1], 11, v25
	s_nop 1
	v_cndmask_b32_e64 v26, v26, v7, s[0:1]
	v_cmp_eq_u32_e64 s[0:1], 12, v25
	s_nop 1
	v_cndmask_b32_e64 v26, v26, v4, s[0:1]
	v_cmp_eq_u32_e64 s[0:1], 13, v25
	s_nop 1
	v_cndmask_b32_e64 v26, v26, v5, s[0:1]
	v_cmp_eq_u32_e64 s[0:1], 14, v25
	s_nop 1
	v_cndmask_b32_e64 v26, v26, v2, s[0:1]
	v_cmp_eq_u32_e64 s[0:1], 15, v25
	s_nop 1
	v_cndmask_b32_e64 v25, v26, v3, s[0:1]
	v_or_b32_e32 v26, 6, v100
	v_cmp_eq_u32_e64 s[0:1], 1, v26
	ds_bpermute_b32 v25, v24, v25
	s_nop 0
	v_cndmask_b32_e64 v27, v0, v23, s[0:1]
	v_cmp_eq_u32_e64 s[0:1], 2, v26
	s_nop 1
	v_cndmask_b32_e64 v27, v27, v22, s[0:1]
	v_cmp_eq_u32_e64 s[0:1], 3, v26
	s_nop 1
	v_cndmask_b32_e64 v27, v27, v21, s[0:1]
	v_cmp_eq_u32_e64 s[0:1], 4, v26
	s_nop 1
	v_cndmask_b32_e64 v27, v27, v12, s[0:1]
	v_cmp_eq_u32_e64 s[0:1], 5, v26
	s_nop 1
	v_cndmask_b32_e64 v27, v27, v14, s[0:1]
	v_cmp_eq_u32_e64 s[0:1], 6, v26
	s_nop 1
	v_cndmask_b32_e64 v10, v27, v10, s[0:1]
	v_cmp_eq_u32_e64 s[0:1], 7, v26
	v_cndmask_b32_e32 v27, v101, v35, vcc
	ds_bpermute_b32 v27, v24, v27
	v_cndmask_b32_e64 v10, v10, v11, s[0:1]
	v_cmp_eq_u32_e64 s[0:1], 8, v26
	s_nop 1
	v_cndmask_b32_e64 v10, v10, v8, s[0:1]
	v_cmp_eq_u32_e64 s[0:1], 9, v26
	s_nop 1
	v_cndmask_b32_e64 v10, v10, v9, s[0:1]
	v_cmp_eq_u32_e64 s[0:1], 10, v26
	s_nop 1
	v_cndmask_b32_e64 v10, v10, v6, s[0:1]
	v_cmp_eq_u32_e64 s[0:1], 11, v26
	s_nop 1
	v_cndmask_b32_e64 v10, v10, v7, s[0:1]
	v_cmp_eq_u32_e64 s[0:1], 12, v26
	s_nop 1
	v_cndmask_b32_e64 v10, v10, v4, s[0:1]
	v_cmp_eq_u32_e64 s[0:1], 13, v26
	s_nop 1
	v_cndmask_b32_e64 v10, v10, v5, s[0:1]
	v_cmp_eq_u32_e64 s[0:1], 14, v26
	s_nop 1
	v_cndmask_b32_e64 v10, v10, v2, s[0:1]
	v_cmp_eq_u32_e64 s[0:1], 15, v26
	v_cndmask_b32_e32 v26, v35, v101, vcc
	s_nop 0
	v_cndmask_b32_e64 v10, v10, v3, s[0:1]
	s_waitcnt lgkmcnt(0)
	v_add_f32_e32 v10, v10, v25
	v_add_f32_e32 v25, v26, v27
	v_bitop3_b32 v26, v144, 15, 8 bitop3:0x6c
	v_cmp_eq_u32_e64 s[0:1], 1, v26
	s_nop 1
	v_cndmask_b32_e64 v27, v0, v23, s[0:1]
	v_cmp_eq_u32_e64 s[0:1], 2, v26
	s_nop 1
	v_cndmask_b32_e64 v27, v27, v22, s[0:1]
	v_cmp_eq_u32_e64 s[0:1], 3, v26
	s_nop 1
	v_cndmask_b32_e64 v27, v27, v21, s[0:1]
	v_cmp_eq_u32_e64 s[0:1], 4, v26
	s_nop 1
	v_cndmask_b32_e64 v27, v27, v12, s[0:1]
	v_cmp_eq_u32_e64 s[0:1], 5, v26
	s_nop 1
	v_cndmask_b32_e64 v27, v27, v14, s[0:1]
	v_cmp_eq_u32_e64 s[0:1], 6, v26
	s_nop 1
	v_cndmask_b32_e64 v27, v27, v10, s[0:1]
	v_cmp_eq_u32_e64 s[0:1], 7, v26
	s_nop 1
	v_cndmask_b32_e64 v27, v27, v11, s[0:1]
	v_cmp_eq_u32_e64 s[0:1], 8, v26
	s_nop 1
	v_cndmask_b32_e64 v27, v27, v8, s[0:1]
	v_cmp_eq_u32_e64 s[0:1], 9, v26
	s_nop 1
	v_cndmask_b32_e64 v27, v27, v9, s[0:1]
	v_cmp_eq_u32_e64 s[0:1], 10, v26
	s_nop 1
	v_cndmask_b32_e64 v27, v27, v6, s[0:1]
	v_cmp_eq_u32_e64 s[0:1], 11, v26
	s_nop 1
	v_cndmask_b32_e64 v27, v27, v7, s[0:1]
	v_cmp_eq_u32_e64 s[0:1], 12, v26
	s_nop 1
	v_cndmask_b32_e64 v27, v27, v4, s[0:1]
	v_cmp_eq_u32_e64 s[0:1], 13, v26
	s_nop 1
	v_cndmask_b32_e64 v27, v27, v5, s[0:1]
	v_cmp_eq_u32_e64 s[0:1], 14, v26
	s_nop 1
	v_cndmask_b32_e64 v27, v27, v2, s[0:1]
	v_cmp_eq_u32_e64 s[0:1], 15, v26
	s_nop 1
	v_cndmask_b32_e64 v26, v27, v3, s[0:1]
	v_or_b32_e32 v27, 7, v100
	v_cmp_eq_u32_e64 s[0:1], 1, v27
	ds_bpermute_b32 v26, v24, v26
	s_nop 0
	v_cndmask_b32_e64 v28, v0, v23, s[0:1]
	v_cmp_eq_u32_e64 s[0:1], 2, v27
	s_nop 1
	v_cndmask_b32_e64 v28, v28, v22, s[0:1]
	v_cmp_eq_u32_e64 s[0:1], 3, v27
	s_nop 1
	v_cndmask_b32_e64 v28, v28, v21, s[0:1]
	v_cmp_eq_u32_e64 s[0:1], 4, v27
	s_nop 1
	v_cndmask_b32_e64 v28, v28, v12, s[0:1]
	v_cmp_eq_u32_e64 s[0:1], 5, v27
	s_nop 1
	v_cndmask_b32_e64 v28, v28, v14, s[0:1]
	v_cmp_eq_u32_e64 s[0:1], 6, v27
	s_nop 1
	v_cndmask_b32_e64 v28, v28, v10, s[0:1]
	v_cmp_eq_u32_e64 s[0:1], 7, v27
	s_nop 1
	v_cndmask_b32_e64 v11, v28, v11, s[0:1]
	v_cmp_eq_u32_e64 s[0:1], 8, v27
	v_cndmask_b32_e32 v28, v13, v34, vcc
	ds_bpermute_b32 v24, v24, v28
	v_cndmask_b32_e64 v11, v11, v8, s[0:1]
	v_cmp_eq_u32_e64 s[0:1], 9, v27
	v_cndmask_b32_e32 v13, v34, v13, vcc
	v_xor_b32_e32 v28, 4, v199
	v_cndmask_b32_e64 v11, v11, v9, s[0:1]
	v_cmp_eq_u32_e64 s[0:1], 10, v27
	s_nop 1
	v_cndmask_b32_e64 v11, v11, v6, s[0:1]
	v_cmp_eq_u32_e64 s[0:1], 11, v27
	s_nop 1
	v_cndmask_b32_e64 v11, v11, v7, s[0:1]
	v_cmp_eq_u32_e64 s[0:1], 12, v27
	s_nop 1
	v_cndmask_b32_e64 v11, v11, v4, s[0:1]
	v_cmp_eq_u32_e64 s[0:1], 13, v27
	s_nop 1
	v_cndmask_b32_e64 v11, v11, v5, s[0:1]
	v_cmp_eq_u32_e64 s[0:1], 14, v27
	s_nop 1
	v_cndmask_b32_e64 v11, v11, v2, s[0:1]
	v_cmp_eq_u32_e64 s[0:1], 15, v27
	s_nop 1
	v_cndmask_b32_e64 v11, v11, v3, s[0:1]
	s_waitcnt lgkmcnt(0)
	v_add_f32_e32 v26, v11, v26
	v_add_f32_e32 v11, v13, v24
	v_bitop3_b32 v24, v144, 4, v144 bitop3:0xc
	v_cmp_eq_u32_e32 vcc, 1, v24
	v_and_b32_e32 v13, 4, v144
	v_cmp_lt_i32_e64 s[0:1], v28, v1
	v_cndmask_b32_e32 v27, v0, v23, vcc
	v_cmp_eq_u32_e32 vcc, 2, v24
	v_cndmask_b32_e64 v28, v199, v28, s[0:1]
	v_lshlrev_b32_e32 v28, 2, v28
	v_cndmask_b32_e32 v27, v27, v22, vcc
	v_cmp_eq_u32_e32 vcc, 3, v24
	v_cmp_eq_u32_e64 s[0:1], 15, v13
	s_nop 0
	v_cndmask_b32_e32 v27, v27, v21, vcc
	v_cmp_eq_u32_e32 vcc, 4, v24
	s_nop 1
	v_cndmask_b32_e32 v27, v27, v12, vcc
	v_cmp_eq_u32_e32 vcc, 5, v24
	s_nop 1
	v_cndmask_b32_e32 v27, v27, v14, vcc
	v_cmp_eq_u32_e32 vcc, 6, v24
	s_nop 1
	v_cndmask_b32_e32 v27, v27, v10, vcc
	v_cmp_eq_u32_e32 vcc, 7, v24
	s_nop 1
	v_cndmask_b32_e32 v27, v27, v26, vcc
	v_cmp_eq_u32_e32 vcc, 8, v24
	s_nop 1
	v_cndmask_b32_e32 v27, v27, v8, vcc
	v_cmp_eq_u32_e32 vcc, 9, v24
	s_nop 1
	v_cndmask_b32_e32 v27, v27, v9, vcc
	v_cmp_eq_u32_e32 vcc, 10, v24
	s_nop 1
	v_cndmask_b32_e32 v27, v27, v6, vcc
	v_cmp_eq_u32_e32 vcc, 11, v24
	s_nop 1
	v_cndmask_b32_e32 v27, v27, v7, vcc
	v_cmp_eq_u32_e32 vcc, 12, v24
	s_nop 1
	v_cndmask_b32_e32 v27, v27, v4, vcc
	v_cmp_eq_u32_e32 vcc, 13, v24
	s_nop 1
	v_cndmask_b32_e32 v27, v27, v5, vcc
	v_cmp_eq_u32_e32 vcc, 14, v24
	s_nop 1
	v_cndmask_b32_e32 v27, v27, v2, vcc
	v_cmp_eq_u32_e32 vcc, 15, v24
	s_nop 1
	v_cndmask_b32_e32 v24, v27, v3, vcc
	v_cmp_eq_u32_e32 vcc, 1, v13
	ds_bpermute_b32 v24, v28, v24
	s_nop 0
	v_cndmask_b32_e32 v0, v0, v23, vcc
	v_cmp_eq_u32_e32 vcc, 2, v13
	s_nop 1
	v_cndmask_b32_e32 v0, v0, v22, vcc
	v_cmp_eq_u32_e32 vcc, 3, v13
	s_nop 1
	v_cndmask_b32_e32 v0, v0, v21, vcc
	v_cmp_ne_u32_e32 vcc, 0, v13
	s_nop 1
	v_cndmask_b32_e32 v0, v0, v12, vcc
	v_cmp_eq_u32_e32 vcc, 5, v13
	s_nop 1
	v_cndmask_b32_e32 v0, v0, v14, vcc
	v_cmp_eq_u32_e32 vcc, 6, v13
	s_nop 1
	v_cndmask_b32_e32 v0, v0, v10, vcc
	v_cmp_eq_u32_e32 vcc, 7, v13
	s_nop 1
	v_cndmask_b32_e32 v0, v0, v26, vcc
	v_cmp_eq_u32_e32 vcc, 8, v13
	s_nop 1
	v_cndmask_b32_e32 v0, v0, v8, vcc
	v_cmp_eq_u32_e32 vcc, 9, v13
	s_nop 1
	v_cndmask_b32_e32 v0, v0, v9, vcc
	v_cmp_eq_u32_e32 vcc, 10, v13
	s_nop 1
	v_cndmask_b32_e32 v0, v0, v6, vcc
	v_cmp_eq_u32_e32 vcc, 11, v13
	s_nop 1
	v_cndmask_b32_e32 v0, v0, v7, vcc
	v_cmp_eq_u32_e32 vcc, 12, v13
	s_nop 1
	v_cndmask_b32_e32 v0, v0, v4, vcc
	v_cmp_eq_u32_e32 vcc, 13, v13
	s_nop 1
	v_cndmask_b32_e32 v0, v0, v5, vcc
	v_cmp_eq_u32_e32 vcc, 14, v13
	s_nop 1
	v_cndmask_b32_e32 v0, v0, v2, vcc
	v_cmp_eq_u32_e32 vcc, 0, v13
	v_cndmask_b32_e64 v0, v0, v3, s[0:1]
	s_waitcnt lgkmcnt(0)
	v_add_f32_e32 v0, v0, v24
	v_cndmask_b32_e32 v27, v15, v16, vcc
	v_cndmask_b32_e32 v15, v16, v15, vcc
	v_bitop3_b32 v16, v144, 5, 4 bitop3:0x6c
	v_cmp_eq_u32_e64 s[0:1], 1, v16
	ds_bpermute_b32 v27, v28, v27
	s_waitcnt lgkmcnt(0)
	v_add_f32_e32 v15, v15, v27
	v_cndmask_b32_e64 v24, v0, v23, s[0:1]
	v_cmp_eq_u32_e64 s[0:1], 2, v16
	v_cndmask_b32_e32 v27, v20, v17, vcc
	v_cndmask_b32_e32 v17, v17, v20, vcc
	v_cndmask_b32_e64 v24, v24, v22, s[0:1]
	v_cmp_eq_u32_e64 s[0:1], 3, v16
	v_bitop3_b32 v20, v144, 6, 4 bitop3:0x6c
	ds_bpermute_b32 v27, v28, v27
	v_cndmask_b32_e64 v24, v24, v21, s[0:1]
	v_cmp_eq_u32_e64 s[0:1], 4, v16
	s_waitcnt lgkmcnt(0)
	v_add_f32_e32 v17, v17, v27
	v_cndmask_b32_e64 v24, v24, v12, s[0:1]
	v_cmp_eq_u32_e64 s[0:1], 5, v16
	s_nop 1
	v_cndmask_b32_e64 v24, v24, v14, s[0:1]
	v_cmp_eq_u32_e64 s[0:1], 6, v16
	s_nop 1
	v_cndmask_b32_e64 v24, v24, v10, s[0:1]
	v_cmp_eq_u32_e64 s[0:1], 7, v16
	s_nop 1
	v_cndmask_b32_e64 v24, v24, v26, s[0:1]
	v_cmp_eq_u32_e64 s[0:1], 8, v16
	s_nop 1
	v_cndmask_b32_e64 v24, v24, v8, s[0:1]
	v_cmp_eq_u32_e64 s[0:1], 9, v16
	s_nop 1
	v_cndmask_b32_e64 v24, v24, v9, s[0:1]
	v_cmp_eq_u32_e64 s[0:1], 10, v16
	s_nop 1
	v_cndmask_b32_e64 v24, v24, v6, s[0:1]
	v_cmp_eq_u32_e64 s[0:1], 11, v16
	s_nop 1
	v_cndmask_b32_e64 v24, v24, v7, s[0:1]
	v_cmp_eq_u32_e64 s[0:1], 12, v16
	s_nop 1
	v_cndmask_b32_e64 v24, v24, v4, s[0:1]
	v_cmp_eq_u32_e64 s[0:1], 13, v16
	s_nop 1
	v_cndmask_b32_e64 v24, v24, v5, s[0:1]
	v_cmp_eq_u32_e64 s[0:1], 14, v16
	s_nop 1
	v_cndmask_b32_e64 v24, v24, v2, s[0:1]
	v_cmp_eq_u32_e64 s[0:1], 15, v16
	s_nop 1
	v_cndmask_b32_e64 v16, v24, v3, s[0:1]
	v_or_b32_e32 v24, 1, v13
	v_cmp_eq_u32_e64 s[0:1], 1, v24
	ds_bpermute_b32 v16, v28, v16
	s_nop 0
	v_cndmask_b32_e64 v23, v0, v23, s[0:1]
	v_cmp_eq_u32_e64 s[0:1], 2, v24
	s_nop 1
	v_cndmask_b32_e64 v23, v23, v22, s[0:1]
	v_cmp_eq_u32_e64 s[0:1], 3, v24
	s_nop 1
	v_cndmask_b32_e64 v23, v23, v21, s[0:1]
	v_cmp_eq_u32_e64 s[0:1], 4, v24
	s_nop 1
	v_cndmask_b32_e64 v23, v23, v12, s[0:1]
	v_cmp_eq_u32_e64 s[0:1], 5, v24
	s_nop 1
	v_cndmask_b32_e64 v23, v23, v14, s[0:1]
	v_cmp_eq_u32_e64 s[0:1], 6, v24
	s_nop 1
	v_cndmask_b32_e64 v23, v23, v10, s[0:1]
	v_cmp_eq_u32_e64 s[0:1], 7, v24
	s_nop 1
	v_cndmask_b32_e64 v23, v23, v26, s[0:1]
	v_cmp_eq_u32_e64 s[0:1], 8, v24
	s_nop 1
	v_cndmask_b32_e64 v23, v23, v8, s[0:1]
	v_cmp_eq_u32_e64 s[0:1], 9, v24
	s_nop 1
	v_cndmask_b32_e64 v23, v23, v9, s[0:1]
	v_cmp_eq_u32_e64 s[0:1], 10, v24
	s_nop 1
	v_cndmask_b32_e64 v23, v23, v6, s[0:1]
	v_cmp_eq_u32_e64 s[0:1], 11, v24
	s_nop 1
	v_cndmask_b32_e64 v23, v23, v7, s[0:1]
	v_cmp_eq_u32_e64 s[0:1], 12, v24
	s_nop 1
	v_cndmask_b32_e64 v23, v23, v4, s[0:1]
	v_cmp_eq_u32_e64 s[0:1], 13, v24
	s_nop 1
	v_cndmask_b32_e64 v23, v23, v5, s[0:1]
	v_cmp_eq_u32_e64 s[0:1], 14, v24
	s_nop 1
	v_cndmask_b32_e64 v23, v23, v2, s[0:1]
	v_cmp_eq_u32_e64 s[0:1], 15, v24
	s_nop 1
	v_cndmask_b32_e64 v23, v23, v3, s[0:1]
	s_waitcnt lgkmcnt(0)
	v_add_f32_e32 v16, v23, v16
	v_cmp_eq_u32_e64 s[0:1], 1, v20
	s_nop 1
	v_cndmask_b32_e64 v23, v0, v16, s[0:1]
	v_cmp_eq_u32_e64 s[0:1], 2, v20
	s_nop 1
	v_cndmask_b32_e64 v23, v23, v22, s[0:1]
	v_cmp_eq_u32_e64 s[0:1], 3, v20
	s_nop 1
	v_cndmask_b32_e64 v23, v23, v21, s[0:1]
	v_cmp_eq_u32_e64 s[0:1], 4, v20
	s_nop 1
	v_cndmask_b32_e64 v23, v23, v12, s[0:1]
	v_cmp_eq_u32_e64 s[0:1], 5, v20
	s_nop 1
	v_cndmask_b32_e64 v23, v23, v14, s[0:1]
	v_cmp_eq_u32_e64 s[0:1], 6, v20
	s_nop 1
	v_cndmask_b32_e64 v23, v23, v10, s[0:1]
	v_cmp_eq_u32_e64 s[0:1], 7, v20
	s_nop 1
	v_cndmask_b32_e64 v23, v23, v26, s[0:1]
	v_cmp_eq_u32_e64 s[0:1], 8, v20
	s_nop 1
	v_cndmask_b32_e64 v23, v23, v8, s[0:1]
	v_cmp_eq_u32_e64 s[0:1], 9, v20
	s_nop 1
	v_cndmask_b32_e64 v23, v23, v9, s[0:1]
	v_cmp_eq_u32_e64 s[0:1], 10, v20
	s_nop 1
	v_cndmask_b32_e64 v23, v23, v6, s[0:1]
	v_cmp_eq_u32_e64 s[0:1], 11, v20
	s_nop 1
	v_cndmask_b32_e64 v23, v23, v7, s[0:1]
	v_cmp_eq_u32_e64 s[0:1], 12, v20
	s_nop 1
	v_cndmask_b32_e64 v23, v23, v4, s[0:1]
	v_cmp_eq_u32_e64 s[0:1], 13, v20
	s_nop 1
	v_cndmask_b32_e64 v23, v23, v5, s[0:1]
	v_cmp_eq_u32_e64 s[0:1], 14, v20
	s_nop 1
	v_cndmask_b32_e64 v23, v23, v2, s[0:1]
	v_cmp_eq_u32_e64 s[0:1], 15, v20
	s_nop 1
	v_cndmask_b32_e64 v20, v23, v3, s[0:1]
	v_or_b32_e32 v23, 2, v13
	v_cmp_eq_u32_e64 s[0:1], 1, v23
	ds_bpermute_b32 v20, v28, v20
	v_or_b32_e32 v13, 3, v13
	v_cndmask_b32_e64 v24, v0, v16, s[0:1]
	v_cmp_eq_u32_e64 s[0:1], 2, v23
	s_nop 1
	v_cndmask_b32_e64 v22, v24, v22, s[0:1]
	v_cmp_eq_u32_e64 s[0:1], 3, v23
	v_cndmask_b32_e32 v24, v18, v25, vcc
	v_cndmask_b32_e32 v18, v25, v18, vcc
	v_cndmask_b32_e64 v22, v22, v21, s[0:1]
	v_cmp_eq_u32_e64 s[0:1], 4, v23
	ds_bpermute_b32 v24, v28, v24
	s_waitcnt lgkmcnt(0)
	v_add_f32_e32 v18, v18, v24
	v_cndmask_b32_e64 v22, v22, v12, s[0:1]
	v_cmp_eq_u32_e64 s[0:1], 5, v23
	s_nop 1
	v_cndmask_b32_e64 v22, v22, v14, s[0:1]
	v_cmp_eq_u32_e64 s[0:1], 6, v23
	s_nop 1
	v_cndmask_b32_e64 v22, v22, v10, s[0:1]
	v_cmp_eq_u32_e64 s[0:1], 7, v23
	s_nop 1
	v_cndmask_b32_e64 v22, v22, v26, s[0:1]
	v_cmp_eq_u32_e64 s[0:1], 8, v23
	s_nop 1
	v_cndmask_b32_e64 v22, v22, v8, s[0:1]
	v_cmp_eq_u32_e64 s[0:1], 9, v23
	s_nop 1
	v_cndmask_b32_e64 v22, v22, v9, s[0:1]
	v_cmp_eq_u32_e64 s[0:1], 10, v23
	s_nop 1
	v_cndmask_b32_e64 v22, v22, v6, s[0:1]
	v_cmp_eq_u32_e64 s[0:1], 11, v23
	s_nop 1
	v_cndmask_b32_e64 v22, v22, v7, s[0:1]
	v_cmp_eq_u32_e64 s[0:1], 12, v23
	s_nop 1
	v_cndmask_b32_e64 v22, v22, v4, s[0:1]
	v_cmp_eq_u32_e64 s[0:1], 13, v23
	s_nop 1
	v_cndmask_b32_e64 v22, v22, v5, s[0:1]
	v_cmp_eq_u32_e64 s[0:1], 14, v23
	s_nop 1
	v_cndmask_b32_e64 v22, v22, v2, s[0:1]
	v_cmp_eq_u32_e64 s[0:1], 15, v23
	s_nop 1
	v_cndmask_b32_e64 v22, v22, v3, s[0:1]
	v_add_f32_e32 v20, v22, v20
	v_bitop3_b32 v22, v144, 7, 4 bitop3:0x6c
	v_cmp_eq_u32_e64 s[0:1], 1, v22
	s_nop 1
	v_cndmask_b32_e64 v23, v0, v16, s[0:1]
	v_cmp_eq_u32_e64 s[0:1], 2, v22
	s_nop 1
	v_cndmask_b32_e64 v23, v23, v20, s[0:1]
	v_cmp_eq_u32_e64 s[0:1], 3, v22
	s_nop 1
	v_cndmask_b32_e64 v23, v23, v21, s[0:1]
	v_cmp_eq_u32_e64 s[0:1], 4, v22
	s_nop 1
	v_cndmask_b32_e64 v23, v23, v12, s[0:1]
	v_cmp_eq_u32_e64 s[0:1], 5, v22
	s_nop 1
	v_cndmask_b32_e64 v23, v23, v14, s[0:1]
	v_cmp_eq_u32_e64 s[0:1], 6, v22
	s_nop 1
	v_cndmask_b32_e64 v23, v23, v10, s[0:1]
	v_cmp_eq_u32_e64 s[0:1], 7, v22
	s_nop 1
	v_cndmask_b32_e64 v23, v23, v26, s[0:1]
	v_cmp_eq_u32_e64 s[0:1], 8, v22
	s_nop 1
	v_cndmask_b32_e64 v23, v23, v8, s[0:1]
	v_cmp_eq_u32_e64 s[0:1], 9, v22
	s_nop 1
	v_cndmask_b32_e64 v23, v23, v9, s[0:1]
	v_cmp_eq_u32_e64 s[0:1], 10, v22
	s_nop 1
	v_cndmask_b32_e64 v23, v23, v6, s[0:1]
	v_cmp_eq_u32_e64 s[0:1], 11, v22
	s_nop 1
	v_cndmask_b32_e64 v23, v23, v7, s[0:1]
	v_cmp_eq_u32_e64 s[0:1], 12, v22
	s_nop 1
	v_cndmask_b32_e64 v23, v23, v4, s[0:1]
	v_cmp_eq_u32_e64 s[0:1], 13, v22
	s_nop 1
	v_cndmask_b32_e64 v23, v23, v5, s[0:1]
	v_cmp_eq_u32_e64 s[0:1], 14, v22
	s_nop 1
	v_cndmask_b32_e64 v23, v23, v2, s[0:1]
	v_cmp_eq_u32_e64 s[0:1], 15, v22
	s_nop 1
	v_cndmask_b32_e64 v22, v23, v3, s[0:1]
	v_cmp_eq_u32_e64 s[0:1], 1, v13
	ds_bpermute_b32 v22, v28, v22
	s_nop 0
	v_cndmask_b32_e64 v23, v0, v16, s[0:1]
	v_cmp_eq_u32_e64 s[0:1], 2, v13
	s_nop 1
	v_cndmask_b32_e64 v23, v23, v20, s[0:1]
	v_cmp_eq_u32_e64 s[0:1], 3, v13
	s_nop 1
	v_cndmask_b32_e64 v21, v23, v21, s[0:1]
	v_cmp_eq_u32_e64 s[0:1], 4, v13
	v_cndmask_b32_e32 v23, v19, v11, vcc
	v_cndmask_b32_e32 v11, v11, v19, vcc
	v_cndmask_b32_e64 v21, v21, v12, s[0:1]
	v_cmp_eq_u32_e64 s[0:1], 5, v13
	v_and_b32_e32 v19, 2, v144
	ds_bpermute_b32 v23, v28, v23
	v_cndmask_b32_e64 v21, v21, v14, s[0:1]
	v_cmp_eq_u32_e64 s[0:1], 6, v13
	s_waitcnt lgkmcnt(0)
	v_add_f32_e32 v11, v11, v23
	v_cndmask_b32_e64 v21, v21, v10, s[0:1]
	v_cmp_eq_u32_e64 s[0:1], 7, v13
	v_xor_b32_e32 v23, 2, v199
	s_nop 0
	v_cndmask_b32_e64 v21, v21, v26, s[0:1]
	v_cmp_eq_u32_e64 s[0:1], 8, v13
	s_nop 1
	v_cndmask_b32_e64 v21, v21, v8, s[0:1]
	v_cmp_eq_u32_e64 s[0:1], 9, v13
	s_nop 1
	v_cndmask_b32_e64 v21, v21, v9, s[0:1]
	v_cmp_eq_u32_e64 s[0:1], 10, v13
	s_nop 1
	v_cndmask_b32_e64 v21, v21, v6, s[0:1]
	v_cmp_eq_u32_e64 s[0:1], 11, v13
	s_nop 1
	v_cndmask_b32_e64 v21, v21, v7, s[0:1]
	v_cmp_eq_u32_e64 s[0:1], 12, v13
	s_nop 1
	v_cndmask_b32_e64 v21, v21, v4, s[0:1]
	v_cmp_eq_u32_e64 s[0:1], 13, v13
	s_nop 1
	v_cndmask_b32_e64 v21, v21, v5, s[0:1]
	v_cmp_eq_u32_e64 s[0:1], 14, v13
	s_nop 1
	v_cndmask_b32_e64 v21, v21, v2, s[0:1]
	v_cmp_eq_u32_e64 s[0:1], 15, v13
	s_nop 1
	v_cndmask_b32_e64 v13, v21, v3, s[0:1]
	v_bitop3_b32 v21, v144, 2, v144 bitop3:0xc
	v_cmp_eq_u32_e32 vcc, 1, v21
	v_add_f32_e32 v13, v13, v22
	v_cmp_lt_i32_e64 s[0:1], v23, v1
	v_cndmask_b32_e32 v22, v0, v16, vcc
	v_cmp_eq_u32_e32 vcc, 2, v21
	v_cndmask_b32_e64 v23, v199, v23, s[0:1]
	v_lshlrev_b32_e32 v23, 2, v23
	v_cndmask_b32_e32 v22, v22, v20, vcc
	v_cmp_eq_u32_e32 vcc, 3, v21
	v_cmp_eq_u32_e64 s[0:1], 15, v19
	s_nop 0
	v_cndmask_b32_e32 v22, v22, v13, vcc
	v_cmp_eq_u32_e32 vcc, 4, v21
	s_nop 1
	v_cndmask_b32_e32 v22, v22, v12, vcc
	v_cmp_eq_u32_e32 vcc, 5, v21
	s_nop 1
	v_cndmask_b32_e32 v22, v22, v14, vcc
	v_cmp_eq_u32_e32 vcc, 6, v21
	s_nop 1
	v_cndmask_b32_e32 v22, v22, v10, vcc
	v_cmp_eq_u32_e32 vcc, 7, v21
	s_nop 1
	v_cndmask_b32_e32 v22, v22, v26, vcc
	v_cmp_eq_u32_e32 vcc, 8, v21
	s_nop 1
	v_cndmask_b32_e32 v22, v22, v8, vcc
	v_cmp_eq_u32_e32 vcc, 9, v21
	s_nop 1
	v_cndmask_b32_e32 v22, v22, v9, vcc
	v_cmp_eq_u32_e32 vcc, 10, v21
	s_nop 1
	v_cndmask_b32_e32 v22, v22, v6, vcc
	v_cmp_eq_u32_e32 vcc, 11, v21
	s_nop 1
	v_cndmask_b32_e32 v22, v22, v7, vcc
	v_cmp_eq_u32_e32 vcc, 12, v21
	s_nop 1
	v_cndmask_b32_e32 v22, v22, v4, vcc
	v_cmp_eq_u32_e32 vcc, 13, v21
	s_nop 1
	v_cndmask_b32_e32 v22, v22, v5, vcc
	v_cmp_eq_u32_e32 vcc, 14, v21
	s_nop 1
	v_cndmask_b32_e32 v22, v22, v2, vcc
	v_cmp_eq_u32_e32 vcc, 15, v21
	s_nop 1
	v_cndmask_b32_e32 v21, v22, v3, vcc
	v_cmp_eq_u32_e32 vcc, 1, v19
	ds_bpermute_b32 v21, v23, v21
	s_nop 0
	v_cndmask_b32_e32 v0, v0, v16, vcc
	v_cmp_ne_u32_e32 vcc, 0, v19
	s_nop 1
	v_cndmask_b32_e32 v0, v0, v20, vcc
	v_cmp_eq_u32_e32 vcc, 3, v19
	s_nop 1
	v_cndmask_b32_e32 v0, v0, v13, vcc
	v_cmp_eq_u32_e32 vcc, 4, v19
	s_nop 1
	v_cndmask_b32_e32 v0, v0, v12, vcc
	v_cmp_eq_u32_e32 vcc, 5, v19
	s_nop 1
	v_cndmask_b32_e32 v0, v0, v14, vcc
	v_cmp_eq_u32_e32 vcc, 6, v19
	s_nop 1
	v_cndmask_b32_e32 v0, v0, v10, vcc
	v_cmp_eq_u32_e32 vcc, 7, v19
	s_nop 1
	v_cndmask_b32_e32 v0, v0, v26, vcc
	v_cmp_eq_u32_e32 vcc, 8, v19
	s_nop 1
	v_cndmask_b32_e32 v0, v0, v8, vcc
	v_cmp_eq_u32_e32 vcc, 9, v19
	s_nop 1
	v_cndmask_b32_e32 v0, v0, v9, vcc
	v_cmp_eq_u32_e32 vcc, 10, v19
	s_nop 1
	v_cndmask_b32_e32 v0, v0, v6, vcc
	v_cmp_eq_u32_e32 vcc, 11, v19
	s_nop 1
	v_cndmask_b32_e32 v0, v0, v7, vcc
	v_cmp_eq_u32_e32 vcc, 12, v19
	s_nop 1
	v_cndmask_b32_e32 v0, v0, v4, vcc
	v_cmp_eq_u32_e32 vcc, 13, v19
	s_nop 1
	v_cndmask_b32_e32 v0, v0, v5, vcc
	v_cmp_eq_u32_e32 vcc, 14, v19
	s_nop 1
	v_cndmask_b32_e32 v0, v0, v2, vcc
	v_cmp_eq_u32_e32 vcc, 0, v19
	v_cndmask_b32_e64 v0, v0, v3, s[0:1]
	v_or_b32_e32 v19, 1, v19
	v_cndmask_b32_e32 v22, v15, v18, vcc
	v_cndmask_b32_e32 v15, v18, v15, vcc
	s_waitcnt lgkmcnt(0)
	v_add_f32_e32 v18, v0, v21
	v_bitop3_b32 v0, v144, 3, 2 bitop3:0x6c
	v_cmp_eq_u32_e64 s[0:1], 1, v0
	ds_bpermute_b32 v22, v23, v22
	s_waitcnt lgkmcnt(0)
	v_add_f32_e32 v15, v15, v22
	v_cndmask_b32_e64 v21, v18, v16, s[0:1]
	v_cmp_eq_u32_e64 s[0:1], 2, v0
	s_nop 1
	v_cndmask_b32_e64 v21, v21, v20, s[0:1]
	v_cmp_eq_u32_e64 s[0:1], 3, v0
	s_nop 1
	v_cndmask_b32_e64 v21, v21, v13, s[0:1]
	v_cmp_eq_u32_e64 s[0:1], 4, v0
	s_nop 1
	v_cndmask_b32_e64 v21, v21, v12, s[0:1]
	v_cmp_eq_u32_e64 s[0:1], 5, v0
	s_nop 1
	v_cndmask_b32_e64 v21, v21, v14, s[0:1]
	v_cmp_eq_u32_e64 s[0:1], 6, v0
	s_nop 1
	v_cndmask_b32_e64 v21, v21, v10, s[0:1]
	v_cmp_eq_u32_e64 s[0:1], 7, v0
	s_nop 1
	v_cndmask_b32_e64 v21, v21, v26, s[0:1]
	v_cmp_eq_u32_e64 s[0:1], 8, v0
	s_nop 1
	v_cndmask_b32_e64 v21, v21, v8, s[0:1]
	v_cmp_eq_u32_e64 s[0:1], 9, v0
	s_nop 1
	v_cndmask_b32_e64 v21, v21, v9, s[0:1]
	v_cmp_eq_u32_e64 s[0:1], 10, v0
	s_nop 1
	v_cndmask_b32_e64 v21, v21, v6, s[0:1]
	v_cmp_eq_u32_e64 s[0:1], 11, v0
	s_nop 1
	v_cndmask_b32_e64 v21, v21, v7, s[0:1]
	v_cmp_eq_u32_e64 s[0:1], 12, v0
	s_nop 1
	v_cndmask_b32_e64 v21, v21, v4, s[0:1]
	v_cmp_eq_u32_e64 s[0:1], 13, v0
	s_nop 1
	v_cndmask_b32_e64 v21, v21, v5, s[0:1]
	v_cmp_eq_u32_e64 s[0:1], 14, v0
	s_nop 1
	v_cndmask_b32_e64 v21, v21, v2, s[0:1]
	v_cmp_eq_u32_e64 s[0:1], 15, v0
	s_nop 1
	v_cndmask_b32_e64 v0, v21, v3, s[0:1]
	v_cmp_eq_u32_e64 s[0:1], 1, v19
	ds_bpermute_b32 v0, v23, v0
	v_cndmask_b32_e32 v21, v17, v11, vcc
	v_cndmask_b32_e64 v16, v18, v16, s[0:1]
	v_cmp_eq_u32_e64 s[0:1], 2, v19
	v_cndmask_b32_e32 v11, v11, v17, vcc
	v_and_b32_e32 v17, 1, v144
	v_cndmask_b32_e64 v16, v16, v20, s[0:1]
	v_cmp_eq_u32_e64 s[0:1], 3, v19
	v_cmp_eq_u32_e32 vcc, 1, v17
	ds_bpermute_b32 v21, v23, v21
	v_cndmask_b32_e64 v16, v16, v13, s[0:1]
	v_cmp_eq_u32_e64 s[0:1], 4, v19
	s_waitcnt lgkmcnt(0)
	v_add_f32_e32 v11, v11, v21
	v_cndmask_b32_e64 v16, v16, v12, s[0:1]
	v_cmp_eq_u32_e64 s[0:1], 5, v19
	v_xor_b32_e32 v21, 1, v199
	v_cmp_lt_i32_e64 s[4:5], v21, v1
	v_cndmask_b32_e64 v16, v16, v14, s[0:1]
	v_cmp_eq_u32_e64 s[0:1], 6, v19
	v_cndmask_b32_e64 v1, v199, v21, s[4:5]
	v_lshlrev_b32_e32 v1, 2, v1
	v_cndmask_b32_e64 v16, v16, v10, s[0:1]
	v_cmp_eq_u32_e64 s[0:1], 7, v19
	s_mov_b64 s[4:5], s[22:23]
	s_nop 0
	v_cndmask_b32_e64 v16, v16, v26, s[0:1]
	v_cmp_eq_u32_e64 s[0:1], 8, v19
	s_nop 1
	v_cndmask_b32_e64 v16, v16, v8, s[0:1]
	v_cmp_eq_u32_e64 s[0:1], 9, v19
	s_nop 1
	v_cndmask_b32_e64 v16, v16, v9, s[0:1]
	v_cmp_eq_u32_e64 s[0:1], 10, v19
	s_nop 1
	v_cndmask_b32_e64 v16, v16, v6, s[0:1]
	v_cmp_eq_u32_e64 s[0:1], 11, v19
	s_nop 1
	v_cndmask_b32_e64 v16, v16, v7, s[0:1]
	v_cmp_eq_u32_e64 s[0:1], 12, v19
	s_nop 1
	v_cndmask_b32_e64 v16, v16, v4, s[0:1]
	v_cmp_eq_u32_e64 s[0:1], 13, v19
	s_nop 1
	v_cndmask_b32_e64 v16, v16, v5, s[0:1]
	v_cmp_eq_u32_e64 s[0:1], 14, v19
	s_nop 1
	v_cndmask_b32_e64 v16, v16, v2, s[0:1]
	v_cmp_eq_u32_e64 s[0:1], 15, v19
	s_nop 1
	v_cndmask_b32_e64 v16, v16, v3, s[0:1]
	v_add_f32_e32 v16, v16, v0
	v_bitop3_b32 v0, v144, 1, v144 bitop3:0xc
	v_cndmask_b32_e32 v19, v16, v18, vcc
	v_cmp_eq_u32_e64 s[0:1], 2, v0
	s_nop 1
	v_cndmask_b32_e64 v19, v19, v20, s[0:1]
	v_cmp_eq_u32_e64 s[0:1], 3, v0
	s_nop 1
	v_cndmask_b32_e64 v19, v19, v13, s[0:1]
	v_cmp_eq_u32_e64 s[0:1], 4, v0
	s_nop 1
	v_cndmask_b32_e64 v19, v19, v12, s[0:1]
	v_cmp_eq_u32_e64 s[0:1], 5, v0
	s_nop 1
	v_cndmask_b32_e64 v19, v19, v14, s[0:1]
	v_cmp_eq_u32_e64 s[0:1], 6, v0
	s_nop 1
	v_cndmask_b32_e64 v19, v19, v10, s[0:1]
	v_cmp_eq_u32_e64 s[0:1], 7, v0
	s_nop 1
	v_cndmask_b32_e64 v19, v19, v26, s[0:1]
	v_cmp_eq_u32_e64 s[0:1], 8, v0
	s_nop 1
	v_cndmask_b32_e64 v19, v19, v8, s[0:1]
	v_cmp_eq_u32_e64 s[0:1], 9, v0
	s_nop 1
	v_cndmask_b32_e64 v19, v19, v9, s[0:1]
	v_cmp_eq_u32_e64 s[0:1], 10, v0
	s_nop 1
	v_cndmask_b32_e64 v19, v19, v6, s[0:1]
	v_cmp_eq_u32_e64 s[0:1], 11, v0
	s_nop 1
	v_cndmask_b32_e64 v19, v19, v7, s[0:1]
	v_cmp_eq_u32_e64 s[0:1], 12, v0
	s_nop 1
	v_cndmask_b32_e64 v19, v19, v4, s[0:1]
	v_cmp_eq_u32_e64 s[0:1], 13, v0
	s_nop 1
	v_cndmask_b32_e64 v19, v19, v5, s[0:1]
	v_cmp_eq_u32_e64 s[0:1], 14, v0
	s_nop 1
	v_cndmask_b32_e64 v19, v19, v2, s[0:1]
	v_cmp_eq_u32_e64 s[0:1], 15, v0
	s_nop 1
	v_cndmask_b32_e64 v0, v19, v3, s[0:1]
	v_cmp_eq_u32_e64 s[0:1], 0, v17
	ds_bpermute_b32 v0, v1, v0
	s_nop 0
	v_cndmask_b32_e64 v19, v15, v11, s[0:1]
	v_cndmask_b32_e64 v11, v11, v15, s[0:1]
	v_cndmask_b32_e32 v15, v18, v16, vcc
	v_cmp_eq_u32_e32 vcc, 2, v17
	ds_bpermute_b32 v1, v1, v19
	s_lshl_b32 s0, s2, 1
	v_cndmask_b32_e32 v15, v15, v20, vcc
	v_cmp_eq_u32_e32 vcc, 3, v17
	s_ashr_i32 s1, s0, 31
	s_add_u32 s0, s0, s34
	v_cndmask_b32_e32 v13, v15, v13, vcc
	v_cmp_eq_u32_e32 vcc, 4, v17
	s_addc_u32 s1, s1, s43
	s_mov_b32 s2, s16
	v_cndmask_b32_e32 v12, v13, v12, vcc
	v_cmp_eq_u32_e32 vcc, 5, v17
	s_nop 1
	v_cndmask_b32_e32 v12, v12, v14, vcc
	v_cmp_eq_u32_e32 vcc, 6, v17
	s_nop 1
	v_cndmask_b32_e32 v10, v12, v10, vcc
	v_cmp_eq_u32_e32 vcc, 7, v17
	s_nop 1
	v_cndmask_b32_e32 v10, v10, v26, vcc
	v_cmp_eq_u32_e32 vcc, 8, v17
	s_nop 1
	v_cndmask_b32_e32 v8, v10, v8, vcc
	v_cmp_eq_u32_e32 vcc, 9, v17
	s_nop 1
	v_cndmask_b32_e32 v8, v8, v9, vcc
	v_cmp_eq_u32_e32 vcc, 10, v17
	s_nop 1
	v_cndmask_b32_e32 v6, v8, v6, vcc
	v_cmp_eq_u32_e32 vcc, 11, v17
	s_nop 1
	v_cndmask_b32_e32 v6, v6, v7, vcc
	v_cmp_eq_u32_e32 vcc, 12, v17
	s_nop 1
	v_cndmask_b32_e32 v4, v6, v4, vcc
	v_cmp_eq_u32_e32 vcc, 13, v17
	s_nop 1
	v_cndmask_b32_e32 v4, v4, v5, vcc
	v_cmp_eq_u32_e32 vcc, 14, v17
	s_nop 1
	v_cndmask_b32_e32 v2, v4, v2, vcc
	v_cmp_eq_u32_e32 vcc, 15, v17
	s_nop 1
	v_cndmask_b32_e32 v10, v2, v3, vcc
	v_lshlrev_b32_e32 v2, 4, v144
	v_and_b32_e32 v2, 0xffffff80, v2
	v_add_u32_e32 v2, v138, v2
	v_and_or_b32 v2, v144, 7, v2
	v_ashrrev_i32_e32 v3, 31, v2
	v_lshlrev_b64 v[2:3], 8, v[2:3]
	v_lshl_add_u64 v[2:3], s[12:13], 0, v[2:3]
	s_waitcnt lgkmcnt(0)
	v_pk_add_f32 v[0:1], v[10:11], v[0:1]
	v_lshl_add_u64 v[2:3], s[0:1], 3, v[2:3]
	s_and_b64 vcc, exec, s[14:15]
	s_mov_b64 s[0:1], s[20:21]
	global_store_dwordx2 v[2:3], v[0:1], off
	s_cbranch_vccz .LBB0_327
	s_waitcnt vmcnt(0)
	s_cmpk_gt_u32 s30, 0xff
	s_cbranch_scc1 .LBB0_338
	s_barrier
